# PEER top-k: sortable keys built in the f16 domain two scores per instruction (integer ops on the stored f16 patterns, same order and tie-breaks), candidate keys one instruction shorter; -528 VALU inst
# baseline (speedup 1.0000x reference)
; __device__ __forceinline__ unsigned f2key(float f) { const unsigned u = __float_as_uint(f); return (u & 0x80000000u) ? ~u : (u | 0x80000000u); }
; #define CE_DESC(a, b) do { const unsigned _mx = (a) > (b) ? (a) : (b), _mn = (a) > (b) ? (b) : (a); (a) = _mx; (b) = _mn; } while (0)
; __device__ __forceinline__ void sort16_desc(unsigned (&k)[16]) {
; #pragma unroll
;     for (int size = 2; size <= 16; size <<= 1)
; #pragma unroll
;         for (int stride = size >> 1; stride > 0; stride >>= 1)
; #pragma unroll
;             for (int i = 0; i < 16; ++i) { const int j = i ^ stride;
;                 if (j > i) { if ((i & size) == 0) CE_DESC(k[i], k[j]); else CE_DESC(k[j], k[i]); } }
; }
; __device__ __forceinline__ void merge16(unsigned (&a)[16], const unsigned (&b)[16]) {
; #pragma unroll
;     for (int i = 0; i < 16; ++i) a[i] = a[i] > b[15 - i] ? a[i] : b[15 - i];
; #pragma unroll
;     for (int stride = 8; stride > 0; stride >>= 1)
; #pragma unroll
;         for (int i = 0; i < 16; ++i) { const int j = i ^ stride; if (j > i) CE_DESC(a[i], a[j]); }
; __device__ __forceinline__ void peer_tile(const Args& A, LAS unsigned char* lds, int tile) {
;     ...
;                 const int hp = 2 * h + p;
;                 unsigned k0[16], k1[16];
;                 { const bf16_t* sp = QRY + m * 2048 + hp * 128 + 32 * g;
;                   const u32x4 s0 = *(const u32x4*)sp, s1 = *(const u32x4*)(sp + 8), s2 = *(const u32x4*)(sp + 16), s3 = *(const u32x4*)(sp + 24);
;                   const unsigned sw[16] = {s0.x, s0.y, s0.z, s0.w, s1.x, s1.y, s1.z, s1.w, s2.x, s2.y, s2.z, s2.w, s3.x, s3.y, s3.z, s3.w};
; #pragma unroll
;                   for (int i = 0; i < 16; ++i) {
;                       const float lo = (float)__builtin_bit_cast(_Float16, (unsigned short)(sw[i] & 0xffffu)), hi = (float)__builtin_bit_cast(_Float16, (unsigned short)(sw[i] >> 16));
;                       const unsigned klo = (f2key(lo) & ~127u) | (unsigned)(127 - (32 * g + 2 * i)), khi = (f2key(hi) & ~127u) | (unsigned)(127 - (32 * g + 2 * i + 1));
;                       if (i < 8) { k0[2 * i] = klo; k0[2 * i + 1] = khi; } else { k1[2 * (i - 8)] = klo; k1[2 * (i - 8) + 1] = khi; } } }
;                 sort16_desc(k0); sort16_desc(k1); merge16(k0, k1);
.LBB0_699:
	s_mov_b64 exec, -1
	s_mov_b32 s33, 0x80000000
	s_mov_b32 s40, 0x7fffff80
	s_mov_b32 s41, 0x7fffffff
	s_mov_b32 s42, 0x000f000f
	s_mov_b32 s43, 0x7fff7fff
	s_mov_b32 s44, 0xffff0000
	v_and_b32_e32 v68, 63, v214
	v_lshrrev_b32_e32 v66, 6, v214
	s_nop 0
	v_readfirstlane_b32 s36, v66
	s_lshl_b32 s0, s2, 18
	s_lshl_b32 s1, s36, 9
	s_add_u32 s34, s54, s0
	s_addc_u32 s35, s55, 0
	s_add_u32 s34, s34, s1
	s_addc_u32 s35, s35, 0
	v_lshrrev_b32_e32 v66, 3, v68
	v_and_b32_e32 v64, 7, v68
	v_lshlrev_b32_e32 v64, 4, v64
	v_mul_u32_u24_e32 v65, 0x90, v66
	v_lshl_add_u32 v66, v66, 12, v64
	s_mul_i32 s0, s36, 0x2400
	s_cmp_eq_u32 s36, 7
	s_cselect_b32 s0, 0x21000, s0
	v_add3_u32 v64, v64, v65, s0
	v_mul_u32_u24_e32 v65, 0x90, v68
	v_add_u32_e32 v65, s0, v65
	v_mul_u32_u24_e32 v67, 0x84, v68
	v_lshlrev_b32_e32 v68, 10, v68
	s_lshl_b32 s1, s36, 7
	s_add_i32 s1, s1, 0x11000
	v_add_u32_e32 v67, s0, v67
	v_add_u32_e32 v68, s1, v68
	s_mov_b64 s[38:39], s[34:35]
	global_load_dwordx4 v[0:3], v66, s[38:39] offset:0
	s_add_u32 s38, s38, 0x8000
	s_addc_u32 s39, s39, 0
	global_load_dwordx4 v[4:7], v66, s[38:39] offset:0
	s_add_u32 s38, s38, 0x8000
	s_addc_u32 s39, s39, 0
	global_load_dwordx4 v[8:11], v66, s[38:39] offset:0
	s_add_u32 s38, s38, 0x8000
	s_addc_u32 s39, s39, 0
	global_load_dwordx4 v[12:15], v66, s[38:39] offset:0
	s_add_u32 s38, s38, 0x8000
	s_addc_u32 s39, s39, 0
	global_load_dwordx4 v[16:19], v66, s[38:39] offset:0
	s_add_u32 s38, s38, 0x8000
	s_addc_u32 s39, s39, 0
	global_load_dwordx4 v[20:23], v66, s[38:39] offset:0
	s_add_u32 s38, s38, 0x8000
	s_addc_u32 s39, s39, 0
	global_load_dwordx4 v[24:27], v66, s[38:39] offset:0
	s_add_u32 s38, s38, 0x8000
	s_addc_u32 s39, s39, 0
	global_load_dwordx4 v[28:31], v66, s[38:39] offset:0
	s_mov_b64 s[38:39], s[34:35]
	global_load_dwordx4 v[32:35], v66, s[38:39] offset:128
	s_add_u32 s38, s38, 0x8000
	s_addc_u32 s39, s39, 0
	global_load_dwordx4 v[36:39], v66, s[38:39] offset:128
	s_add_u32 s38, s38, 0x8000
	s_addc_u32 s39, s39, 0
	global_load_dwordx4 v[40:43], v66, s[38:39] offset:128
	s_add_u32 s38, s38, 0x8000
	s_addc_u32 s39, s39, 0
	global_load_dwordx4 v[44:47], v66, s[38:39] offset:128
	s_add_u32 s38, s38, 0x8000
	s_addc_u32 s39, s39, 0
	global_load_dwordx4 v[48:51], v66, s[38:39] offset:128
	s_add_u32 s38, s38, 0x8000
	s_addc_u32 s39, s39, 0
	global_load_dwordx4 v[52:55], v66, s[38:39] offset:128
	s_add_u32 s38, s38, 0x8000
	s_addc_u32 s39, s39, 0
	global_load_dwordx4 v[56:59], v66, s[38:39] offset:128
	s_add_u32 s38, s38, 0x8000
	s_addc_u32 s39, s39, 0
	global_load_dwordx4 v[60:63], v66, s[38:39] offset:128
	s_waitcnt vmcnt(8)
	ds_write_b128 v64, v[0:3] offset:0
	ds_write_b128 v64, v[4:7] offset:1152
	ds_write_b128 v64, v[8:11] offset:2304
	ds_write_b128 v64, v[12:15] offset:3456
	ds_write_b128 v64, v[16:19] offset:4608
	ds_write_b128 v64, v[20:23] offset:5760
	ds_write_b128 v64, v[24:27] offset:6912
	ds_write_b128 v64, v[28:31] offset:8064
	s_waitcnt lgkmcnt(0)
	ds_read_b128 v[0:3], v65 offset:0
	ds_read_b128 v[4:7], v65 offset:16
	ds_read_b128 v[8:11], v65 offset:32
	ds_read_b128 v[12:15], v65 offset:48
	ds_read_b128 v[16:19], v65 offset:64
	ds_read_b128 v[20:23], v65 offset:80
	ds_read_b128 v[24:27], v65 offset:96
	ds_read_b128 v[28:31], v65 offset:112
	s_waitcnt lgkmcnt(0)
	v_pk_ashrrev_i16 v70, s42, v0
	v_bitop3_b32 v70, v0, v70, s43 bitop3:0x2d
	v_lshl_or_b32 v71, v70, 16, 63
	v_and_or_b32 v72, v70, s44, 62
	v_pk_ashrrev_i16 v70, s42, v1
	v_bitop3_b32 v70, v1, v70, s43 bitop3:0x2d
	v_lshl_or_b32 v73, v70, 16, 61
	v_and_or_b32 v74, v70, s44, 60
	v_pk_ashrrev_i16 v70, s42, v2
	v_bitop3_b32 v70, v2, v70, s43 bitop3:0x2d
	v_lshl_or_b32 v75, v70, 16, 59
	v_and_or_b32 v76, v70, s44, 58
	v_pk_ashrrev_i16 v70, s42, v3
	v_bitop3_b32 v70, v3, v70, s43 bitop3:0x2d
	v_lshl_or_b32 v77, v70, 16, 57
	v_and_or_b32 v78, v70, s44, 56
	v_pk_ashrrev_i16 v70, s42, v4
	v_bitop3_b32 v70, v4, v70, s43 bitop3:0x2d
	v_lshl_or_b32 v79, v70, 16, 55
	v_and_or_b32 v80, v70, s44, 54
	v_pk_ashrrev_i16 v70, s42, v5
	v_bitop3_b32 v70, v5, v70, s43 bitop3:0x2d
	v_lshl_or_b32 v81, v70, 16, 53
	v_and_or_b32 v82, v70, s44, 52
	v_pk_ashrrev_i16 v70, s42, v6
	v_bitop3_b32 v70, v6, v70, s43 bitop3:0x2d
	v_lshl_or_b32 v83, v70, 16, 51
	v_and_or_b32 v84, v70, s44, 50
	v_pk_ashrrev_i16 v70, s42, v7
	v_bitop3_b32 v70, v7, v70, s43 bitop3:0x2d
	v_lshl_or_b32 v85, v70, 16, 49
	v_and_or_b32 v86, v70, s44, 48
	v_max_u32_e32 v70, v71, v84
	v_min_u32_e32 v84, v71, v84
	v_max_u32_e32 v71, v72, v83
	v_min_u32_e32 v83, v72, v83
	v_max_u32_e32 v72, v73, v86
	v_min_u32_e32 v86, v73, v86
	v_max_u32_e32 v73, v74, v85
	v_min_u32_e32 v85, v74, v85
	v_max_u32_e32 v74, v75, v79
	v_min_u32_e32 v79, v75, v79
	v_max_u32_e32 v75, v76, v77
	v_min_u32_e32 v77, v76, v77
	v_max_u32_e32 v76, v78, v82
	v_min_u32_e32 v82, v78, v82
	v_max_u32_e32 v78, v80, v81
	v_min_u32_e32 v81, v80, v81
	v_max_u32_e32 v80, v70, v75
	v_min_u32_e32 v75, v70, v75
	v_max_u32_e32 v70, v71, v76
	v_min_u32_e32 v76, v71, v76
	v_max_u32_e32 v71, v72, v78
	v_min_u32_e32 v78, v72, v78
	v_max_u32_e32 v72, v73, v74
	v_min_u32_e32 v74, v73, v74
	v_max_u32_e32 v73, v77, v84
	v_min_u32_e32 v84, v77, v84
	v_max_u32_e32 v77, v79, v85
	v_min_u32_e32 v85, v79, v85
	v_max_u32_e32 v79, v81, v86
	v_min_u32_e32 v86, v81, v86
	v_max_u32_e32 v81, v82, v83
	v_min_u32_e32 v83, v82, v83
	v_max_u32_e32 v82, v80, v70
	v_min_u32_e32 v70, v80, v70
	v_max_u32_e32 v80, v71, v72
	v_min_u32_e32 v72, v71, v72
	v_max_u32_e32 v71, v74, v75
	v_min_u32_e32 v75, v74, v75
	v_max_u32_e32 v74, v73, v77
	v_min_u32_e32 v77, v73, v77
	v_max_u32_e32 v73, v76, v78
	v_min_u32_e32 v78, v76, v78
	v_max_u32_e32 v76, v79, v81
; __device__ __forceinline__ unsigned f2key(float f) { const unsigned u = __float_as_uint(f); return (u & 0x80000000u) ? ~u : (u | 0x80000000u); }
; #define CE_DESC(a, b) do { const unsigned _mx = (a) > (b) ? (a) : (b), _mn = (a) > (b) ? (b) : (a); (a) = _mx; (b) = _mn; } while (0)
; __device__ __forceinline__ void sort16_desc(unsigned (&k)[16]) {
; #pragma unroll
;     for (int size = 2; size <= 16; size <<= 1)
; #pragma unroll
;         for (int stride = size >> 1; stride > 0; stride >>= 1)
; #pragma unroll
;             for (int i = 0; i < 16; ++i) { const int j = i ^ stride;
;                 if (j > i) { if ((i & size) == 0) CE_DESC(k[i], k[j]); else CE_DESC(k[j], k[i]); } }
; }
; __device__ __forceinline__ void merge16(unsigned (&a)[16], const unsigned (&b)[16]) {
; #pragma unroll
;     for (int i = 0; i < 16; ++i) a[i] = a[i] > b[15 - i] ? a[i] : b[15 - i];
; #pragma unroll
;     for (int stride = 8; stride > 0; stride >>= 1)
; #pragma unroll
;         for (int i = 0; i < 16; ++i) { const int j = i ^ stride; if (j > i) CE_DESC(a[i], a[j]); }
; __device__ __forceinline__ void peer_tile(const Args& A, LAS unsigned char* lds, int tile) {
;     ...
;                 const int hp = 2 * h + p;
;                 unsigned k0[16], k1[16];
;                 { const bf16_t* sp = QRY + m * 2048 + hp * 128 + 32 * g;
;                   const u32x4 s0 = *(const u32x4*)sp, s1 = *(const u32x4*)(sp + 8), s2 = *(const u32x4*)(sp + 16), s3 = *(const u32x4*)(sp + 24);
;                   const unsigned sw[16] = {s0.x, s0.y, s0.z, s0.w, s1.x, s1.y, s1.z, s1.w, s2.x, s2.y, s2.z, s2.w, s3.x, s3.y, s3.z, s3.w};
; #pragma unroll
;                   for (int i = 0; i < 16; ++i) {
;                       const float lo = (float)__builtin_bit_cast(_Float16, (unsigned short)(sw[i] & 0xffffu)), hi = (float)__builtin_bit_cast(_Float16, (unsigned short)(sw[i] >> 16));
;                       const unsigned klo = (f2key(lo) & ~127u) | (unsigned)(127 - (32 * g + 2 * i)), khi = (f2key(hi) & ~127u) | (unsigned)(127 - (32 * g + 2 * i + 1));
;                       if (i < 8) { k0[2 * i] = klo; k0[2 * i + 1] = khi; } else { k1[2 * (i - 8)] = klo; k1[2 * (i - 8) + 1] = khi; } } }
;                 sort16_desc(k0); sort16_desc(k1); merge16(k0, k1);
	v_min_u32_e32 v81, v79, v81
	v_max_u32_e32 v79, v83, v84
	v_min_u32_e32 v84, v83, v84
	v_max_u32_e32 v83, v85, v86
	v_min_u32_e32 v86, v85, v86
	v_max_u32_e32 v85, v82, v80
	v_min_u32_e32 v80, v82, v80
	v_max_u32_e32 v82, v70, v72
	v_min_u32_e32 v72, v70, v72
	v_max_u32_e32 v70, v71, v76
	v_min_u32_e32 v76, v71, v76
	v_max_u32_e32 v71, v75, v81
	v_min_u32_e32 v81, v75, v81
	v_max_u32_e32 v75, v74, v73
	v_min_u32_e32 v73, v74, v73
	v_max_u32_e32 v74, v77, v78
	v_min_u32_e32 v78, v77, v78
	v_max_u32_e32 v77, v79, v83
	v_min_u32_e32 v83, v79, v83
	v_max_u32_e32 v79, v84, v86
	v_min_u32_e32 v86, v84, v86
	v_max_u32_e32 v84, v82, v80
	v_min_u32_e32 v80, v82, v80
	v_max_u32_e32 v82, v72, v77
	v_min_u32_e32 v77, v72, v77
	v_max_u32_e32 v72, v70, v75
	v_min_u32_e32 v75, v70, v75
	v_max_u32_e32 v70, v71, v73
	v_min_u32_e32 v73, v71, v73
	v_max_u32_e32 v71, v74, v76
	v_min_u32_e32 v76, v74, v76
	v_max_u32_e32 v74, v78, v81
	v_min_u32_e32 v81, v78, v81
	v_max_u32_e32 v78, v79, v83
	v_min_u32_e32 v83, v79, v83
	v_max_u32_e32 v79, v84, v72
	v_min_u32_e32 v72, v84, v72
	v_max_u32_e32 v84, v80, v75
	v_min_u32_e32 v75, v80, v75
	v_max_u32_e32 v80, v70, v71
	v_min_u32_e32 v71, v70, v71
	v_max_u32_e32 v70, v73, v76
	v_min_u32_e32 v76, v73, v76
	v_max_u32_e32 v73, v74, v78
	v_min_u32_e32 v78, v74, v78
	v_max_u32_e32 v74, v81, v83
	v_min_u32_e32 v83, v81, v83
	v_max_u32_e32 v81, v84, v72
	v_min_u32_e32 v72, v84, v72
	v_max_u32_e32 v84, v82, v75
	v_min_u32_e32 v75, v82, v75
	v_max_u32_e32 v82, v73, v77
	v_min_u32_e32 v77, v73, v77
	v_max_u32_e32 v73, v74, v78
	v_min_u32_e32 v78, v74, v78
	v_max_u32_e32 v74, v84, v80
	v_min_u32_e32 v80, v84, v80
	v_max_u32_e32 v84, v75, v71
	v_min_u32_e32 v71, v75, v71
	v_max_u32_e32 v75, v70, v82
	v_min_u32_e32 v82, v70, v82
	v_max_u32_e32 v70, v76, v77
	v_min_u32_e32 v77, v76, v77
	v_max_u32_e32 v76, v74, v72
	v_min_u32_e32 v72, v74, v72
	v_max_u32_e32 v74, v80, v84
	v_min_u32_e32 v84, v80, v84
	v_max_u32_e32 v80, v75, v71
	v_min_u32_e32 v71, v75, v71
	v_max_u32_e32 v75, v82, v70
	v_min_u32_e32 v70, v82, v70
	v_max_u32_e32 v82, v73, v77
	v_min_u32_e32 v77, v73, v77
	v_max_u32_e32 v73, v84, v80
	v_min_u32_e32 v80, v84, v80
	v_max_u32_e32 v84, v71, v75
	v_min_u32_e32 v75, v71, v75
	v_pk_ashrrev_i16 v71, s42, v8
	v_bitop3_b32 v71, v8, v71, s43 bitop3:0x2d
	v_lshl_or_b32 v87, v71, 16, 47
	v_and_or_b32 v88, v71, s44, 46
	v_pk_ashrrev_i16 v71, s42, v9
	v_bitop3_b32 v71, v9, v71, s43 bitop3:0x2d
	v_lshl_or_b32 v89, v71, 16, 45
	v_and_or_b32 v90, v71, s44, 44
	v_pk_ashrrev_i16 v71, s42, v10
	v_bitop3_b32 v71, v10, v71, s43 bitop3:0x2d
	v_lshl_or_b32 v91, v71, 16, 43
	v_and_or_b32 v92, v71, s44, 42
	v_pk_ashrrev_i16 v71, s42, v11
	v_bitop3_b32 v71, v11, v71, s43 bitop3:0x2d
	v_lshl_or_b32 v93, v71, 16, 41
	v_and_or_b32 v94, v71, s44, 40
	v_pk_ashrrev_i16 v71, s42, v12
	v_bitop3_b32 v71, v12, v71, s43 bitop3:0x2d
	v_lshl_or_b32 v95, v71, 16, 39
	v_and_or_b32 v96, v71, s44, 38
	v_pk_ashrrev_i16 v71, s42, v13
	v_bitop3_b32 v71, v13, v71, s43 bitop3:0x2d
	v_lshl_or_b32 v97, v71, 16, 37
	v_and_or_b32 v98, v71, s44, 36
	v_pk_ashrrev_i16 v71, s42, v14
	v_bitop3_b32 v71, v14, v71, s43 bitop3:0x2d
	v_lshl_or_b32 v99, v71, 16, 35
	v_and_or_b32 v100, v71, s44, 34
	v_pk_ashrrev_i16 v71, s42, v15
	v_bitop3_b32 v71, v15, v71, s43 bitop3:0x2d
	v_lshl_or_b32 v101, v71, 16, 33
	v_and_or_b32 v102, v71, s44, 32
	v_max_u32_e32 v71, v87, v100
	v_min_u32_e32 v100, v87, v100
	v_max_u32_e32 v87, v88, v99
	v_min_u32_e32 v99, v88, v99
	v_max_u32_e32 v88, v89, v102
	v_min_u32_e32 v102, v89, v102
	v_max_u32_e32 v89, v90, v101
	v_min_u32_e32 v101, v90, v101
	v_max_u32_e32 v90, v91, v95
	v_min_u32_e32 v95, v91, v95
	v_max_u32_e32 v91, v92, v93
	v_min_u32_e32 v93, v92, v93
	v_max_u32_e32 v92, v94, v98
	v_min_u32_e32 v98, v94, v98
	v_max_u32_e32 v94, v96, v97
	v_min_u32_e32 v97, v96, v97
	v_max_u32_e32 v96, v71, v91
	v_min_u32_e32 v91, v71, v91
	v_max_u32_e32 v71, v87, v92
	v_min_u32_e32 v92, v87, v92
	v_max_u32_e32 v87, v88, v94
	v_min_u32_e32 v94, v88, v94
	v_max_u32_e32 v88, v89, v90
	v_min_u32_e32 v90, v89, v90
	v_max_u32_e32 v89, v93, v100
	v_min_u32_e32 v100, v93, v100
	v_max_u32_e32 v93, v95, v101
	v_min_u32_e32 v101, v95, v101
	v_max_u32_e32 v95, v97, v102
	v_min_u32_e32 v102, v97, v102
	v_max_u32_e32 v97, v98, v99
	v_min_u32_e32 v99, v98, v99
	v_max_u32_e32 v98, v96, v71
	v_min_u32_e32 v71, v96, v71
	v_max_u32_e32 v96, v87, v88
	v_min_u32_e32 v88, v87, v88
	v_max_u32_e32 v87, v90, v91
	v_min_u32_e32 v91, v90, v91
	v_max_u32_e32 v90, v89, v93
	v_min_u32_e32 v93, v89, v93
	v_max_u32_e32 v89, v92, v94
	v_min_u32_e32 v94, v92, v94
	v_max_u32_e32 v92, v95, v97
	v_min_u32_e32 v97, v95, v97
	v_max_u32_e32 v95, v99, v100
	v_min_u32_e32 v100, v99, v100
	v_max_u32_e32 v99, v101, v102
	v_min_u32_e32 v102, v101, v102
	v_max_u32_e32 v101, v98, v96
	v_min_u32_e32 v96, v98, v96
	v_max_u32_e32 v98, v71, v88
	v_min_u32_e32 v88, v71, v88
	v_max_u32_e32 v71, v87, v92
	v_min_u32_e32 v92, v87, v92
	v_max_u32_e32 v87, v91, v97
	v_min_u32_e32 v97, v91, v97
	v_max_u32_e32 v91, v90, v89
	v_min_u32_e32 v89, v90, v89
	v_max_u32_e32 v90, v93, v94
	v_min_u32_e32 v94, v93, v94
	v_max_u32_e32 v93, v95, v99
	v_min_u32_e32 v99, v95, v99
	v_max_u32_e32 v95, v100, v102
	v_min_u32_e32 v102, v100, v102
	v_max_u32_e32 v100, v98, v96
	v_min_u32_e32 v96, v98, v96
	v_max_u32_e32 v98, v88, v93
	v_min_u32_e32 v93, v88, v93
	v_max_u32_e32 v88, v71, v91
	v_min_u32_e32 v91, v71, v91
	v_max_u32_e32 v71, v87, v89
	v_min_u32_e32 v89, v87, v89
	v_max_u32_e32 v87, v90, v92
	v_min_u32_e32 v92, v90, v92
	v_max_u32_e32 v90, v94, v97
	v_min_u32_e32 v97, v94, v97
	v_max_u32_e32 v94, v95, v99
; __device__ __forceinline__ unsigned f2key(float f) { const unsigned u = __float_as_uint(f); return (u & 0x80000000u) ? ~u : (u | 0x80000000u); }
; #define CE_DESC(a, b) do { const unsigned _mx = (a) > (b) ? (a) : (b), _mn = (a) > (b) ? (b) : (a); (a) = _mx; (b) = _mn; } while (0)
; __device__ __forceinline__ void sort16_desc(unsigned (&k)[16]) {
; #pragma unroll
;     for (int size = 2; size <= 16; size <<= 1)
; #pragma unroll
;         for (int stride = size >> 1; stride > 0; stride >>= 1)
; #pragma unroll
;             for (int i = 0; i < 16; ++i) { const int j = i ^ stride;
;                 if (j > i) { if ((i & size) == 0) CE_DESC(k[i], k[j]); else CE_DESC(k[j], k[i]); } }
; }
; __device__ __forceinline__ void merge16(unsigned (&a)[16], const unsigned (&b)[16]) {
; #pragma unroll
;     for (int i = 0; i < 16; ++i) a[i] = a[i] > b[15 - i] ? a[i] : b[15 - i];
; #pragma unroll
;     for (int stride = 8; stride > 0; stride >>= 1)
; #pragma unroll
;         for (int i = 0; i < 16; ++i) { const int j = i ^ stride; if (j > i) CE_DESC(a[i], a[j]); }
; }
; __device__ __forceinline__ void peer_tile(const Args& A, LAS unsigned char* lds, int tile) {
;     ...
;                 const int hp = 2 * h + p;
;                 unsigned k0[16], k1[16];
;                 { const bf16_t* sp = QRY + m * 2048 + hp * 128 + 32 * g;
;                   const u32x4 s0 = *(const u32x4*)sp, s1 = *(const u32x4*)(sp + 8), s2 = *(const u32x4*)(sp + 16), s3 = *(const u32x4*)(sp + 24);
;                   const unsigned sw[16] = {s0.x, s0.y, s0.z, s0.w, s1.x, s1.y, s1.z, s1.w, s2.x, s2.y, s2.z, s2.w, s3.x, s3.y, s3.z, s3.w};
; #pragma unroll
;                   for (int i = 0; i < 16; ++i) {
;                       const float lo = (float)__builtin_bit_cast(_Float16, (unsigned short)(sw[i] & 0xffffu)), hi = (float)__builtin_bit_cast(_Float16, (unsigned short)(sw[i] >> 16));
;                       const unsigned klo = (f2key(lo) & ~127u) | (unsigned)(127 - (32 * g + 2 * i)), khi = (f2key(hi) & ~127u) | (unsigned)(127 - (32 * g + 2 * i + 1));
;                       if (i < 8) { k0[2 * i] = klo; k0[2 * i + 1] = khi; } else { k1[2 * (i - 8)] = klo; k1[2 * (i - 8) + 1] = khi; } } }
;                 sort16_desc(k0); sort16_desc(k1); merge16(k0, k1);
	v_min_u32_e32 v99, v95, v99
	v_max_u32_e32 v95, v100, v88
	v_min_u32_e32 v88, v100, v88
	v_max_u32_e32 v100, v96, v91
	v_min_u32_e32 v91, v96, v91
	v_max_u32_e32 v96, v71, v87
	v_min_u32_e32 v87, v71, v87
	v_max_u32_e32 v71, v89, v92
	v_min_u32_e32 v92, v89, v92
	v_max_u32_e32 v89, v90, v94
	v_min_u32_e32 v94, v90, v94
	v_max_u32_e32 v90, v97, v99
	v_min_u32_e32 v99, v97, v99
	v_max_u32_e32 v97, v100, v88
	v_min_u32_e32 v88, v100, v88
	v_max_u32_e32 v100, v98, v91
	v_min_u32_e32 v91, v98, v91
	v_max_u32_e32 v98, v89, v93
	v_min_u32_e32 v93, v89, v93
	v_max_u32_e32 v89, v90, v94
	v_min_u32_e32 v94, v90, v94
	v_max_u32_e32 v90, v100, v96
	v_min_u32_e32 v96, v100, v96
	v_max_u32_e32 v100, v91, v87
	v_min_u32_e32 v87, v91, v87
	v_max_u32_e32 v91, v71, v98
	v_min_u32_e32 v98, v71, v98
	v_max_u32_e32 v71, v92, v93
	v_min_u32_e32 v93, v92, v93
	v_max_u32_e32 v92, v90, v88
	v_min_u32_e32 v88, v90, v88
	v_max_u32_e32 v90, v96, v100
	v_min_u32_e32 v100, v96, v100
	v_max_u32_e32 v96, v91, v87
	v_min_u32_e32 v87, v91, v87
	v_max_u32_e32 v91, v98, v71
	v_min_u32_e32 v71, v98, v71
	v_max_u32_e32 v98, v89, v93
	v_min_u32_e32 v93, v89, v93
	v_max_u32_e32 v89, v100, v96
	v_min_u32_e32 v96, v100, v96
	v_max_u32_e32 v100, v87, v91
	v_min_u32_e32 v91, v87, v91
	v_max_u32_e32 v85, v85, v102
	v_max_u32_e32 v79, v79, v99
	v_max_u32_e32 v81, v81, v94
	v_max_u32_e32 v76, v76, v93
	v_max_u32_e32 v72, v72, v98
	v_max_u32_e32 v74, v74, v71
	v_max_u32_e32 v73, v73, v91
	v_max_u32_e32 v80, v80, v100
	v_max_u32_e32 v84, v84, v96
	v_max_u32_e32 v75, v75, v89
	v_max_u32_e32 v70, v70, v90
	v_max_u32_e32 v82, v82, v88
	v_max_u32_e32 v77, v77, v92
	v_max_u32_e32 v78, v78, v97
	v_max_u32_e32 v83, v83, v95
	v_max_u32_e32 v86, v86, v101
	v_max_u32_e32 v102, v85, v84
	v_min_u32_e32 v84, v85, v84
	v_max_u32_e32 v85, v79, v75
	v_min_u32_e32 v75, v79, v75
	v_max_u32_e32 v79, v81, v70
	v_min_u32_e32 v70, v81, v70
	v_max_u32_e32 v81, v76, v82
	v_min_u32_e32 v82, v76, v82
	v_max_u32_e32 v76, v72, v77
	v_min_u32_e32 v77, v72, v77
	v_max_u32_e32 v72, v74, v78
	v_min_u32_e32 v78, v74, v78
	v_max_u32_e32 v74, v73, v83
	v_min_u32_e32 v83, v73, v83
	v_max_u32_e32 v73, v80, v86
	v_min_u32_e32 v86, v80, v86
	v_max_u32_e32 v80, v102, v76
	v_min_u32_e32 v76, v102, v76
	v_max_u32_e32 v102, v85, v72
	v_min_u32_e32 v72, v85, v72
	v_max_u32_e32 v85, v79, v74
	v_min_u32_e32 v74, v79, v74
	v_max_u32_e32 v79, v81, v73
	v_min_u32_e32 v73, v81, v73
	v_max_u32_e32 v81, v84, v77
	v_min_u32_e32 v77, v84, v77
	v_max_u32_e32 v84, v75, v78
	v_min_u32_e32 v78, v75, v78
	v_max_u32_e32 v75, v70, v83
	v_min_u32_e32 v83, v70, v83
	v_max_u32_e32 v70, v82, v86
	v_min_u32_e32 v86, v82, v86
	v_max_u32_e32 v82, v80, v85
	v_min_u32_e32 v85, v80, v85
	v_max_u32_e32 v80, v102, v79
	v_min_u32_e32 v79, v102, v79
	v_max_u32_e32 v102, v76, v74
	v_min_u32_e32 v74, v76, v74
	v_max_u32_e32 v76, v72, v73
	v_min_u32_e32 v73, v72, v73
	v_max_u32_e32 v72, v81, v75
	v_min_u32_e32 v75, v81, v75
	v_max_u32_e32 v81, v84, v70
	v_min_u32_e32 v70, v84, v70
	v_max_u32_e32 v84, v77, v83
	v_min_u32_e32 v83, v77, v83
	v_max_u32_e32 v77, v78, v86
	v_min_u32_e32 v86, v78, v86
	v_max_u32_e32 v78, v82, v80
	v_min_u32_e32 v80, v82, v80
	v_max_u32_e32 v82, v85, v79
	v_min_u32_e32 v79, v85, v79
	v_max_u32_e32 v85, v102, v76
	v_min_u32_e32 v76, v102, v76
	v_max_u32_e32 v102, v74, v73
	v_min_u32_e32 v73, v74, v73
	v_max_u32_e32 v74, v72, v81
	v_min_u32_e32 v81, v72, v81
	v_max_u32_e32 v72, v75, v70
	v_min_u32_e32 v70, v75, v70
	v_max_u32_e32 v75, v84, v77
	v_min_u32_e32 v77, v84, v77
	v_max_u32_e32 v84, v83, v86
	v_min_u32_e32 v86, v83, v86
	v_pk_ashrrev_i16 v83, s42, v16
	v_bitop3_b32 v83, v16, v83, s43 bitop3:0x2d
	v_lshl_or_b32 v99, v83, 16, 31
	v_and_or_b32 v94, v83, s44, 30
	v_pk_ashrrev_i16 v83, s42, v17
	v_bitop3_b32 v83, v17, v83, s43 bitop3:0x2d
	v_lshl_or_b32 v93, v83, 16, 29
	v_and_or_b32 v98, v83, s44, 28
	v_pk_ashrrev_i16 v83, s42, v18
	v_bitop3_b32 v83, v18, v83, s43 bitop3:0x2d
	v_lshl_or_b32 v71, v83, 16, 27
	v_and_or_b32 v91, v83, s44, 26
	v_pk_ashrrev_i16 v83, s42, v19
	v_bitop3_b32 v83, v19, v83, s43 bitop3:0x2d
	v_lshl_or_b32 v100, v83, 16, 25
	v_and_or_b32 v96, v83, s44, 24
	v_pk_ashrrev_i16 v83, s42, v20
	v_bitop3_b32 v83, v20, v83, s43 bitop3:0x2d
	v_lshl_or_b32 v89, v83, 16, 23
	v_and_or_b32 v90, v83, s44, 22
	v_pk_ashrrev_i16 v83, s42, v21
	v_bitop3_b32 v83, v21, v83, s43 bitop3:0x2d
	v_lshl_or_b32 v88, v83, 16, 21
	v_and_or_b32 v92, v83, s44, 20
	v_pk_ashrrev_i16 v83, s42, v22
	v_bitop3_b32 v83, v22, v83, s43 bitop3:0x2d
	v_lshl_or_b32 v97, v83, 16, 19
	v_and_or_b32 v95, v83, s44, 18
	v_pk_ashrrev_i16 v83, s42, v23
	v_bitop3_b32 v83, v23, v83, s43 bitop3:0x2d
	v_lshl_or_b32 v101, v83, 16, 17
	v_and_or_b32 v87, v83, s44, 16
	v_max_u32_e32 v83, v99, v95
	v_min_u32_e32 v95, v99, v95
	v_max_u32_e32 v99, v94, v97
	v_min_u32_e32 v97, v94, v97
	v_max_u32_e32 v94, v93, v87
	v_min_u32_e32 v87, v93, v87
	v_max_u32_e32 v93, v98, v101
	v_min_u32_e32 v101, v98, v101
	v_max_u32_e32 v98, v71, v89
	v_min_u32_e32 v89, v71, v89
	v_max_u32_e32 v71, v91, v100
	v_min_u32_e32 v100, v91, v100
	v_max_u32_e32 v91, v96, v92
	v_min_u32_e32 v92, v96, v92
	v_max_u32_e32 v96, v90, v88
	v_min_u32_e32 v88, v90, v88
	v_max_u32_e32 v90, v83, v71
	v_min_u32_e32 v71, v83, v71
	v_max_u32_e32 v83, v99, v91
	v_min_u32_e32 v91, v99, v91
	v_max_u32_e32 v99, v94, v96
	v_min_u32_e32 v96, v94, v96
	v_max_u32_e32 v94, v93, v98
	v_min_u32_e32 v98, v93, v98
	v_max_u32_e32 v93, v100, v95
	v_min_u32_e32 v95, v100, v95
	v_max_u32_e32 v100, v89, v101
	v_min_u32_e32 v101, v89, v101
	v_max_u32_e32 v89, v88, v87
	v_min_u32_e32 v87, v88, v87
	v_max_u32_e32 v88, v92, v97
; __device__ __forceinline__ unsigned f2key(float f) { const unsigned u = __float_as_uint(f); return (u & 0x80000000u) ? ~u : (u | 0x80000000u); }
; #define CE_DESC(a, b) do { const unsigned _mx = (a) > (b) ? (a) : (b), _mn = (a) > (b) ? (b) : (a); (a) = _mx; (b) = _mn; } while (0)
; __device__ __forceinline__ void sort16_desc(unsigned (&k)[16]) {
; #pragma unroll
;     for (int size = 2; size <= 16; size <<= 1)
; #pragma unroll
;         for (int stride = size >> 1; stride > 0; stride >>= 1)
; #pragma unroll
;             for (int i = 0; i < 16; ++i) { const int j = i ^ stride;
;                 if (j > i) { if ((i & size) == 0) CE_DESC(k[i], k[j]); else CE_DESC(k[j], k[i]); } }
; }
; __device__ __forceinline__ void merge16(unsigned (&a)[16], const unsigned (&b)[16]) {
; #pragma unroll
;     for (int i = 0; i < 16; ++i) a[i] = a[i] > b[15 - i] ? a[i] : b[15 - i];
; #pragma unroll
;     for (int stride = 8; stride > 0; stride >>= 1)
; #pragma unroll
;         for (int i = 0; i < 16; ++i) { const int j = i ^ stride; if (j > i) CE_DESC(a[i], a[j]); }
; }
; __device__ __forceinline__ void peer_tile(const Args& A, LAS unsigned char* lds, int tile) {
;     ...
;                 const int hp = 2 * h + p;
;                 unsigned k0[16], k1[16];
;                 { const bf16_t* sp = QRY + m * 2048 + hp * 128 + 32 * g;
;                   const u32x4 s0 = *(const u32x4*)sp, s1 = *(const u32x4*)(sp + 8), s2 = *(const u32x4*)(sp + 16), s3 = *(const u32x4*)(sp + 24);
;                   const unsigned sw[16] = {s0.x, s0.y, s0.z, s0.w, s1.x, s1.y, s1.z, s1.w, s2.x, s2.y, s2.z, s2.w, s3.x, s3.y, s3.z, s3.w};
; #pragma unroll
;                   for (int i = 0; i < 16; ++i) {
;                       const float lo = (float)__builtin_bit_cast(_Float16, (unsigned short)(sw[i] & 0xffffu)), hi = (float)__builtin_bit_cast(_Float16, (unsigned short)(sw[i] >> 16));
;                       const unsigned klo = (f2key(lo) & ~127u) | (unsigned)(127 - (32 * g + 2 * i)), khi = (f2key(hi) & ~127u) | (unsigned)(127 - (32 * g + 2 * i + 1));
;                       if (i < 8) { k0[2 * i] = klo; k0[2 * i + 1] = khi; } else { k1[2 * (i - 8)] = klo; k1[2 * (i - 8) + 1] = khi; } } }
;                 sort16_desc(k0); sort16_desc(k1); merge16(k0, k1);
	v_min_u32_e32 v97, v92, v97
	v_max_u32_e32 v92, v90, v83
	v_min_u32_e32 v83, v90, v83
	v_max_u32_e32 v90, v99, v94
	v_min_u32_e32 v94, v99, v94
	v_max_u32_e32 v99, v98, v71
	v_min_u32_e32 v71, v98, v71
	v_max_u32_e32 v98, v93, v100
	v_min_u32_e32 v100, v93, v100
	v_max_u32_e32 v93, v91, v96
	v_min_u32_e32 v96, v91, v96
	v_max_u32_e32 v91, v89, v88
	v_min_u32_e32 v88, v89, v88
	v_max_u32_e32 v89, v97, v95
	v_min_u32_e32 v95, v97, v95
	v_max_u32_e32 v97, v101, v87
	v_min_u32_e32 v87, v101, v87
	v_max_u32_e32 v101, v92, v90
	v_min_u32_e32 v90, v92, v90
	v_max_u32_e32 v92, v83, v94
	v_min_u32_e32 v94, v83, v94
	v_max_u32_e32 v83, v99, v91
	v_min_u32_e32 v91, v99, v91
	v_max_u32_e32 v99, v71, v88
	v_min_u32_e32 v88, v71, v88
	v_max_u32_e32 v71, v98, v93
	v_min_u32_e32 v93, v98, v93
	v_max_u32_e32 v98, v100, v96
	v_min_u32_e32 v96, v100, v96
	v_max_u32_e32 v100, v89, v97
	v_min_u32_e32 v97, v89, v97
	v_max_u32_e32 v89, v95, v87
	v_min_u32_e32 v87, v95, v87
	v_max_u32_e32 v95, v92, v90
	v_min_u32_e32 v90, v92, v90
	v_max_u32_e32 v92, v94, v100
	v_min_u32_e32 v100, v94, v100
	v_max_u32_e32 v94, v83, v71
	v_min_u32_e32 v71, v83, v71
	v_max_u32_e32 v83, v99, v93
	v_min_u32_e32 v93, v99, v93
	v_max_u32_e32 v99, v98, v91
	v_min_u32_e32 v91, v98, v91
	v_max_u32_e32 v98, v96, v88
	v_min_u32_e32 v88, v96, v88
	v_max_u32_e32 v96, v89, v97
	v_min_u32_e32 v97, v89, v97
	v_max_u32_e32 v89, v95, v94
	v_min_u32_e32 v94, v95, v94
	v_max_u32_e32 v95, v90, v71
	v_min_u32_e32 v71, v90, v71
	v_max_u32_e32 v90, v83, v99
	v_min_u32_e32 v99, v83, v99
	v_max_u32_e32 v83, v93, v91
	v_min_u32_e32 v91, v93, v91
	v_max_u32_e32 v93, v98, v96
	v_min_u32_e32 v96, v98, v96
	v_max_u32_e32 v98, v88, v97
	v_min_u32_e32 v97, v88, v97
	v_max_u32_e32 v88, v95, v94
	v_min_u32_e32 v94, v95, v94
	v_max_u32_e32 v95, v92, v71
	v_min_u32_e32 v71, v92, v71
	v_max_u32_e32 v92, v93, v100
	v_min_u32_e32 v100, v93, v100
	v_max_u32_e32 v93, v98, v96
	v_min_u32_e32 v96, v98, v96
	v_max_u32_e32 v98, v95, v90
	v_min_u32_e32 v90, v95, v90
	v_max_u32_e32 v95, v71, v99
	v_min_u32_e32 v99, v71, v99
	v_max_u32_e32 v71, v83, v92
	v_min_u32_e32 v92, v83, v92
	v_max_u32_e32 v83, v91, v100
	v_min_u32_e32 v100, v91, v100
	v_max_u32_e32 v91, v98, v94
	v_min_u32_e32 v94, v98, v94
	v_max_u32_e32 v98, v90, v95
	v_min_u32_e32 v95, v90, v95
	v_max_u32_e32 v90, v71, v99
	v_min_u32_e32 v99, v71, v99
	v_max_u32_e32 v71, v92, v83
	v_min_u32_e32 v83, v92, v83
	v_max_u32_e32 v92, v93, v100
	v_min_u32_e32 v100, v93, v100
	v_max_u32_e32 v93, v95, v90
	v_min_u32_e32 v90, v95, v90
	v_max_u32_e32 v95, v99, v71
	v_min_u32_e32 v71, v99, v71
	v_max_u32_e32 v78, v78, v87
	v_max_u32_e32 v80, v80, v97
	v_max_u32_e32 v82, v82, v96
	v_max_u32_e32 v79, v79, v100
	v_max_u32_e32 v85, v85, v92
	v_max_u32_e32 v76, v76, v83
	v_max_u32_e32 v102, v102, v71
	v_max_u32_e32 v73, v73, v95
	v_max_u32_e32 v74, v74, v90
	v_max_u32_e32 v81, v81, v93
	v_max_u32_e32 v72, v72, v98
	v_max_u32_e32 v70, v70, v94
	v_max_u32_e32 v75, v75, v91
	v_max_u32_e32 v77, v77, v88
	v_max_u32_e32 v84, v84, v89
	v_max_u32_e32 v86, v86, v101
	v_max_u32_e32 v87, v78, v74
	v_min_u32_e32 v74, v78, v74
	v_max_u32_e32 v78, v80, v81
	v_min_u32_e32 v81, v80, v81
	v_max_u32_e32 v80, v82, v72
	v_min_u32_e32 v72, v82, v72
	v_max_u32_e32 v82, v79, v70
	v_min_u32_e32 v70, v79, v70
	v_max_u32_e32 v79, v85, v75
	v_min_u32_e32 v75, v85, v75
	v_max_u32_e32 v85, v76, v77
	v_min_u32_e32 v77, v76, v77
	v_max_u32_e32 v76, v102, v84
	v_min_u32_e32 v84, v102, v84
	v_max_u32_e32 v102, v73, v86
	v_min_u32_e32 v86, v73, v86
	v_max_u32_e32 v73, v87, v79
	v_min_u32_e32 v79, v87, v79
	v_max_u32_e32 v87, v78, v85
	v_min_u32_e32 v85, v78, v85
	v_max_u32_e32 v78, v80, v76
	v_min_u32_e32 v76, v80, v76
	v_max_u32_e32 v80, v82, v102
	v_min_u32_e32 v102, v82, v102
	v_max_u32_e32 v82, v74, v75
	v_min_u32_e32 v75, v74, v75
	v_max_u32_e32 v74, v81, v77
	v_min_u32_e32 v77, v81, v77
	v_max_u32_e32 v81, v72, v84
	v_min_u32_e32 v84, v72, v84
	v_max_u32_e32 v72, v70, v86
	v_min_u32_e32 v86, v70, v86
	v_max_u32_e32 v70, v73, v78
	v_min_u32_e32 v78, v73, v78
	v_max_u32_e32 v73, v87, v80
	v_min_u32_e32 v80, v87, v80
	v_max_u32_e32 v87, v79, v76
	v_min_u32_e32 v76, v79, v76
	v_max_u32_e32 v79, v85, v102
	v_min_u32_e32 v102, v85, v102
	v_max_u32_e32 v85, v82, v81
	v_min_u32_e32 v81, v82, v81
	v_max_u32_e32 v82, v74, v72
	v_min_u32_e32 v72, v74, v72
	v_max_u32_e32 v74, v75, v84
	v_min_u32_e32 v84, v75, v84
	v_max_u32_e32 v75, v77, v86
	v_min_u32_e32 v86, v77, v86
	v_max_u32_e32 v77, v70, v73
	v_min_u32_e32 v73, v70, v73
	v_max_u32_e32 v70, v78, v80
	v_min_u32_e32 v80, v78, v80
	v_max_u32_e32 v78, v87, v79
	v_min_u32_e32 v79, v87, v79
	v_max_u32_e32 v87, v76, v102
	v_min_u32_e32 v102, v76, v102
	v_max_u32_e32 v76, v85, v82
	v_min_u32_e32 v82, v85, v82
	v_max_u32_e32 v85, v81, v72
	v_min_u32_e32 v72, v81, v72
	v_max_u32_e32 v81, v74, v75
	v_min_u32_e32 v75, v74, v75
	v_max_u32_e32 v74, v84, v86
	v_min_u32_e32 v86, v84, v86
	v_pk_ashrrev_i16 v84, s42, v24
	v_bitop3_b32 v84, v24, v84, s43 bitop3:0x2d
	v_lshl_or_b32 v97, v84, 16, 15
	v_and_or_b32 v96, v84, s44, 14
	v_pk_ashrrev_i16 v84, s42, v25
	v_bitop3_b32 v84, v25, v84, s43 bitop3:0x2d
	v_lshl_or_b32 v100, v84, 16, 13
	v_and_or_b32 v92, v84, s44, 12
	v_pk_ashrrev_i16 v84, s42, v26
	v_bitop3_b32 v84, v26, v84, s43 bitop3:0x2d
	v_lshl_or_b32 v83, v84, 16, 11
	v_and_or_b32 v71, v84, s44, 10
	v_pk_ashrrev_i16 v84, s42, v27
	v_bitop3_b32 v84, v27, v84, s43 bitop3:0x2d
	v_lshl_or_b32 v95, v84, 16, 9
	v_and_or_b32 v90, v84, s44, 8
	v_pk_ashrrev_i16 v84, s42, v28
	v_bitop3_b32 v84, v28, v84, s43 bitop3:0x2d
	v_lshl_or_b32 v93, v84, 16, 7
	v_and_or_b32 v98, v84, s44, 6
; __device__ __forceinline__ unsigned f2key(float f) { const unsigned u = __float_as_uint(f); return (u & 0x80000000u) ? ~u : (u | 0x80000000u); }
; #define CE_DESC(a, b) do { const unsigned _mx = (a) > (b) ? (a) : (b), _mn = (a) > (b) ? (b) : (a); (a) = _mx; (b) = _mn; } while (0)
; __device__ __forceinline__ void sort16_desc(unsigned (&k)[16]) {
; #pragma unroll
;     for (int size = 2; size <= 16; size <<= 1)
; #pragma unroll
;         for (int stride = size >> 1; stride > 0; stride >>= 1)
; #pragma unroll
;             for (int i = 0; i < 16; ++i) { const int j = i ^ stride;
;                 if (j > i) { if ((i & size) == 0) CE_DESC(k[i], k[j]); else CE_DESC(k[j], k[i]); } }
; }
; __device__ __forceinline__ void merge16(unsigned (&a)[16], const unsigned (&b)[16]) {
; #pragma unroll
;     for (int i = 0; i < 16; ++i) a[i] = a[i] > b[15 - i] ? a[i] : b[15 - i];
; #pragma unroll
;     for (int stride = 8; stride > 0; stride >>= 1)
; #pragma unroll
;         for (int i = 0; i < 16; ++i) { const int j = i ^ stride; if (j > i) CE_DESC(a[i], a[j]); }
; }
; __device__ __forceinline__ void peer_tile(const Args& A, LAS unsigned char* lds, int tile) {
;     ...
;                 const int hp = 2 * h + p;
;                 unsigned k0[16], k1[16];
;                 { const bf16_t* sp = QRY + m * 2048 + hp * 128 + 32 * g;
;                   const u32x4 s0 = *(const u32x4*)sp, s1 = *(const u32x4*)(sp + 8), s2 = *(const u32x4*)(sp + 16), s3 = *(const u32x4*)(sp + 24);
;                   const unsigned sw[16] = {s0.x, s0.y, s0.z, s0.w, s1.x, s1.y, s1.z, s1.w, s2.x, s2.y, s2.z, s2.w, s3.x, s3.y, s3.z, s3.w};
; #pragma unroll
;                   for (int i = 0; i < 16; ++i) {
;                       const float lo = (float)__builtin_bit_cast(_Float16, (unsigned short)(sw[i] & 0xffffu)), hi = (float)__builtin_bit_cast(_Float16, (unsigned short)(sw[i] >> 16));
;                       const unsigned klo = (f2key(lo) & ~127u) | (unsigned)(127 - (32 * g + 2 * i)), khi = (f2key(hi) & ~127u) | (unsigned)(127 - (32 * g + 2 * i + 1));
;                       if (i < 8) { k0[2 * i] = klo; k0[2 * i + 1] = khi; } else { k1[2 * (i - 8)] = klo; k1[2 * (i - 8) + 1] = khi; } } }
;                 sort16_desc(k0); sort16_desc(k1); merge16(k0, k1);
	v_pk_ashrrev_i16 v84, s42, v29
	v_bitop3_b32 v84, v29, v84, s43 bitop3:0x2d
	v_lshl_or_b32 v94, v84, 16, 5
	v_and_or_b32 v91, v84, s44, 4
	v_pk_ashrrev_i16 v84, s42, v30
	v_bitop3_b32 v84, v30, v84, s43 bitop3:0x2d
	v_lshl_or_b32 v88, v84, 16, 3
	v_and_or_b32 v89, v84, s44, 2
	v_pk_ashrrev_i16 v84, s42, v31
	v_bitop3_b32 v84, v31, v84, s43 bitop3:0x2d
	v_lshl_or_b32 v101, v84, 16, 1
	v_and_or_b32 v99, v84, s44, 0
	v_max_u32_e32 v84, v97, v89
	v_min_u32_e32 v89, v97, v89
	v_max_u32_e32 v97, v96, v88
	v_min_u32_e32 v88, v96, v88
	v_max_u32_e32 v96, v100, v99
	v_min_u32_e32 v99, v100, v99
	v_max_u32_e32 v100, v92, v101
	v_min_u32_e32 v101, v92, v101
	v_max_u32_e32 v92, v83, v93
	v_min_u32_e32 v93, v83, v93
	v_max_u32_e32 v83, v71, v95
	v_min_u32_e32 v95, v71, v95
	v_max_u32_e32 v71, v90, v91
	v_min_u32_e32 v91, v90, v91
	v_max_u32_e32 v90, v98, v94
	v_min_u32_e32 v94, v98, v94
	v_max_u32_e32 v98, v84, v83
	v_min_u32_e32 v83, v84, v83
	v_max_u32_e32 v84, v97, v71
	v_min_u32_e32 v71, v97, v71
	v_max_u32_e32 v97, v96, v90
	v_min_u32_e32 v90, v96, v90
	v_max_u32_e32 v96, v100, v92
	v_min_u32_e32 v92, v100, v92
	v_max_u32_e32 v100, v95, v89
	v_min_u32_e32 v89, v95, v89
	v_max_u32_e32 v95, v93, v101
	v_min_u32_e32 v101, v93, v101
	v_max_u32_e32 v93, v94, v99
	v_min_u32_e32 v99, v94, v99
	v_max_u32_e32 v94, v91, v88
	v_min_u32_e32 v88, v91, v88
	v_max_u32_e32 v91, v98, v84
	v_min_u32_e32 v84, v98, v84
	v_max_u32_e32 v98, v97, v96
	v_min_u32_e32 v96, v97, v96
	v_max_u32_e32 v97, v92, v83
	v_min_u32_e32 v83, v92, v83
	v_max_u32_e32 v92, v100, v95
	v_min_u32_e32 v95, v100, v95
	v_max_u32_e32 v100, v71, v90
	v_min_u32_e32 v90, v71, v90
	v_max_u32_e32 v71, v93, v94
	v_min_u32_e32 v94, v93, v94
	v_max_u32_e32 v93, v88, v89
	v_min_u32_e32 v89, v88, v89
	v_max_u32_e32 v88, v101, v99
	v_min_u32_e32 v99, v101, v99
	v_max_u32_e32 v101, v91, v98
	v_min_u32_e32 v98, v91, v98
	v_max_u32_e32 v91, v84, v96
	v_min_u32_e32 v96, v84, v96
	v_max_u32_e32 v84, v97, v71
	v_min_u32_e32 v71, v97, v71
	v_max_u32_e32 v97, v83, v94
	v_min_u32_e32 v94, v83, v94
	v_max_u32_e32 v83, v92, v100
	v_min_u32_e32 v100, v92, v100
	v_max_u32_e32 v92, v95, v90
	v_min_u32_e32 v90, v95, v90
	v_max_u32_e32 v95, v93, v88
	v_min_u32_e32 v88, v93, v88
	v_max_u32_e32 v93, v89, v99
	v_min_u32_e32 v99, v89, v99
	v_max_u32_e32 v89, v91, v98
	v_min_u32_e32 v98, v91, v98
	v_max_u32_e32 v91, v96, v95
	v_min_u32_e32 v95, v96, v95
	v_max_u32_e32 v96, v84, v83
	v_min_u32_e32 v83, v84, v83
	v_max_u32_e32 v84, v97, v100
	v_min_u32_e32 v100, v97, v100
	v_max_u32_e32 v97, v92, v71
	v_min_u32_e32 v71, v92, v71
	v_max_u32_e32 v92, v90, v94
	v_min_u32_e32 v94, v90, v94
	v_max_u32_e32 v90, v93, v88
	v_min_u32_e32 v88, v93, v88
	v_max_u32_e32 v93, v89, v96
	v_min_u32_e32 v96, v89, v96
	v_max_u32_e32 v89, v98, v83
	v_min_u32_e32 v83, v98, v83
	v_max_u32_e32 v98, v84, v97
	v_min_u32_e32 v97, v84, v97
	v_max_u32_e32 v84, v100, v71
	v_min_u32_e32 v71, v100, v71
	v_max_u32_e32 v100, v92, v90
	v_min_u32_e32 v90, v92, v90
	v_max_u32_e32 v92, v94, v88
	v_min_u32_e32 v88, v94, v88
	v_max_u32_e32 v94, v89, v96
	v_min_u32_e32 v96, v89, v96
	v_max_u32_e32 v89, v91, v83
	v_min_u32_e32 v83, v91, v83
	v_max_u32_e32 v91, v100, v95
	v_min_u32_e32 v95, v100, v95
	v_max_u32_e32 v100, v92, v90
	v_min_u32_e32 v90, v92, v90
	v_max_u32_e32 v92, v89, v98
	v_min_u32_e32 v98, v89, v98
	v_max_u32_e32 v89, v83, v97
	v_min_u32_e32 v97, v83, v97
	v_max_u32_e32 v83, v84, v91
	v_min_u32_e32 v91, v84, v91
	v_max_u32_e32 v84, v71, v95
	v_min_u32_e32 v95, v71, v95
	v_max_u32_e32 v71, v92, v96
	v_min_u32_e32 v96, v92, v96
	v_max_u32_e32 v92, v98, v89
	v_min_u32_e32 v89, v98, v89
	v_max_u32_e32 v98, v83, v97
	v_min_u32_e32 v97, v83, v97
	v_max_u32_e32 v83, v91, v84
	v_min_u32_e32 v84, v91, v84
	v_max_u32_e32 v91, v100, v95
	v_min_u32_e32 v95, v100, v95
	v_max_u32_e32 v100, v89, v98
	v_min_u32_e32 v98, v89, v98
	v_max_u32_e32 v89, v97, v83
	v_min_u32_e32 v83, v97, v83
	v_max_u32_e32 v77, v77, v99
	v_max_u32_e32 v73, v73, v88
	v_max_u32_e32 v70, v70, v90
	v_max_u32_e32 v80, v80, v95
	v_max_u32_e32 v78, v78, v91
	v_max_u32_e32 v79, v79, v84
	v_max_u32_e32 v87, v87, v83
	v_max_u32_e32 v102, v102, v89
	v_max_u32_e32 v76, v76, v98
	v_max_u32_e32 v82, v82, v100
	v_max_u32_e32 v85, v85, v92
	v_max_u32_e32 v72, v72, v96
	v_max_u32_e32 v81, v81, v71
	v_max_u32_e32 v75, v75, v94
	v_max_u32_e32 v74, v74, v93
	v_max_u32_e32 v86, v86, v101
	v_max_u32_e32 v99, v77, v76
	v_min_u32_e32 v76, v77, v76
	v_max_u32_e32 v77, v73, v82
	v_min_u32_e32 v82, v73, v82
	v_max_u32_e32 v73, v70, v85
	v_min_u32_e32 v85, v70, v85
	v_max_u32_e32 v70, v80, v72
	v_min_u32_e32 v72, v80, v72
	v_max_u32_e32 v80, v78, v81
	v_min_u32_e32 v81, v78, v81
	v_max_u32_e32 v78, v79, v75
	v_min_u32_e32 v75, v79, v75
	v_max_u32_e32 v79, v87, v74
	v_min_u32_e32 v74, v87, v74
	v_max_u32_e32 v87, v102, v86
	v_min_u32_e32 v86, v102, v86
	v_max_u32_e32 v102, v99, v80
	v_min_u32_e32 v80, v99, v80
	v_max_u32_e32 v99, v77, v78
	v_min_u32_e32 v78, v77, v78
	v_max_u32_e32 v77, v73, v79
	v_min_u32_e32 v79, v73, v79
	v_max_u32_e32 v73, v70, v87
	v_min_u32_e32 v87, v70, v87
	v_max_u32_e32 v70, v76, v81
	v_min_u32_e32 v81, v76, v81
	v_max_u32_e32 v76, v82, v75
	v_min_u32_e32 v75, v82, v75
	v_max_u32_e32 v82, v85, v74
	v_min_u32_e32 v74, v85, v74
	v_max_u32_e32 v85, v72, v86
	v_min_u32_e32 v86, v72, v86
	v_max_u32_e32 v72, v102, v77
	v_min_u32_e32 v77, v102, v77
	v_max_u32_e32 v102, v99, v73
	v_min_u32_e32 v73, v99, v73
	v_max_u32_e32 v99, v80, v79
	v_min_u32_e32 v79, v80, v79
	v_max_u32_e32 v80, v78, v87
	v_min_u32_e32 v87, v78, v87
	v_max_u32_e32 v78, v70, v82
	v_min_u32_e32 v82, v70, v82
	v_max_u32_e32 v70, v76, v85
; __device__ __forceinline__ void sort16_desc(unsigned (&k)[16]) {
; #pragma unroll
;     for (int size = 2; size <= 16; size <<= 1)
; #pragma unroll
;         for (int stride = size >> 1; stride > 0; stride >>= 1)
; #pragma unroll
;             for (int i = 0; i < 16; ++i) { const int j = i ^ stride;
;                 if (j > i) { if ((i & size) == 0) CE_DESC(k[i], k[j]); else CE_DESC(k[j], k[i]); } }
; }
; __device__ __forceinline__ void merge16(unsigned (&a)[16], const unsigned (&b)[16]) {
; #pragma unroll
;     for (int i = 0; i < 16; ++i) a[i] = a[i] > b[15 - i] ? a[i] : b[15 - i];
; #pragma unroll
;     for (int stride = 8; stride > 0; stride >>= 1)
; #pragma unroll
;         for (int i = 0; i < 16; ++i) { const int j = i ^ stride; if (j > i) CE_DESC(a[i], a[j]); }
; }
; __device__ __forceinline__ void peer_tile(const Args& A, LAS unsigned char* lds, int tile) {
;     ...
;                 const int hp = 2 * h + p;
;                 unsigned k0[16], k1[16];
;                 { const bf16_t* sp = QRY + m * 2048 + hp * 128 + 32 * g;
;                   const u32x4 s0 = *(const u32x4*)sp, s1 = *(const u32x4*)(sp + 8), s2 = *(const u32x4*)(sp + 16), s3 = *(const u32x4*)(sp + 24);
;                   const unsigned sw[16] = {s0.x, s0.y, s0.z, s0.w, s1.x, s1.y, s1.z, s1.w, s2.x, s2.y, s2.z, s2.w, s3.x, s3.y, s3.z, s3.w};
; #pragma unroll
;                   for (int i = 0; i < 16; ++i) {
;                       const float lo = (float)__builtin_bit_cast(_Float16, (unsigned short)(sw[i] & 0xffffu)), hi = (float)__builtin_bit_cast(_Float16, (unsigned short)(sw[i] >> 16));
;                       const unsigned klo = (f2key(lo) & ~127u) | (unsigned)(127 - (32 * g + 2 * i)), khi = (f2key(hi) & ~127u) | (unsigned)(127 - (32 * g + 2 * i + 1));
;                       if (i < 8) { k0[2 * i] = klo; k0[2 * i + 1] = khi; } else { k1[2 * (i - 8)] = klo; k1[2 * (i - 8) + 1] = khi; } } }
;                 sort16_desc(k0); sort16_desc(k1); merge16(k0, k1);
; #pragma unroll
;                 for (int msk = 16; msk <= 32; msk <<= 1) {
; #pragma unroll
;                     for (int i = 0; i < 16; ++i) k1[i] = (unsigned)__shfl_xor((int)k0[i], msk);
;                     merge16(k0, k1); }
; #pragma unroll
;                 for (int i = 0; i < 16; ++i) LA[hh][p][i] = k0[i];
	v_min_u32_e32 v85, v76, v85
	v_max_u32_e32 v76, v81, v74
	v_min_u32_e32 v74, v81, v74
	v_max_u32_e32 v81, v75, v86
	v_min_u32_e32 v86, v75, v86
	v_max_u32_e32 v75, v72, v102
	v_min_u32_e32 v102, v72, v102
	v_max_u32_e32 v72, v77, v73
	v_min_u32_e32 v73, v77, v73
	v_max_u32_e32 v77, v99, v80
	v_min_u32_e32 v80, v99, v80
	v_max_u32_e32 v99, v79, v87
	v_min_u32_e32 v87, v79, v87
	v_max_u32_e32 v79, v78, v70
	v_min_u32_e32 v70, v78, v70
	v_max_u32_e32 v78, v82, v85
	v_min_u32_e32 v85, v82, v85
	v_max_u32_e32 v82, v76, v81
	v_min_u32_e32 v81, v76, v81
	v_max_u32_e32 v76, v74, v86
	v_min_u32_e32 v86, v74, v86
	v_or_b32_e32 v75, 64, v75
	v_or_b32_e32 v102, 64, v102
	v_or_b32_e32 v72, 64, v72
	v_or_b32_e32 v73, 64, v73
	v_or_b32_e32 v77, 64, v77
	v_or_b32_e32 v80, 64, v80
	v_or_b32_e32 v99, 64, v99
	v_or_b32_e32 v87, 64, v87
	v_or_b32_e32 v79, 64, v79
	v_or_b32_e32 v70, 64, v70
	v_or_b32_e32 v78, 64, v78
	v_or_b32_e32 v85, 64, v85
	v_or_b32_e32 v82, 64, v82
	v_or_b32_e32 v81, 64, v81
	v_or_b32_e32 v76, 64, v76
	v_or_b32_e32 v86, 64, v86
	s_mov_b64 s[38:39], s[34:35]
	global_load_dwordx4 v[0:3], v66, s[38:39] offset:256
	s_add_u32 s38, s38, 0x8000
	s_addc_u32 s39, s39, 0
	global_load_dwordx4 v[4:7], v66, s[38:39] offset:256
	s_add_u32 s38, s38, 0x8000
	s_addc_u32 s39, s39, 0
	global_load_dwordx4 v[8:11], v66, s[38:39] offset:256
	s_add_u32 s38, s38, 0x8000
	s_addc_u32 s39, s39, 0
	global_load_dwordx4 v[12:15], v66, s[38:39] offset:256
	s_add_u32 s38, s38, 0x8000
	s_addc_u32 s39, s39, 0
	global_load_dwordx4 v[16:19], v66, s[38:39] offset:256
	s_add_u32 s38, s38, 0x8000
	s_addc_u32 s39, s39, 0
	global_load_dwordx4 v[20:23], v66, s[38:39] offset:256
	s_add_u32 s38, s38, 0x8000
	s_addc_u32 s39, s39, 0
	global_load_dwordx4 v[24:27], v66, s[38:39] offset:256
	s_add_u32 s38, s38, 0x8000
	s_addc_u32 s39, s39, 0
	global_load_dwordx4 v[28:31], v66, s[38:39] offset:256
	s_waitcnt vmcnt(8)
	ds_write_b128 v64, v[32:35] offset:0
	ds_write_b128 v64, v[36:39] offset:1152
	ds_write_b128 v64, v[40:43] offset:2304
	ds_write_b128 v64, v[44:47] offset:3456
	ds_write_b128 v64, v[48:51] offset:4608
	ds_write_b128 v64, v[52:55] offset:5760
	ds_write_b128 v64, v[56:59] offset:6912
	ds_write_b128 v64, v[60:63] offset:8064
	s_waitcnt lgkmcnt(0)
	ds_read_b128 v[32:35], v65 offset:0
	ds_read_b128 v[36:39], v65 offset:16
	ds_read_b128 v[40:43], v65 offset:32
	ds_read_b128 v[44:47], v65 offset:48
	ds_read_b128 v[48:51], v65 offset:64
	ds_read_b128 v[52:55], v65 offset:80
	ds_read_b128 v[56:59], v65 offset:96
	ds_read_b128 v[60:63], v65 offset:112
	s_waitcnt lgkmcnt(0)
	v_pk_ashrrev_i16 v74, s42, v32
	v_bitop3_b32 v74, v32, v74, s43 bitop3:0x2d
	v_lshl_or_b32 v88, v74, 16, 63
	v_and_or_b32 v90, v74, s44, 62
	v_pk_ashrrev_i16 v74, s42, v33
	v_bitop3_b32 v74, v33, v74, s43 bitop3:0x2d
	v_lshl_or_b32 v95, v74, 16, 61
	v_and_or_b32 v91, v74, s44, 60
	v_pk_ashrrev_i16 v74, s42, v34
	v_bitop3_b32 v74, v34, v74, s43 bitop3:0x2d
	v_lshl_or_b32 v84, v74, 16, 59
	v_and_or_b32 v83, v74, s44, 58
	v_pk_ashrrev_i16 v74, s42, v35
	v_bitop3_b32 v74, v35, v74, s43 bitop3:0x2d
	v_lshl_or_b32 v89, v74, 16, 57
	v_and_or_b32 v98, v74, s44, 56
	v_pk_ashrrev_i16 v74, s42, v36
	v_bitop3_b32 v74, v36, v74, s43 bitop3:0x2d
	v_lshl_or_b32 v100, v74, 16, 55
	v_and_or_b32 v92, v74, s44, 54
	v_pk_ashrrev_i16 v74, s42, v37
	v_bitop3_b32 v74, v37, v74, s43 bitop3:0x2d
	v_lshl_or_b32 v96, v74, 16, 53
	v_and_or_b32 v71, v74, s44, 52
	v_pk_ashrrev_i16 v74, s42, v38
	v_bitop3_b32 v74, v38, v74, s43 bitop3:0x2d
	v_lshl_or_b32 v94, v74, 16, 51
	v_and_or_b32 v93, v74, s44, 50
	v_pk_ashrrev_i16 v74, s42, v39
	v_bitop3_b32 v74, v39, v74, s43 bitop3:0x2d
	v_lshl_or_b32 v101, v74, 16, 49
	v_and_or_b32 v97, v74, s44, 48
	v_max_u32_e32 v74, v88, v93
	v_min_u32_e32 v93, v88, v93
	v_max_u32_e32 v88, v90, v94
	v_min_u32_e32 v94, v90, v94
	v_max_u32_e32 v90, v95, v97
	v_min_u32_e32 v97, v95, v97
	v_max_u32_e32 v95, v91, v101
	v_min_u32_e32 v101, v91, v101
	v_max_u32_e32 v91, v84, v100
	v_min_u32_e32 v100, v84, v100
	v_max_u32_e32 v84, v83, v89
	v_min_u32_e32 v89, v83, v89
	v_max_u32_e32 v83, v98, v71
	v_min_u32_e32 v71, v98, v71
	v_max_u32_e32 v98, v92, v96
	v_min_u32_e32 v96, v92, v96
	v_max_u32_e32 v92, v74, v84
	v_min_u32_e32 v84, v74, v84
	v_max_u32_e32 v74, v88, v83
	v_min_u32_e32 v83, v88, v83
	v_max_u32_e32 v88, v90, v98
	v_min_u32_e32 v98, v90, v98
	v_max_u32_e32 v90, v95, v91
	v_min_u32_e32 v91, v95, v91
	v_max_u32_e32 v95, v89, v93
	v_min_u32_e32 v93, v89, v93
	v_max_u32_e32 v89, v100, v101
	v_min_u32_e32 v101, v100, v101
	v_max_u32_e32 v100, v96, v97
	v_min_u32_e32 v97, v96, v97
	v_max_u32_e32 v96, v71, v94
	v_min_u32_e32 v94, v71, v94
	v_max_u32_e32 v71, v92, v74
	v_min_u32_e32 v74, v92, v74
	v_max_u32_e32 v92, v88, v90
	v_min_u32_e32 v90, v88, v90
	v_max_u32_e32 v88, v91, v84
	v_min_u32_e32 v84, v91, v84
	v_max_u32_e32 v91, v95, v89
	v_min_u32_e32 v89, v95, v89
	v_max_u32_e32 v95, v83, v98
	v_min_u32_e32 v98, v83, v98
	v_max_u32_e32 v83, v100, v96
	v_min_u32_e32 v96, v100, v96
	v_max_u32_e32 v100, v94, v93
	v_min_u32_e32 v93, v94, v93
	v_max_u32_e32 v94, v101, v97
	v_min_u32_e32 v97, v101, v97
	v_max_u32_e32 v101, v71, v92
	v_min_u32_e32 v92, v71, v92
	v_max_u32_e32 v71, v74, v90
	v_min_u32_e32 v90, v74, v90
	v_max_u32_e32 v74, v88, v83
	v_min_u32_e32 v83, v88, v83
	v_max_u32_e32 v88, v84, v96
	v_min_u32_e32 v96, v84, v96
	v_max_u32_e32 v84, v91, v95
	v_min_u32_e32 v95, v91, v95
	v_max_u32_e32 v91, v89, v98
	v_min_u32_e32 v98, v89, v98
	v_max_u32_e32 v89, v100, v94
	v_min_u32_e32 v94, v100, v94
	v_max_u32_e32 v100, v93, v97
	v_min_u32_e32 v97, v93, v97
	v_max_u32_e32 v93, v71, v92
	v_min_u32_e32 v92, v71, v92
; __device__ __forceinline__ unsigned f2key(float f) { const unsigned u = __float_as_uint(f); return (u & 0x80000000u) ? ~u : (u | 0x80000000u); }
; #define CE_DESC(a, b) do { const unsigned _mx = (a) > (b) ? (a) : (b), _mn = (a) > (b) ? (b) : (a); (a) = _mx; (b) = _mn; } while (0)
; __device__ __forceinline__ void sort16_desc(unsigned (&k)[16]) {
; #pragma unroll
;     for (int size = 2; size <= 16; size <<= 1)
; #pragma unroll
;         for (int stride = size >> 1; stride > 0; stride >>= 1)
; #pragma unroll
;             for (int i = 0; i < 16; ++i) { const int j = i ^ stride;
;                 if (j > i) { if ((i & size) == 0) CE_DESC(k[i], k[j]); else CE_DESC(k[j], k[i]); } }
; }
; __device__ __forceinline__ void merge16(unsigned (&a)[16], const unsigned (&b)[16]) {
; #pragma unroll
;     for (int i = 0; i < 16; ++i) a[i] = a[i] > b[15 - i] ? a[i] : b[15 - i];
; #pragma unroll
;     for (int stride = 8; stride > 0; stride >>= 1)
; #pragma unroll
;         for (int i = 0; i < 16; ++i) { const int j = i ^ stride; if (j > i) CE_DESC(a[i], a[j]); }
; }
; __device__ __forceinline__ void peer_tile(const Args& A, LAS unsigned char* lds, int tile) {
;     ...
;                 const int hp = 2 * h + p;
;                 unsigned k0[16], k1[16];
;                 { const bf16_t* sp = QRY + m * 2048 + hp * 128 + 32 * g;
;                   const u32x4 s0 = *(const u32x4*)sp, s1 = *(const u32x4*)(sp + 8), s2 = *(const u32x4*)(sp + 16), s3 = *(const u32x4*)(sp + 24);
;                   const unsigned sw[16] = {s0.x, s0.y, s0.z, s0.w, s1.x, s1.y, s1.z, s1.w, s2.x, s2.y, s2.z, s2.w, s3.x, s3.y, s3.z, s3.w};
; #pragma unroll
;                   for (int i = 0; i < 16; ++i) {
;                       const float lo = (float)__builtin_bit_cast(_Float16, (unsigned short)(sw[i] & 0xffffu)), hi = (float)__builtin_bit_cast(_Float16, (unsigned short)(sw[i] >> 16));
;                       const unsigned klo = (f2key(lo) & ~127u) | (unsigned)(127 - (32 * g + 2 * i)), khi = (f2key(hi) & ~127u) | (unsigned)(127 - (32 * g + 2 * i + 1));
;                       if (i < 8) { k0[2 * i] = klo; k0[2 * i + 1] = khi; } else { k1[2 * (i - 8)] = klo; k1[2 * (i - 8) + 1] = khi; } } }
;                 sort16_desc(k0); sort16_desc(k1); merge16(k0, k1);
	v_max_u32_e32 v71, v90, v89
	v_min_u32_e32 v89, v90, v89
	v_max_u32_e32 v90, v74, v84
	v_min_u32_e32 v84, v74, v84
	v_max_u32_e32 v74, v88, v95
	v_min_u32_e32 v95, v88, v95
	v_max_u32_e32 v88, v91, v83
	v_min_u32_e32 v83, v91, v83
	v_max_u32_e32 v91, v98, v96
	v_min_u32_e32 v96, v98, v96
	v_max_u32_e32 v98, v100, v94
	v_min_u32_e32 v94, v100, v94
	v_max_u32_e32 v100, v93, v90
	v_min_u32_e32 v90, v93, v90
	v_max_u32_e32 v93, v92, v84
	v_min_u32_e32 v84, v92, v84
	v_max_u32_e32 v92, v74, v88
	v_min_u32_e32 v88, v74, v88
	v_max_u32_e32 v74, v95, v83
	v_min_u32_e32 v83, v95, v83
	v_max_u32_e32 v95, v91, v98
	v_min_u32_e32 v98, v91, v98
	v_max_u32_e32 v91, v96, v94
	v_min_u32_e32 v94, v96, v94
	v_max_u32_e32 v96, v93, v90
	v_min_u32_e32 v90, v93, v90
	v_max_u32_e32 v93, v71, v84
	v_min_u32_e32 v84, v71, v84
	v_max_u32_e32 v71, v95, v89
	v_min_u32_e32 v89, v95, v89
	v_max_u32_e32 v95, v91, v98
	v_min_u32_e32 v98, v91, v98
	v_max_u32_e32 v91, v93, v92
	v_min_u32_e32 v92, v93, v92
	v_max_u32_e32 v93, v84, v88
	v_min_u32_e32 v88, v84, v88
	v_max_u32_e32 v84, v74, v71
	v_min_u32_e32 v71, v74, v71
	v_max_u32_e32 v74, v83, v89
	v_min_u32_e32 v89, v83, v89
	v_max_u32_e32 v83, v91, v90
	v_min_u32_e32 v90, v91, v90
	v_max_u32_e32 v91, v92, v93
	v_min_u32_e32 v93, v92, v93
	v_max_u32_e32 v92, v84, v88
	v_min_u32_e32 v88, v84, v88
	v_max_u32_e32 v84, v71, v74
	v_min_u32_e32 v74, v71, v74
	v_max_u32_e32 v71, v95, v89
	v_min_u32_e32 v89, v95, v89
	v_max_u32_e32 v95, v93, v92
	v_min_u32_e32 v92, v93, v92
	v_max_u32_e32 v93, v88, v84
	v_min_u32_e32 v84, v88, v84
	v_max_u32_e32 v75, v75, v97
	v_max_u32_e32 v102, v102, v94
	v_max_u32_e32 v72, v72, v98
	v_max_u32_e32 v73, v73, v89
	v_max_u32_e32 v77, v77, v71
	v_max_u32_e32 v80, v80, v74
	v_max_u32_e32 v99, v99, v84
	v_max_u32_e32 v87, v87, v93
	v_max_u32_e32 v79, v79, v92
	v_max_u32_e32 v70, v70, v95
	v_max_u32_e32 v78, v78, v91
	v_max_u32_e32 v85, v85, v90
	v_max_u32_e32 v82, v82, v83
	v_max_u32_e32 v81, v81, v96
	v_max_u32_e32 v76, v76, v100
	v_max_u32_e32 v86, v86, v101
	v_max_u32_e32 v97, v75, v79
	v_min_u32_e32 v79, v75, v79
	v_max_u32_e32 v75, v102, v70
	v_min_u32_e32 v70, v102, v70
	v_max_u32_e32 v102, v72, v78
	v_min_u32_e32 v78, v72, v78
	v_max_u32_e32 v72, v73, v85
	v_min_u32_e32 v85, v73, v85
	v_max_u32_e32 v73, v77, v82
	v_min_u32_e32 v82, v77, v82
	v_max_u32_e32 v77, v80, v81
	v_min_u32_e32 v81, v80, v81
	v_max_u32_e32 v80, v99, v76
	v_min_u32_e32 v76, v99, v76
	v_max_u32_e32 v99, v87, v86
	v_min_u32_e32 v86, v87, v86
	v_max_u32_e32 v87, v97, v73
	v_min_u32_e32 v73, v97, v73
	v_max_u32_e32 v97, v75, v77
	v_min_u32_e32 v77, v75, v77
	v_max_u32_e32 v75, v102, v80
	v_min_u32_e32 v80, v102, v80
	v_max_u32_e32 v102, v72, v99
	v_min_u32_e32 v99, v72, v99
	v_max_u32_e32 v72, v79, v82
	v_min_u32_e32 v82, v79, v82
	v_max_u32_e32 v79, v70, v81
	v_min_u32_e32 v81, v70, v81
	v_max_u32_e32 v70, v78, v76
	v_min_u32_e32 v76, v78, v76
	v_max_u32_e32 v78, v85, v86
	v_min_u32_e32 v86, v85, v86
	v_max_u32_e32 v85, v87, v75
	v_min_u32_e32 v75, v87, v75
	v_max_u32_e32 v87, v97, v102
	v_min_u32_e32 v102, v97, v102
	v_max_u32_e32 v97, v73, v80
	v_min_u32_e32 v80, v73, v80
	v_max_u32_e32 v73, v77, v99
	v_min_u32_e32 v99, v77, v99
	v_max_u32_e32 v77, v72, v70
	v_min_u32_e32 v70, v72, v70
	v_max_u32_e32 v72, v79, v78
	v_min_u32_e32 v78, v79, v78
	v_max_u32_e32 v79, v82, v76
	v_min_u32_e32 v76, v82, v76
	v_max_u32_e32 v82, v81, v86
	v_min_u32_e32 v86, v81, v86
	v_max_u32_e32 v81, v85, v87
	v_min_u32_e32 v87, v85, v87
	v_max_u32_e32 v85, v75, v102
	v_min_u32_e32 v102, v75, v102
	v_max_u32_e32 v75, v97, v73
	v_min_u32_e32 v73, v97, v73
	v_max_u32_e32 v97, v80, v99
	v_min_u32_e32 v99, v80, v99
	v_max_u32_e32 v80, v77, v72
	v_min_u32_e32 v72, v77, v72
	v_max_u32_e32 v77, v70, v78
	v_min_u32_e32 v78, v70, v78
	v_max_u32_e32 v70, v79, v82
	v_min_u32_e32 v82, v79, v82
	v_max_u32_e32 v79, v76, v86
	v_min_u32_e32 v86, v76, v86
	v_pk_ashrrev_i16 v76, s42, v40
	v_bitop3_b32 v76, v40, v76, s43 bitop3:0x2d
	v_lshl_or_b32 v94, v76, 16, 47
	v_and_or_b32 v98, v76, s44, 46
	v_pk_ashrrev_i16 v76, s42, v41
	v_bitop3_b32 v76, v41, v76, s43 bitop3:0x2d
	v_lshl_or_b32 v89, v76, 16, 45
	v_and_or_b32 v71, v76, s44, 44
	v_pk_ashrrev_i16 v76, s42, v42
	v_bitop3_b32 v76, v42, v76, s43 bitop3:0x2d
	v_lshl_or_b32 v74, v76, 16, 43
	v_and_or_b32 v84, v76, s44, 42
	v_pk_ashrrev_i16 v76, s42, v43
	v_bitop3_b32 v76, v43, v76, s43 bitop3:0x2d
	v_lshl_or_b32 v93, v76, 16, 41
	v_and_or_b32 v92, v76, s44, 40
	v_pk_ashrrev_i16 v76, s42, v44
	v_bitop3_b32 v76, v44, v76, s43 bitop3:0x2d
	v_lshl_or_b32 v95, v76, 16, 39
	v_and_or_b32 v91, v76, s44, 38
	v_pk_ashrrev_i16 v76, s42, v45
	v_bitop3_b32 v76, v45, v76, s43 bitop3:0x2d
	v_lshl_or_b32 v90, v76, 16, 37
	v_and_or_b32 v83, v76, s44, 36
	v_pk_ashrrev_i16 v76, s42, v46
	v_bitop3_b32 v76, v46, v76, s43 bitop3:0x2d
	v_lshl_or_b32 v96, v76, 16, 35
	v_and_or_b32 v100, v76, s44, 34
	v_pk_ashrrev_i16 v76, s42, v47
	v_bitop3_b32 v76, v47, v76, s43 bitop3:0x2d
	v_lshl_or_b32 v101, v76, 16, 33
	v_and_or_b32 v88, v76, s44, 32
	v_max_u32_e32 v76, v94, v100
	v_min_u32_e32 v100, v94, v100
	v_max_u32_e32 v94, v98, v96
	v_min_u32_e32 v96, v98, v96
	v_max_u32_e32 v98, v89, v88
	v_min_u32_e32 v88, v89, v88
	v_max_u32_e32 v89, v71, v101
	v_min_u32_e32 v101, v71, v101
	v_max_u32_e32 v71, v74, v95
	v_min_u32_e32 v95, v74, v95
	v_max_u32_e32 v74, v84, v93
	v_min_u32_e32 v93, v84, v93
	v_max_u32_e32 v84, v92, v83
	v_min_u32_e32 v83, v92, v83
	v_max_u32_e32 v92, v91, v90
	v_min_u32_e32 v90, v91, v90
	v_max_u32_e32 v91, v76, v74
	v_min_u32_e32 v74, v76, v74
	v_max_u32_e32 v76, v94, v84
	v_min_u32_e32 v84, v94, v84
	v_max_u32_e32 v94, v98, v92
; __device__ __forceinline__ unsigned f2key(float f) { const unsigned u = __float_as_uint(f); return (u & 0x80000000u) ? ~u : (u | 0x80000000u); }
; #define CE_DESC(a, b) do { const unsigned _mx = (a) > (b) ? (a) : (b), _mn = (a) > (b) ? (b) : (a); (a) = _mx; (b) = _mn; } while (0)
; __device__ __forceinline__ void sort16_desc(unsigned (&k)[16]) {
; #pragma unroll
;     for (int size = 2; size <= 16; size <<= 1)
; #pragma unroll
;         for (int stride = size >> 1; stride > 0; stride >>= 1)
; #pragma unroll
;             for (int i = 0; i < 16; ++i) { const int j = i ^ stride;
;                 if (j > i) { if ((i & size) == 0) CE_DESC(k[i], k[j]); else CE_DESC(k[j], k[i]); } }
; }
; __device__ __forceinline__ void merge16(unsigned (&a)[16], const unsigned (&b)[16]) {
; #pragma unroll
;     for (int i = 0; i < 16; ++i) a[i] = a[i] > b[15 - i] ? a[i] : b[15 - i];
; #pragma unroll
;     for (int stride = 8; stride > 0; stride >>= 1)
; #pragma unroll
;         for (int i = 0; i < 16; ++i) { const int j = i ^ stride; if (j > i) CE_DESC(a[i], a[j]); }
; }
; __device__ __forceinline__ void peer_tile(const Args& A, LAS unsigned char* lds, int tile) {
;     ...
;                 const int hp = 2 * h + p;
;                 unsigned k0[16], k1[16];
;                 { const bf16_t* sp = QRY + m * 2048 + hp * 128 + 32 * g;
;                   const u32x4 s0 = *(const u32x4*)sp, s1 = *(const u32x4*)(sp + 8), s2 = *(const u32x4*)(sp + 16), s3 = *(const u32x4*)(sp + 24);
;                   const unsigned sw[16] = {s0.x, s0.y, s0.z, s0.w, s1.x, s1.y, s1.z, s1.w, s2.x, s2.y, s2.z, s2.w, s3.x, s3.y, s3.z, s3.w};
; #pragma unroll
;                   for (int i = 0; i < 16; ++i) {
;                       const float lo = (float)__builtin_bit_cast(_Float16, (unsigned short)(sw[i] & 0xffffu)), hi = (float)__builtin_bit_cast(_Float16, (unsigned short)(sw[i] >> 16));
;                       const unsigned klo = (f2key(lo) & ~127u) | (unsigned)(127 - (32 * g + 2 * i)), khi = (f2key(hi) & ~127u) | (unsigned)(127 - (32 * g + 2 * i + 1));
;                       if (i < 8) { k0[2 * i] = klo; k0[2 * i + 1] = khi; } else { k1[2 * (i - 8)] = klo; k1[2 * (i - 8) + 1] = khi; } } }
;                 sort16_desc(k0); sort16_desc(k1); merge16(k0, k1);
	v_min_u32_e32 v92, v98, v92
	v_max_u32_e32 v98, v89, v71
	v_min_u32_e32 v71, v89, v71
	v_max_u32_e32 v89, v93, v100
	v_min_u32_e32 v100, v93, v100
	v_max_u32_e32 v93, v95, v101
	v_min_u32_e32 v101, v95, v101
	v_max_u32_e32 v95, v90, v88
	v_min_u32_e32 v88, v90, v88
	v_max_u32_e32 v90, v83, v96
	v_min_u32_e32 v96, v83, v96
	v_max_u32_e32 v83, v91, v76
	v_min_u32_e32 v76, v91, v76
	v_max_u32_e32 v91, v94, v98
	v_min_u32_e32 v98, v94, v98
	v_max_u32_e32 v94, v71, v74
	v_min_u32_e32 v74, v71, v74
	v_max_u32_e32 v71, v89, v93
	v_min_u32_e32 v93, v89, v93
	v_max_u32_e32 v89, v84, v92
	v_min_u32_e32 v92, v84, v92
	v_max_u32_e32 v84, v95, v90
	v_min_u32_e32 v90, v95, v90
	v_max_u32_e32 v95, v96, v100
	v_min_u32_e32 v100, v96, v100
	v_max_u32_e32 v96, v101, v88
	v_min_u32_e32 v88, v101, v88
	v_max_u32_e32 v101, v83, v91
	v_min_u32_e32 v91, v83, v91
	v_max_u32_e32 v83, v76, v98
	v_min_u32_e32 v98, v76, v98
	v_max_u32_e32 v76, v94, v84
	v_min_u32_e32 v84, v94, v84
	v_max_u32_e32 v94, v74, v90
	v_min_u32_e32 v90, v74, v90
	v_max_u32_e32 v74, v71, v89
	v_min_u32_e32 v89, v71, v89
	v_max_u32_e32 v71, v93, v92
	v_min_u32_e32 v92, v93, v92
	v_max_u32_e32 v93, v95, v96
	v_min_u32_e32 v96, v95, v96
	v_max_u32_e32 v95, v100, v88
	v_min_u32_e32 v88, v100, v88
	v_max_u32_e32 v100, v83, v91
	v_min_u32_e32 v91, v83, v91
	v_max_u32_e32 v83, v98, v93
	v_min_u32_e32 v93, v98, v93
	v_max_u32_e32 v98, v76, v74
	v_min_u32_e32 v74, v76, v74
	v_max_u32_e32 v76, v94, v89
	v_min_u32_e32 v89, v94, v89
	v_max_u32_e32 v94, v71, v84
	v_min_u32_e32 v84, v71, v84
	v_max_u32_e32 v71, v92, v90
	v_min_u32_e32 v90, v92, v90
	v_max_u32_e32 v92, v95, v96
	v_min_u32_e32 v96, v95, v96
	v_max_u32_e32 v95, v100, v98
	v_min_u32_e32 v98, v100, v98
	v_max_u32_e32 v100, v91, v74
	v_min_u32_e32 v74, v91, v74
	v_max_u32_e32 v91, v76, v94
	v_min_u32_e32 v94, v76, v94
	v_max_u32_e32 v76, v89, v84
	v_min_u32_e32 v84, v89, v84
	v_max_u32_e32 v89, v71, v92
	v_min_u32_e32 v92, v71, v92
	v_max_u32_e32 v71, v90, v96
	v_min_u32_e32 v96, v90, v96
	v_max_u32_e32 v90, v100, v98
	v_min_u32_e32 v98, v100, v98
	v_max_u32_e32 v100, v83, v74
	v_min_u32_e32 v74, v83, v74
	v_max_u32_e32 v83, v89, v93
	v_min_u32_e32 v93, v89, v93
	v_max_u32_e32 v89, v71, v92
	v_min_u32_e32 v92, v71, v92
	v_max_u32_e32 v71, v100, v91
	v_min_u32_e32 v91, v100, v91
	v_max_u32_e32 v100, v74, v94
	v_min_u32_e32 v94, v74, v94
	v_max_u32_e32 v74, v76, v83
	v_min_u32_e32 v83, v76, v83
	v_max_u32_e32 v76, v84, v93
	v_min_u32_e32 v93, v84, v93
	v_max_u32_e32 v84, v71, v98
	v_min_u32_e32 v98, v71, v98
	v_max_u32_e32 v71, v91, v100
	v_min_u32_e32 v100, v91, v100
	v_max_u32_e32 v91, v74, v94
	v_min_u32_e32 v94, v74, v94
	v_max_u32_e32 v74, v83, v76
	v_min_u32_e32 v76, v83, v76
	v_max_u32_e32 v83, v89, v93
	v_min_u32_e32 v93, v89, v93
	v_max_u32_e32 v89, v100, v91
	v_min_u32_e32 v91, v100, v91
	v_max_u32_e32 v100, v94, v74
	v_min_u32_e32 v74, v94, v74
	v_max_u32_e32 v81, v81, v88
	v_max_u32_e32 v87, v87, v96
	v_max_u32_e32 v85, v85, v92
	v_max_u32_e32 v102, v102, v93
	v_max_u32_e32 v75, v75, v83
	v_max_u32_e32 v73, v73, v76
	v_max_u32_e32 v97, v97, v74
	v_max_u32_e32 v99, v99, v100
	v_max_u32_e32 v80, v80, v91
	v_max_u32_e32 v72, v72, v89
	v_max_u32_e32 v77, v77, v71
	v_max_u32_e32 v78, v78, v98
	v_max_u32_e32 v70, v70, v84
	v_max_u32_e32 v82, v82, v90
	v_max_u32_e32 v79, v79, v95
	v_max_u32_e32 v86, v86, v101
	v_max_u32_e32 v88, v81, v80
	v_min_u32_e32 v80, v81, v80
	v_max_u32_e32 v81, v87, v72
	v_min_u32_e32 v72, v87, v72
	v_max_u32_e32 v87, v85, v77
	v_min_u32_e32 v77, v85, v77
	v_max_u32_e32 v85, v102, v78
	v_min_u32_e32 v78, v102, v78
	v_max_u32_e32 v102, v75, v70
	v_min_u32_e32 v70, v75, v70
	v_max_u32_e32 v75, v73, v82
	v_min_u32_e32 v82, v73, v82
	v_max_u32_e32 v73, v97, v79
	v_min_u32_e32 v79, v97, v79
	v_max_u32_e32 v97, v99, v86
	v_min_u32_e32 v86, v99, v86
	v_max_u32_e32 v99, v88, v102
	v_min_u32_e32 v102, v88, v102
	v_max_u32_e32 v88, v81, v75
	v_min_u32_e32 v75, v81, v75
	v_max_u32_e32 v81, v87, v73
	v_min_u32_e32 v73, v87, v73
	v_max_u32_e32 v87, v85, v97
	v_min_u32_e32 v97, v85, v97
	v_max_u32_e32 v85, v80, v70
	v_min_u32_e32 v70, v80, v70
	v_max_u32_e32 v80, v72, v82
	v_min_u32_e32 v82, v72, v82
	v_max_u32_e32 v72, v77, v79
	v_min_u32_e32 v79, v77, v79
	v_max_u32_e32 v77, v78, v86
	v_min_u32_e32 v86, v78, v86
	v_max_u32_e32 v78, v99, v81
	v_min_u32_e32 v81, v99, v81
	v_max_u32_e32 v99, v88, v87
	v_min_u32_e32 v87, v88, v87
	v_max_u32_e32 v88, v102, v73
	v_min_u32_e32 v73, v102, v73
	v_max_u32_e32 v102, v75, v97
	v_min_u32_e32 v97, v75, v97
	v_max_u32_e32 v75, v85, v72
	v_min_u32_e32 v72, v85, v72
	v_max_u32_e32 v85, v80, v77
	v_min_u32_e32 v77, v80, v77
	v_max_u32_e32 v80, v70, v79
	v_min_u32_e32 v79, v70, v79
	v_max_u32_e32 v70, v82, v86
	v_min_u32_e32 v86, v82, v86
	v_max_u32_e32 v82, v78, v99
	v_min_u32_e32 v99, v78, v99
	v_max_u32_e32 v78, v81, v87
	v_min_u32_e32 v87, v81, v87
	v_max_u32_e32 v81, v88, v102
	v_min_u32_e32 v102, v88, v102
	v_max_u32_e32 v88, v73, v97
	v_min_u32_e32 v97, v73, v97
	v_max_u32_e32 v73, v75, v85
	v_min_u32_e32 v85, v75, v85
	v_max_u32_e32 v75, v72, v77
	v_min_u32_e32 v77, v72, v77
	v_max_u32_e32 v72, v80, v70
	v_min_u32_e32 v70, v80, v70
	v_max_u32_e32 v80, v79, v86
	v_min_u32_e32 v86, v79, v86
	v_pk_ashrrev_i16 v79, s42, v48
	v_bitop3_b32 v79, v48, v79, s43 bitop3:0x2d
	v_lshl_or_b32 v96, v79, 16, 31
	v_and_or_b32 v92, v79, s44, 30
	v_pk_ashrrev_i16 v79, s42, v49
	v_bitop3_b32 v79, v49, v79, s43 bitop3:0x2d
	v_lshl_or_b32 v93, v79, 16, 29
	v_and_or_b32 v83, v79, s44, 28
	v_pk_ashrrev_i16 v79, s42, v50
	v_bitop3_b32 v79, v50, v79, s43 bitop3:0x2d
	v_lshl_or_b32 v76, v79, 16, 27
; __device__ __forceinline__ unsigned f2key(float f) { const unsigned u = __float_as_uint(f); return (u & 0x80000000u) ? ~u : (u | 0x80000000u); }
; #define CE_DESC(a, b) do { const unsigned _mx = (a) > (b) ? (a) : (b), _mn = (a) > (b) ? (b) : (a); (a) = _mx; (b) = _mn; } while (0)
; __device__ __forceinline__ void sort16_desc(unsigned (&k)[16]) {
; #pragma unroll
;     for (int size = 2; size <= 16; size <<= 1)
; #pragma unroll
;         for (int stride = size >> 1; stride > 0; stride >>= 1)
; #pragma unroll
;             for (int i = 0; i < 16; ++i) { const int j = i ^ stride;
;                 if (j > i) { if ((i & size) == 0) CE_DESC(k[i], k[j]); else CE_DESC(k[j], k[i]); } }
; }
; __device__ __forceinline__ void merge16(unsigned (&a)[16], const unsigned (&b)[16]) {
; #pragma unroll
;     for (int i = 0; i < 16; ++i) a[i] = a[i] > b[15 - i] ? a[i] : b[15 - i];
; #pragma unroll
;     for (int stride = 8; stride > 0; stride >>= 1)
; #pragma unroll
;         for (int i = 0; i < 16; ++i) { const int j = i ^ stride; if (j > i) CE_DESC(a[i], a[j]); }
; }
; __device__ __forceinline__ void peer_tile(const Args& A, LAS unsigned char* lds, int tile) {
;     ...
;                 const int hp = 2 * h + p;
;                 unsigned k0[16], k1[16];
;                 { const bf16_t* sp = QRY + m * 2048 + hp * 128 + 32 * g;
;                   const u32x4 s0 = *(const u32x4*)sp, s1 = *(const u32x4*)(sp + 8), s2 = *(const u32x4*)(sp + 16), s3 = *(const u32x4*)(sp + 24);
;                   const unsigned sw[16] = {s0.x, s0.y, s0.z, s0.w, s1.x, s1.y, s1.z, s1.w, s2.x, s2.y, s2.z, s2.w, s3.x, s3.y, s3.z, s3.w};
; #pragma unroll
;                   for (int i = 0; i < 16; ++i) {
;                       const float lo = (float)__builtin_bit_cast(_Float16, (unsigned short)(sw[i] & 0xffffu)), hi = (float)__builtin_bit_cast(_Float16, (unsigned short)(sw[i] >> 16));
;                       const unsigned klo = (f2key(lo) & ~127u) | (unsigned)(127 - (32 * g + 2 * i)), khi = (f2key(hi) & ~127u) | (unsigned)(127 - (32 * g + 2 * i + 1));
;                       if (i < 8) { k0[2 * i] = klo; k0[2 * i + 1] = khi; } else { k1[2 * (i - 8)] = klo; k1[2 * (i - 8) + 1] = khi; } } }
;                 sort16_desc(k0); sort16_desc(k1); merge16(k0, k1);
	v_and_or_b32 v74, v79, s44, 26
	v_pk_ashrrev_i16 v79, s42, v51
	v_bitop3_b32 v79, v51, v79, s43 bitop3:0x2d
	v_lshl_or_b32 v100, v79, 16, 25
	v_and_or_b32 v91, v79, s44, 24
	v_pk_ashrrev_i16 v79, s42, v52
	v_bitop3_b32 v79, v52, v79, s43 bitop3:0x2d
	v_lshl_or_b32 v89, v79, 16, 23
	v_and_or_b32 v71, v79, s44, 22
	v_pk_ashrrev_i16 v79, s42, v53
	v_bitop3_b32 v79, v53, v79, s43 bitop3:0x2d
	v_lshl_or_b32 v98, v79, 16, 21
	v_and_or_b32 v84, v79, s44, 20
	v_pk_ashrrev_i16 v79, s42, v54
	v_bitop3_b32 v79, v54, v79, s43 bitop3:0x2d
	v_lshl_or_b32 v90, v79, 16, 19
	v_and_or_b32 v95, v79, s44, 18
	v_pk_ashrrev_i16 v79, s42, v55
	v_bitop3_b32 v79, v55, v79, s43 bitop3:0x2d
	v_lshl_or_b32 v101, v79, 16, 17
	v_and_or_b32 v94, v79, s44, 16
	v_max_u32_e32 v79, v96, v95
	v_min_u32_e32 v95, v96, v95
	v_max_u32_e32 v96, v92, v90
	v_min_u32_e32 v90, v92, v90
	v_max_u32_e32 v92, v93, v94
	v_min_u32_e32 v94, v93, v94
	v_max_u32_e32 v93, v83, v101
	v_min_u32_e32 v101, v83, v101
	v_max_u32_e32 v83, v76, v89
	v_min_u32_e32 v89, v76, v89
	v_max_u32_e32 v76, v74, v100
	v_min_u32_e32 v100, v74, v100
	v_max_u32_e32 v74, v91, v84
	v_min_u32_e32 v84, v91, v84
	v_max_u32_e32 v91, v71, v98
	v_min_u32_e32 v98, v71, v98
	v_max_u32_e32 v71, v79, v76
	v_min_u32_e32 v76, v79, v76
	v_max_u32_e32 v79, v96, v74
	v_min_u32_e32 v74, v96, v74
	v_max_u32_e32 v96, v92, v91
	v_min_u32_e32 v91, v92, v91
	v_max_u32_e32 v92, v93, v83
	v_min_u32_e32 v83, v93, v83
	v_max_u32_e32 v93, v100, v95
	v_min_u32_e32 v95, v100, v95
	v_max_u32_e32 v100, v89, v101
	v_min_u32_e32 v101, v89, v101
	v_max_u32_e32 v89, v98, v94
	v_min_u32_e32 v94, v98, v94
	v_max_u32_e32 v98, v84, v90
	v_min_u32_e32 v90, v84, v90
	v_max_u32_e32 v84, v71, v79
	v_min_u32_e32 v79, v71, v79
	v_max_u32_e32 v71, v96, v92
	v_min_u32_e32 v92, v96, v92
	v_max_u32_e32 v96, v83, v76
	v_min_u32_e32 v76, v83, v76
	v_max_u32_e32 v83, v93, v100
	v_min_u32_e32 v100, v93, v100
	v_max_u32_e32 v93, v74, v91
	v_min_u32_e32 v91, v74, v91
	v_max_u32_e32 v74, v89, v98
	v_min_u32_e32 v98, v89, v98
	v_max_u32_e32 v89, v90, v95
	v_min_u32_e32 v95, v90, v95
	v_max_u32_e32 v90, v101, v94
	v_min_u32_e32 v94, v101, v94
	v_max_u32_e32 v101, v84, v71
	v_min_u32_e32 v71, v84, v71
	v_max_u32_e32 v84, v79, v92
	v_min_u32_e32 v92, v79, v92
	v_max_u32_e32 v79, v96, v74
	v_min_u32_e32 v74, v96, v74
	v_max_u32_e32 v96, v76, v98
	v_min_u32_e32 v98, v76, v98
	v_max_u32_e32 v76, v83, v93
	v_min_u32_e32 v93, v83, v93
	v_max_u32_e32 v83, v100, v91
	v_min_u32_e32 v91, v100, v91
	v_max_u32_e32 v100, v89, v90
	v_min_u32_e32 v90, v89, v90
	v_max_u32_e32 v89, v95, v94
	v_min_u32_e32 v94, v95, v94
	v_max_u32_e32 v95, v84, v71
	v_min_u32_e32 v71, v84, v71
	v_max_u32_e32 v84, v92, v100
	v_min_u32_e32 v100, v92, v100
	v_max_u32_e32 v92, v79, v76
	v_min_u32_e32 v76, v79, v76
	v_max_u32_e32 v79, v96, v93
	v_min_u32_e32 v93, v96, v93
	v_max_u32_e32 v96, v83, v74
	v_min_u32_e32 v74, v83, v74
	v_max_u32_e32 v83, v91, v98
	v_min_u32_e32 v98, v91, v98
	v_max_u32_e32 v91, v89, v90
	v_min_u32_e32 v90, v89, v90
	v_max_u32_e32 v89, v95, v92
	v_min_u32_e32 v92, v95, v92
	v_max_u32_e32 v95, v71, v76
	v_min_u32_e32 v76, v71, v76
	v_max_u32_e32 v71, v79, v96
	v_min_u32_e32 v96, v79, v96
	v_max_u32_e32 v79, v93, v74
	v_min_u32_e32 v74, v93, v74
	v_max_u32_e32 v93, v83, v91
	v_min_u32_e32 v91, v83, v91
	v_max_u32_e32 v83, v98, v90
	v_min_u32_e32 v90, v98, v90
	v_max_u32_e32 v98, v95, v92
	v_min_u32_e32 v92, v95, v92
	v_max_u32_e32 v95, v84, v76
	v_min_u32_e32 v76, v84, v76
	v_max_u32_e32 v84, v93, v100
	v_min_u32_e32 v100, v93, v100
	v_max_u32_e32 v93, v83, v91
	v_min_u32_e32 v91, v83, v91
	v_max_u32_e32 v83, v95, v71
	v_min_u32_e32 v71, v95, v71
	v_max_u32_e32 v95, v76, v96
	v_min_u32_e32 v96, v76, v96
	v_max_u32_e32 v76, v79, v84
	v_min_u32_e32 v84, v79, v84
	v_max_u32_e32 v79, v74, v100
	v_min_u32_e32 v100, v74, v100
	v_max_u32_e32 v74, v83, v92
	v_min_u32_e32 v92, v83, v92
	v_max_u32_e32 v83, v71, v95
	v_min_u32_e32 v95, v71, v95
	v_max_u32_e32 v71, v76, v96
	v_min_u32_e32 v96, v76, v96
	v_max_u32_e32 v76, v84, v79
	v_min_u32_e32 v79, v84, v79
	v_max_u32_e32 v84, v93, v100
	v_min_u32_e32 v100, v93, v100
	v_max_u32_e32 v93, v95, v71
	v_min_u32_e32 v71, v95, v71
	v_max_u32_e32 v95, v96, v76
	v_min_u32_e32 v76, v96, v76
	v_max_u32_e32 v82, v82, v94
	v_max_u32_e32 v99, v99, v90
	v_max_u32_e32 v78, v78, v91
	v_max_u32_e32 v87, v87, v100
	v_max_u32_e32 v81, v81, v84
	v_max_u32_e32 v102, v102, v79
	v_max_u32_e32 v88, v88, v76
	v_max_u32_e32 v97, v97, v95
	v_max_u32_e32 v73, v73, v71
	v_max_u32_e32 v85, v85, v93
	v_max_u32_e32 v75, v75, v83
	v_max_u32_e32 v77, v77, v92
	v_max_u32_e32 v72, v72, v74
	v_max_u32_e32 v70, v70, v98
	v_max_u32_e32 v80, v80, v89
	v_max_u32_e32 v86, v86, v101
	v_max_u32_e32 v94, v82, v73
	v_min_u32_e32 v73, v82, v73
	v_max_u32_e32 v82, v99, v85
	v_min_u32_e32 v85, v99, v85
	v_max_u32_e32 v99, v78, v75
	v_min_u32_e32 v75, v78, v75
	v_max_u32_e32 v78, v87, v77
	v_min_u32_e32 v77, v87, v77
	v_max_u32_e32 v87, v81, v72
	v_min_u32_e32 v72, v81, v72
	v_max_u32_e32 v81, v102, v70
	v_min_u32_e32 v70, v102, v70
	v_max_u32_e32 v102, v88, v80
	v_min_u32_e32 v80, v88, v80
	v_max_u32_e32 v88, v97, v86
	v_min_u32_e32 v86, v97, v86
	v_max_u32_e32 v97, v94, v87
	v_min_u32_e32 v87, v94, v87
	v_max_u32_e32 v94, v82, v81
	v_min_u32_e32 v81, v82, v81
	v_max_u32_e32 v82, v99, v102
	v_min_u32_e32 v102, v99, v102
	v_max_u32_e32 v99, v78, v88
	v_min_u32_e32 v88, v78, v88
	v_max_u32_e32 v78, v73, v72
	v_min_u32_e32 v72, v73, v72
	v_max_u32_e32 v73, v85, v70
	v_min_u32_e32 v70, v85, v70
	v_max_u32_e32 v85, v75, v80
	v_min_u32_e32 v80, v75, v80
	v_max_u32_e32 v75, v77, v86
	v_min_u32_e32 v86, v77, v86
; __device__ __forceinline__ unsigned f2key(float f) { const unsigned u = __float_as_uint(f); return (u & 0x80000000u) ? ~u : (u | 0x80000000u); }
; #define CE_DESC(a, b) do { const unsigned _mx = (a) > (b) ? (a) : (b), _mn = (a) > (b) ? (b) : (a); (a) = _mx; (b) = _mn; } while (0)
; __device__ __forceinline__ void sort16_desc(unsigned (&k)[16]) {
; #pragma unroll
;     for (int size = 2; size <= 16; size <<= 1)
; #pragma unroll
;         for (int stride = size >> 1; stride > 0; stride >>= 1)
; #pragma unroll
;             for (int i = 0; i < 16; ++i) { const int j = i ^ stride;
;                 if (j > i) { if ((i & size) == 0) CE_DESC(k[i], k[j]); else CE_DESC(k[j], k[i]); } }
; }
; __device__ __forceinline__ void merge16(unsigned (&a)[16], const unsigned (&b)[16]) {
; #pragma unroll
;     for (int i = 0; i < 16; ++i) a[i] = a[i] > b[15 - i] ? a[i] : b[15 - i];
; #pragma unroll
;     for (int stride = 8; stride > 0; stride >>= 1)
; #pragma unroll
;         for (int i = 0; i < 16; ++i) { const int j = i ^ stride; if (j > i) CE_DESC(a[i], a[j]); }
; }
; __device__ __forceinline__ void peer_tile(const Args& A, LAS unsigned char* lds, int tile) {
;     ...
;                 const int hp = 2 * h + p;
;                 unsigned k0[16], k1[16];
;                 { const bf16_t* sp = QRY + m * 2048 + hp * 128 + 32 * g;
;                   const u32x4 s0 = *(const u32x4*)sp, s1 = *(const u32x4*)(sp + 8), s2 = *(const u32x4*)(sp + 16), s3 = *(const u32x4*)(sp + 24);
;                   const unsigned sw[16] = {s0.x, s0.y, s0.z, s0.w, s1.x, s1.y, s1.z, s1.w, s2.x, s2.y, s2.z, s2.w, s3.x, s3.y, s3.z, s3.w};
; #pragma unroll
;                   for (int i = 0; i < 16; ++i) {
;                       const float lo = (float)__builtin_bit_cast(_Float16, (unsigned short)(sw[i] & 0xffffu)), hi = (float)__builtin_bit_cast(_Float16, (unsigned short)(sw[i] >> 16));
;                       const unsigned klo = (f2key(lo) & ~127u) | (unsigned)(127 - (32 * g + 2 * i)), khi = (f2key(hi) & ~127u) | (unsigned)(127 - (32 * g + 2 * i + 1));
;                       if (i < 8) { k0[2 * i] = klo; k0[2 * i + 1] = khi; } else { k1[2 * (i - 8)] = klo; k1[2 * (i - 8) + 1] = khi; } } }
;                 sort16_desc(k0); sort16_desc(k1); merge16(k0, k1);
	v_max_u32_e32 v77, v97, v82
	v_min_u32_e32 v82, v97, v82
	v_max_u32_e32 v97, v94, v99
	v_min_u32_e32 v99, v94, v99
	v_max_u32_e32 v94, v87, v102
	v_min_u32_e32 v102, v87, v102
	v_max_u32_e32 v87, v81, v88
	v_min_u32_e32 v88, v81, v88
	v_max_u32_e32 v81, v78, v85
	v_min_u32_e32 v85, v78, v85
	v_max_u32_e32 v78, v73, v75
	v_min_u32_e32 v75, v73, v75
	v_max_u32_e32 v73, v72, v80
	v_min_u32_e32 v80, v72, v80
	v_max_u32_e32 v72, v70, v86
	v_min_u32_e32 v86, v70, v86
	v_max_u32_e32 v70, v77, v97
	v_min_u32_e32 v97, v77, v97
	v_max_u32_e32 v77, v82, v99
	v_min_u32_e32 v99, v82, v99
	v_max_u32_e32 v82, v94, v87
	v_min_u32_e32 v87, v94, v87
	v_max_u32_e32 v94, v102, v88
	v_min_u32_e32 v88, v102, v88
	v_max_u32_e32 v102, v81, v78
	v_min_u32_e32 v78, v81, v78
	v_max_u32_e32 v81, v85, v75
	v_min_u32_e32 v75, v85, v75
	v_max_u32_e32 v85, v73, v72
	v_min_u32_e32 v72, v73, v72
	v_max_u32_e32 v73, v80, v86
	v_min_u32_e32 v86, v80, v86
	v_pk_ashrrev_i16 v80, s42, v56
	v_bitop3_b32 v80, v56, v80, s43 bitop3:0x2d
	v_lshl_or_b32 v90, v80, 16, 15
	v_and_or_b32 v91, v80, s44, 14
	v_pk_ashrrev_i16 v80, s42, v57
	v_bitop3_b32 v80, v57, v80, s43 bitop3:0x2d
	v_lshl_or_b32 v100, v80, 16, 13
	v_and_or_b32 v84, v80, s44, 12
	v_pk_ashrrev_i16 v80, s42, v58
	v_bitop3_b32 v80, v58, v80, s43 bitop3:0x2d
	v_lshl_or_b32 v79, v80, 16, 11
	v_and_or_b32 v76, v80, s44, 10
	v_pk_ashrrev_i16 v80, s42, v59
	v_bitop3_b32 v80, v59, v80, s43 bitop3:0x2d
	v_lshl_or_b32 v95, v80, 16, 9
	v_and_or_b32 v71, v80, s44, 8
	v_pk_ashrrev_i16 v80, s42, v60
	v_bitop3_b32 v80, v60, v80, s43 bitop3:0x2d
	v_lshl_or_b32 v93, v80, 16, 7
	v_and_or_b32 v83, v80, s44, 6
	v_pk_ashrrev_i16 v80, s42, v61
	v_bitop3_b32 v80, v61, v80, s43 bitop3:0x2d
	v_lshl_or_b32 v92, v80, 16, 5
	v_and_or_b32 v74, v80, s44, 4
	v_pk_ashrrev_i16 v80, s42, v62
	v_bitop3_b32 v80, v62, v80, s43 bitop3:0x2d
	v_lshl_or_b32 v98, v80, 16, 3
	v_and_or_b32 v89, v80, s44, 2
	v_pk_ashrrev_i16 v80, s42, v63
	v_bitop3_b32 v80, v63, v80, s43 bitop3:0x2d
	v_lshl_or_b32 v101, v80, 16, 1
	v_and_or_b32 v96, v80, s44, 0
	v_max_u32_e32 v80, v90, v89
	v_min_u32_e32 v89, v90, v89
	v_max_u32_e32 v90, v91, v98
	v_min_u32_e32 v98, v91, v98
	v_max_u32_e32 v91, v100, v96
	v_min_u32_e32 v96, v100, v96
	v_max_u32_e32 v100, v84, v101
	v_min_u32_e32 v101, v84, v101
	v_max_u32_e32 v84, v79, v93
	v_min_u32_e32 v93, v79, v93
	v_max_u32_e32 v79, v76, v95
	v_min_u32_e32 v95, v76, v95
	v_max_u32_e32 v76, v71, v74
	v_min_u32_e32 v74, v71, v74
	v_max_u32_e32 v71, v83, v92
	v_min_u32_e32 v92, v83, v92
	v_max_u32_e32 v83, v80, v79
	v_min_u32_e32 v79, v80, v79
	v_max_u32_e32 v80, v90, v76
	v_min_u32_e32 v76, v90, v76
	v_max_u32_e32 v90, v91, v71
	v_min_u32_e32 v71, v91, v71
	v_max_u32_e32 v91, v100, v84
	v_min_u32_e32 v84, v100, v84
	v_max_u32_e32 v100, v95, v89
	v_min_u32_e32 v89, v95, v89
	v_max_u32_e32 v95, v93, v101
	v_min_u32_e32 v101, v93, v101
	v_max_u32_e32 v93, v92, v96
	v_min_u32_e32 v96, v92, v96
	v_max_u32_e32 v92, v74, v98
	v_min_u32_e32 v98, v74, v98
	v_max_u32_e32 v74, v83, v80
	v_min_u32_e32 v80, v83, v80
	v_max_u32_e32 v83, v90, v91
	v_min_u32_e32 v91, v90, v91
	v_max_u32_e32 v90, v84, v79
	v_min_u32_e32 v79, v84, v79
	v_max_u32_e32 v84, v100, v95
	v_min_u32_e32 v95, v100, v95
	v_max_u32_e32 v100, v76, v71
	v_min_u32_e32 v71, v76, v71
	v_max_u32_e32 v76, v93, v92
	v_min_u32_e32 v92, v93, v92
	v_max_u32_e32 v93, v98, v89
	v_min_u32_e32 v89, v98, v89
	v_max_u32_e32 v98, v101, v96
	v_min_u32_e32 v96, v101, v96
	v_max_u32_e32 v101, v74, v83
	v_min_u32_e32 v83, v74, v83
	v_max_u32_e32 v74, v80, v91
	v_min_u32_e32 v91, v80, v91
	v_max_u32_e32 v80, v90, v76
	v_min_u32_e32 v76, v90, v76
	v_max_u32_e32 v90, v79, v92
	v_min_u32_e32 v92, v79, v92
	v_max_u32_e32 v79, v84, v100
	v_min_u32_e32 v100, v84, v100
	v_max_u32_e32 v84, v95, v71
	v_min_u32_e32 v71, v95, v71
	v_max_u32_e32 v95, v93, v98
	v_min_u32_e32 v98, v93, v98
	v_max_u32_e32 v93, v89, v96
	v_min_u32_e32 v96, v89, v96
	v_max_u32_e32 v89, v74, v83
	v_min_u32_e32 v83, v74, v83
	v_max_u32_e32 v74, v91, v95
	v_min_u32_e32 v95, v91, v95
	v_max_u32_e32 v91, v80, v79
	v_min_u32_e32 v79, v80, v79
	v_max_u32_e32 v80, v90, v100
	v_min_u32_e32 v100, v90, v100
	v_max_u32_e32 v90, v84, v76
	v_min_u32_e32 v76, v84, v76
	v_max_u32_e32 v84, v71, v92
	v_min_u32_e32 v92, v71, v92
	v_max_u32_e32 v71, v93, v98
	v_min_u32_e32 v98, v93, v98
	v_max_u32_e32 v93, v89, v91
	v_min_u32_e32 v91, v89, v91
	v_max_u32_e32 v89, v83, v79
	v_min_u32_e32 v79, v83, v79
	v_max_u32_e32 v83, v80, v90
	v_min_u32_e32 v90, v80, v90
	v_max_u32_e32 v80, v100, v76
	v_min_u32_e32 v76, v100, v76
	v_max_u32_e32 v100, v84, v71
	v_min_u32_e32 v71, v84, v71
	v_max_u32_e32 v84, v92, v98
	v_min_u32_e32 v98, v92, v98
	v_max_u32_e32 v92, v89, v91
	v_min_u32_e32 v91, v89, v91
	v_max_u32_e32 v89, v74, v79
	v_min_u32_e32 v79, v74, v79
	v_max_u32_e32 v74, v100, v95
	v_min_u32_e32 v95, v100, v95
	v_max_u32_e32 v100, v84, v71
	v_min_u32_e32 v71, v84, v71
	v_max_u32_e32 v84, v89, v83
	v_min_u32_e32 v83, v89, v83
	v_max_u32_e32 v89, v79, v90
	v_min_u32_e32 v90, v79, v90
	v_max_u32_e32 v79, v80, v74
	v_min_u32_e32 v74, v80, v74
	v_max_u32_e32 v80, v76, v95
	v_min_u32_e32 v95, v76, v95
	v_max_u32_e32 v76, v84, v91
	v_min_u32_e32 v91, v84, v91
	v_max_u32_e32 v84, v83, v89
	v_min_u32_e32 v89, v83, v89
	v_max_u32_e32 v83, v79, v90
	v_min_u32_e32 v90, v79, v90
	v_max_u32_e32 v79, v74, v80
	v_min_u32_e32 v80, v74, v80
	v_max_u32_e32 v74, v100, v95
	v_min_u32_e32 v95, v100, v95
	v_max_u32_e32 v100, v89, v83
	v_min_u32_e32 v83, v89, v83
	v_max_u32_e32 v89, v90, v79
	v_min_u32_e32 v79, v90, v79
	v_max_u32_e32 v70, v70, v96
	v_max_u32_e32 v97, v97, v98
	v_max_u32_e32 v77, v77, v71
; __device__ __forceinline__ void sort16_desc(unsigned (&k)[16]) {
; #pragma unroll
;     for (int size = 2; size <= 16; size <<= 1)
; #pragma unroll
;         for (int stride = size >> 1; stride > 0; stride >>= 1)
; #pragma unroll
;             for (int i = 0; i < 16; ++i) { const int j = i ^ stride;
;                 if (j > i) { if ((i & size) == 0) CE_DESC(k[i], k[j]); else CE_DESC(k[j], k[i]); } }
; }
; __device__ __forceinline__ void merge16(unsigned (&a)[16], const unsigned (&b)[16]) {
; #pragma unroll
;     for (int i = 0; i < 16; ++i) a[i] = a[i] > b[15 - i] ? a[i] : b[15 - i];
; #pragma unroll
;     for (int stride = 8; stride > 0; stride >>= 1)
; #pragma unroll
;         for (int i = 0; i < 16; ++i) { const int j = i ^ stride; if (j > i) CE_DESC(a[i], a[j]); }
; }
; __device__ __forceinline__ void peer_tile(const Args& A, LAS unsigned char* lds, int tile) {
;     ...
;                 const int hp = 2 * h + p;
;                 unsigned k0[16], k1[16];
;                 { const bf16_t* sp = QRY + m * 2048 + hp * 128 + 32 * g;
;                   const u32x4 s0 = *(const u32x4*)sp, s1 = *(const u32x4*)(sp + 8), s2 = *(const u32x4*)(sp + 16), s3 = *(const u32x4*)(sp + 24);
;                   const unsigned sw[16] = {s0.x, s0.y, s0.z, s0.w, s1.x, s1.y, s1.z, s1.w, s2.x, s2.y, s2.z, s2.w, s3.x, s3.y, s3.z, s3.w};
; #pragma unroll
;                   for (int i = 0; i < 16; ++i) {
;                       const float lo = (float)__builtin_bit_cast(_Float16, (unsigned short)(sw[i] & 0xffffu)), hi = (float)__builtin_bit_cast(_Float16, (unsigned short)(sw[i] >> 16));
;                       const unsigned klo = (f2key(lo) & ~127u) | (unsigned)(127 - (32 * g + 2 * i)), khi = (f2key(hi) & ~127u) | (unsigned)(127 - (32 * g + 2 * i + 1));
;                       if (i < 8) { k0[2 * i] = klo; k0[2 * i + 1] = khi; } else { k1[2 * (i - 8)] = klo; k1[2 * (i - 8) + 1] = khi; } } }
;                 sort16_desc(k0); sort16_desc(k1); merge16(k0, k1);
; #pragma unroll
;                 for (int msk = 16; msk <= 32; msk <<= 1) {
; #pragma unroll
;                     for (int i = 0; i < 16; ++i) k1[i] = (unsigned)__shfl_xor((int)k0[i], msk);
;                     merge16(k0, k1); }
; #pragma unroll
;                 for (int i = 0; i < 16; ++i) LA[hh][p][i] = k0[i];
	v_max_u32_e32 v99, v99, v95
	v_max_u32_e32 v82, v82, v74
	v_max_u32_e32 v87, v87, v80
	v_max_u32_e32 v94, v94, v79
	v_max_u32_e32 v88, v88, v89
	v_max_u32_e32 v102, v102, v83
	v_max_u32_e32 v78, v78, v100
	v_max_u32_e32 v81, v81, v84
	v_max_u32_e32 v75, v75, v91
	v_max_u32_e32 v85, v85, v76
	v_max_u32_e32 v72, v72, v92
	v_max_u32_e32 v73, v73, v93
	v_max_u32_e32 v86, v86, v101
	v_max_u32_e32 v96, v70, v102
	v_min_u32_e32 v102, v70, v102
	v_max_u32_e32 v70, v97, v78
	v_min_u32_e32 v78, v97, v78
	v_max_u32_e32 v97, v77, v81
	v_min_u32_e32 v81, v77, v81
	v_max_u32_e32 v77, v99, v75
	v_min_u32_e32 v75, v99, v75
	v_max_u32_e32 v99, v82, v85
	v_min_u32_e32 v85, v82, v85
	v_max_u32_e32 v82, v87, v72
	v_min_u32_e32 v72, v87, v72
	v_max_u32_e32 v87, v94, v73
	v_min_u32_e32 v73, v94, v73
	v_max_u32_e32 v94, v88, v86
	v_min_u32_e32 v86, v88, v86
	v_max_u32_e32 v88, v96, v99
	v_min_u32_e32 v99, v96, v99
	v_max_u32_e32 v96, v70, v82
	v_min_u32_e32 v82, v70, v82
	v_max_u32_e32 v70, v97, v87
	v_min_u32_e32 v87, v97, v87
	v_max_u32_e32 v97, v77, v94
	v_min_u32_e32 v94, v77, v94
	v_max_u32_e32 v77, v102, v85
	v_min_u32_e32 v85, v102, v85
	v_max_u32_e32 v102, v78, v72
	v_min_u32_e32 v72, v78, v72
	v_max_u32_e32 v78, v81, v73
	v_min_u32_e32 v73, v81, v73
	v_max_u32_e32 v81, v75, v86
	v_min_u32_e32 v86, v75, v86
	v_max_u32_e32 v75, v88, v70
	v_min_u32_e32 v70, v88, v70
	v_max_u32_e32 v88, v96, v97
	v_min_u32_e32 v97, v96, v97
	v_max_u32_e32 v96, v99, v87
	v_min_u32_e32 v87, v99, v87
	v_max_u32_e32 v99, v82, v94
	v_min_u32_e32 v94, v82, v94
	v_max_u32_e32 v82, v77, v78
	v_min_u32_e32 v78, v77, v78
	v_max_u32_e32 v77, v102, v81
	v_min_u32_e32 v81, v102, v81
	v_max_u32_e32 v102, v85, v73
	v_min_u32_e32 v73, v85, v73
	v_max_u32_e32 v85, v72, v86
	v_min_u32_e32 v86, v72, v86
	v_max_u32_e32 v72, v75, v88
	v_min_u32_e32 v88, v75, v88
	v_max_u32_e32 v75, v70, v97
	v_min_u32_e32 v97, v70, v97
	v_max_u32_e32 v70, v96, v99
	v_min_u32_e32 v99, v96, v99
	v_max_u32_e32 v96, v87, v94
	v_min_u32_e32 v94, v87, v94
	v_max_u32_e32 v87, v82, v77
	v_min_u32_e32 v77, v82, v77
	v_max_u32_e32 v82, v78, v81
	v_min_u32_e32 v81, v78, v81
	v_max_u32_e32 v78, v102, v85
	v_min_u32_e32 v85, v102, v85
	v_max_u32_e32 v102, v73, v86
	v_min_u32_e32 v86, v73, v86
	s_mov_b64 s[38:39], s[34:35]
	global_load_dwordx4 v[32:35], v66, s[38:39] offset:384
	s_add_u32 s38, s38, 0x8000
	s_addc_u32 s39, s39, 0
	global_load_dwordx4 v[36:39], v66, s[38:39] offset:384
	s_add_u32 s38, s38, 0x8000
	s_addc_u32 s39, s39, 0
	global_load_dwordx4 v[40:43], v66, s[38:39] offset:384
	s_add_u32 s38, s38, 0x8000
	s_addc_u32 s39, s39, 0
	global_load_dwordx4 v[44:47], v66, s[38:39] offset:384
	s_add_u32 s38, s38, 0x8000
	s_addc_u32 s39, s39, 0
	global_load_dwordx4 v[48:51], v66, s[38:39] offset:384
	s_add_u32 s38, s38, 0x8000
	s_addc_u32 s39, s39, 0
	global_load_dwordx4 v[52:55], v66, s[38:39] offset:384
	s_add_u32 s38, s38, 0x8000
	s_addc_u32 s39, s39, 0
	global_load_dwordx4 v[56:59], v66, s[38:39] offset:384
	s_add_u32 s38, s38, 0x8000
	s_addc_u32 s39, s39, 0
	global_load_dwordx4 v[60:63], v66, s[38:39] offset:384
	s_waitcnt vmcnt(8)
	ds_write_b128 v64, v[0:3] offset:0
	ds_write_b128 v64, v[4:7] offset:1152
	ds_write_b128 v64, v[8:11] offset:2304
	ds_write_b128 v64, v[12:15] offset:3456
	ds_write_b128 v64, v[16:19] offset:4608
	ds_write_b128 v64, v[20:23] offset:5760
	ds_write_b128 v64, v[24:27] offset:6912
	ds_write_b128 v64, v[28:31] offset:8064
	s_waitcnt lgkmcnt(0)
	ds_read_b128 v[0:3], v65 offset:0
	ds_read_b128 v[4:7], v65 offset:16
	ds_read_b128 v[8:11], v65 offset:32
	ds_read_b128 v[12:15], v65 offset:48
	ds_read_b128 v[16:19], v65 offset:64
	ds_read_b128 v[20:23], v65 offset:80
	ds_read_b128 v[24:27], v65 offset:96
	ds_read_b128 v[28:31], v65 offset:112
	s_waitcnt lgkmcnt(0)
	v_pk_ashrrev_i16 v73, s42, v0
	v_bitop3_b32 v73, v0, v73, s43 bitop3:0x2d
	v_lshl_or_b32 v98, v73, 16, 63
	v_and_or_b32 v71, v73, s44, 62
	v_pk_ashrrev_i16 v73, s42, v1
	v_bitop3_b32 v73, v1, v73, s43 bitop3:0x2d
	v_lshl_or_b32 v95, v73, 16, 61
	v_and_or_b32 v74, v73, s44, 60
	v_pk_ashrrev_i16 v73, s42, v2
	v_bitop3_b32 v73, v2, v73, s43 bitop3:0x2d
	v_lshl_or_b32 v80, v73, 16, 59
	v_and_or_b32 v79, v73, s44, 58
	v_pk_ashrrev_i16 v73, s42, v3
	v_bitop3_b32 v73, v3, v73, s43 bitop3:0x2d
	v_lshl_or_b32 v89, v73, 16, 57
	v_and_or_b32 v83, v73, s44, 56
	v_pk_ashrrev_i16 v73, s42, v4
	v_bitop3_b32 v73, v4, v73, s43 bitop3:0x2d
	v_lshl_or_b32 v100, v73, 16, 55
	v_and_or_b32 v84, v73, s44, 54
	v_pk_ashrrev_i16 v73, s42, v5
	v_bitop3_b32 v73, v5, v73, s43 bitop3:0x2d
	v_lshl_or_b32 v91, v73, 16, 53
	v_and_or_b32 v76, v73, s44, 52
	v_pk_ashrrev_i16 v73, s42, v6
	v_bitop3_b32 v73, v6, v73, s43 bitop3:0x2d
	v_lshl_or_b32 v92, v73, 16, 51
	v_and_or_b32 v93, v73, s44, 50
	v_pk_ashrrev_i16 v73, s42, v7
	v_bitop3_b32 v73, v7, v73, s43 bitop3:0x2d
	v_lshl_or_b32 v101, v73, 16, 49
	v_and_or_b32 v90, v73, s44, 48
	v_max_u32_e32 v73, v98, v93
	v_min_u32_e32 v93, v98, v93
	v_max_u32_e32 v98, v71, v92
	v_min_u32_e32 v92, v71, v92
	v_max_u32_e32 v71, v95, v90
	v_min_u32_e32 v90, v95, v90
	v_max_u32_e32 v95, v74, v101
	v_min_u32_e32 v101, v74, v101
	v_max_u32_e32 v74, v80, v100
	v_min_u32_e32 v100, v80, v100
	v_max_u32_e32 v80, v79, v89
	v_min_u32_e32 v89, v79, v89
	v_max_u32_e32 v79, v83, v76
	v_min_u32_e32 v76, v83, v76
	v_max_u32_e32 v83, v84, v91
	v_min_u32_e32 v91, v84, v91
	v_max_u32_e32 v84, v73, v80
	v_min_u32_e32 v80, v73, v80
	v_max_u32_e32 v73, v98, v79
	v_min_u32_e32 v79, v98, v79
	v_max_u32_e32 v98, v71, v83
	v_min_u32_e32 v83, v71, v83
	v_max_u32_e32 v71, v95, v74
	v_min_u32_e32 v74, v95, v74
	v_max_u32_e32 v95, v89, v93
	v_min_u32_e32 v93, v89, v93
; __device__ __forceinline__ unsigned f2key(float f) { const unsigned u = __float_as_uint(f); return (u & 0x80000000u) ? ~u : (u | 0x80000000u); }
; #define CE_DESC(a, b) do { const unsigned _mx = (a) > (b) ? (a) : (b), _mn = (a) > (b) ? (b) : (a); (a) = _mx; (b) = _mn; } while (0)
; __device__ __forceinline__ void sort16_desc(unsigned (&k)[16]) {
; #pragma unroll
;     for (int size = 2; size <= 16; size <<= 1)
; #pragma unroll
;         for (int stride = size >> 1; stride > 0; stride >>= 1)
; #pragma unroll
;             for (int i = 0; i < 16; ++i) { const int j = i ^ stride;
;                 if (j > i) { if ((i & size) == 0) CE_DESC(k[i], k[j]); else CE_DESC(k[j], k[i]); } }
; }
; __device__ __forceinline__ void merge16(unsigned (&a)[16], const unsigned (&b)[16]) {
; #pragma unroll
;     for (int i = 0; i < 16; ++i) a[i] = a[i] > b[15 - i] ? a[i] : b[15 - i];
; #pragma unroll
;     for (int stride = 8; stride > 0; stride >>= 1)
; #pragma unroll
;         for (int i = 0; i < 16; ++i) { const int j = i ^ stride; if (j > i) CE_DESC(a[i], a[j]); }
; }
; __device__ __forceinline__ void peer_tile(const Args& A, LAS unsigned char* lds, int tile) {
;     ...
;                 { const bf16_t* sp = QRY + m * 2048 + hp * 128 + 32 * g;
;                   const u32x4 s0 = *(const u32x4*)sp, s1 = *(const u32x4*)(sp + 8), s2 = *(const u32x4*)(sp + 16), s3 = *(const u32x4*)(sp + 24);
;                   const unsigned sw[16] = {s0.x, s0.y, s0.z, s0.w, s1.x, s1.y, s1.z, s1.w, s2.x, s2.y, s2.z, s2.w, s3.x, s3.y, s3.z, s3.w};
; #pragma unroll
;                   for (int i = 0; i < 16; ++i) {
;                       const float lo = (float)__builtin_bit_cast(_Float16, (unsigned short)(sw[i] & 0xffffu)), hi = (float)__builtin_bit_cast(_Float16, (unsigned short)(sw[i] >> 16));
;                       const unsigned klo = (f2key(lo) & ~127u) | (unsigned)(127 - (32 * g + 2 * i)), khi = (f2key(hi) & ~127u) | (unsigned)(127 - (32 * g + 2 * i + 1));
;                       if (i < 8) { k0[2 * i] = klo; k0[2 * i + 1] = khi; } else { k1[2 * (i - 8)] = klo; k1[2 * (i - 8) + 1] = khi; } } }
;                 sort16_desc(k0); sort16_desc(k1); merge16(k0, k1);
	v_max_u32_e32 v89, v100, v101
	v_min_u32_e32 v101, v100, v101
	v_max_u32_e32 v100, v91, v90
	v_min_u32_e32 v90, v91, v90
	v_max_u32_e32 v91, v76, v92
	v_min_u32_e32 v92, v76, v92
	v_max_u32_e32 v76, v84, v73
	v_min_u32_e32 v73, v84, v73
	v_max_u32_e32 v84, v98, v71
	v_min_u32_e32 v71, v98, v71
	v_max_u32_e32 v98, v74, v80
	v_min_u32_e32 v80, v74, v80
	v_max_u32_e32 v74, v95, v89
	v_min_u32_e32 v89, v95, v89
	v_max_u32_e32 v95, v79, v83
	v_min_u32_e32 v83, v79, v83
	v_max_u32_e32 v79, v100, v91
	v_min_u32_e32 v91, v100, v91
	v_max_u32_e32 v100, v92, v93
	v_min_u32_e32 v93, v92, v93
	v_max_u32_e32 v92, v101, v90
	v_min_u32_e32 v90, v101, v90
	v_max_u32_e32 v101, v76, v84
	v_min_u32_e32 v84, v76, v84
	v_max_u32_e32 v76, v73, v71
	v_min_u32_e32 v71, v73, v71
	v_max_u32_e32 v73, v98, v79
	v_min_u32_e32 v79, v98, v79
	v_max_u32_e32 v98, v80, v91
	v_min_u32_e32 v91, v80, v91
	v_max_u32_e32 v80, v74, v95
	v_min_u32_e32 v95, v74, v95
	v_max_u32_e32 v74, v89, v83
	v_min_u32_e32 v83, v89, v83
	v_max_u32_e32 v89, v100, v92
	v_min_u32_e32 v92, v100, v92
	v_max_u32_e32 v100, v93, v90
	v_min_u32_e32 v90, v93, v90
	v_max_u32_e32 v93, v76, v84
	v_min_u32_e32 v84, v76, v84
	v_max_u32_e32 v76, v71, v89
	v_min_u32_e32 v89, v71, v89
	v_max_u32_e32 v71, v73, v80
	v_min_u32_e32 v80, v73, v80
	v_max_u32_e32 v73, v98, v95
	v_min_u32_e32 v95, v98, v95
	v_max_u32_e32 v98, v74, v79
	v_min_u32_e32 v79, v74, v79
	v_max_u32_e32 v74, v83, v91
	v_min_u32_e32 v91, v83, v91
	v_max_u32_e32 v83, v100, v92
	v_min_u32_e32 v92, v100, v92
	v_max_u32_e32 v100, v93, v71
	v_min_u32_e32 v71, v93, v71
	v_max_u32_e32 v93, v84, v80
	v_min_u32_e32 v80, v84, v80
	v_max_u32_e32 v84, v73, v98
	v_min_u32_e32 v98, v73, v98
	v_max_u32_e32 v73, v95, v79
	v_min_u32_e32 v79, v95, v79
	v_max_u32_e32 v95, v74, v83
	v_min_u32_e32 v83, v74, v83
	v_max_u32_e32 v74, v91, v92
	v_min_u32_e32 v92, v91, v92
	v_max_u32_e32 v91, v93, v71
	v_min_u32_e32 v71, v93, v71
	v_max_u32_e32 v93, v76, v80
	v_min_u32_e32 v80, v76, v80
	v_max_u32_e32 v76, v95, v89
	v_min_u32_e32 v89, v95, v89
	v_max_u32_e32 v95, v74, v83
	v_min_u32_e32 v83, v74, v83
	v_max_u32_e32 v74, v93, v84
	v_min_u32_e32 v84, v93, v84
	v_max_u32_e32 v93, v80, v98
	v_min_u32_e32 v98, v80, v98
	v_max_u32_e32 v80, v73, v76
	v_min_u32_e32 v76, v73, v76
	v_max_u32_e32 v73, v79, v89
	v_min_u32_e32 v89, v79, v89
	v_max_u32_e32 v79, v74, v71
	v_min_u32_e32 v71, v74, v71
	v_max_u32_e32 v74, v84, v93
	v_min_u32_e32 v93, v84, v93
	v_max_u32_e32 v84, v80, v98
	v_min_u32_e32 v98, v80, v98
	v_max_u32_e32 v80, v76, v73
	v_min_u32_e32 v73, v76, v73
	v_max_u32_e32 v76, v95, v89
	v_min_u32_e32 v89, v95, v89
	v_max_u32_e32 v95, v93, v84
	v_min_u32_e32 v84, v93, v84
	v_max_u32_e32 v93, v98, v80
	v_min_u32_e32 v80, v98, v80
	v_pk_ashrrev_i16 v98, s42, v8
	v_bitop3_b32 v98, v8, v98, s43 bitop3:0x2d
	v_lshl_or_b32 v103, v98, 16, 47
	v_and_or_b32 v104, v98, s44, 46
	v_pk_ashrrev_i16 v98, s42, v9
	v_bitop3_b32 v98, v9, v98, s43 bitop3:0x2d
	v_lshl_or_b32 v105, v98, 16, 45
	v_and_or_b32 v106, v98, s44, 44
	v_pk_ashrrev_i16 v98, s42, v10
	v_bitop3_b32 v98, v10, v98, s43 bitop3:0x2d
	v_lshl_or_b32 v107, v98, 16, 43
	v_and_or_b32 v108, v98, s44, 42
	v_pk_ashrrev_i16 v98, s42, v11
	v_bitop3_b32 v98, v11, v98, s43 bitop3:0x2d
	v_lshl_or_b32 v109, v98, 16, 41
	v_and_or_b32 v110, v98, s44, 40
	v_pk_ashrrev_i16 v98, s42, v12
	v_bitop3_b32 v98, v12, v98, s43 bitop3:0x2d
	v_lshl_or_b32 v111, v98, 16, 39
	v_and_or_b32 v112, v98, s44, 38
	v_pk_ashrrev_i16 v98, s42, v13
	v_bitop3_b32 v98, v13, v98, s43 bitop3:0x2d
	v_lshl_or_b32 v114, v98, 16, 37
	v_and_or_b32 v115, v98, s44, 36
	v_pk_ashrrev_i16 v98, s42, v14
	v_bitop3_b32 v98, v14, v98, s43 bitop3:0x2d
	v_lshl_or_b32 v116, v98, 16, 35
	v_and_or_b32 v117, v98, s44, 34
	v_pk_ashrrev_i16 v98, s42, v15
	v_bitop3_b32 v98, v15, v98, s43 bitop3:0x2d
	v_lshl_or_b32 v118, v98, 16, 33
	v_and_or_b32 v119, v98, s44, 32
	v_max_u32_e32 v98, v103, v117
	v_min_u32_e32 v117, v103, v117
	v_max_u32_e32 v103, v104, v116
	v_min_u32_e32 v116, v104, v116
	v_max_u32_e32 v104, v105, v119
	v_min_u32_e32 v119, v105, v119
	v_max_u32_e32 v105, v106, v118
	v_min_u32_e32 v118, v106, v118
	v_max_u32_e32 v106, v107, v111
	v_min_u32_e32 v111, v107, v111
	v_max_u32_e32 v107, v108, v109
	v_min_u32_e32 v109, v108, v109
	v_max_u32_e32 v108, v110, v115
	v_min_u32_e32 v115, v110, v115
	v_max_u32_e32 v110, v112, v114
	v_min_u32_e32 v114, v112, v114
	v_max_u32_e32 v112, v98, v107
	v_min_u32_e32 v107, v98, v107
	v_max_u32_e32 v98, v103, v108
	v_min_u32_e32 v108, v103, v108
	v_max_u32_e32 v103, v104, v110
	v_min_u32_e32 v110, v104, v110
	v_max_u32_e32 v104, v105, v106
	v_min_u32_e32 v106, v105, v106
	v_max_u32_e32 v105, v109, v117
	v_min_u32_e32 v117, v109, v117
	v_max_u32_e32 v109, v111, v118
	v_min_u32_e32 v118, v111, v118
	v_max_u32_e32 v111, v114, v119
	v_min_u32_e32 v119, v114, v119
	v_max_u32_e32 v114, v115, v116
	v_min_u32_e32 v116, v115, v116
	v_max_u32_e32 v115, v112, v98
	v_min_u32_e32 v98, v112, v98
	v_max_u32_e32 v112, v103, v104
	v_min_u32_e32 v104, v103, v104
	v_max_u32_e32 v103, v106, v107
	v_min_u32_e32 v107, v106, v107
	v_max_u32_e32 v106, v105, v109
	v_min_u32_e32 v109, v105, v109
	v_max_u32_e32 v105, v108, v110
	v_min_u32_e32 v110, v108, v110
	v_max_u32_e32 v108, v111, v114
	v_min_u32_e32 v114, v111, v114
	v_max_u32_e32 v111, v116, v117
	v_min_u32_e32 v117, v116, v117
	v_max_u32_e32 v116, v118, v119
	v_min_u32_e32 v119, v118, v119
	v_max_u32_e32 v118, v115, v112
	v_min_u32_e32 v112, v115, v112
	v_max_u32_e32 v115, v98, v104
	v_min_u32_e32 v104, v98, v104
	v_max_u32_e32 v98, v103, v108
	v_min_u32_e32 v108, v103, v108
	v_max_u32_e32 v103, v107, v114
; __device__ __forceinline__ unsigned f2key(float f) { const unsigned u = __float_as_uint(f); return (u & 0x80000000u) ? ~u : (u | 0x80000000u); }
; #define CE_DESC(a, b) do { const unsigned _mx = (a) > (b) ? (a) : (b), _mn = (a) > (b) ? (b) : (a); (a) = _mx; (b) = _mn; } while (0)
; __device__ __forceinline__ void merge16(unsigned (&a)[16], const unsigned (&b)[16]) {
; #pragma unroll
;     for (int i = 0; i < 16; ++i) a[i] = a[i] > b[15 - i] ? a[i] : b[15 - i];
; #pragma unroll
;     for (int stride = 8; stride > 0; stride >>= 1)
; #pragma unroll
;         for (int i = 0; i < 16; ++i) { const int j = i ^ stride; if (j > i) CE_DESC(a[i], a[j]); }
; }
; __device__ __forceinline__ void peer_tile(const Args& A, LAS unsigned char* lds, int tile) {
;     ...
;                 { const bf16_t* sp = QRY + m * 2048 + hp * 128 + 32 * g;
;                   const u32x4 s0 = *(const u32x4*)sp, s1 = *(const u32x4*)(sp + 8), s2 = *(const u32x4*)(sp + 16), s3 = *(const u32x4*)(sp + 24);
;                   const unsigned sw[16] = {s0.x, s0.y, s0.z, s0.w, s1.x, s1.y, s1.z, s1.w, s2.x, s2.y, s2.z, s2.w, s3.x, s3.y, s3.z, s3.w};
; #pragma unroll
;                   for (int i = 0; i < 16; ++i) {
;                       const float lo = (float)__builtin_bit_cast(_Float16, (unsigned short)(sw[i] & 0xffffu)), hi = (float)__builtin_bit_cast(_Float16, (unsigned short)(sw[i] >> 16));
;                       const unsigned klo = (f2key(lo) & ~127u) | (unsigned)(127 - (32 * g + 2 * i)), khi = (f2key(hi) & ~127u) | (unsigned)(127 - (32 * g + 2 * i + 1));
;                       if (i < 8) { k0[2 * i] = klo; k0[2 * i + 1] = khi; } else { k1[2 * (i - 8)] = klo; k1[2 * (i - 8) + 1] = khi; } } }
;                 sort16_desc(k0); sort16_desc(k1); merge16(k0, k1);
	v_min_u32_e32 v114, v107, v114
	v_max_u32_e32 v107, v106, v105
	v_min_u32_e32 v105, v106, v105
	v_max_u32_e32 v106, v109, v110
	v_min_u32_e32 v110, v109, v110
	v_max_u32_e32 v109, v111, v116
	v_min_u32_e32 v116, v111, v116
	v_max_u32_e32 v111, v117, v119
	v_min_u32_e32 v119, v117, v119
	v_max_u32_e32 v117, v115, v112
	v_min_u32_e32 v112, v115, v112
	v_max_u32_e32 v115, v104, v109
	v_min_u32_e32 v109, v104, v109
	v_max_u32_e32 v104, v98, v107
	v_min_u32_e32 v107, v98, v107
	v_max_u32_e32 v98, v103, v105
	v_min_u32_e32 v105, v103, v105
	v_max_u32_e32 v103, v106, v108
	v_min_u32_e32 v108, v106, v108
	v_max_u32_e32 v106, v110, v114
	v_min_u32_e32 v114, v110, v114
	v_max_u32_e32 v110, v111, v116
	v_min_u32_e32 v116, v111, v116
	v_max_u32_e32 v111, v117, v104
	v_min_u32_e32 v104, v117, v104
	v_max_u32_e32 v117, v112, v107
	v_min_u32_e32 v107, v112, v107
	v_max_u32_e32 v112, v98, v103
	v_min_u32_e32 v103, v98, v103
	v_max_u32_e32 v98, v105, v108
	v_min_u32_e32 v108, v105, v108
	v_max_u32_e32 v105, v106, v110
	v_min_u32_e32 v110, v106, v110
	v_max_u32_e32 v106, v114, v116
	v_min_u32_e32 v116, v114, v116
	v_max_u32_e32 v114, v117, v104
	v_min_u32_e32 v104, v117, v104
	v_max_u32_e32 v117, v115, v107
	v_min_u32_e32 v107, v115, v107
	v_max_u32_e32 v115, v105, v109
	v_min_u32_e32 v109, v105, v109
	v_max_u32_e32 v105, v106, v110
	v_min_u32_e32 v110, v106, v110
	v_max_u32_e32 v106, v117, v112
	v_min_u32_e32 v112, v117, v112
	v_max_u32_e32 v117, v107, v103
	v_min_u32_e32 v103, v107, v103
	v_max_u32_e32 v107, v98, v115
	v_min_u32_e32 v115, v98, v115
	v_max_u32_e32 v98, v108, v109
	v_min_u32_e32 v109, v108, v109
	v_max_u32_e32 v108, v106, v104
	v_min_u32_e32 v104, v106, v104
	v_max_u32_e32 v106, v112, v117
	v_min_u32_e32 v117, v112, v117
	v_max_u32_e32 v112, v107, v103
	v_min_u32_e32 v103, v107, v103
	v_max_u32_e32 v107, v115, v98
	v_min_u32_e32 v98, v115, v98
	v_max_u32_e32 v115, v105, v109
	v_min_u32_e32 v109, v105, v109
	v_max_u32_e32 v105, v117, v112
	v_min_u32_e32 v112, v117, v112
	v_max_u32_e32 v117, v103, v107
	v_min_u32_e32 v107, v103, v107
	v_max_u32_e32 v101, v101, v119
	v_max_u32_e32 v100, v100, v116
	v_max_u32_e32 v91, v91, v110
	v_max_u32_e32 v79, v79, v109
	v_max_u32_e32 v71, v71, v115
	v_max_u32_e32 v74, v74, v98
	v_max_u32_e32 v95, v95, v107
	v_max_u32_e32 v84, v84, v117
	v_max_u32_e32 v93, v93, v112
	v_max_u32_e32 v80, v80, v105
	v_max_u32_e32 v73, v73, v106
	v_max_u32_e32 v76, v76, v104
	v_max_u32_e32 v89, v89, v108
	v_max_u32_e32 v83, v83, v114
	v_max_u32_e32 v92, v92, v111
	v_max_u32_e32 v90, v90, v118
	v_max_u32_e32 v119, v101, v93
	v_min_u32_e32 v93, v101, v93
	v_max_u32_e32 v101, v100, v80
	v_min_u32_e32 v80, v100, v80
	v_max_u32_e32 v100, v91, v73
	v_min_u32_e32 v73, v91, v73
	v_max_u32_e32 v91, v79, v76
	v_min_u32_e32 v76, v79, v76
	v_max_u32_e32 v79, v71, v89
	v_min_u32_e32 v89, v71, v89
	v_max_u32_e32 v71, v74, v83
	v_min_u32_e32 v83, v74, v83
	v_max_u32_e32 v74, v95, v92
	v_min_u32_e32 v92, v95, v92
	v_max_u32_e32 v95, v84, v90
	v_min_u32_e32 v90, v84, v90
	v_max_u32_e32 v84, v119, v79
	v_min_u32_e32 v79, v119, v79
	v_max_u32_e32 v119, v101, v71
	v_min_u32_e32 v71, v101, v71
	v_max_u32_e32 v101, v100, v74
	v_min_u32_e32 v74, v100, v74
	v_max_u32_e32 v100, v91, v95
	v_min_u32_e32 v95, v91, v95
	v_max_u32_e32 v91, v93, v89
	v_min_u32_e32 v89, v93, v89
	v_max_u32_e32 v93, v80, v83
	v_min_u32_e32 v83, v80, v83
	v_max_u32_e32 v80, v73, v92
	v_min_u32_e32 v92, v73, v92
	v_max_u32_e32 v73, v76, v90
	v_min_u32_e32 v90, v76, v90
	v_max_u32_e32 v76, v84, v101
	v_min_u32_e32 v101, v84, v101
	v_max_u32_e32 v84, v119, v100
	v_min_u32_e32 v100, v119, v100
	v_max_u32_e32 v119, v79, v74
	v_min_u32_e32 v74, v79, v74
	v_max_u32_e32 v79, v71, v95
	v_min_u32_e32 v95, v71, v95
	v_max_u32_e32 v71, v91, v80
	v_min_u32_e32 v80, v91, v80
	v_max_u32_e32 v91, v93, v73
	v_min_u32_e32 v73, v93, v73
	v_max_u32_e32 v93, v89, v92
	v_min_u32_e32 v92, v89, v92
	v_max_u32_e32 v89, v83, v90
	v_min_u32_e32 v90, v83, v90
	v_max_u32_e32 v83, v76, v84
	v_min_u32_e32 v84, v76, v84
	v_max_u32_e32 v76, v101, v100
	v_min_u32_e32 v100, v101, v100
	v_max_u32_e32 v101, v119, v79
	v_min_u32_e32 v79, v119, v79
	v_max_u32_e32 v119, v74, v95
	v_min_u32_e32 v95, v74, v95
	v_max_u32_e32 v74, v71, v91
	v_min_u32_e32 v91, v71, v91
	v_max_u32_e32 v71, v80, v73
	v_min_u32_e32 v73, v80, v73
	v_max_u32_e32 v80, v93, v89
	v_min_u32_e32 v89, v93, v89
	v_max_u32_e32 v93, v92, v90
	v_min_u32_e32 v90, v92, v90
	v_pk_ashrrev_i16 v92, s42, v16
	v_bitop3_b32 v92, v16, v92, s43 bitop3:0x2d
	v_lshl_or_b32 v116, v92, 16, 31
	v_and_or_b32 v110, v92, s44, 30
	v_pk_ashrrev_i16 v92, s42, v17
	v_bitop3_b32 v92, v17, v92, s43 bitop3:0x2d
	v_lshl_or_b32 v109, v92, 16, 29
	v_and_or_b32 v115, v92, s44, 28
	v_pk_ashrrev_i16 v92, s42, v18
	v_bitop3_b32 v92, v18, v92, s43 bitop3:0x2d
	v_lshl_or_b32 v98, v92, 16, 27
	v_and_or_b32 v107, v92, s44, 26
	v_pk_ashrrev_i16 v92, s42, v19
	v_bitop3_b32 v92, v19, v92, s43 bitop3:0x2d
	v_lshl_or_b32 v117, v92, 16, 25
	v_and_or_b32 v112, v92, s44, 24
	v_pk_ashrrev_i16 v92, s42, v20
	v_bitop3_b32 v92, v20, v92, s43 bitop3:0x2d
	v_lshl_or_b32 v105, v92, 16, 23
	v_and_or_b32 v106, v92, s44, 22
	v_pk_ashrrev_i16 v92, s42, v21
	v_bitop3_b32 v92, v21, v92, s43 bitop3:0x2d
	v_lshl_or_b32 v104, v92, 16, 21
	v_and_or_b32 v108, v92, s44, 20
	v_pk_ashrrev_i16 v92, s42, v22
	v_bitop3_b32 v92, v22, v92, s43 bitop3:0x2d
	v_lshl_or_b32 v114, v92, 16, 19
	v_and_or_b32 v111, v92, s44, 18
	v_pk_ashrrev_i16 v92, s42, v23
	v_bitop3_b32 v92, v23, v92, s43 bitop3:0x2d
	v_lshl_or_b32 v118, v92, 16, 17
	v_and_or_b32 v103, v92, s44, 16
	v_max_u32_e32 v92, v116, v111
	v_min_u32_e32 v111, v116, v111
; #define CE_DESC(a, b) do { const unsigned _mx = (a) > (b) ? (a) : (b), _mn = (a) > (b) ? (b) : (a); (a) = _mx; (b) = _mn; } while (0)
; __device__ __forceinline__ void sort16_desc(unsigned (&k)[16]) {
; #pragma unroll
;     for (int size = 2; size <= 16; size <<= 1)
; #pragma unroll
;         for (int stride = size >> 1; stride > 0; stride >>= 1)
; #pragma unroll
;             for (int i = 0; i < 16; ++i) { const int j = i ^ stride;
;                 if (j > i) { if ((i & size) == 0) CE_DESC(k[i], k[j]); else CE_DESC(k[j], k[i]); } }
; }
; __device__ __forceinline__ void merge16(unsigned (&a)[16], const unsigned (&b)[16]) {
; #pragma unroll
;     for (int i = 0; i < 16; ++i) a[i] = a[i] > b[15 - i] ? a[i] : b[15 - i];
; #pragma unroll
;     for (int stride = 8; stride > 0; stride >>= 1)
; #pragma unroll
;         for (int i = 0; i < 16; ++i) { const int j = i ^ stride; if (j > i) CE_DESC(a[i], a[j]); }
; }
	v_max_u32_e32 v116, v110, v114
	v_min_u32_e32 v114, v110, v114
	v_max_u32_e32 v110, v109, v103
	v_min_u32_e32 v103, v109, v103
	v_max_u32_e32 v109, v115, v118
	v_min_u32_e32 v118, v115, v118
	v_max_u32_e32 v115, v98, v105
	v_min_u32_e32 v105, v98, v105
	v_max_u32_e32 v98, v107, v117
	v_min_u32_e32 v117, v107, v117
	v_max_u32_e32 v107, v112, v108
	v_min_u32_e32 v108, v112, v108
	v_max_u32_e32 v112, v106, v104
	v_min_u32_e32 v104, v106, v104
	v_max_u32_e32 v106, v92, v98
	v_min_u32_e32 v98, v92, v98
	v_max_u32_e32 v92, v116, v107
	v_min_u32_e32 v107, v116, v107
	v_max_u32_e32 v116, v110, v112
	v_min_u32_e32 v112, v110, v112
	v_max_u32_e32 v110, v109, v115
	v_min_u32_e32 v115, v109, v115
	v_max_u32_e32 v109, v117, v111
	v_min_u32_e32 v111, v117, v111
	v_max_u32_e32 v117, v105, v118
	v_min_u32_e32 v118, v105, v118
	v_max_u32_e32 v105, v104, v103
	v_min_u32_e32 v103, v104, v103
	v_max_u32_e32 v104, v108, v114
	v_min_u32_e32 v114, v108, v114
	v_max_u32_e32 v108, v106, v92
	v_min_u32_e32 v92, v106, v92
	v_max_u32_e32 v106, v116, v110
	v_min_u32_e32 v110, v116, v110
	v_max_u32_e32 v116, v115, v98
	v_min_u32_e32 v98, v115, v98
	v_max_u32_e32 v115, v109, v117
	v_min_u32_e32 v117, v109, v117
	v_max_u32_e32 v109, v107, v112
	v_min_u32_e32 v112, v107, v112
	v_max_u32_e32 v107, v105, v104
	v_min_u32_e32 v104, v105, v104
	v_max_u32_e32 v105, v114, v111
	v_min_u32_e32 v111, v114, v111
	v_max_u32_e32 v114, v118, v103
	v_min_u32_e32 v103, v118, v103
	v_max_u32_e32 v118, v108, v106
	v_min_u32_e32 v106, v108, v106
	v_max_u32_e32 v108, v92, v110
	v_min_u32_e32 v110, v92, v110
	v_max_u32_e32 v92, v116, v107
	v_min_u32_e32 v107, v116, v107
	v_max_u32_e32 v116, v98, v104
	v_min_u32_e32 v104, v98, v104
	v_max_u32_e32 v98, v115, v109
	v_min_u32_e32 v109, v115, v109
	v_max_u32_e32 v115, v117, v112
	v_min_u32_e32 v112, v117, v112
	v_max_u32_e32 v117, v105, v114
	v_min_u32_e32 v114, v105, v114
	v_max_u32_e32 v105, v111, v103
	v_min_u32_e32 v103, v111, v103
	v_max_u32_e32 v111, v108, v106
	v_min_u32_e32 v106, v108, v106
	v_max_u32_e32 v108, v110, v117
	v_min_u32_e32 v117, v110, v117
	v_max_u32_e32 v110, v92, v98
	v_min_u32_e32 v98, v92, v98
	v_max_u32_e32 v92, v116, v109
	v_min_u32_e32 v109, v116, v109
	v_max_u32_e32 v116, v115, v107
	v_min_u32_e32 v107, v115, v107
	v_max_u32_e32 v115, v112, v104
	v_min_u32_e32 v104, v112, v104
	v_max_u32_e32 v112, v105, v114
	v_min_u32_e32 v114, v105, v114
	v_max_u32_e32 v105, v111, v110
	v_min_u32_e32 v110, v111, v110
	v_max_u32_e32 v111, v106, v98
	v_min_u32_e32 v98, v106, v98
	v_max_u32_e32 v106, v92, v116
	v_min_u32_e32 v116, v92, v116
	v_max_u32_e32 v92, v109, v107
	v_min_u32_e32 v107, v109, v107
	v_max_u32_e32 v109, v115, v112
	v_min_u32_e32 v112, v115, v112
	v_max_u32_e32 v115, v104, v114
	v_min_u32_e32 v114, v104, v114
	v_max_u32_e32 v104, v111, v110
	v_min_u32_e32 v110, v111, v110
	v_max_u32_e32 v111, v108, v98
	v_min_u32_e32 v98, v108, v98
	v_max_u32_e32 v108, v109, v117
	v_min_u32_e32 v117, v109, v117
	v_max_u32_e32 v109, v115, v112
	v_min_u32_e32 v112, v115, v112
	v_max_u32_e32 v115, v111, v106
	v_min_u32_e32 v106, v111, v106
	v_max_u32_e32 v111, v98, v116
	v_min_u32_e32 v116, v98, v116
	v_max_u32_e32 v98, v92, v108
	v_min_u32_e32 v108, v92, v108
	v_max_u32_e32 v92, v107, v117
	v_min_u32_e32 v117, v107, v117
	v_max_u32_e32 v107, v115, v110
	v_min_u32_e32 v110, v115, v110
	v_max_u32_e32 v115, v106, v111
	v_min_u32_e32 v111, v106, v111
	v_max_u32_e32 v106, v98, v116
	v_min_u32_e32 v116, v98, v116
	v_max_u32_e32 v98, v108, v92
	v_min_u32_e32 v92, v108, v92
	v_max_u32_e32 v108, v109, v117
	v_min_u32_e32 v117, v109, v117
	v_max_u32_e32 v109, v111, v106
	v_min_u32_e32 v106, v111, v106
	v_max_u32_e32 v111, v116, v98
	v_min_u32_e32 v98, v116, v98
	v_max_u32_e32 v83, v83, v103
	v_max_u32_e32 v84, v84, v114
	v_max_u32_e32 v76, v76, v112
	v_max_u32_e32 v100, v100, v117
	v_max_u32_e32 v101, v101, v108
	v_max_u32_e32 v79, v79, v92
	v_max_u32_e32 v119, v119, v98
	v_max_u32_e32 v95, v95, v111
	v_max_u32_e32 v74, v74, v106
	v_max_u32_e32 v91, v91, v109
	v_max_u32_e32 v71, v71, v115
	v_max_u32_e32 v73, v73, v110
	v_max_u32_e32 v80, v80, v107
	v_max_u32_e32 v89, v89, v104
	v_max_u32_e32 v93, v93, v105
	v_max_u32_e32 v90, v90, v118
	v_max_u32_e32 v103, v83, v74
	v_min_u32_e32 v74, v83, v74
	v_max_u32_e32 v83, v84, v91
	v_min_u32_e32 v91, v84, v91
	v_max_u32_e32 v84, v76, v71
	v_min_u32_e32 v71, v76, v71
	v_max_u32_e32 v76, v100, v73
	v_min_u32_e32 v73, v100, v73
	v_max_u32_e32 v100, v101, v80
	v_min_u32_e32 v80, v101, v80
	v_max_u32_e32 v101, v79, v89
	v_min_u32_e32 v89, v79, v89
	v_max_u32_e32 v79, v119, v93
	v_min_u32_e32 v93, v119, v93
	v_max_u32_e32 v119, v95, v90
	v_min_u32_e32 v90, v95, v90
	v_max_u32_e32 v95, v103, v100
	v_min_u32_e32 v100, v103, v100
	v_max_u32_e32 v103, v83, v101
	v_min_u32_e32 v101, v83, v101
	v_max_u32_e32 v83, v84, v79
	v_min_u32_e32 v79, v84, v79
	v_max_u32_e32 v84, v76, v119
	v_min_u32_e32 v119, v76, v119
	v_max_u32_e32 v76, v74, v80
	v_min_u32_e32 v80, v74, v80
	v_max_u32_e32 v74, v91, v89
	v_min_u32_e32 v89, v91, v89
	v_max_u32_e32 v91, v71, v93
	v_min_u32_e32 v93, v71, v93
	v_max_u32_e32 v71, v73, v90
	v_min_u32_e32 v90, v73, v90
	v_max_u32_e32 v73, v95, v83
	v_min_u32_e32 v83, v95, v83
	v_max_u32_e32 v95, v103, v84
	v_min_u32_e32 v84, v103, v84
	v_max_u32_e32 v103, v100, v79
	v_min_u32_e32 v79, v100, v79
	v_max_u32_e32 v100, v101, v119
	v_min_u32_e32 v119, v101, v119
	v_max_u32_e32 v101, v76, v91
	v_min_u32_e32 v91, v76, v91
	v_max_u32_e32 v76, v74, v71
	v_min_u32_e32 v71, v74, v71
	v_max_u32_e32 v74, v80, v93
	v_min_u32_e32 v93, v80, v93
	v_max_u32_e32 v80, v89, v90
	v_min_u32_e32 v90, v89, v90
; __device__ __forceinline__ unsigned f2key(float f) { const unsigned u = __float_as_uint(f); return (u & 0x80000000u) ? ~u : (u | 0x80000000u); }
; #define CE_DESC(a, b) do { const unsigned _mx = (a) > (b) ? (a) : (b), _mn = (a) > (b) ? (b) : (a); (a) = _mx; (b) = _mn; } while (0)
; __device__ __forceinline__ void sort16_desc(unsigned (&k)[16]) {
; #pragma unroll
;     for (int size = 2; size <= 16; size <<= 1)
; #pragma unroll
;         for (int stride = size >> 1; stride > 0; stride >>= 1)
; #pragma unroll
;             for (int i = 0; i < 16; ++i) { const int j = i ^ stride;
;                 if (j > i) { if ((i & size) == 0) CE_DESC(k[i], k[j]); else CE_DESC(k[j], k[i]); } }
; }
; __device__ __forceinline__ void merge16(unsigned (&a)[16], const unsigned (&b)[16]) {
; #pragma unroll
;     for (int i = 0; i < 16; ++i) a[i] = a[i] > b[15 - i] ? a[i] : b[15 - i];
; #pragma unroll
;     for (int stride = 8; stride > 0; stride >>= 1)
; #pragma unroll
;         for (int i = 0; i < 16; ++i) { const int j = i ^ stride; if (j > i) CE_DESC(a[i], a[j]); }
; }
; __device__ __forceinline__ void peer_tile(const Args& A, LAS unsigned char* lds, int tile) {
;     ...
;                 { const bf16_t* sp = QRY + m * 2048 + hp * 128 + 32 * g;
;                   const u32x4 s0 = *(const u32x4*)sp, s1 = *(const u32x4*)(sp + 8), s2 = *(const u32x4*)(sp + 16), s3 = *(const u32x4*)(sp + 24);
;                   const unsigned sw[16] = {s0.x, s0.y, s0.z, s0.w, s1.x, s1.y, s1.z, s1.w, s2.x, s2.y, s2.z, s2.w, s3.x, s3.y, s3.z, s3.w};
; #pragma unroll
;                   for (int i = 0; i < 16; ++i) {
;                       const float lo = (float)__builtin_bit_cast(_Float16, (unsigned short)(sw[i] & 0xffffu)), hi = (float)__builtin_bit_cast(_Float16, (unsigned short)(sw[i] >> 16));
;                       const unsigned klo = (f2key(lo) & ~127u) | (unsigned)(127 - (32 * g + 2 * i)), khi = (f2key(hi) & ~127u) | (unsigned)(127 - (32 * g + 2 * i + 1));
;                       if (i < 8) { k0[2 * i] = klo; k0[2 * i + 1] = khi; } else { k1[2 * (i - 8)] = klo; k1[2 * (i - 8) + 1] = khi; } } }
;                 sort16_desc(k0); sort16_desc(k1); merge16(k0, k1);
	v_max_u32_e32 v89, v73, v95
	v_min_u32_e32 v95, v73, v95
	v_max_u32_e32 v73, v83, v84
	v_min_u32_e32 v84, v83, v84
	v_max_u32_e32 v83, v103, v100
	v_min_u32_e32 v100, v103, v100
	v_max_u32_e32 v103, v79, v119
	v_min_u32_e32 v119, v79, v119
	v_max_u32_e32 v79, v101, v76
	v_min_u32_e32 v76, v101, v76
	v_max_u32_e32 v101, v91, v71
	v_min_u32_e32 v71, v91, v71
	v_max_u32_e32 v91, v74, v80
	v_min_u32_e32 v80, v74, v80
	v_max_u32_e32 v74, v93, v90
	v_min_u32_e32 v90, v93, v90
	v_pk_ashrrev_i16 v93, s42, v24
	v_bitop3_b32 v93, v24, v93, s43 bitop3:0x2d
	v_lshl_or_b32 v114, v93, 16, 15
	v_and_or_b32 v112, v93, s44, 14
	v_pk_ashrrev_i16 v93, s42, v25
	v_bitop3_b32 v93, v25, v93, s43 bitop3:0x2d
	v_lshl_or_b32 v117, v93, 16, 13
	v_and_or_b32 v108, v93, s44, 12
	v_pk_ashrrev_i16 v93, s42, v26
	v_bitop3_b32 v93, v26, v93, s43 bitop3:0x2d
	v_lshl_or_b32 v92, v93, 16, 11
	v_and_or_b32 v98, v93, s44, 10
	v_pk_ashrrev_i16 v93, s42, v27
	v_bitop3_b32 v93, v27, v93, s43 bitop3:0x2d
	v_lshl_or_b32 v111, v93, 16, 9
	v_and_or_b32 v106, v93, s44, 8
	v_pk_ashrrev_i16 v93, s42, v28
	v_bitop3_b32 v93, v28, v93, s43 bitop3:0x2d
	v_lshl_or_b32 v109, v93, 16, 7
	v_and_or_b32 v115, v93, s44, 6
	v_pk_ashrrev_i16 v93, s42, v29
	v_bitop3_b32 v93, v29, v93, s43 bitop3:0x2d
	v_lshl_or_b32 v110, v93, 16, 5
	v_and_or_b32 v107, v93, s44, 4
	v_pk_ashrrev_i16 v93, s42, v30
	v_bitop3_b32 v93, v30, v93, s43 bitop3:0x2d
	v_lshl_or_b32 v104, v93, 16, 3
	v_and_or_b32 v105, v93, s44, 2
	v_pk_ashrrev_i16 v93, s42, v31
	v_bitop3_b32 v93, v31, v93, s43 bitop3:0x2d
	v_lshl_or_b32 v118, v93, 16, 1
	v_and_or_b32 v116, v93, s44, 0
	v_max_u32_e32 v93, v114, v105
	v_min_u32_e32 v105, v114, v105
	v_max_u32_e32 v114, v112, v104
	v_min_u32_e32 v104, v112, v104
	v_max_u32_e32 v112, v117, v116
	v_min_u32_e32 v116, v117, v116
	v_max_u32_e32 v117, v108, v118
	v_min_u32_e32 v118, v108, v118
	v_max_u32_e32 v108, v92, v109
	v_min_u32_e32 v109, v92, v109
	v_max_u32_e32 v92, v98, v111
	v_min_u32_e32 v111, v98, v111
	v_max_u32_e32 v98, v106, v107
	v_min_u32_e32 v107, v106, v107
	v_max_u32_e32 v106, v115, v110
	v_min_u32_e32 v110, v115, v110
	v_max_u32_e32 v115, v93, v92
	v_min_u32_e32 v92, v93, v92
	v_max_u32_e32 v93, v114, v98
	v_min_u32_e32 v98, v114, v98
	v_max_u32_e32 v114, v112, v106
	v_min_u32_e32 v106, v112, v106
	v_max_u32_e32 v112, v117, v108
	v_min_u32_e32 v108, v117, v108
	v_max_u32_e32 v117, v111, v105
	v_min_u32_e32 v105, v111, v105
	v_max_u32_e32 v111, v109, v118
	v_min_u32_e32 v118, v109, v118
	v_max_u32_e32 v109, v110, v116
	v_min_u32_e32 v116, v110, v116
	v_max_u32_e32 v110, v107, v104
	v_min_u32_e32 v104, v107, v104
	v_max_u32_e32 v107, v115, v93
	v_min_u32_e32 v93, v115, v93
	v_max_u32_e32 v115, v114, v112
	v_min_u32_e32 v112, v114, v112
	v_max_u32_e32 v114, v108, v92
	v_min_u32_e32 v92, v108, v92
	v_max_u32_e32 v108, v117, v111
	v_min_u32_e32 v111, v117, v111
	v_max_u32_e32 v117, v98, v106
	v_min_u32_e32 v106, v98, v106
	v_max_u32_e32 v98, v109, v110
	v_min_u32_e32 v110, v109, v110
	v_max_u32_e32 v109, v104, v105
	v_min_u32_e32 v105, v104, v105
	v_max_u32_e32 v104, v118, v116
	v_min_u32_e32 v116, v118, v116
	v_max_u32_e32 v118, v107, v115
	v_min_u32_e32 v115, v107, v115
	v_max_u32_e32 v107, v93, v112
	v_min_u32_e32 v112, v93, v112
	v_max_u32_e32 v93, v114, v98
	v_min_u32_e32 v98, v114, v98
	v_max_u32_e32 v114, v92, v110
	v_min_u32_e32 v110, v92, v110
	v_max_u32_e32 v92, v108, v117
	v_min_u32_e32 v117, v108, v117
	v_max_u32_e32 v108, v111, v106
	v_min_u32_e32 v106, v111, v106
	v_max_u32_e32 v111, v109, v104
	v_min_u32_e32 v104, v109, v104
	v_max_u32_e32 v109, v105, v116
	v_min_u32_e32 v116, v105, v116
	v_max_u32_e32 v105, v107, v115
	v_min_u32_e32 v115, v107, v115
	v_max_u32_e32 v107, v112, v111
	v_min_u32_e32 v111, v112, v111
	v_max_u32_e32 v112, v93, v92
	v_min_u32_e32 v92, v93, v92
	v_max_u32_e32 v93, v114, v117
	v_min_u32_e32 v117, v114, v117
	v_max_u32_e32 v114, v108, v98
	v_min_u32_e32 v98, v108, v98
	v_max_u32_e32 v108, v106, v110
	v_min_u32_e32 v110, v106, v110
	v_max_u32_e32 v106, v109, v104
	v_min_u32_e32 v104, v109, v104
	v_max_u32_e32 v109, v105, v112
	v_min_u32_e32 v112, v105, v112
	v_max_u32_e32 v105, v115, v92
	v_min_u32_e32 v92, v115, v92
	v_max_u32_e32 v115, v93, v114
	v_min_u32_e32 v114, v93, v114
	v_max_u32_e32 v93, v117, v98
	v_min_u32_e32 v98, v117, v98
	v_max_u32_e32 v117, v108, v106
	v_min_u32_e32 v106, v108, v106
	v_max_u32_e32 v108, v110, v104
	v_min_u32_e32 v104, v110, v104
	v_max_u32_e32 v110, v105, v112
	v_min_u32_e32 v112, v105, v112
	v_max_u32_e32 v105, v107, v92
	v_min_u32_e32 v92, v107, v92
	v_max_u32_e32 v107, v117, v111
	v_min_u32_e32 v111, v117, v111
	v_max_u32_e32 v117, v108, v106
	v_min_u32_e32 v106, v108, v106
	v_max_u32_e32 v108, v105, v115
	v_min_u32_e32 v115, v105, v115
	v_max_u32_e32 v105, v92, v114
	v_min_u32_e32 v114, v92, v114
	v_max_u32_e32 v92, v93, v107
	v_min_u32_e32 v107, v93, v107
	v_max_u32_e32 v93, v98, v111
	v_min_u32_e32 v111, v98, v111
	v_max_u32_e32 v98, v108, v112
	v_min_u32_e32 v112, v108, v112
	v_max_u32_e32 v108, v115, v105
	v_min_u32_e32 v105, v115, v105
	v_max_u32_e32 v115, v92, v114
	v_min_u32_e32 v114, v92, v114
	v_max_u32_e32 v92, v107, v93
	v_min_u32_e32 v93, v107, v93
	v_max_u32_e32 v107, v117, v111
	v_min_u32_e32 v111, v117, v111
	v_max_u32_e32 v117, v105, v115
	v_min_u32_e32 v115, v105, v115
	v_max_u32_e32 v105, v114, v92
	v_min_u32_e32 v92, v114, v92
	v_max_u32_e32 v89, v89, v116
	v_max_u32_e32 v95, v95, v104
	v_max_u32_e32 v73, v73, v106
	v_max_u32_e32 v84, v84, v111
	v_max_u32_e32 v83, v83, v107
	v_max_u32_e32 v100, v100, v93
	v_max_u32_e32 v103, v103, v92
	v_max_u32_e32 v119, v119, v105
	v_max_u32_e32 v79, v79, v115
; __device__ __forceinline__ unsigned f2key(float f) { const unsigned u = __float_as_uint(f); return (u & 0x80000000u) ? ~u : (u | 0x80000000u); }
; __device__ __forceinline__ void peer_tile(const Args& A, LAS unsigned char* lds, int tile) {
;     ...
;                 { const bf16_t* sp = QRY + m * 2048 + hp * 128 + 32 * g;
;                   const u32x4 s0 = *(const u32x4*)sp, s1 = *(const u32x4*)(sp + 8), s2 = *(const u32x4*)(sp + 16), s3 = *(const u32x4*)(sp + 24);
;                   const unsigned sw[16] = {s0.x, s0.y, s0.z, s0.w, s1.x, s1.y, s1.z, s1.w, s2.x, s2.y, s2.z, s2.w, s3.x, s3.y, s3.z, s3.w};
; #pragma unroll
;                   for (int i = 0; i < 16; ++i) {
;                       const float lo = (float)__builtin_bit_cast(_Float16, (unsigned short)(sw[i] & 0xffffu)), hi = (float)__builtin_bit_cast(_Float16, (unsigned short)(sw[i] >> 16));
;                       const unsigned klo = (f2key(lo) & ~127u) | (unsigned)(127 - (32 * g + 2 * i)), khi = (f2key(hi) & ~127u) | (unsigned)(127 - (32 * g + 2 * i + 1));
;                       if (i < 8) { k0[2 * i] = klo; k0[2 * i + 1] = khi; } else { k1[2 * (i - 8)] = klo; k1[2 * (i - 8) + 1] = khi; } } }
;                 sort16_desc(k0); sort16_desc(k1); merge16(k0, k1);
; #pragma unroll
;                 for (int msk = 16; msk <= 32; msk <<= 1) {
; #pragma unroll
;                     for (int i = 0; i < 16; ++i) k1[i] = (unsigned)__shfl_xor((int)k0[i], msk);
;                     merge16(k0, k1); }
	v_max_u32_e32 v76, v76, v117
	v_max_u32_e32 v101, v101, v108
	v_max_u32_e32 v71, v71, v112
	v_max_u32_e32 v91, v91, v98
	v_max_u32_e32 v80, v80, v110
	v_max_u32_e32 v74, v74, v109
	v_max_u32_e32 v90, v90, v118
	v_max_u32_e32 v116, v89, v79
	v_min_u32_e32 v79, v89, v79
	v_max_u32_e32 v89, v95, v76
	v_min_u32_e32 v76, v95, v76
	v_max_u32_e32 v95, v73, v101
	v_min_u32_e32 v101, v73, v101
	v_max_u32_e32 v73, v84, v71
	v_min_u32_e32 v71, v84, v71
	v_max_u32_e32 v84, v83, v91
	v_min_u32_e32 v91, v83, v91
	v_max_u32_e32 v83, v100, v80
	v_min_u32_e32 v80, v100, v80
	v_max_u32_e32 v100, v103, v74
	v_min_u32_e32 v74, v103, v74
	v_max_u32_e32 v103, v119, v90
	v_min_u32_e32 v90, v119, v90
	v_max_u32_e32 v119, v116, v84
	v_min_u32_e32 v84, v116, v84
	v_max_u32_e32 v116, v89, v83
	v_min_u32_e32 v83, v89, v83
	v_max_u32_e32 v89, v95, v100
	v_min_u32_e32 v100, v95, v100
	v_max_u32_e32 v95, v73, v103
	v_min_u32_e32 v103, v73, v103
	v_max_u32_e32 v73, v79, v91
	v_min_u32_e32 v91, v79, v91
	v_max_u32_e32 v79, v76, v80
	v_min_u32_e32 v80, v76, v80
	v_max_u32_e32 v76, v101, v74
	v_min_u32_e32 v74, v101, v74
	v_max_u32_e32 v101, v71, v90
	v_min_u32_e32 v90, v71, v90
	v_max_u32_e32 v71, v119, v89
	v_min_u32_e32 v89, v119, v89
	v_max_u32_e32 v119, v116, v95
	v_min_u32_e32 v95, v116, v95
	v_max_u32_e32 v116, v84, v100
	v_min_u32_e32 v100, v84, v100
	v_max_u32_e32 v84, v83, v103
	v_min_u32_e32 v103, v83, v103
	v_max_u32_e32 v83, v73, v76
	v_min_u32_e32 v76, v73, v76
	v_max_u32_e32 v73, v79, v101
	v_min_u32_e32 v101, v79, v101
	v_max_u32_e32 v79, v91, v74
	v_min_u32_e32 v74, v91, v74
	v_max_u32_e32 v91, v80, v90
	v_min_u32_e32 v90, v80, v90
	v_max_u32_e32 v80, v71, v119
	v_min_u32_e32 v119, v71, v119
	v_max_u32_e32 v71, v89, v95
	v_min_u32_e32 v95, v89, v95
	v_max_u32_e32 v89, v116, v84
	v_min_u32_e32 v84, v116, v84
	v_max_u32_e32 v116, v100, v103
	v_min_u32_e32 v103, v100, v103
	v_max_u32_e32 v100, v83, v73
	v_min_u32_e32 v73, v83, v73
	v_max_u32_e32 v83, v76, v101
	v_min_u32_e32 v101, v76, v101
	v_max_u32_e32 v76, v79, v91
	v_min_u32_e32 v91, v79, v91
	v_max_u32_e32 v79, v74, v90
	v_min_u32_e32 v90, v74, v90
	v_or_b32_e32 v80, 64, v80
	v_or_b32_e32 v119, 64, v119
	v_or_b32_e32 v71, 64, v71
	v_or_b32_e32 v95, 64, v95
	v_or_b32_e32 v89, 64, v89
	v_or_b32_e32 v84, 64, v84
	v_or_b32_e32 v116, 64, v116
	v_or_b32_e32 v103, 64, v103
	v_or_b32_e32 v100, 64, v100
	v_or_b32_e32 v73, 64, v73
	v_or_b32_e32 v83, 64, v83
	v_or_b32_e32 v101, 64, v101
	v_or_b32_e32 v76, 64, v76
	v_or_b32_e32 v91, 64, v91
	v_or_b32_e32 v79, 64, v79
	v_or_b32_e32 v90, 64, v90
	s_waitcnt vmcnt(0)
	ds_write_b128 v64, v[32:35] offset:0
	ds_write_b128 v64, v[36:39] offset:1152
	ds_write_b128 v64, v[40:43] offset:2304
	ds_write_b128 v64, v[44:47] offset:3456
	ds_write_b128 v64, v[48:51] offset:4608
	ds_write_b128 v64, v[52:55] offset:5760
	ds_write_b128 v64, v[56:59] offset:6912
	ds_write_b128 v64, v[60:63] offset:8064
	s_waitcnt lgkmcnt(0)
	ds_read_b128 v[32:35], v65 offset:0
	ds_read_b128 v[36:39], v65 offset:16
	ds_read_b128 v[40:43], v65 offset:32
	ds_read_b128 v[44:47], v65 offset:48
	ds_read_b128 v[48:51], v65 offset:64
	ds_read_b128 v[52:55], v65 offset:80
	ds_read_b128 v[56:59], v65 offset:96
	ds_read_b128 v[60:63], v65 offset:112
	s_waitcnt lgkmcnt(0)
	v_pk_ashrrev_i16 v74, s42, v32
	v_bitop3_b32 v74, v32, v74, s43 bitop3:0x2d
	v_lshl_or_b32 v104, v74, 16, 63
	v_and_or_b32 v106, v74, s44, 62
	v_pk_ashrrev_i16 v74, s42, v33
	v_bitop3_b32 v74, v33, v74, s43 bitop3:0x2d
	v_lshl_or_b32 v111, v74, 16, 61
	v_and_or_b32 v107, v74, s44, 60
	v_pk_ashrrev_i16 v74, s42, v34
	v_bitop3_b32 v74, v34, v74, s43 bitop3:0x2d
	v_lshl_or_b32 v93, v74, 16, 59
	v_and_or_b32 v92, v74, s44, 58
	v_pk_ashrrev_i16 v74, s42, v35
	v_bitop3_b32 v74, v35, v74, s43 bitop3:0x2d
	v_lshl_or_b32 v105, v74, 16, 57
	v_and_or_b32 v115, v74, s44, 56
	v_pk_ashrrev_i16 v74, s42, v36
	v_bitop3_b32 v74, v36, v74, s43 bitop3:0x2d
	v_lshl_or_b32 v117, v74, 16, 55
	v_and_or_b32 v108, v74, s44, 54
	v_pk_ashrrev_i16 v74, s42, v37
	v_bitop3_b32 v74, v37, v74, s43 bitop3:0x2d
	v_lshl_or_b32 v112, v74, 16, 53
	v_and_or_b32 v98, v74, s44, 52
	v_pk_ashrrev_i16 v74, s42, v38
	v_bitop3_b32 v74, v38, v74, s43 bitop3:0x2d
	v_lshl_or_b32 v110, v74, 16, 51
	v_and_or_b32 v109, v74, s44, 50
	v_pk_ashrrev_i16 v74, s42, v39
	v_bitop3_b32 v74, v39, v74, s43 bitop3:0x2d
	v_lshl_or_b32 v118, v74, 16, 49
	v_and_or_b32 v114, v74, s44, 48
	v_max_u32_e32 v74, v104, v109
	v_min_u32_e32 v109, v104, v109
	v_max_u32_e32 v104, v106, v110
	v_min_u32_e32 v110, v106, v110
	v_max_u32_e32 v106, v111, v114
	v_min_u32_e32 v114, v111, v114
	v_max_u32_e32 v111, v107, v118
	v_min_u32_e32 v118, v107, v118
	v_max_u32_e32 v107, v93, v117
	v_min_u32_e32 v117, v93, v117
	v_max_u32_e32 v93, v92, v105
	v_min_u32_e32 v105, v92, v105
	v_max_u32_e32 v92, v115, v98
	v_min_u32_e32 v98, v115, v98
	v_max_u32_e32 v115, v108, v112
	v_min_u32_e32 v112, v108, v112
	v_max_u32_e32 v108, v74, v93
	v_min_u32_e32 v93, v74, v93
	v_max_u32_e32 v74, v104, v92
	v_min_u32_e32 v92, v104, v92
	v_max_u32_e32 v104, v106, v115
	v_min_u32_e32 v115, v106, v115
	v_max_u32_e32 v106, v111, v107
	v_min_u32_e32 v107, v111, v107
	v_max_u32_e32 v111, v105, v109
	v_min_u32_e32 v109, v105, v109
	v_max_u32_e32 v105, v117, v118
	v_min_u32_e32 v118, v117, v118
	v_max_u32_e32 v117, v112, v114
	v_min_u32_e32 v114, v112, v114
	v_max_u32_e32 v112, v98, v110
	v_min_u32_e32 v110, v98, v110
	v_max_u32_e32 v98, v108, v74
	v_min_u32_e32 v74, v108, v74
	v_max_u32_e32 v108, v104, v106
	v_min_u32_e32 v106, v104, v106
	v_max_u32_e32 v104, v107, v93
	v_min_u32_e32 v93, v107, v93
	v_max_u32_e32 v107, v111, v105
	v_min_u32_e32 v105, v111, v105
; __device__ __forceinline__ unsigned f2key(float f) { const unsigned u = __float_as_uint(f); return (u & 0x80000000u) ? ~u : (u | 0x80000000u); }
; #define CE_DESC(a, b) do { const unsigned _mx = (a) > (b) ? (a) : (b), _mn = (a) > (b) ? (b) : (a); (a) = _mx; (b) = _mn; } while (0)
; __device__ __forceinline__ void sort16_desc(unsigned (&k)[16]) {
; #pragma unroll
;     for (int size = 2; size <= 16; size <<= 1)
; #pragma unroll
;         for (int stride = size >> 1; stride > 0; stride >>= 1)
; #pragma unroll
;             for (int i = 0; i < 16; ++i) { const int j = i ^ stride;
;                 if (j > i) { if ((i & size) == 0) CE_DESC(k[i], k[j]); else CE_DESC(k[j], k[i]); } }
; }
; __device__ __forceinline__ void merge16(unsigned (&a)[16], const unsigned (&b)[16]) {
; #pragma unroll
;     for (int i = 0; i < 16; ++i) a[i] = a[i] > b[15 - i] ? a[i] : b[15 - i];
; #pragma unroll
;     for (int stride = 8; stride > 0; stride >>= 1)
; #pragma unroll
;         for (int i = 0; i < 16; ++i) { const int j = i ^ stride; if (j > i) CE_DESC(a[i], a[j]); }
; }
; __device__ __forceinline__ void peer_tile(const Args& A, LAS unsigned char* lds, int tile) {
;     ...
;                 { const bf16_t* sp = QRY + m * 2048 + hp * 128 + 32 * g;
;                   const u32x4 s0 = *(const u32x4*)sp, s1 = *(const u32x4*)(sp + 8), s2 = *(const u32x4*)(sp + 16), s3 = *(const u32x4*)(sp + 24);
;                   const unsigned sw[16] = {s0.x, s0.y, s0.z, s0.w, s1.x, s1.y, s1.z, s1.w, s2.x, s2.y, s2.z, s2.w, s3.x, s3.y, s3.z, s3.w};
; #pragma unroll
;                   for (int i = 0; i < 16; ++i) {
;                       const float lo = (float)__builtin_bit_cast(_Float16, (unsigned short)(sw[i] & 0xffffu)), hi = (float)__builtin_bit_cast(_Float16, (unsigned short)(sw[i] >> 16));
;                       const unsigned klo = (f2key(lo) & ~127u) | (unsigned)(127 - (32 * g + 2 * i)), khi = (f2key(hi) & ~127u) | (unsigned)(127 - (32 * g + 2 * i + 1));
;                       if (i < 8) { k0[2 * i] = klo; k0[2 * i + 1] = khi; } else { k1[2 * (i - 8)] = klo; k1[2 * (i - 8) + 1] = khi; } } }
;                 sort16_desc(k0); sort16_desc(k1); merge16(k0, k1);
	v_max_u32_e32 v111, v92, v115
	v_min_u32_e32 v115, v92, v115
	v_max_u32_e32 v92, v117, v112
	v_min_u32_e32 v112, v117, v112
	v_max_u32_e32 v117, v110, v109
	v_min_u32_e32 v109, v110, v109
	v_max_u32_e32 v110, v118, v114
	v_min_u32_e32 v114, v118, v114
	v_max_u32_e32 v118, v98, v108
	v_min_u32_e32 v108, v98, v108
	v_max_u32_e32 v98, v74, v106
	v_min_u32_e32 v106, v74, v106
	v_max_u32_e32 v74, v104, v92
	v_min_u32_e32 v92, v104, v92
	v_max_u32_e32 v104, v93, v112
	v_min_u32_e32 v112, v93, v112
	v_max_u32_e32 v93, v107, v111
	v_min_u32_e32 v111, v107, v111
	v_max_u32_e32 v107, v105, v115
	v_min_u32_e32 v115, v105, v115
	v_max_u32_e32 v105, v117, v110
	v_min_u32_e32 v110, v117, v110
	v_max_u32_e32 v117, v109, v114
	v_min_u32_e32 v114, v109, v114
	v_max_u32_e32 v109, v98, v108
	v_min_u32_e32 v108, v98, v108
	v_max_u32_e32 v98, v106, v105
	v_min_u32_e32 v105, v106, v105
	v_max_u32_e32 v106, v74, v93
	v_min_u32_e32 v93, v74, v93
	v_max_u32_e32 v74, v104, v111
	v_min_u32_e32 v111, v104, v111
	v_max_u32_e32 v104, v107, v92
	v_min_u32_e32 v92, v107, v92
	v_max_u32_e32 v107, v115, v112
	v_min_u32_e32 v112, v115, v112
	v_max_u32_e32 v115, v117, v110
	v_min_u32_e32 v110, v117, v110
	v_max_u32_e32 v117, v109, v106
	v_min_u32_e32 v106, v109, v106
	v_max_u32_e32 v109, v108, v93
	v_min_u32_e32 v93, v108, v93
	v_max_u32_e32 v108, v74, v104
	v_min_u32_e32 v104, v74, v104
	v_max_u32_e32 v74, v111, v92
	v_min_u32_e32 v92, v111, v92
	v_max_u32_e32 v111, v107, v115
	v_min_u32_e32 v115, v107, v115
	v_max_u32_e32 v107, v112, v110
	v_min_u32_e32 v110, v112, v110
	v_max_u32_e32 v112, v109, v106
	v_min_u32_e32 v106, v109, v106
	v_max_u32_e32 v109, v98, v93
	v_min_u32_e32 v93, v98, v93
	v_max_u32_e32 v98, v111, v105
	v_min_u32_e32 v105, v111, v105
	v_max_u32_e32 v111, v107, v115
	v_min_u32_e32 v115, v107, v115
	v_max_u32_e32 v107, v109, v108
	v_min_u32_e32 v108, v109, v108
	v_max_u32_e32 v109, v93, v104
	v_min_u32_e32 v104, v93, v104
	v_max_u32_e32 v93, v74, v98
	v_min_u32_e32 v98, v74, v98
	v_max_u32_e32 v74, v92, v105
	v_min_u32_e32 v105, v92, v105
	v_max_u32_e32 v92, v107, v106
	v_min_u32_e32 v106, v107, v106
	v_max_u32_e32 v107, v108, v109
	v_min_u32_e32 v109, v108, v109
	v_max_u32_e32 v108, v93, v104
	v_min_u32_e32 v104, v93, v104
	v_max_u32_e32 v93, v98, v74
	v_min_u32_e32 v74, v98, v74
	v_max_u32_e32 v98, v111, v105
	v_min_u32_e32 v105, v111, v105
	v_max_u32_e32 v111, v109, v108
	v_min_u32_e32 v108, v109, v108
	v_max_u32_e32 v109, v104, v93
	v_min_u32_e32 v93, v104, v93
	v_max_u32_e32 v80, v80, v114
	v_max_u32_e32 v119, v119, v110
	v_max_u32_e32 v71, v71, v115
	v_max_u32_e32 v95, v95, v105
	v_max_u32_e32 v89, v89, v98
	v_max_u32_e32 v84, v84, v74
	v_max_u32_e32 v116, v116, v93
	v_max_u32_e32 v103, v103, v109
	v_max_u32_e32 v100, v100, v108
	v_max_u32_e32 v73, v73, v111
	v_max_u32_e32 v83, v83, v107
	v_max_u32_e32 v101, v101, v106
	v_max_u32_e32 v76, v76, v92
	v_max_u32_e32 v91, v91, v112
	v_max_u32_e32 v79, v79, v117
	v_max_u32_e32 v90, v90, v118
	v_max_u32_e32 v114, v80, v100
	v_min_u32_e32 v100, v80, v100
	v_max_u32_e32 v80, v119, v73
	v_min_u32_e32 v73, v119, v73
	v_max_u32_e32 v119, v71, v83
	v_min_u32_e32 v83, v71, v83
	v_max_u32_e32 v71, v95, v101
	v_min_u32_e32 v101, v95, v101
	v_max_u32_e32 v95, v89, v76
	v_min_u32_e32 v76, v89, v76
	v_max_u32_e32 v89, v84, v91
	v_min_u32_e32 v91, v84, v91
	v_max_u32_e32 v84, v116, v79
	v_min_u32_e32 v79, v116, v79
	v_max_u32_e32 v116, v103, v90
	v_min_u32_e32 v90, v103, v90
	v_max_u32_e32 v103, v114, v95
	v_min_u32_e32 v95, v114, v95
	v_max_u32_e32 v114, v80, v89
	v_min_u32_e32 v89, v80, v89
	v_max_u32_e32 v80, v119, v84
	v_min_u32_e32 v84, v119, v84
	v_max_u32_e32 v119, v71, v116
	v_min_u32_e32 v116, v71, v116
	v_max_u32_e32 v71, v100, v76
	v_min_u32_e32 v76, v100, v76
	v_max_u32_e32 v100, v73, v91
	v_min_u32_e32 v91, v73, v91
	v_max_u32_e32 v73, v83, v79
	v_min_u32_e32 v79, v83, v79
	v_max_u32_e32 v83, v101, v90
	v_min_u32_e32 v90, v101, v90
	v_max_u32_e32 v101, v103, v80
	v_min_u32_e32 v80, v103, v80
	v_max_u32_e32 v103, v114, v119
	v_min_u32_e32 v119, v114, v119
	v_max_u32_e32 v114, v95, v84
	v_min_u32_e32 v84, v95, v84
	v_max_u32_e32 v95, v89, v116
	v_min_u32_e32 v116, v89, v116
	v_max_u32_e32 v89, v71, v73
	v_min_u32_e32 v73, v71, v73
	v_max_u32_e32 v71, v100, v83
	v_min_u32_e32 v83, v100, v83
	v_max_u32_e32 v100, v76, v79
	v_min_u32_e32 v79, v76, v79
	v_max_u32_e32 v76, v91, v90
	v_min_u32_e32 v90, v91, v90
	v_max_u32_e32 v91, v101, v103
	v_min_u32_e32 v103, v101, v103
	v_max_u32_e32 v101, v80, v119
	v_min_u32_e32 v119, v80, v119
	v_max_u32_e32 v80, v114, v95
	v_min_u32_e32 v95, v114, v95
	v_max_u32_e32 v114, v84, v116
	v_min_u32_e32 v116, v84, v116
	v_max_u32_e32 v84, v89, v71
	v_min_u32_e32 v71, v89, v71
	v_max_u32_e32 v89, v73, v83
	v_min_u32_e32 v83, v73, v83
	v_max_u32_e32 v73, v100, v76
	v_min_u32_e32 v76, v100, v76
	v_max_u32_e32 v100, v79, v90
	v_min_u32_e32 v90, v79, v90
	v_pk_ashrrev_i16 v79, s42, v40
	v_bitop3_b32 v79, v40, v79, s43 bitop3:0x2d
	v_lshl_or_b32 v110, v79, 16, 47
	v_and_or_b32 v115, v79, s44, 46
	v_pk_ashrrev_i16 v79, s42, v41
	v_bitop3_b32 v79, v41, v79, s43 bitop3:0x2d
	v_lshl_or_b32 v105, v79, 16, 45
	v_and_or_b32 v98, v79, s44, 44
	v_pk_ashrrev_i16 v79, s42, v42
	v_bitop3_b32 v79, v42, v79, s43 bitop3:0x2d
	v_lshl_or_b32 v74, v79, 16, 43
	v_and_or_b32 v93, v79, s44, 42
	v_pk_ashrrev_i16 v79, s42, v43
	v_bitop3_b32 v79, v43, v79, s43 bitop3:0x2d
	v_lshl_or_b32 v109, v79, 16, 41
	v_and_or_b32 v108, v79, s44, 40
	v_pk_ashrrev_i16 v79, s42, v44
	v_bitop3_b32 v79, v44, v79, s43 bitop3:0x2d
	v_lshl_or_b32 v111, v79, 16, 39
	v_and_or_b32 v107, v79, s44, 38
	v_pk_ashrrev_i16 v79, s42, v45
; __device__ __forceinline__ unsigned f2key(float f) { const unsigned u = __float_as_uint(f); return (u & 0x80000000u) ? ~u : (u | 0x80000000u); }
; #define CE_DESC(a, b) do { const unsigned _mx = (a) > (b) ? (a) : (b), _mn = (a) > (b) ? (b) : (a); (a) = _mx; (b) = _mn; } while (0)
; __device__ __forceinline__ void sort16_desc(unsigned (&k)[16]) {
; #pragma unroll
;     for (int size = 2; size <= 16; size <<= 1)
; #pragma unroll
;         for (int stride = size >> 1; stride > 0; stride >>= 1)
; #pragma unroll
;             for (int i = 0; i < 16; ++i) { const int j = i ^ stride;
;                 if (j > i) { if ((i & size) == 0) CE_DESC(k[i], k[j]); else CE_DESC(k[j], k[i]); } }
; }
; __device__ __forceinline__ void merge16(unsigned (&a)[16], const unsigned (&b)[16]) {
; #pragma unroll
;     for (int i = 0; i < 16; ++i) a[i] = a[i] > b[15 - i] ? a[i] : b[15 - i];
; #pragma unroll
;     for (int stride = 8; stride > 0; stride >>= 1)
; #pragma unroll
;         for (int i = 0; i < 16; ++i) { const int j = i ^ stride; if (j > i) CE_DESC(a[i], a[j]); }
; }
; __device__ __forceinline__ void peer_tile(const Args& A, LAS unsigned char* lds, int tile) {
;     ...
;                 { const bf16_t* sp = QRY + m * 2048 + hp * 128 + 32 * g;
;                   const u32x4 s0 = *(const u32x4*)sp, s1 = *(const u32x4*)(sp + 8), s2 = *(const u32x4*)(sp + 16), s3 = *(const u32x4*)(sp + 24);
;                   const unsigned sw[16] = {s0.x, s0.y, s0.z, s0.w, s1.x, s1.y, s1.z, s1.w, s2.x, s2.y, s2.z, s2.w, s3.x, s3.y, s3.z, s3.w};
; #pragma unroll
;                   for (int i = 0; i < 16; ++i) {
;                       const float lo = (float)__builtin_bit_cast(_Float16, (unsigned short)(sw[i] & 0xffffu)), hi = (float)__builtin_bit_cast(_Float16, (unsigned short)(sw[i] >> 16));
;                       const unsigned klo = (f2key(lo) & ~127u) | (unsigned)(127 - (32 * g + 2 * i)), khi = (f2key(hi) & ~127u) | (unsigned)(127 - (32 * g + 2 * i + 1));
;                       if (i < 8) { k0[2 * i] = klo; k0[2 * i + 1] = khi; } else { k1[2 * (i - 8)] = klo; k1[2 * (i - 8) + 1] = khi; } } }
;                 sort16_desc(k0); sort16_desc(k1); merge16(k0, k1);
	v_bitop3_b32 v79, v45, v79, s43 bitop3:0x2d
	v_lshl_or_b32 v106, v79, 16, 37
	v_and_or_b32 v92, v79, s44, 36
	v_pk_ashrrev_i16 v79, s42, v46
	v_bitop3_b32 v79, v46, v79, s43 bitop3:0x2d
	v_lshl_or_b32 v112, v79, 16, 35
	v_and_or_b32 v117, v79, s44, 34
	v_pk_ashrrev_i16 v79, s42, v47
	v_bitop3_b32 v79, v47, v79, s43 bitop3:0x2d
	v_lshl_or_b32 v118, v79, 16, 33
	v_and_or_b32 v104, v79, s44, 32
	v_max_u32_e32 v79, v110, v117
	v_min_u32_e32 v117, v110, v117
	v_max_u32_e32 v110, v115, v112
	v_min_u32_e32 v112, v115, v112
	v_max_u32_e32 v115, v105, v104
	v_min_u32_e32 v104, v105, v104
	v_max_u32_e32 v105, v98, v118
	v_min_u32_e32 v118, v98, v118
	v_max_u32_e32 v98, v74, v111
	v_min_u32_e32 v111, v74, v111
	v_max_u32_e32 v74, v93, v109
	v_min_u32_e32 v109, v93, v109
	v_max_u32_e32 v93, v108, v92
	v_min_u32_e32 v92, v108, v92
	v_max_u32_e32 v108, v107, v106
	v_min_u32_e32 v106, v107, v106
	v_max_u32_e32 v107, v79, v74
	v_min_u32_e32 v74, v79, v74
	v_max_u32_e32 v79, v110, v93
	v_min_u32_e32 v93, v110, v93
	v_max_u32_e32 v110, v115, v108
	v_min_u32_e32 v108, v115, v108
	v_max_u32_e32 v115, v105, v98
	v_min_u32_e32 v98, v105, v98
	v_max_u32_e32 v105, v109, v117
	v_min_u32_e32 v117, v109, v117
	v_max_u32_e32 v109, v111, v118
	v_min_u32_e32 v118, v111, v118
	v_max_u32_e32 v111, v106, v104
	v_min_u32_e32 v104, v106, v104
	v_max_u32_e32 v106, v92, v112
	v_min_u32_e32 v112, v92, v112
	v_max_u32_e32 v92, v107, v79
	v_min_u32_e32 v79, v107, v79
	v_max_u32_e32 v107, v110, v115
	v_min_u32_e32 v115, v110, v115
	v_max_u32_e32 v110, v98, v74
	v_min_u32_e32 v74, v98, v74
	v_max_u32_e32 v98, v105, v109
	v_min_u32_e32 v109, v105, v109
	v_max_u32_e32 v105, v93, v108
	v_min_u32_e32 v108, v93, v108
	v_max_u32_e32 v93, v111, v106
	v_min_u32_e32 v106, v111, v106
	v_max_u32_e32 v111, v112, v117
	v_min_u32_e32 v117, v112, v117
	v_max_u32_e32 v112, v118, v104
	v_min_u32_e32 v104, v118, v104
	v_max_u32_e32 v118, v92, v107
	v_min_u32_e32 v107, v92, v107
	v_max_u32_e32 v92, v79, v115
	v_min_u32_e32 v115, v79, v115
	v_max_u32_e32 v79, v110, v93
	v_min_u32_e32 v93, v110, v93
	v_max_u32_e32 v110, v74, v106
	v_min_u32_e32 v106, v74, v106
	v_max_u32_e32 v74, v98, v105
	v_min_u32_e32 v105, v98, v105
	v_max_u32_e32 v98, v109, v108
	v_min_u32_e32 v108, v109, v108
	v_max_u32_e32 v109, v111, v112
	v_min_u32_e32 v112, v111, v112
	v_max_u32_e32 v111, v117, v104
	v_min_u32_e32 v104, v117, v104
	v_max_u32_e32 v117, v92, v107
	v_min_u32_e32 v107, v92, v107
	v_max_u32_e32 v92, v115, v109
	v_min_u32_e32 v109, v115, v109
	v_max_u32_e32 v115, v79, v74
	v_min_u32_e32 v74, v79, v74
	v_max_u32_e32 v79, v110, v105
	v_min_u32_e32 v105, v110, v105
	v_max_u32_e32 v110, v98, v93
	v_min_u32_e32 v93, v98, v93
	v_max_u32_e32 v98, v108, v106
	v_min_u32_e32 v106, v108, v106
	v_max_u32_e32 v108, v111, v112
	v_min_u32_e32 v112, v111, v112
	v_max_u32_e32 v111, v117, v115
	v_min_u32_e32 v115, v117, v115
	v_max_u32_e32 v117, v107, v74
	v_min_u32_e32 v74, v107, v74
	v_max_u32_e32 v107, v79, v110
	v_min_u32_e32 v110, v79, v110
	v_max_u32_e32 v79, v105, v93
	v_min_u32_e32 v93, v105, v93
	v_max_u32_e32 v105, v98, v108
	v_min_u32_e32 v108, v98, v108
	v_max_u32_e32 v98, v106, v112
	v_min_u32_e32 v112, v106, v112
	v_max_u32_e32 v106, v117, v115
	v_min_u32_e32 v115, v117, v115
	v_max_u32_e32 v117, v92, v74
	v_min_u32_e32 v74, v92, v74
	v_max_u32_e32 v92, v105, v109
	v_min_u32_e32 v109, v105, v109
	v_max_u32_e32 v105, v98, v108
	v_min_u32_e32 v108, v98, v108
	v_max_u32_e32 v98, v117, v107
	v_min_u32_e32 v107, v117, v107
	v_max_u32_e32 v117, v74, v110
	v_min_u32_e32 v110, v74, v110
	v_max_u32_e32 v74, v79, v92
	v_min_u32_e32 v92, v79, v92
	v_max_u32_e32 v79, v93, v109
	v_min_u32_e32 v109, v93, v109
	v_max_u32_e32 v93, v98, v115
	v_min_u32_e32 v115, v98, v115
	v_max_u32_e32 v98, v107, v117
	v_min_u32_e32 v117, v107, v117
	v_max_u32_e32 v107, v74, v110
	v_min_u32_e32 v110, v74, v110
	v_max_u32_e32 v74, v92, v79
	v_min_u32_e32 v79, v92, v79
	v_max_u32_e32 v92, v105, v109
	v_min_u32_e32 v109, v105, v109
	v_max_u32_e32 v105, v117, v107
	v_min_u32_e32 v107, v117, v107
	v_max_u32_e32 v117, v110, v74
	v_min_u32_e32 v74, v110, v74
	v_max_u32_e32 v91, v91, v104
	v_max_u32_e32 v103, v103, v112
	v_max_u32_e32 v101, v101, v108
	v_max_u32_e32 v119, v119, v109
	v_max_u32_e32 v80, v80, v92
	v_max_u32_e32 v95, v95, v79
	v_max_u32_e32 v114, v114, v74
	v_max_u32_e32 v116, v116, v117
	v_max_u32_e32 v84, v84, v107
	v_max_u32_e32 v71, v71, v105
	v_max_u32_e32 v89, v89, v98
	v_max_u32_e32 v83, v83, v115
	v_max_u32_e32 v73, v73, v93
	v_max_u32_e32 v76, v76, v106
	v_max_u32_e32 v100, v100, v111
	v_max_u32_e32 v90, v90, v118
	v_max_u32_e32 v104, v91, v84
	v_min_u32_e32 v84, v91, v84
	v_max_u32_e32 v91, v103, v71
	v_min_u32_e32 v71, v103, v71
	v_max_u32_e32 v103, v101, v89
	v_min_u32_e32 v89, v101, v89
	v_max_u32_e32 v101, v119, v83
	v_min_u32_e32 v83, v119, v83
	v_max_u32_e32 v119, v80, v73
	v_min_u32_e32 v73, v80, v73
	v_max_u32_e32 v80, v95, v76
	v_min_u32_e32 v76, v95, v76
	v_max_u32_e32 v95, v114, v100
	v_min_u32_e32 v100, v114, v100
	v_max_u32_e32 v114, v116, v90
	v_min_u32_e32 v90, v116, v90
	v_max_u32_e32 v116, v104, v119
	v_min_u32_e32 v119, v104, v119
	v_max_u32_e32 v104, v91, v80
	v_min_u32_e32 v80, v91, v80
	v_max_u32_e32 v91, v103, v95
	v_min_u32_e32 v95, v103, v95
	v_max_u32_e32 v103, v101, v114
	v_min_u32_e32 v114, v101, v114
	v_max_u32_e32 v101, v84, v73
	v_min_u32_e32 v73, v84, v73
	v_max_u32_e32 v84, v71, v76
	v_min_u32_e32 v76, v71, v76
	v_max_u32_e32 v71, v89, v100
	v_min_u32_e32 v100, v89, v100
	v_max_u32_e32 v89, v83, v90
	v_min_u32_e32 v90, v83, v90
	v_max_u32_e32 v83, v116, v91
	v_min_u32_e32 v91, v116, v91
; __device__ __forceinline__ unsigned f2key(float f) { const unsigned u = __float_as_uint(f); return (u & 0x80000000u) ? ~u : (u | 0x80000000u); }
; #define CE_DESC(a, b) do { const unsigned _mx = (a) > (b) ? (a) : (b), _mn = (a) > (b) ? (b) : (a); (a) = _mx; (b) = _mn; } while (0)
; __device__ __forceinline__ void sort16_desc(unsigned (&k)[16]) {
; #pragma unroll
;     for (int size = 2; size <= 16; size <<= 1)
; #pragma unroll
;         for (int stride = size >> 1; stride > 0; stride >>= 1)
; #pragma unroll
;             for (int i = 0; i < 16; ++i) { const int j = i ^ stride;
;                 if (j > i) { if ((i & size) == 0) CE_DESC(k[i], k[j]); else CE_DESC(k[j], k[i]); } }
; }
; __device__ __forceinline__ void merge16(unsigned (&a)[16], const unsigned (&b)[16]) {
; #pragma unroll
;     for (int i = 0; i < 16; ++i) a[i] = a[i] > b[15 - i] ? a[i] : b[15 - i];
; #pragma unroll
;     for (int stride = 8; stride > 0; stride >>= 1)
; #pragma unroll
;         for (int i = 0; i < 16; ++i) { const int j = i ^ stride; if (j > i) CE_DESC(a[i], a[j]); }
; }
; __device__ __forceinline__ void peer_tile(const Args& A, LAS unsigned char* lds, int tile) {
;     ...
;                 { const bf16_t* sp = QRY + m * 2048 + hp * 128 + 32 * g;
;                   const u32x4 s0 = *(const u32x4*)sp, s1 = *(const u32x4*)(sp + 8), s2 = *(const u32x4*)(sp + 16), s3 = *(const u32x4*)(sp + 24);
;                   const unsigned sw[16] = {s0.x, s0.y, s0.z, s0.w, s1.x, s1.y, s1.z, s1.w, s2.x, s2.y, s2.z, s2.w, s3.x, s3.y, s3.z, s3.w};
; #pragma unroll
;                   for (int i = 0; i < 16; ++i) {
;                       const float lo = (float)__builtin_bit_cast(_Float16, (unsigned short)(sw[i] & 0xffffu)), hi = (float)__builtin_bit_cast(_Float16, (unsigned short)(sw[i] >> 16));
;                       const unsigned klo = (f2key(lo) & ~127u) | (unsigned)(127 - (32 * g + 2 * i)), khi = (f2key(hi) & ~127u) | (unsigned)(127 - (32 * g + 2 * i + 1));
;                       if (i < 8) { k0[2 * i] = klo; k0[2 * i + 1] = khi; } else { k1[2 * (i - 8)] = klo; k1[2 * (i - 8) + 1] = khi; } } }
;                 sort16_desc(k0); sort16_desc(k1); merge16(k0, k1);
	v_max_u32_e32 v116, v104, v103
	v_min_u32_e32 v103, v104, v103
	v_max_u32_e32 v104, v119, v95
	v_min_u32_e32 v95, v119, v95
	v_max_u32_e32 v119, v80, v114
	v_min_u32_e32 v114, v80, v114
	v_max_u32_e32 v80, v101, v71
	v_min_u32_e32 v71, v101, v71
	v_max_u32_e32 v101, v84, v89
	v_min_u32_e32 v89, v84, v89
	v_max_u32_e32 v84, v73, v100
	v_min_u32_e32 v100, v73, v100
	v_max_u32_e32 v73, v76, v90
	v_min_u32_e32 v90, v76, v90
	v_max_u32_e32 v76, v83, v116
	v_min_u32_e32 v116, v83, v116
	v_max_u32_e32 v83, v91, v103
	v_min_u32_e32 v103, v91, v103
	v_max_u32_e32 v91, v104, v119
	v_min_u32_e32 v119, v104, v119
	v_max_u32_e32 v104, v95, v114
	v_min_u32_e32 v114, v95, v114
	v_max_u32_e32 v95, v80, v101
	v_min_u32_e32 v101, v80, v101
	v_max_u32_e32 v80, v71, v89
	v_min_u32_e32 v89, v71, v89
	v_max_u32_e32 v71, v84, v73
	v_min_u32_e32 v73, v84, v73
	v_max_u32_e32 v84, v100, v90
	v_min_u32_e32 v90, v100, v90
	v_pk_ashrrev_i16 v100, s42, v48
	v_bitop3_b32 v100, v48, v100, s43 bitop3:0x2d
	v_lshl_or_b32 v112, v100, 16, 31
	v_and_or_b32 v108, v100, s44, 30
	v_pk_ashrrev_i16 v100, s42, v49
	v_bitop3_b32 v100, v49, v100, s43 bitop3:0x2d
	v_lshl_or_b32 v109, v100, 16, 29
	v_and_or_b32 v92, v100, s44, 28
	v_pk_ashrrev_i16 v100, s42, v50
	v_bitop3_b32 v100, v50, v100, s43 bitop3:0x2d
	v_lshl_or_b32 v79, v100, 16, 27
	v_and_or_b32 v74, v100, s44, 26
	v_pk_ashrrev_i16 v100, s42, v51
	v_bitop3_b32 v100, v51, v100, s43 bitop3:0x2d
	v_lshl_or_b32 v117, v100, 16, 25
	v_and_or_b32 v107, v100, s44, 24
	v_pk_ashrrev_i16 v100, s42, v52
	v_bitop3_b32 v100, v52, v100, s43 bitop3:0x2d
	v_lshl_or_b32 v105, v100, 16, 23
	v_and_or_b32 v98, v100, s44, 22
	v_pk_ashrrev_i16 v100, s42, v53
	v_bitop3_b32 v100, v53, v100, s43 bitop3:0x2d
	v_lshl_or_b32 v115, v100, 16, 21
	v_and_or_b32 v93, v100, s44, 20
	v_pk_ashrrev_i16 v100, s42, v54
	v_bitop3_b32 v100, v54, v100, s43 bitop3:0x2d
	v_lshl_or_b32 v106, v100, 16, 19
	v_and_or_b32 v111, v100, s44, 18
	v_pk_ashrrev_i16 v100, s42, v55
	v_bitop3_b32 v100, v55, v100, s43 bitop3:0x2d
	v_lshl_or_b32 v118, v100, 16, 17
	v_and_or_b32 v110, v100, s44, 16
	v_max_u32_e32 v100, v112, v111
	v_min_u32_e32 v111, v112, v111
	v_max_u32_e32 v112, v108, v106
	v_min_u32_e32 v106, v108, v106
	v_max_u32_e32 v108, v109, v110
	v_min_u32_e32 v110, v109, v110
	v_max_u32_e32 v109, v92, v118
	v_min_u32_e32 v118, v92, v118
	v_max_u32_e32 v92, v79, v105
	v_min_u32_e32 v105, v79, v105
	v_max_u32_e32 v79, v74, v117
	v_min_u32_e32 v117, v74, v117
	v_max_u32_e32 v74, v107, v93
	v_min_u32_e32 v93, v107, v93
	v_max_u32_e32 v107, v98, v115
	v_min_u32_e32 v115, v98, v115
	v_max_u32_e32 v98, v100, v79
	v_min_u32_e32 v79, v100, v79
	v_max_u32_e32 v100, v112, v74
	v_min_u32_e32 v74, v112, v74
	v_max_u32_e32 v112, v108, v107
	v_min_u32_e32 v107, v108, v107
	v_max_u32_e32 v108, v109, v92
	v_min_u32_e32 v92, v109, v92
	v_max_u32_e32 v109, v117, v111
	v_min_u32_e32 v111, v117, v111
	v_max_u32_e32 v117, v105, v118
	v_min_u32_e32 v118, v105, v118
	v_max_u32_e32 v105, v115, v110
	v_min_u32_e32 v110, v115, v110
	v_max_u32_e32 v115, v93, v106
	v_min_u32_e32 v106, v93, v106
	v_max_u32_e32 v93, v98, v100
	v_min_u32_e32 v100, v98, v100
	v_max_u32_e32 v98, v112, v108
	v_min_u32_e32 v108, v112, v108
	v_max_u32_e32 v112, v92, v79
	v_min_u32_e32 v79, v92, v79
	v_max_u32_e32 v92, v109, v117
	v_min_u32_e32 v117, v109, v117
	v_max_u32_e32 v109, v74, v107
	v_min_u32_e32 v107, v74, v107
	v_max_u32_e32 v74, v105, v115
	v_min_u32_e32 v115, v105, v115
	v_max_u32_e32 v105, v106, v111
	v_min_u32_e32 v111, v106, v111
	v_max_u32_e32 v106, v118, v110
	v_min_u32_e32 v110, v118, v110
	v_max_u32_e32 v118, v93, v98
	v_min_u32_e32 v98, v93, v98
	v_max_u32_e32 v93, v100, v108
	v_min_u32_e32 v108, v100, v108
	v_max_u32_e32 v100, v112, v74
	v_min_u32_e32 v74, v112, v74
	v_max_u32_e32 v112, v79, v115
	v_min_u32_e32 v115, v79, v115
	v_max_u32_e32 v79, v92, v109
	v_min_u32_e32 v109, v92, v109
	v_max_u32_e32 v92, v117, v107
	v_min_u32_e32 v107, v117, v107
	v_max_u32_e32 v117, v105, v106
	v_min_u32_e32 v106, v105, v106
	v_max_u32_e32 v105, v111, v110
	v_min_u32_e32 v110, v111, v110
	v_max_u32_e32 v111, v93, v98
	v_min_u32_e32 v98, v93, v98
	v_max_u32_e32 v93, v108, v117
	v_min_u32_e32 v117, v108, v117
	v_max_u32_e32 v108, v100, v79
	v_min_u32_e32 v79, v100, v79
	v_max_u32_e32 v100, v112, v109
	v_min_u32_e32 v109, v112, v109
	v_max_u32_e32 v112, v92, v74
	v_min_u32_e32 v74, v92, v74
	v_max_u32_e32 v92, v107, v115
	v_min_u32_e32 v115, v107, v115
	v_max_u32_e32 v107, v105, v106
	v_min_u32_e32 v106, v105, v106
	v_max_u32_e32 v105, v111, v108
	v_min_u32_e32 v108, v111, v108
	v_max_u32_e32 v111, v98, v79
	v_min_u32_e32 v79, v98, v79
	v_max_u32_e32 v98, v100, v112
	v_min_u32_e32 v112, v100, v112
	v_max_u32_e32 v100, v109, v74
	v_min_u32_e32 v74, v109, v74
	v_max_u32_e32 v109, v92, v107
	v_min_u32_e32 v107, v92, v107
	v_max_u32_e32 v92, v115, v106
	v_min_u32_e32 v106, v115, v106
	v_max_u32_e32 v115, v111, v108
	v_min_u32_e32 v108, v111, v108
	v_max_u32_e32 v111, v93, v79
	v_min_u32_e32 v79, v93, v79
	v_max_u32_e32 v93, v109, v117
	v_min_u32_e32 v117, v109, v117
	v_max_u32_e32 v109, v92, v107
	v_min_u32_e32 v107, v92, v107
	v_max_u32_e32 v92, v111, v98
	v_min_u32_e32 v98, v111, v98
	v_max_u32_e32 v111, v79, v112
	v_min_u32_e32 v112, v79, v112
	v_max_u32_e32 v79, v100, v93
	v_min_u32_e32 v93, v100, v93
	v_max_u32_e32 v100, v74, v117
	v_min_u32_e32 v117, v74, v117
	v_max_u32_e32 v74, v92, v108
	v_min_u32_e32 v108, v92, v108
	v_max_u32_e32 v92, v98, v111
	v_min_u32_e32 v111, v98, v111
	v_max_u32_e32 v98, v79, v112
	v_min_u32_e32 v112, v79, v112
	v_max_u32_e32 v79, v93, v100
	v_min_u32_e32 v100, v93, v100
	v_max_u32_e32 v93, v109, v117
; __device__ __forceinline__ unsigned f2key(float f) { const unsigned u = __float_as_uint(f); return (u & 0x80000000u) ? ~u : (u | 0x80000000u); }
; #define CE_DESC(a, b) do { const unsigned _mx = (a) > (b) ? (a) : (b), _mn = (a) > (b) ? (b) : (a); (a) = _mx; (b) = _mn; } while (0)
; __device__ __forceinline__ void sort16_desc(unsigned (&k)[16]) {
; #pragma unroll
;     for (int size = 2; size <= 16; size <<= 1)
; #pragma unroll
;         for (int stride = size >> 1; stride > 0; stride >>= 1)
; #pragma unroll
;             for (int i = 0; i < 16; ++i) { const int j = i ^ stride;
;                 if (j > i) { if ((i & size) == 0) CE_DESC(k[i], k[j]); else CE_DESC(k[j], k[i]); } }
; }
; __device__ __forceinline__ void merge16(unsigned (&a)[16], const unsigned (&b)[16]) {
; #pragma unroll
;     for (int i = 0; i < 16; ++i) a[i] = a[i] > b[15 - i] ? a[i] : b[15 - i];
; #pragma unroll
;     for (int stride = 8; stride > 0; stride >>= 1)
; #pragma unroll
;         for (int i = 0; i < 16; ++i) { const int j = i ^ stride; if (j > i) CE_DESC(a[i], a[j]); }
; }
; __device__ __forceinline__ void peer_tile(const Args& A, LAS unsigned char* lds, int tile) {
;     ...
;                 { const bf16_t* sp = QRY + m * 2048 + hp * 128 + 32 * g;
;                   const u32x4 s0 = *(const u32x4*)sp, s1 = *(const u32x4*)(sp + 8), s2 = *(const u32x4*)(sp + 16), s3 = *(const u32x4*)(sp + 24);
;                   const unsigned sw[16] = {s0.x, s0.y, s0.z, s0.w, s1.x, s1.y, s1.z, s1.w, s2.x, s2.y, s2.z, s2.w, s3.x, s3.y, s3.z, s3.w};
; #pragma unroll
;                   for (int i = 0; i < 16; ++i) {
;                       const float lo = (float)__builtin_bit_cast(_Float16, (unsigned short)(sw[i] & 0xffffu)), hi = (float)__builtin_bit_cast(_Float16, (unsigned short)(sw[i] >> 16));
;                       const unsigned klo = (f2key(lo) & ~127u) | (unsigned)(127 - (32 * g + 2 * i)), khi = (f2key(hi) & ~127u) | (unsigned)(127 - (32 * g + 2 * i + 1));
;                       if (i < 8) { k0[2 * i] = klo; k0[2 * i + 1] = khi; } else { k1[2 * (i - 8)] = klo; k1[2 * (i - 8) + 1] = khi; } } }
;                 sort16_desc(k0); sort16_desc(k1); merge16(k0, k1);
	v_min_u32_e32 v117, v109, v117
	v_max_u32_e32 v109, v111, v98
	v_min_u32_e32 v98, v111, v98
	v_max_u32_e32 v111, v112, v79
	v_min_u32_e32 v79, v112, v79
	v_max_u32_e32 v76, v76, v110
	v_max_u32_e32 v116, v116, v106
	v_max_u32_e32 v83, v83, v107
	v_max_u32_e32 v103, v103, v117
	v_max_u32_e32 v91, v91, v93
	v_max_u32_e32 v119, v119, v100
	v_max_u32_e32 v104, v104, v79
	v_max_u32_e32 v114, v114, v111
	v_max_u32_e32 v95, v95, v98
	v_max_u32_e32 v101, v101, v109
	v_max_u32_e32 v80, v80, v92
	v_max_u32_e32 v89, v89, v108
	v_max_u32_e32 v71, v71, v74
	v_max_u32_e32 v73, v73, v115
	v_max_u32_e32 v84, v84, v105
	v_max_u32_e32 v90, v90, v118
	v_max_u32_e32 v110, v76, v95
	v_min_u32_e32 v95, v76, v95
	v_max_u32_e32 v76, v116, v101
	v_min_u32_e32 v101, v116, v101
	v_max_u32_e32 v116, v83, v80
	v_min_u32_e32 v80, v83, v80
	v_max_u32_e32 v83, v103, v89
	v_min_u32_e32 v89, v103, v89
	v_max_u32_e32 v103, v91, v71
	v_min_u32_e32 v71, v91, v71
	v_max_u32_e32 v91, v119, v73
	v_min_u32_e32 v73, v119, v73
	v_max_u32_e32 v119, v104, v84
	v_min_u32_e32 v84, v104, v84
	v_max_u32_e32 v104, v114, v90
	v_min_u32_e32 v90, v114, v90
	v_max_u32_e32 v114, v110, v103
	v_min_u32_e32 v103, v110, v103
	v_max_u32_e32 v110, v76, v91
	v_min_u32_e32 v91, v76, v91
	v_max_u32_e32 v76, v116, v119
	v_min_u32_e32 v119, v116, v119
	v_max_u32_e32 v116, v83, v104
	v_min_u32_e32 v104, v83, v104
	v_max_u32_e32 v83, v95, v71
	v_min_u32_e32 v71, v95, v71
	v_max_u32_e32 v95, v101, v73
	v_min_u32_e32 v73, v101, v73
	v_max_u32_e32 v101, v80, v84
	v_min_u32_e32 v84, v80, v84
	v_max_u32_e32 v80, v89, v90
	v_min_u32_e32 v90, v89, v90
	v_max_u32_e32 v89, v114, v76
	v_min_u32_e32 v76, v114, v76
	v_max_u32_e32 v114, v110, v116
	v_min_u32_e32 v116, v110, v116
	v_max_u32_e32 v110, v103, v119
	v_min_u32_e32 v119, v103, v119
	v_max_u32_e32 v103, v91, v104
	v_min_u32_e32 v104, v91, v104
	v_max_u32_e32 v91, v83, v101
	v_min_u32_e32 v101, v83, v101
	v_max_u32_e32 v83, v95, v80
	v_min_u32_e32 v80, v95, v80
	v_max_u32_e32 v95, v71, v84
	v_min_u32_e32 v84, v71, v84
	v_max_u32_e32 v71, v73, v90
	v_min_u32_e32 v90, v73, v90
	v_max_u32_e32 v73, v89, v114
	v_min_u32_e32 v114, v89, v114
	v_max_u32_e32 v89, v76, v116
	v_min_u32_e32 v116, v76, v116
	v_max_u32_e32 v76, v110, v103
	v_min_u32_e32 v103, v110, v103
	v_max_u32_e32 v110, v119, v104
	v_min_u32_e32 v104, v119, v104
	v_max_u32_e32 v119, v91, v83
	v_min_u32_e32 v83, v91, v83
	v_max_u32_e32 v91, v101, v80
	v_min_u32_e32 v80, v101, v80
	v_max_u32_e32 v101, v95, v71
	v_min_u32_e32 v71, v95, v71
	v_max_u32_e32 v95, v84, v90
	v_min_u32_e32 v90, v84, v90
	v_pk_ashrrev_i16 v84, s42, v56
	v_bitop3_b32 v84, v56, v84, s43 bitop3:0x2d
	v_lshl_or_b32 v106, v84, 16, 15
	v_and_or_b32 v107, v84, s44, 14
	v_pk_ashrrev_i16 v84, s42, v57
	v_bitop3_b32 v84, v57, v84, s43 bitop3:0x2d
	v_lshl_or_b32 v117, v84, 16, 13
	v_and_or_b32 v93, v84, s44, 12
	v_pk_ashrrev_i16 v84, s42, v58
	v_bitop3_b32 v84, v58, v84, s43 bitop3:0x2d
	v_lshl_or_b32 v100, v84, 16, 11
	v_and_or_b32 v79, v84, s44, 10
	v_pk_ashrrev_i16 v84, s42, v59
	v_bitop3_b32 v84, v59, v84, s43 bitop3:0x2d
	v_lshl_or_b32 v111, v84, 16, 9
	v_and_or_b32 v98, v84, s44, 8
	v_pk_ashrrev_i16 v84, s42, v60
	v_bitop3_b32 v84, v60, v84, s43 bitop3:0x2d
	v_lshl_or_b32 v109, v84, 16, 7
	v_and_or_b32 v92, v84, s44, 6
	v_pk_ashrrev_i16 v84, s42, v61
	v_bitop3_b32 v84, v61, v84, s43 bitop3:0x2d
	v_lshl_or_b32 v108, v84, 16, 5
	v_and_or_b32 v74, v84, s44, 4
	v_pk_ashrrev_i16 v84, s42, v62
	v_bitop3_b32 v84, v62, v84, s43 bitop3:0x2d
	v_lshl_or_b32 v115, v84, 16, 3
	v_and_or_b32 v105, v84, s44, 2
	v_pk_ashrrev_i16 v84, s42, v63
	v_bitop3_b32 v84, v63, v84, s43 bitop3:0x2d
	v_lshl_or_b32 v118, v84, 16, 1
	v_and_or_b32 v112, v84, s44, 0
	v_max_u32_e32 v84, v106, v105
	v_min_u32_e32 v105, v106, v105
	v_max_u32_e32 v106, v107, v115
	v_min_u32_e32 v115, v107, v115
	v_max_u32_e32 v107, v117, v112
	v_min_u32_e32 v112, v117, v112
	v_max_u32_e32 v117, v93, v118
	v_min_u32_e32 v118, v93, v118
	v_max_u32_e32 v93, v100, v109
	v_min_u32_e32 v109, v100, v109
	v_max_u32_e32 v100, v79, v111
	v_min_u32_e32 v111, v79, v111
	v_max_u32_e32 v79, v98, v74
	v_min_u32_e32 v74, v98, v74
	v_max_u32_e32 v98, v92, v108
	v_min_u32_e32 v108, v92, v108
	v_max_u32_e32 v92, v84, v100
	v_min_u32_e32 v100, v84, v100
	v_max_u32_e32 v84, v106, v79
	v_min_u32_e32 v79, v106, v79
	v_max_u32_e32 v106, v107, v98
	v_min_u32_e32 v98, v107, v98
	v_max_u32_e32 v107, v117, v93
	v_min_u32_e32 v93, v117, v93
	v_max_u32_e32 v117, v111, v105
	v_min_u32_e32 v105, v111, v105
	v_max_u32_e32 v111, v109, v118
	v_min_u32_e32 v118, v109, v118
	v_max_u32_e32 v109, v108, v112
	v_min_u32_e32 v112, v108, v112
	v_max_u32_e32 v108, v74, v115
	v_min_u32_e32 v115, v74, v115
	v_max_u32_e32 v74, v92, v84
	v_min_u32_e32 v84, v92, v84
	v_max_u32_e32 v92, v106, v107
	v_min_u32_e32 v107, v106, v107
	v_max_u32_e32 v106, v93, v100
	v_min_u32_e32 v100, v93, v100
	v_max_u32_e32 v93, v117, v111
	v_min_u32_e32 v111, v117, v111
	v_max_u32_e32 v117, v79, v98
	v_min_u32_e32 v98, v79, v98
	v_max_u32_e32 v79, v109, v108
	v_min_u32_e32 v108, v109, v108
	v_max_u32_e32 v109, v115, v105
	v_min_u32_e32 v105, v115, v105
	v_max_u32_e32 v115, v118, v112
	v_min_u32_e32 v112, v118, v112
	v_max_u32_e32 v118, v74, v92
	v_min_u32_e32 v92, v74, v92
	v_max_u32_e32 v74, v84, v107
	v_min_u32_e32 v107, v84, v107
	v_max_u32_e32 v84, v106, v79
	v_min_u32_e32 v79, v106, v79
	v_max_u32_e32 v106, v100, v108
	v_min_u32_e32 v108, v100, v108
	v_max_u32_e32 v100, v93, v117
	v_min_u32_e32 v117, v93, v117
	v_max_u32_e32 v93, v111, v98
	v_min_u32_e32 v98, v111, v98
	v_max_u32_e32 v111, v109, v115
	v_min_u32_e32 v115, v109, v115
; __device__ __forceinline__ float key2f(unsigned k) { const unsigned u = (k & 0x80000000u) ? (k & 0x7fffffffu) : ~k; return __uint_as_float(u); }
; #define CE_DESC(a, b) do { const unsigned _mx = (a) > (b) ? (a) : (b), _mn = (a) > (b) ? (b) : (a); (a) = _mx; (b) = _mn; } while (0)
; __device__ __forceinline__ void merge16(unsigned (&a)[16], const unsigned (&b)[16]) {
; #pragma unroll
;     for (int i = 0; i < 16; ++i) a[i] = a[i] > b[15 - i] ? a[i] : b[15 - i];
; #pragma unroll
;     for (int stride = 8; stride > 0; stride >>= 1)
; #pragma unroll
;         for (int i = 0; i < 16; ++i) { const int j = i ^ stride; if (j > i) CE_DESC(a[i], a[j]); }
; }
; __device__ __forceinline__ void peer_tile(const Args& A, LAS unsigned char* lds, int tile) {
;     ...
;             unsigned L2[2][16];
; #pragma unroll
;             for (int p = 0; p < 2; ++p)
; #pragma unroll
;                 for (int i = 0; i < 16; ++i) L2[p][i] = (g & 2) ? ((g & 1) ? LA[3][p][i] : LA[2][p][i]) : ((g & 1) ? LA[1][p][i] : LA[0][p][i]);
;             float va[16], vb[16];
; #pragma unroll
;             for (int i = 0; i < 16; ++i) { va[i] = key2f(L2[0][i] & ~127u); vb[i] = key2f(L2[1][i] & ~127u); idx[i] = 127u - (L2[0][i] & 127u); idx[16 + i] = 127u - (L2[1][i] & 127u); }
	v_max_u32_e32 v109, v105, v112
	v_min_u32_e32 v112, v105, v112
	v_max_u32_e32 v105, v74, v92
	v_min_u32_e32 v92, v74, v92
	v_max_u32_e32 v74, v107, v111
	v_min_u32_e32 v111, v107, v111
	v_max_u32_e32 v107, v84, v100
	v_min_u32_e32 v100, v84, v100
	v_max_u32_e32 v84, v106, v117
	v_min_u32_e32 v117, v106, v117
	v_max_u32_e32 v106, v93, v79
	v_min_u32_e32 v79, v93, v79
	v_max_u32_e32 v93, v98, v108
	v_min_u32_e32 v108, v98, v108
	v_max_u32_e32 v98, v109, v115
	v_min_u32_e32 v115, v109, v115
	v_max_u32_e32 v109, v105, v107
	v_min_u32_e32 v107, v105, v107
	v_max_u32_e32 v105, v92, v100
	v_min_u32_e32 v100, v92, v100
	v_max_u32_e32 v92, v84, v106
	v_min_u32_e32 v106, v84, v106
	v_max_u32_e32 v84, v117, v79
	v_min_u32_e32 v79, v117, v79
	v_max_u32_e32 v117, v93, v98
	v_min_u32_e32 v98, v93, v98
	v_max_u32_e32 v93, v108, v115
	v_min_u32_e32 v115, v108, v115
	v_max_u32_e32 v108, v105, v107
	v_min_u32_e32 v107, v105, v107
	v_max_u32_e32 v105, v74, v100
	v_min_u32_e32 v100, v74, v100
	v_max_u32_e32 v74, v117, v111
	v_min_u32_e32 v111, v117, v111
	v_max_u32_e32 v117, v93, v98
	v_min_u32_e32 v98, v93, v98
	v_max_u32_e32 v93, v105, v92
	v_min_u32_e32 v92, v105, v92
	v_max_u32_e32 v105, v100, v106
	v_min_u32_e32 v106, v100, v106
	v_max_u32_e32 v100, v84, v74
	v_min_u32_e32 v74, v84, v74
	v_max_u32_e32 v84, v79, v111
	v_min_u32_e32 v111, v79, v111
	v_max_u32_e32 v79, v93, v107
	v_min_u32_e32 v107, v93, v107
	v_max_u32_e32 v93, v92, v105
	v_min_u32_e32 v105, v92, v105
	v_max_u32_e32 v92, v100, v106
	v_min_u32_e32 v106, v100, v106
	v_max_u32_e32 v100, v74, v84
	v_min_u32_e32 v84, v74, v84
	v_max_u32_e32 v74, v117, v111
	v_min_u32_e32 v111, v117, v111
	v_max_u32_e32 v117, v105, v92
	v_min_u32_e32 v92, v105, v92
	v_max_u32_e32 v105, v106, v100
	v_min_u32_e32 v100, v106, v100
	v_max_u32_e32 v73, v73, v112
	v_max_u32_e32 v114, v114, v115
	v_max_u32_e32 v89, v89, v98
	v_max_u32_e32 v116, v116, v111
	v_max_u32_e32 v76, v76, v74
	v_max_u32_e32 v103, v103, v84
	v_max_u32_e32 v110, v110, v100
	v_max_u32_e32 v104, v104, v105
	v_max_u32_e32 v119, v119, v92
	v_max_u32_e32 v83, v83, v117
	v_max_u32_e32 v91, v91, v93
	v_max_u32_e32 v80, v80, v107
	v_max_u32_e32 v101, v101, v79
	v_max_u32_e32 v71, v71, v108
	v_max_u32_e32 v95, v95, v109
	v_max_u32_e32 v90, v90, v118
	v_max_u32_e32 v112, v73, v119
	v_min_u32_e32 v119, v73, v119
	v_max_u32_e32 v73, v114, v83
	v_min_u32_e32 v83, v114, v83
	v_max_u32_e32 v114, v89, v91
	v_min_u32_e32 v91, v89, v91
	v_max_u32_e32 v89, v116, v80
	v_min_u32_e32 v80, v116, v80
	v_max_u32_e32 v116, v76, v101
	v_min_u32_e32 v101, v76, v101
	v_max_u32_e32 v76, v103, v71
	v_min_u32_e32 v71, v103, v71
	v_max_u32_e32 v103, v110, v95
	v_min_u32_e32 v95, v110, v95
	v_max_u32_e32 v110, v104, v90
	v_min_u32_e32 v90, v104, v90
	v_max_u32_e32 v104, v112, v116
	v_min_u32_e32 v116, v112, v116
	v_max_u32_e32 v112, v73, v76
	v_min_u32_e32 v76, v73, v76
	v_max_u32_e32 v73, v114, v103
	v_min_u32_e32 v103, v114, v103
	v_max_u32_e32 v114, v89, v110
	v_min_u32_e32 v110, v89, v110
	v_max_u32_e32 v89, v119, v101
	v_min_u32_e32 v101, v119, v101
	v_max_u32_e32 v119, v83, v71
	v_min_u32_e32 v71, v83, v71
	v_max_u32_e32 v83, v91, v95
	v_min_u32_e32 v95, v91, v95
	v_max_u32_e32 v91, v80, v90
	v_min_u32_e32 v90, v80, v90
	v_max_u32_e32 v80, v104, v73
	v_min_u32_e32 v73, v104, v73
	v_max_u32_e32 v104, v112, v114
	v_min_u32_e32 v114, v112, v114
	v_max_u32_e32 v112, v116, v103
	v_min_u32_e32 v103, v116, v103
	v_max_u32_e32 v116, v76, v110
	v_min_u32_e32 v110, v76, v110
	v_max_u32_e32 v76, v89, v83
	v_min_u32_e32 v83, v89, v83
	v_max_u32_e32 v89, v119, v91
	v_min_u32_e32 v91, v119, v91
	v_max_u32_e32 v119, v101, v95
	v_min_u32_e32 v95, v101, v95
	v_max_u32_e32 v101, v71, v90
	v_min_u32_e32 v90, v71, v90
	v_max_u32_e32 v71, v80, v104
	v_min_u32_e32 v104, v80, v104
	v_max_u32_e32 v80, v73, v114
	v_min_u32_e32 v114, v73, v114
	v_max_u32_e32 v73, v112, v116
	v_min_u32_e32 v116, v112, v116
	v_max_u32_e32 v112, v103, v110
	v_min_u32_e32 v110, v103, v110
	v_max_u32_e32 v103, v76, v89
	v_min_u32_e32 v89, v76, v89
	v_max_u32_e32 v76, v83, v91
	v_min_u32_e32 v91, v83, v91
	v_max_u32_e32 v83, v119, v101
	v_min_u32_e32 v101, v119, v101
	v_max_u32_e32 v119, v95, v90
	v_min_u32_e32 v90, v95, v90
	v_xor_b32_e32 v95, 0x7f, v72
	v_xor_b32_e32 v115, 0x7f, v88
	v_and_b32_e32 v95, 0x7f, v95
	v_and_b32_e32 v115, 0x7f, v115
	ds_write2_b32 v67, v95, v115 offset0:0 offset1:1
	v_xor_b32_e32 v115, 0x7f, v75
	v_xor_b32_e32 v95, 0x7f, v97
	v_and_b32_e32 v115, 0x7f, v115
	v_and_b32_e32 v95, 0x7f, v95
	ds_write2_b32 v67, v115, v95 offset0:2 offset1:3
	v_xor_b32_e32 v95, 0x7f, v70
	v_xor_b32_e32 v115, 0x7f, v99
	v_and_b32_e32 v95, 0x7f, v95
	v_and_b32_e32 v115, 0x7f, v115
	ds_write2_b32 v67, v95, v115 offset0:4 offset1:5
	v_xor_b32_e32 v115, 0x7f, v96
	v_xor_b32_e32 v95, 0x7f, v94
	v_and_b32_e32 v115, 0x7f, v115
	v_and_b32_e32 v95, 0x7f, v95
	ds_write2_b32 v67, v115, v95 offset0:6 offset1:7
	v_xor_b32_e32 v95, 0x7f, v87
	v_xor_b32_e32 v115, 0x7f, v77
	v_and_b32_e32 v95, 0x7f, v95
	v_and_b32_e32 v115, 0x7f, v115
	ds_write2_b32 v67, v95, v115 offset0:8 offset1:9
	v_xor_b32_e32 v115, 0x7f, v82
	v_xor_b32_e32 v95, 0x7f, v81
	v_and_b32_e32 v115, 0x7f, v115
	v_and_b32_e32 v95, 0x7f, v95
	ds_write2_b32 v67, v115, v95 offset0:10 offset1:11
	v_xor_b32_e32 v95, 0x7f, v78
	v_xor_b32_e32 v115, 0x7f, v85
	v_and_b32_e32 v95, 0x7f, v95
	v_and_b32_e32 v115, 0x7f, v115
	ds_write2_b32 v67, v95, v115 offset0:12 offset1:13
	v_xor_b32_e32 v115, 0x7f, v102
	v_xor_b32_e32 v95, 0x7f, v86
	v_and_b32_e32 v115, 0x7f, v115
	v_and_b32_e32 v95, 0x7f, v95
	ds_write2_b32 v67, v115, v95 offset0:14 offset1:15
	v_xor_b32_e32 v95, 0x7f, v71
; __device__ __forceinline__ float key2f(unsigned k) { const unsigned u = (k & 0x80000000u) ? (k & 0x7fffffffu) : ~k; return __uint_as_float(u); }
; __device__ __forceinline__ void peer_tile(const Args& A, LAS unsigned char* lds, int tile) {
;     ...
;             float va[16], vb[16];
; #pragma unroll
;             for (int i = 0; i < 16; ++i) { va[i] = key2f(L2[0][i] & ~127u); vb[i] = key2f(L2[1][i] & ~127u); idx[i] = 127u - (L2[0][i] & 127u); idx[16 + i] = 127u - (L2[1][i] & 127u); }
	v_xor_b32_e32 v115, 0x7f, v104
	v_and_b32_e32 v95, 0x7f, v95
	v_and_b32_e32 v115, 0x7f, v115
	ds_write2_b32 v67, v95, v115 offset0:16 offset1:17
	v_xor_b32_e32 v115, 0x7f, v80
	v_xor_b32_e32 v95, 0x7f, v114
	v_and_b32_e32 v115, 0x7f, v115
	v_and_b32_e32 v95, 0x7f, v95
	ds_write2_b32 v67, v115, v95 offset0:18 offset1:19
	v_xor_b32_e32 v95, 0x7f, v73
	v_xor_b32_e32 v115, 0x7f, v116
	v_and_b32_e32 v95, 0x7f, v95
	v_and_b32_e32 v115, 0x7f, v115
	ds_write2_b32 v67, v95, v115 offset0:20 offset1:21
	v_xor_b32_e32 v115, 0x7f, v112
	v_xor_b32_e32 v95, 0x7f, v110
	v_and_b32_e32 v115, 0x7f, v115
	v_and_b32_e32 v95, 0x7f, v95
	ds_write2_b32 v67, v115, v95 offset0:22 offset1:23
	v_xor_b32_e32 v95, 0x7f, v103
	v_xor_b32_e32 v115, 0x7f, v89
	v_and_b32_e32 v95, 0x7f, v95
	v_and_b32_e32 v115, 0x7f, v115
	ds_write2_b32 v67, v95, v115 offset0:24 offset1:25
	v_xor_b32_e32 v115, 0x7f, v76
	v_xor_b32_e32 v95, 0x7f, v91
	v_and_b32_e32 v115, 0x7f, v115
	v_and_b32_e32 v95, 0x7f, v95
	ds_write2_b32 v67, v115, v95 offset0:26 offset1:27
	v_xor_b32_e32 v95, 0x7f, v83
	v_xor_b32_e32 v115, 0x7f, v101
	v_and_b32_e32 v95, 0x7f, v95
	v_and_b32_e32 v115, 0x7f, v115
	ds_write2_b32 v67, v95, v115 offset0:28 offset1:29
	v_xor_b32_e32 v115, 0x7f, v119
	v_xor_b32_e32 v95, 0x7f, v90
	v_and_b32_e32 v115, 0x7f, v115
	v_and_b32_e32 v95, 0x7f, v95
	ds_write2_b32 v67, v115, v95 offset0:30 offset1:31
	v_ashrrev_i32_e32 v115, 31, v72
	v_bitop3_b32 v115, v72, v115, s41 bitop3:0x87
	v_cvt_f32_f16_sdwa v95, v115 dst_sel:DWORD dst_unused:UNUSED_PAD src0_sel:WORD_1
	v_ashrrev_i32_e32 v98, 31, v88
	v_bitop3_b32 v98, v88, v98, s41 bitop3:0x87
	v_cvt_f32_f16_sdwa v115, v98 dst_sel:DWORD dst_unused:UNUSED_PAD src0_sel:WORD_1
	v_ashrrev_i32_e32 v111, 31, v75
	v_bitop3_b32 v111, v75, v111, s41 bitop3:0x87
	v_cvt_f32_f16_sdwa v98, v111 dst_sel:DWORD dst_unused:UNUSED_PAD src0_sel:WORD_1
	v_ashrrev_i32_e32 v74, 31, v97
	v_bitop3_b32 v74, v97, v74, s41 bitop3:0x87
	v_cvt_f32_f16_sdwa v111, v74 dst_sel:DWORD dst_unused:UNUSED_PAD src0_sel:WORD_1
	v_ashrrev_i32_e32 v84, 31, v70
	v_bitop3_b32 v84, v70, v84, s41 bitop3:0x87
	v_cvt_f32_f16_sdwa v74, v84 dst_sel:DWORD dst_unused:UNUSED_PAD src0_sel:WORD_1
	v_ashrrev_i32_e32 v100, 31, v99
	v_bitop3_b32 v100, v99, v100, s41 bitop3:0x87
	v_cvt_f32_f16_sdwa v84, v100 dst_sel:DWORD dst_unused:UNUSED_PAD src0_sel:WORD_1
	v_ashrrev_i32_e32 v105, 31, v96
	v_bitop3_b32 v105, v96, v105, s41 bitop3:0x87
	v_cvt_f32_f16_sdwa v100, v105 dst_sel:DWORD dst_unused:UNUSED_PAD src0_sel:WORD_1
	v_ashrrev_i32_e32 v92, 31, v94
	v_bitop3_b32 v92, v94, v92, s41 bitop3:0x87
	v_cvt_f32_f16_sdwa v105, v92 dst_sel:DWORD dst_unused:UNUSED_PAD src0_sel:WORD_1
	v_ashrrev_i32_e32 v117, 31, v87
	v_bitop3_b32 v117, v87, v117, s41 bitop3:0x87
	v_cvt_f32_f16_sdwa v92, v117 dst_sel:DWORD dst_unused:UNUSED_PAD src0_sel:WORD_1
	v_ashrrev_i32_e32 v93, 31, v77
	v_bitop3_b32 v93, v77, v93, s41 bitop3:0x87
	v_cvt_f32_f16_sdwa v117, v93 dst_sel:DWORD dst_unused:UNUSED_PAD src0_sel:WORD_1
	v_ashrrev_i32_e32 v107, 31, v82
	v_bitop3_b32 v107, v82, v107, s41 bitop3:0x87
	v_cvt_f32_f16_sdwa v93, v107 dst_sel:DWORD dst_unused:UNUSED_PAD src0_sel:WORD_1
	v_ashrrev_i32_e32 v79, 31, v81
	v_bitop3_b32 v79, v81, v79, s41 bitop3:0x87
	v_cvt_f32_f16_sdwa v107, v79 dst_sel:DWORD dst_unused:UNUSED_PAD src0_sel:WORD_1
	v_ashrrev_i32_e32 v108, 31, v78
	v_bitop3_b32 v108, v78, v108, s41 bitop3:0x87
	v_cvt_f32_f16_sdwa v79, v108 dst_sel:DWORD dst_unused:UNUSED_PAD src0_sel:WORD_1
	v_ashrrev_i32_e32 v109, 31, v85
	v_bitop3_b32 v109, v85, v109, s41 bitop3:0x87
	v_cvt_f32_f16_sdwa v108, v109 dst_sel:DWORD dst_unused:UNUSED_PAD src0_sel:WORD_1
	v_ashrrev_i32_e32 v118, 31, v102
	v_bitop3_b32 v118, v102, v118, s41 bitop3:0x87
	v_cvt_f32_f16_sdwa v109, v118 dst_sel:DWORD dst_unused:UNUSED_PAD src0_sel:WORD_1
	v_ashrrev_i32_e32 v106, 31, v86
	v_bitop3_b32 v106, v86, v106, s41 bitop3:0x87
	v_cvt_f32_f16_sdwa v118, v106 dst_sel:DWORD dst_unused:UNUSED_PAD src0_sel:WORD_1
	v_ashrrev_i32_e32 v120, 31, v71
	v_bitop3_b32 v120, v71, v120, s41 bitop3:0x87
	v_cvt_f32_f16_sdwa v106, v120 dst_sel:DWORD dst_unused:UNUSED_PAD src0_sel:WORD_1
	v_ashrrev_i32_e32 v121, 31, v104
	v_bitop3_b32 v121, v104, v121, s41 bitop3:0x87
	v_cvt_f32_f16_sdwa v120, v121 dst_sel:DWORD dst_unused:UNUSED_PAD src0_sel:WORD_1
	v_ashrrev_i32_e32 v122, 31, v80
	v_bitop3_b32 v122, v80, v122, s41 bitop3:0x87
	v_cvt_f32_f16_sdwa v121, v122 dst_sel:DWORD dst_unused:UNUSED_PAD src0_sel:WORD_1
	v_ashrrev_i32_e32 v123, 31, v114
	v_bitop3_b32 v123, v114, v123, s41 bitop3:0x87
	v_cvt_f32_f16_sdwa v122, v123 dst_sel:DWORD dst_unused:UNUSED_PAD src0_sel:WORD_1
	v_ashrrev_i32_e32 v124, 31, v73
	v_bitop3_b32 v124, v73, v124, s41 bitop3:0x87
	v_cvt_f32_f16_sdwa v123, v124 dst_sel:DWORD dst_unused:UNUSED_PAD src0_sel:WORD_1
	v_ashrrev_i32_e32 v125, 31, v116
	v_bitop3_b32 v125, v116, v125, s41 bitop3:0x87
	v_cvt_f32_f16_sdwa v124, v125 dst_sel:DWORD dst_unused:UNUSED_PAD src0_sel:WORD_1
	v_ashrrev_i32_e32 v126, 31, v112
	v_bitop3_b32 v126, v112, v126, s41 bitop3:0x87
	v_cvt_f32_f16_sdwa v125, v126 dst_sel:DWORD dst_unused:UNUSED_PAD src0_sel:WORD_1
	v_ashrrev_i32_e32 v127, 31, v110
	v_bitop3_b32 v127, v110, v127, s41 bitop3:0x87
	v_cvt_f32_f16_sdwa v126, v127 dst_sel:DWORD dst_unused:UNUSED_PAD src0_sel:WORD_1
	v_ashrrev_i32_e32 v128, 31, v103
	v_bitop3_b32 v128, v103, v128, s41 bitop3:0x87
	v_cvt_f32_f16_sdwa v127, v128 dst_sel:DWORD dst_unused:UNUSED_PAD src0_sel:WORD_1
	v_ashrrev_i32_e32 v129, 31, v89
	v_bitop3_b32 v129, v89, v129, s41 bitop3:0x87
	v_cvt_f32_f16_sdwa v128, v129 dst_sel:DWORD dst_unused:UNUSED_PAD src0_sel:WORD_1
	v_ashrrev_i32_e32 v130, 31, v76
; __device__ __forceinline__ float key2f(unsigned k) { const unsigned u = (k & 0x80000000u) ? (k & 0x7fffffffu) : ~k; return __uint_as_float(u); }
; #define CK(i, j) ((f2key(va[i] + vb[j]) & ~255u) | (unsigned)(255 - (16 * (i) + (j))))
; __device__ __forceinline__ void peer_tile(const Args& A, LAS unsigned char* lds, int tile) {
;     ...
;             float va[16], vb[16];
; #pragma unroll
;             for (int i = 0; i < 16; ++i) { va[i] = key2f(L2[0][i] & ~127u); vb[i] = key2f(L2[1][i] & ~127u); idx[i] = 127u - (L2[0][i] & 127u); idx[16 + i] = 127u - (L2[1][i] & 127u); }
;     ...
;             unsigned Lf[16], Bt[16];
; #pragma unroll
;             for (int j = 0; j < 16; ++j) Lf[j] = CK(0, j);
; #pragma unroll
;             for (int j = 0; j < 8; ++j) Bt[j] = CK(1, j);
; #pragma unroll
;             for (int j = 0; j < 5; ++j) Bt[8 + j] = CK(2, j);
; #pragma unroll
;             for (int j = 0; j < 3; ++j) Bt[13 + j] = CK(4, j);
	v_bitop3_b32 v130, v76, v130, s41 bitop3:0x87
	v_cvt_f32_f16_sdwa v129, v130 dst_sel:DWORD dst_unused:UNUSED_PAD src0_sel:WORD_1
	v_ashrrev_i32_e32 v131, 31, v91
	v_bitop3_b32 v131, v91, v131, s41 bitop3:0x87
	v_cvt_f32_f16_sdwa v130, v131 dst_sel:DWORD dst_unused:UNUSED_PAD src0_sel:WORD_1
	v_ashrrev_i32_e32 v132, 31, v83
	v_bitop3_b32 v132, v83, v132, s41 bitop3:0x87
	v_cvt_f32_f16_sdwa v131, v132 dst_sel:DWORD dst_unused:UNUSED_PAD src0_sel:WORD_1
	v_ashrrev_i32_e32 v133, 31, v101
	v_bitop3_b32 v133, v101, v133, s41 bitop3:0x87
	v_cvt_f32_f16_sdwa v132, v133 dst_sel:DWORD dst_unused:UNUSED_PAD src0_sel:WORD_1
	v_ashrrev_i32_e32 v134, 31, v119
	v_bitop3_b32 v134, v119, v134, s41 bitop3:0x87
	v_cvt_f32_f16_sdwa v133, v134 dst_sel:DWORD dst_unused:UNUSED_PAD src0_sel:WORD_1
	v_ashrrev_i32_e32 v135, 31, v90
	v_bitop3_b32 v135, v90, v135, s41 bitop3:0x87
	v_cvt_f32_f16_sdwa v134, v135 dst_sel:DWORD dst_unused:UNUSED_PAD src0_sel:WORD_1
	v_add_f32_e32 v90, v95, v106
	v_ashrrev_i32_e32 v119, 31, v90
	v_bitop3_b32 v90, v90, v119, s41 bitop3:0x78
	v_and_b32_e32 v90, 0xffffff00, v90
	v_xor_b32_e32 v90, 0x800000ff, v90
	v_add_f32_e32 v119, v95, v120
	v_ashrrev_i32_e32 v101, 31, v119
	v_bitop3_b32 v119, v119, v101, s41 bitop3:0x78
	v_and_b32_e32 v119, 0xffffff00, v119
	v_xor_b32_e32 v119, 0x800000fe, v119
	v_add_f32_e32 v101, v95, v121
	v_ashrrev_i32_e32 v83, 31, v101
	v_bitop3_b32 v101, v101, v83, s41 bitop3:0x78
	v_and_b32_e32 v101, 0xffffff00, v101
	v_xor_b32_e32 v101, 0x800000fd, v101
	v_add_f32_e32 v83, v95, v122
	v_ashrrev_i32_e32 v91, 31, v83
	v_bitop3_b32 v83, v83, v91, s41 bitop3:0x78
	v_and_b32_e32 v83, 0xffffff00, v83
	v_xor_b32_e32 v83, 0x800000fc, v83
	v_add_f32_e32 v91, v95, v123
	v_ashrrev_i32_e32 v76, 31, v91
	v_bitop3_b32 v91, v91, v76, s41 bitop3:0x78
	v_and_b32_e32 v91, 0xffffff00, v91
	v_xor_b32_e32 v91, 0x800000fb, v91
	v_add_f32_e32 v76, v95, v124
	v_ashrrev_i32_e32 v89, 31, v76
	v_bitop3_b32 v76, v76, v89, s41 bitop3:0x78
	v_and_b32_e32 v76, 0xffffff00, v76
	v_xor_b32_e32 v76, 0x800000fa, v76
	v_add_f32_e32 v89, v95, v125
	v_ashrrev_i32_e32 v103, 31, v89
	v_bitop3_b32 v89, v89, v103, s41 bitop3:0x78
	v_and_b32_e32 v89, 0xffffff00, v89
	v_xor_b32_e32 v89, 0x800000f9, v89
	v_add_f32_e32 v103, v95, v126
	v_ashrrev_i32_e32 v110, 31, v103
	v_bitop3_b32 v103, v103, v110, s41 bitop3:0x78
	v_and_b32_e32 v103, 0xffffff00, v103
	v_xor_b32_e32 v103, 0x800000f8, v103
	v_add_f32_e32 v110, v95, v127
	v_ashrrev_i32_e32 v112, 31, v110
	v_bitop3_b32 v110, v110, v112, s41 bitop3:0x78
	v_and_b32_e32 v110, 0xffffff00, v110
	v_xor_b32_e32 v110, 0x800000f7, v110
	v_add_f32_e32 v112, v95, v128
	v_ashrrev_i32_e32 v116, 31, v112
	v_bitop3_b32 v112, v112, v116, s41 bitop3:0x78
	v_and_b32_e32 v112, 0xffffff00, v112
	v_xor_b32_e32 v112, 0x800000f6, v112
	v_add_f32_e32 v116, v95, v129
	v_ashrrev_i32_e32 v73, 31, v116
	v_bitop3_b32 v116, v116, v73, s41 bitop3:0x78
	v_and_b32_e32 v116, 0xffffff00, v116
	v_xor_b32_e32 v116, 0x800000f5, v116
	v_add_f32_e32 v73, v95, v130
	v_ashrrev_i32_e32 v114, 31, v73
	v_bitop3_b32 v73, v73, v114, s41 bitop3:0x78
	v_and_b32_e32 v73, 0xffffff00, v73
	v_xor_b32_e32 v73, 0x800000f4, v73
	v_add_f32_e32 v114, v95, v131
	v_ashrrev_i32_e32 v80, 31, v114
	v_bitop3_b32 v114, v114, v80, s41 bitop3:0x78
	v_and_b32_e32 v114, 0xffffff00, v114
	v_xor_b32_e32 v114, 0x800000f3, v114
	v_add_f32_e32 v80, v95, v132
	v_ashrrev_i32_e32 v104, 31, v80
	v_bitop3_b32 v80, v80, v104, s41 bitop3:0x78
	v_and_b32_e32 v80, 0xffffff00, v80
	v_xor_b32_e32 v80, 0x800000f2, v80
	v_add_f32_e32 v104, v95, v133
	v_ashrrev_i32_e32 v71, 31, v104
	v_bitop3_b32 v104, v104, v71, s41 bitop3:0x78
	v_and_b32_e32 v104, 0xffffff00, v104
	v_xor_b32_e32 v104, 0x800000f1, v104
	v_add_f32_e32 v71, v95, v134
	v_ashrrev_i32_e32 v86, 31, v71
	v_bitop3_b32 v71, v71, v86, s41 bitop3:0x78
	v_and_b32_e32 v71, 0xffffff00, v71
	v_xor_b32_e32 v71, 0x800000f0, v71
	v_add_f32_e32 v86, v115, v106
	v_ashrrev_i32_e32 v102, 31, v86
	v_bitop3_b32 v86, v86, v102, s41 bitop3:0x78
	v_and_b32_e32 v86, 0xffffff00, v86
	v_xor_b32_e32 v86, 0x800000ef, v86
	v_add_f32_e32 v102, v115, v120
	v_ashrrev_i32_e32 v85, 31, v102
	v_bitop3_b32 v102, v102, v85, s41 bitop3:0x78
	v_and_b32_e32 v102, 0xffffff00, v102
	v_xor_b32_e32 v102, 0x800000ee, v102
	v_add_f32_e32 v85, v115, v121
	v_ashrrev_i32_e32 v78, 31, v85
	v_bitop3_b32 v85, v85, v78, s41 bitop3:0x78
	v_and_b32_e32 v85, 0xffffff00, v85
	v_xor_b32_e32 v85, 0x800000ed, v85
	v_add_f32_e32 v78, v115, v122
	v_ashrrev_i32_e32 v81, 31, v78
	v_bitop3_b32 v78, v78, v81, s41 bitop3:0x78
	v_and_b32_e32 v78, 0xffffff00, v78
	v_xor_b32_e32 v78, 0x800000ec, v78
	v_add_f32_e32 v81, v115, v123
	v_ashrrev_i32_e32 v82, 31, v81
	v_bitop3_b32 v81, v81, v82, s41 bitop3:0x78
	v_and_b32_e32 v81, 0xffffff00, v81
	v_xor_b32_e32 v81, 0x800000eb, v81
	v_add_f32_e32 v82, v115, v124
	v_ashrrev_i32_e32 v77, 31, v82
	v_bitop3_b32 v82, v82, v77, s41 bitop3:0x78
	v_and_b32_e32 v82, 0xffffff00, v82
	v_xor_b32_e32 v82, 0x800000ea, v82
	v_add_f32_e32 v77, v115, v125
	v_ashrrev_i32_e32 v87, 31, v77
	v_bitop3_b32 v77, v77, v87, s41 bitop3:0x78
	v_and_b32_e32 v77, 0xffffff00, v77
	v_xor_b32_e32 v77, 0x800000e9, v77
	v_add_f32_e32 v87, v115, v126
	v_ashrrev_i32_e32 v94, 31, v87
	v_bitop3_b32 v87, v87, v94, s41 bitop3:0x78
	v_and_b32_e32 v87, 0xffffff00, v87
	v_xor_b32_e32 v87, 0x800000e8, v87
	v_add_f32_e32 v94, v98, v106
	v_ashrrev_i32_e32 v96, 31, v94
	v_bitop3_b32 v94, v94, v96, s41 bitop3:0x78
	v_and_b32_e32 v94, 0xffffff00, v94
	v_xor_b32_e32 v94, 0x800000df, v94
	v_add_f32_e32 v96, v98, v120
	v_ashrrev_i32_e32 v99, 31, v96
	v_bitop3_b32 v96, v96, v99, s41 bitop3:0x78
; #define CK(i, j) ((f2key(va[i] + vb[j]) & ~255u) | (unsigned)(255 - (16 * (i) + (j))))
; __device__ __forceinline__ void peer_tile(const Args& A, LAS unsigned char* lds, int tile) {
;     ...
;             unsigned Lf[16], Bt[16];
; #pragma unroll
;             for (int j = 0; j < 16; ++j) Lf[j] = CK(0, j);
; #pragma unroll
;             for (int j = 0; j < 8; ++j) Bt[j] = CK(1, j);
; #pragma unroll
;             for (int j = 0; j < 5; ++j) Bt[8 + j] = CK(2, j);
; #pragma unroll
;             for (int j = 0; j < 3; ++j) Bt[13 + j] = CK(4, j);
;             sort16_desc(Bt); merge16(Lf, Bt);
	v_and_b32_e32 v96, 0xffffff00, v96
	v_xor_b32_e32 v96, 0x800000de, v96
	v_add_f32_e32 v99, v98, v121
	v_ashrrev_i32_e32 v70, 31, v99
	v_bitop3_b32 v99, v99, v70, s41 bitop3:0x78
	v_and_b32_e32 v99, 0xffffff00, v99
	v_xor_b32_e32 v99, 0x800000dd, v99
	v_add_f32_e32 v70, v98, v122
	v_ashrrev_i32_e32 v97, 31, v70
	v_bitop3_b32 v70, v70, v97, s41 bitop3:0x78
	v_and_b32_e32 v70, 0xffffff00, v70
	v_xor_b32_e32 v70, 0x800000dc, v70
	v_add_f32_e32 v97, v98, v123
	v_ashrrev_i32_e32 v75, 31, v97
	v_bitop3_b32 v97, v97, v75, s41 bitop3:0x78
	v_and_b32_e32 v97, 0xffffff00, v97
	v_xor_b32_e32 v97, 0x800000db, v97
	v_add_f32_e32 v75, v74, v106
	v_ashrrev_i32_e32 v88, 31, v75
	v_bitop3_b32 v75, v75, v88, s41 bitop3:0x78
	v_and_b32_e32 v75, 0xffffff00, v75
	v_xor_b32_e32 v75, 0x800000bf, v75
	v_add_f32_e32 v88, v74, v120
	v_ashrrev_i32_e32 v72, 31, v88
	v_bitop3_b32 v88, v88, v72, s41 bitop3:0x78
	v_and_b32_e32 v88, 0xffffff00, v88
	v_xor_b32_e32 v88, 0x800000be, v88
	v_add_f32_e32 v72, v74, v121
	v_ashrrev_i32_e32 v135, 31, v72
	v_bitop3_b32 v72, v72, v135, s41 bitop3:0x78
	v_and_b32_e32 v72, 0xffffff00, v72
	v_xor_b32_e32 v72, 0x800000bd, v72
	v_max_u32_e32 v135, v86, v75
	v_min_u32_e32 v75, v86, v75
	v_max_u32_e32 v86, v102, v97
	v_min_u32_e32 v97, v102, v97
	v_max_u32_e32 v102, v85, v72
	v_min_u32_e32 v72, v85, v72
	v_max_u32_e32 v85, v78, v88
	v_min_u32_e32 v88, v78, v88
	v_max_u32_e32 v78, v81, v94
	v_min_u32_e32 v94, v81, v94
	v_max_u32_e32 v81, v82, v77
	v_min_u32_e32 v77, v82, v77
	v_max_u32_e32 v82, v87, v70
	v_min_u32_e32 v70, v87, v70
	v_max_u32_e32 v87, v96, v99
	v_min_u32_e32 v99, v96, v99
	v_max_u32_e32 v96, v135, v81
	v_min_u32_e32 v81, v135, v81
	v_max_u32_e32 v135, v86, v82
	v_min_u32_e32 v82, v86, v82
	v_max_u32_e32 v86, v102, v87
	v_min_u32_e32 v87, v102, v87
	v_max_u32_e32 v102, v85, v78
	v_min_u32_e32 v78, v85, v78
	v_max_u32_e32 v85, v77, v75
	v_min_u32_e32 v75, v77, v75
	v_max_u32_e32 v77, v94, v88
	v_min_u32_e32 v88, v94, v88
	v_max_u32_e32 v94, v99, v72
	v_min_u32_e32 v72, v99, v72
	v_max_u32_e32 v99, v70, v97
	v_min_u32_e32 v97, v70, v97
	v_max_u32_e32 v70, v96, v135
	v_min_u32_e32 v135, v96, v135
	v_max_u32_e32 v96, v86, v102
	v_min_u32_e32 v102, v86, v102
	v_max_u32_e32 v86, v78, v81
	v_min_u32_e32 v81, v78, v81
	v_max_u32_e32 v78, v85, v77
	v_min_u32_e32 v77, v85, v77
	v_max_u32_e32 v85, v82, v87
	v_min_u32_e32 v87, v82, v87
	v_max_u32_e32 v82, v94, v99
	v_min_u32_e32 v99, v94, v99
	v_max_u32_e32 v94, v97, v75
	v_min_u32_e32 v75, v97, v75
	v_max_u32_e32 v97, v88, v72
	v_min_u32_e32 v72, v88, v72
	v_max_u32_e32 v88, v70, v96
	v_min_u32_e32 v96, v70, v96
	v_max_u32_e32 v70, v135, v102
	v_min_u32_e32 v102, v135, v102
	v_max_u32_e32 v135, v86, v82
	v_min_u32_e32 v82, v86, v82
	v_max_u32_e32 v86, v81, v99
	v_min_u32_e32 v99, v81, v99
	v_max_u32_e32 v81, v78, v85
	v_min_u32_e32 v85, v78, v85
	v_max_u32_e32 v78, v77, v87
	v_min_u32_e32 v87, v77, v87
	v_max_u32_e32 v77, v94, v97
	v_min_u32_e32 v97, v94, v97
	v_max_u32_e32 v94, v75, v72
	v_min_u32_e32 v72, v75, v72
	v_max_u32_e32 v75, v70, v96
	v_min_u32_e32 v96, v70, v96
	v_max_u32_e32 v70, v102, v77
	v_min_u32_e32 v77, v102, v77
	v_max_u32_e32 v102, v135, v81
	v_min_u32_e32 v81, v135, v81
	v_max_u32_e32 v135, v86, v85
	v_min_u32_e32 v85, v86, v85
	v_max_u32_e32 v86, v78, v82
	v_min_u32_e32 v82, v78, v82
	v_max_u32_e32 v78, v87, v99
	v_min_u32_e32 v99, v87, v99
	v_max_u32_e32 v87, v94, v97
	v_min_u32_e32 v97, v94, v97
	v_max_u32_e32 v94, v75, v102
	v_min_u32_e32 v102, v75, v102
	v_max_u32_e32 v75, v96, v81
	v_min_u32_e32 v81, v96, v81
	v_max_u32_e32 v96, v135, v86
	v_min_u32_e32 v86, v135, v86
	v_max_u32_e32 v135, v85, v82
	v_min_u32_e32 v82, v85, v82
	v_max_u32_e32 v85, v78, v87
	v_min_u32_e32 v87, v78, v87
	v_max_u32_e32 v78, v99, v97
	v_min_u32_e32 v97, v99, v97
	v_max_u32_e32 v99, v75, v102
	v_min_u32_e32 v102, v75, v102
	v_max_u32_e32 v75, v70, v81
	v_min_u32_e32 v81, v70, v81
	v_max_u32_e32 v70, v85, v77
	v_min_u32_e32 v77, v85, v77
	v_max_u32_e32 v85, v78, v87
	v_min_u32_e32 v87, v78, v87
	v_max_u32_e32 v78, v75, v96
	v_min_u32_e32 v96, v75, v96
	v_max_u32_e32 v75, v81, v86
	v_min_u32_e32 v86, v81, v86
	v_max_u32_e32 v81, v135, v70
	v_min_u32_e32 v70, v135, v70
	v_max_u32_e32 v135, v82, v77
	v_min_u32_e32 v77, v82, v77
	v_max_u32_e32 v82, v78, v102
	v_min_u32_e32 v102, v78, v102
	v_max_u32_e32 v78, v96, v75
	v_min_u32_e32 v75, v96, v75
	v_max_u32_e32 v96, v81, v86
	v_min_u32_e32 v86, v81, v86
	v_max_u32_e32 v81, v70, v135
	v_min_u32_e32 v135, v70, v135
	v_max_u32_e32 v70, v85, v77
	v_min_u32_e32 v77, v85, v77
	v_max_u32_e32 v85, v75, v96
	v_min_u32_e32 v96, v75, v96
	v_max_u32_e32 v75, v86, v81
	v_min_u32_e32 v81, v86, v81
	v_max_u32_e32 v90, v90, v72
	v_max_u32_e32 v119, v119, v97
	v_max_u32_e32 v101, v101, v87
	v_max_u32_e32 v83, v83, v77
	v_max_u32_e32 v91, v91, v70
	v_max_u32_e32 v76, v76, v135
	v_max_u32_e32 v89, v89, v81
	v_max_u32_e32 v103, v103, v75
	v_max_u32_e32 v110, v110, v96
	v_max_u32_e32 v112, v112, v85
	v_max_u32_e32 v116, v116, v78
	v_max_u32_e32 v73, v73, v102
	v_max_u32_e32 v114, v114, v82
	v_max_u32_e32 v80, v80, v99
	v_max_u32_e32 v104, v104, v94
	v_max_u32_e32 v71, v71, v88
	v_max_u32_e32 v72, v90, v110
	v_min_u32_e32 v110, v90, v110
	v_max_u32_e32 v90, v119, v112
	v_min_u32_e32 v112, v119, v112
	v_max_u32_e32 v119, v101, v116
	v_min_u32_e32 v116, v101, v116
	v_max_u32_e32 v101, v83, v73
	v_min_u32_e32 v73, v83, v73
	v_max_u32_e32 v83, v91, v114
	v_min_u32_e32 v114, v91, v114
	v_max_u32_e32 v91, v76, v80
	v_min_u32_e32 v80, v76, v80
	v_max_u32_e32 v76, v89, v104
	v_min_u32_e32 v104, v89, v104
	v_max_u32_e32 v89, v103, v71
	v_min_u32_e32 v71, v103, v71
; #define CK(i, j) ((f2key(va[i] + vb[j]) & ~255u) | (unsigned)(255 - (16 * (i) + (j))))
; __device__ __forceinline__ void peer_tile(const Args& A, LAS unsigned char* lds, int tile) {
;     ...
;             sort16_desc(Bt); merge16(Lf, Bt);
; #pragma unroll
;             for (int j = 0; j < 4; ++j) Bt[j] = CK(3, j);
;             Bt[4] = CK(5, 0); Bt[5] = CK(5, 1); Bt[6] = CK(6, 0); Bt[7] = CK(6, 1); Bt[8] = CK(7, 0); Bt[9] = CK(7, 1);
;             Bt[10] = CK(8, 0); Bt[11] = CK(9, 0); Bt[12] = CK(10, 0); Bt[13] = CK(11, 0); Bt[14] = CK(12, 0); Bt[15] = CK(13, 0);
;             sort16_desc(Bt); merge16(Lf, Bt);
	v_max_u32_e32 v103, v72, v83
	v_min_u32_e32 v83, v72, v83
	v_max_u32_e32 v72, v90, v91
	v_min_u32_e32 v91, v90, v91
	v_max_u32_e32 v90, v119, v76
	v_min_u32_e32 v76, v119, v76
	v_max_u32_e32 v119, v101, v89
	v_min_u32_e32 v89, v101, v89
	v_max_u32_e32 v101, v110, v114
	v_min_u32_e32 v114, v110, v114
	v_max_u32_e32 v110, v112, v80
	v_min_u32_e32 v80, v112, v80
	v_max_u32_e32 v112, v116, v104
	v_min_u32_e32 v104, v116, v104
	v_max_u32_e32 v116, v73, v71
	v_min_u32_e32 v71, v73, v71
	v_max_u32_e32 v73, v103, v90
	v_min_u32_e32 v90, v103, v90
	v_max_u32_e32 v103, v72, v119
	v_min_u32_e32 v119, v72, v119
	v_max_u32_e32 v72, v83, v76
	v_min_u32_e32 v76, v83, v76
	v_max_u32_e32 v83, v91, v89
	v_min_u32_e32 v89, v91, v89
	v_max_u32_e32 v91, v101, v112
	v_min_u32_e32 v112, v101, v112
	v_max_u32_e32 v101, v110, v116
	v_min_u32_e32 v116, v110, v116
	v_max_u32_e32 v110, v114, v104
	v_min_u32_e32 v104, v114, v104
	v_max_u32_e32 v114, v80, v71
	v_min_u32_e32 v71, v80, v71
	v_max_u32_e32 v80, v73, v103
	v_min_u32_e32 v103, v73, v103
	v_max_u32_e32 v73, v90, v119
	v_min_u32_e32 v119, v90, v119
	v_max_u32_e32 v90, v72, v83
	v_min_u32_e32 v83, v72, v83
	v_max_u32_e32 v72, v76, v89
	v_min_u32_e32 v89, v76, v89
	v_max_u32_e32 v76, v91, v101
	v_min_u32_e32 v101, v91, v101
	v_max_u32_e32 v91, v112, v116
	v_min_u32_e32 v116, v112, v116
	v_max_u32_e32 v112, v110, v114
	v_min_u32_e32 v114, v110, v114
	v_max_u32_e32 v110, v104, v71
	v_min_u32_e32 v71, v104, v71
	v_add_f32_e32 v104, v111, v106
	v_ashrrev_i32_e32 v97, 31, v104
	v_bitop3_b32 v104, v104, v97, s41 bitop3:0x78
	v_and_b32_e32 v104, 0xffffff00, v104
	v_xor_b32_e32 v104, 0x800000cf, v104
	v_add_f32_e32 v97, v111, v120
	v_ashrrev_i32_e32 v87, 31, v97
	v_bitop3_b32 v97, v97, v87, s41 bitop3:0x78
	v_and_b32_e32 v97, 0xffffff00, v97
	v_xor_b32_e32 v97, 0x800000ce, v97
	v_add_f32_e32 v87, v111, v121
	v_ashrrev_i32_e32 v77, 31, v87
	v_bitop3_b32 v87, v87, v77, s41 bitop3:0x78
	v_and_b32_e32 v87, 0xffffff00, v87
	v_xor_b32_e32 v87, 0x800000cd, v87
	v_add_f32_e32 v77, v111, v122
	v_ashrrev_i32_e32 v70, 31, v77
	v_bitop3_b32 v77, v77, v70, s41 bitop3:0x78
	v_and_b32_e32 v77, 0xffffff00, v77
	v_xor_b32_e32 v77, 0x800000cc, v77
	v_add_f32_e32 v70, v84, v106
	v_ashrrev_i32_e32 v135, 31, v70
	v_bitop3_b32 v70, v70, v135, s41 bitop3:0x78
	v_and_b32_e32 v70, 0xffffff00, v70
	v_xor_b32_e32 v70, 0x800000af, v70
	v_add_f32_e32 v135, v84, v120
	v_ashrrev_i32_e32 v81, 31, v135
	v_bitop3_b32 v135, v135, v81, s41 bitop3:0x78
	v_and_b32_e32 v135, 0xffffff00, v135
	v_xor_b32_e32 v135, 0x800000ae, v135
	v_add_f32_e32 v81, v100, v106
	v_ashrrev_i32_e32 v75, 31, v81
	v_bitop3_b32 v81, v81, v75, s41 bitop3:0x78
	v_and_b32_e32 v81, 0xffffff00, v81
	v_xor_b32_e32 v81, 0x8000009f, v81
	v_add_f32_e32 v75, v100, v120
	v_ashrrev_i32_e32 v96, 31, v75
	v_bitop3_b32 v75, v75, v96, s41 bitop3:0x78
	v_and_b32_e32 v75, 0xffffff00, v75
	v_xor_b32_e32 v75, 0x8000009e, v75
	v_add_f32_e32 v96, v105, v106
	v_ashrrev_i32_e32 v85, 31, v96
	v_bitop3_b32 v96, v96, v85, s41 bitop3:0x78
	v_and_b32_e32 v96, 0xffffff00, v96
	v_xor_b32_e32 v96, 0x8000008f, v96
	v_add_f32_e32 v85, v105, v120
	v_ashrrev_i32_e32 v78, 31, v85
	v_bitop3_b32 v85, v85, v78, s41 bitop3:0x78
	v_and_b32_e32 v85, 0xffffff00, v85
	v_xor_b32_e32 v85, 0x8000008e, v85
	v_add_f32_e32 v78, v92, v106
	v_ashrrev_i32_e32 v102, 31, v78
	v_bitop3_b32 v78, v78, v102, s41 bitop3:0x78
	v_and_b32_e32 v78, 0xffffff00, v78
	v_xor_b32_e32 v78, 0x8000007f, v78
	v_add_f32_e32 v102, v117, v106
	v_ashrrev_i32_e32 v82, 31, v102
	v_bitop3_b32 v102, v102, v82, s41 bitop3:0x78
	v_and_b32_e32 v102, 0xffffff00, v102
	v_xor_b32_e32 v102, 0x8000006f, v102
	v_add_f32_e32 v82, v93, v106
	v_ashrrev_i32_e32 v99, 31, v82
	v_bitop3_b32 v82, v82, v99, s41 bitop3:0x78
	v_and_b32_e32 v82, 0xffffff00, v82
	v_xor_b32_e32 v82, 0x8000005f, v82
	v_add_f32_e32 v99, v107, v106
	v_ashrrev_i32_e32 v94, 31, v99
	v_bitop3_b32 v99, v99, v94, s41 bitop3:0x78
	v_and_b32_e32 v99, 0xffffff00, v99
	v_xor_b32_e32 v99, 0x8000004f, v99
	v_add_f32_e32 v94, v79, v106
	v_ashrrev_i32_e32 v88, 31, v94
	v_bitop3_b32 v94, v94, v88, s41 bitop3:0x78
	v_and_b32_e32 v94, 0xffffff00, v94
	v_xor_b32_e32 v94, 0x8000003f, v94
	v_add_f32_e32 v88, v108, v106
	v_ashrrev_i32_e32 v86, 31, v88
	v_bitop3_b32 v88, v88, v86, s41 bitop3:0x78
	v_and_b32_e32 v88, 0xffffff00, v88
	v_xor_b32_e32 v88, 0x8000002f, v88
	v_max_u32_e32 v86, v104, v99
	v_min_u32_e32 v99, v104, v99
	v_max_u32_e32 v104, v97, v82
	v_min_u32_e32 v82, v97, v82
	v_max_u32_e32 v97, v87, v88
	v_min_u32_e32 v88, v87, v88
	v_max_u32_e32 v87, v77, v94
	v_min_u32_e32 v94, v77, v94
	v_max_u32_e32 v77, v70, v96
	v_min_u32_e32 v96, v70, v96
	v_max_u32_e32 v70, v135, v81
	v_min_u32_e32 v81, v135, v81
	v_max_u32_e32 v135, v75, v102
	v_min_u32_e32 v102, v75, v102
	v_max_u32_e32 v75, v85, v78
	v_min_u32_e32 v78, v85, v78
	v_max_u32_e32 v85, v86, v70
	v_min_u32_e32 v70, v86, v70
	v_max_u32_e32 v86, v104, v135
	v_min_u32_e32 v135, v104, v135
	v_max_u32_e32 v104, v97, v75
	v_min_u32_e32 v75, v97, v75
	v_max_u32_e32 v97, v87, v77
	v_min_u32_e32 v77, v87, v77
	v_max_u32_e32 v87, v81, v99
	v_min_u32_e32 v99, v81, v99
	v_max_u32_e32 v81, v96, v94
	v_min_u32_e32 v94, v96, v94
	v_max_u32_e32 v96, v78, v88
	v_min_u32_e32 v88, v78, v88
	v_max_u32_e32 v78, v102, v82
	v_min_u32_e32 v82, v102, v82
	v_max_u32_e32 v102, v85, v86
	v_min_u32_e32 v86, v85, v86
	v_max_u32_e32 v85, v104, v97
	v_min_u32_e32 v97, v104, v97
	v_max_u32_e32 v104, v77, v70
	v_min_u32_e32 v70, v77, v70
	v_max_u32_e32 v77, v87, v81
	v_min_u32_e32 v81, v87, v81
	v_max_u32_e32 v87, v135, v75
	v_min_u32_e32 v75, v135, v75
	v_max_u32_e32 v135, v96, v78
; #define CE_DESC(a, b) do { const unsigned _mx = (a) > (b) ? (a) : (b), _mn = (a) > (b) ? (b) : (a); (a) = _mx; (b) = _mn; } while (0)
; #define CK(i, j) ((f2key(va[i] + vb[j]) & ~255u) | (unsigned)(255 - (16 * (i) + (j))))
; __device__ __forceinline__ void peer_tile(const Args& A, LAS unsigned char* lds, int tile) {
;     ...
;             sort16_desc(Bt); merge16(Lf, Bt);
; #pragma unroll
;             for (int j = 0; j < 4; ++j) Bt[j] = CK(3, j);
;             Bt[4] = CK(5, 0); Bt[5] = CK(5, 1); Bt[6] = CK(6, 0); Bt[7] = CK(6, 1); Bt[8] = CK(7, 0); Bt[9] = CK(7, 1);
;             Bt[10] = CK(8, 0); Bt[11] = CK(9, 0); Bt[12] = CK(10, 0); Bt[13] = CK(11, 0); Bt[14] = CK(12, 0); Bt[15] = CK(13, 0);
;             sort16_desc(Bt); merge16(Lf, Bt);
;             { unsigned x0 = CK(14, 0), x1 = CK(15, 0);
; #pragma unroll
;               for (int i = 0; i < 16; ++i) CE_DESC(Lf[i], x0);
; #pragma unroll
;               for (int i = 0; i < 16; ++i) CE_DESC(Lf[i], x1); }
	v_min_u32_e32 v78, v96, v78
	v_max_u32_e32 v96, v82, v99
	v_min_u32_e32 v99, v82, v99
	v_max_u32_e32 v82, v94, v88
	v_min_u32_e32 v88, v94, v88
	v_max_u32_e32 v94, v102, v85
	v_min_u32_e32 v85, v102, v85
	v_max_u32_e32 v102, v86, v97
	v_min_u32_e32 v97, v86, v97
	v_max_u32_e32 v86, v104, v135
	v_min_u32_e32 v135, v104, v135
	v_max_u32_e32 v104, v70, v78
	v_min_u32_e32 v78, v70, v78
	v_max_u32_e32 v70, v77, v87
	v_min_u32_e32 v87, v77, v87
	v_max_u32_e32 v77, v81, v75
	v_min_u32_e32 v75, v81, v75
	v_max_u32_e32 v81, v96, v82
	v_min_u32_e32 v82, v96, v82
	v_max_u32_e32 v96, v99, v88
	v_min_u32_e32 v88, v99, v88
	v_max_u32_e32 v99, v102, v85
	v_min_u32_e32 v85, v102, v85
	v_max_u32_e32 v102, v97, v81
	v_min_u32_e32 v81, v97, v81
	v_max_u32_e32 v97, v86, v70
	v_min_u32_e32 v70, v86, v70
	v_max_u32_e32 v86, v104, v87
	v_min_u32_e32 v87, v104, v87
	v_max_u32_e32 v104, v77, v135
	v_min_u32_e32 v135, v77, v135
	v_max_u32_e32 v77, v75, v78
	v_min_u32_e32 v78, v75, v78
	v_max_u32_e32 v75, v96, v82
	v_min_u32_e32 v82, v96, v82
	v_max_u32_e32 v96, v99, v97
	v_min_u32_e32 v97, v99, v97
	v_max_u32_e32 v99, v85, v70
	v_min_u32_e32 v70, v85, v70
	v_max_u32_e32 v85, v86, v104
	v_min_u32_e32 v104, v86, v104
	v_max_u32_e32 v86, v87, v135
	v_min_u32_e32 v135, v87, v135
	v_max_u32_e32 v87, v77, v75
	v_min_u32_e32 v75, v77, v75
	v_max_u32_e32 v77, v78, v82
	v_min_u32_e32 v82, v78, v82
	v_max_u32_e32 v78, v99, v97
	v_min_u32_e32 v97, v99, v97
	v_max_u32_e32 v99, v102, v70
	v_min_u32_e32 v70, v102, v70
	v_max_u32_e32 v102, v87, v81
	v_min_u32_e32 v81, v87, v81
	v_max_u32_e32 v87, v77, v75
	v_min_u32_e32 v75, v77, v75
	v_max_u32_e32 v77, v99, v85
	v_min_u32_e32 v85, v99, v85
	v_max_u32_e32 v99, v70, v104
	v_min_u32_e32 v104, v70, v104
	v_max_u32_e32 v70, v86, v102
	v_min_u32_e32 v102, v86, v102
	v_max_u32_e32 v86, v135, v81
	v_min_u32_e32 v81, v135, v81
	v_max_u32_e32 v135, v77, v97
	v_min_u32_e32 v97, v77, v97
	v_max_u32_e32 v77, v85, v99
	v_min_u32_e32 v99, v85, v99
	v_max_u32_e32 v85, v70, v104
	v_min_u32_e32 v104, v70, v104
	v_max_u32_e32 v70, v102, v86
	v_min_u32_e32 v86, v102, v86
	v_max_u32_e32 v102, v87, v81
	v_min_u32_e32 v81, v87, v81
	v_max_u32_e32 v87, v99, v85
	v_min_u32_e32 v85, v99, v85
	v_max_u32_e32 v99, v104, v70
	v_min_u32_e32 v70, v104, v70
	v_max_u32_e32 v80, v80, v88
	v_max_u32_e32 v103, v103, v82
	v_max_u32_e32 v73, v73, v75
	v_max_u32_e32 v119, v119, v81
	v_max_u32_e32 v90, v90, v102
	v_max_u32_e32 v83, v83, v86
	v_max_u32_e32 v72, v72, v70
	v_max_u32_e32 v89, v89, v99
	v_max_u32_e32 v76, v76, v85
	v_max_u32_e32 v101, v101, v87
	v_max_u32_e32 v91, v91, v77
	v_max_u32_e32 v116, v116, v97
	v_max_u32_e32 v112, v112, v135
	v_max_u32_e32 v114, v114, v78
	v_max_u32_e32 v110, v110, v96
	v_max_u32_e32 v71, v71, v94
	v_max_u32_e32 v88, v80, v76
	v_min_u32_e32 v76, v80, v76
	v_max_u32_e32 v80, v103, v101
	v_min_u32_e32 v101, v103, v101
	v_max_u32_e32 v103, v73, v91
	v_min_u32_e32 v91, v73, v91
	v_max_u32_e32 v73, v119, v116
	v_min_u32_e32 v116, v119, v116
	v_max_u32_e32 v119, v90, v112
	v_min_u32_e32 v112, v90, v112
	v_max_u32_e32 v90, v83, v114
	v_min_u32_e32 v114, v83, v114
	v_max_u32_e32 v83, v72, v110
	v_min_u32_e32 v110, v72, v110
	v_max_u32_e32 v72, v89, v71
	v_min_u32_e32 v71, v89, v71
	v_max_u32_e32 v89, v88, v119
	v_min_u32_e32 v119, v88, v119
	v_max_u32_e32 v88, v80, v90
	v_min_u32_e32 v90, v80, v90
	v_max_u32_e32 v80, v103, v83
	v_min_u32_e32 v83, v103, v83
	v_max_u32_e32 v103, v73, v72
	v_min_u32_e32 v72, v73, v72
	v_max_u32_e32 v73, v76, v112
	v_min_u32_e32 v112, v76, v112
	v_max_u32_e32 v76, v101, v114
	v_min_u32_e32 v114, v101, v114
	v_max_u32_e32 v101, v91, v110
	v_min_u32_e32 v110, v91, v110
	v_max_u32_e32 v91, v116, v71
	v_min_u32_e32 v71, v116, v71
	v_max_u32_e32 v116, v89, v80
	v_min_u32_e32 v80, v89, v80
	v_max_u32_e32 v89, v88, v103
	v_min_u32_e32 v103, v88, v103
	v_max_u32_e32 v88, v119, v83
	v_min_u32_e32 v83, v119, v83
	v_max_u32_e32 v119, v90, v72
	v_min_u32_e32 v72, v90, v72
	v_max_u32_e32 v90, v73, v101
	v_min_u32_e32 v101, v73, v101
	v_max_u32_e32 v73, v76, v91
	v_min_u32_e32 v91, v76, v91
	v_max_u32_e32 v76, v112, v110
	v_min_u32_e32 v110, v112, v110
	v_max_u32_e32 v112, v114, v71
	v_min_u32_e32 v71, v114, v71
	v_max_u32_e32 v114, v116, v89
	v_min_u32_e32 v89, v116, v89
	v_max_u32_e32 v116, v80, v103
	v_min_u32_e32 v103, v80, v103
	v_max_u32_e32 v80, v88, v119
	v_min_u32_e32 v119, v88, v119
	v_max_u32_e32 v88, v83, v72
	v_min_u32_e32 v72, v83, v72
	v_max_u32_e32 v83, v90, v73
	v_min_u32_e32 v73, v90, v73
	v_max_u32_e32 v90, v101, v91
	v_min_u32_e32 v91, v101, v91
	v_max_u32_e32 v101, v76, v112
	v_min_u32_e32 v112, v76, v112
	v_max_u32_e32 v76, v110, v71
	v_min_u32_e32 v71, v110, v71
	v_add_f32_e32 v110, v109, v106
	v_ashrrev_i32_e32 v82, 31, v110
	v_bitop3_b32 v110, v110, v82, s41 bitop3:0x78
	v_and_b32_e32 v110, 0xffffff00, v110
	v_xor_b32_e32 v110, 0x8000001f, v110
	v_max_u32_e32 v82, v114, v110
	v_min_u32_e32 v110, v114, v110
	v_max_u32_e32 v114, v89, v110
	v_min_u32_e32 v110, v89, v110
	v_max_u32_e32 v89, v116, v110
	v_min_u32_e32 v110, v116, v110
	v_max_u32_e32 v116, v103, v110
	v_min_u32_e32 v110, v103, v110
	v_max_u32_e32 v103, v80, v110
	v_min_u32_e32 v110, v80, v110
	v_max_u32_e32 v80, v119, v110
	v_min_u32_e32 v110, v119, v110
	v_max_u32_e32 v119, v88, v110
	v_min_u32_e32 v110, v88, v110
	v_max_u32_e32 v88, v72, v110
	v_min_u32_e32 v110, v72, v110
	v_max_u32_e32 v72, v83, v110
	v_min_u32_e32 v110, v83, v110
	v_max_u32_e32 v83, v73, v110
	v_min_u32_e32 v110, v73, v110
	v_max_u32_e32 v73, v90, v110
	v_min_u32_e32 v110, v90, v110
	v_max_u32_e32 v90, v91, v110
	v_min_u32_e32 v110, v91, v110
	v_max_u32_e32 v91, v101, v110
; __device__ __forceinline__ float key2f(unsigned k) { const unsigned u = (k & 0x80000000u) ? (k & 0x7fffffffu) : ~k; return __uint_as_float(u); }
; #define CE_DESC(a, b) do { const unsigned _mx = (a) > (b) ? (a) : (b), _mn = (a) > (b) ? (b) : (a); (a) = _mx; (b) = _mn; } while (0)
; #define CK(i, j) ((f2key(va[i] + vb[j]) & ~255u) | (unsigned)(255 - (16 * (i) + (j))))
; __device__ __forceinline__ void peer_tile(const Args& A, LAS unsigned char* lds, int tile) {
;     ...
;             { unsigned x0 = CK(14, 0), x1 = CK(15, 0);
; #pragma unroll
;               for (int i = 0; i < 16; ++i) CE_DESC(Lf[i], x0);
; #pragma unroll
;               for (int i = 0; i < 16; ++i) CE_DESC(Lf[i], x1); }
;     ...
;             float fv[16], den = 0.f; const float f0 = key2f(Lf[0] & ~255u);
; #pragma unroll
;             for (int k = 0; k < 16; ++k) { fv[k] = __expf(key2f(Lf[k] & ~255u) - f0); den += fv[k]; }
;             const float rden = 1.f / den;
	v_min_u32_e32 v110, v101, v110
	v_max_u32_e32 v101, v112, v110
	v_min_u32_e32 v110, v112, v110
	v_max_u32_e32 v112, v76, v110
	v_min_u32_e32 v110, v76, v110
	v_max_u32_e32 v76, v71, v110
	v_min_u32_e32 v110, v71, v110
	v_add_f32_e32 v110, v118, v106
	v_ashrrev_i32_e32 v71, 31, v110
	v_bitop3_b32 v110, v110, v71, s41 bitop3:0x78
	v_and_b32_e32 v110, 0xffffff00, v110
	v_xor_b32_e32 v110, 0x8000000f, v110
	v_max_u32_e32 v71, v82, v110
	v_min_u32_e32 v110, v82, v110
	v_max_u32_e32 v82, v114, v110
	v_min_u32_e32 v110, v114, v110
	v_max_u32_e32 v114, v89, v110
	v_min_u32_e32 v110, v89, v110
	v_max_u32_e32 v89, v116, v110
	v_min_u32_e32 v110, v116, v110
	v_max_u32_e32 v116, v103, v110
	v_min_u32_e32 v110, v103, v110
	v_max_u32_e32 v103, v80, v110
	v_min_u32_e32 v110, v80, v110
	v_max_u32_e32 v80, v119, v110
	v_min_u32_e32 v110, v119, v110
	v_max_u32_e32 v119, v88, v110
	v_min_u32_e32 v110, v88, v110
	v_max_u32_e32 v88, v72, v110
	v_min_u32_e32 v110, v72, v110
	v_max_u32_e32 v72, v83, v110
	v_min_u32_e32 v110, v83, v110
	v_max_u32_e32 v83, v73, v110
	v_min_u32_e32 v110, v73, v110
	v_max_u32_e32 v73, v90, v110
	v_min_u32_e32 v110, v90, v110
	v_max_u32_e32 v90, v91, v110
	v_min_u32_e32 v110, v91, v110
	v_max_u32_e32 v91, v101, v110
	v_min_u32_e32 v110, v101, v110
	v_max_u32_e32 v101, v112, v110
	v_min_u32_e32 v110, v112, v110
	v_max_u32_e32 v112, v76, v110
	v_min_u32_e32 v110, v76, v110
	v_ashrrev_i32_e32 v133, 31, v71
	v_and_b32_e32 v134, 0xffffff00, v71
	v_bitop3_b32 v134, v134, v133, s41 bitop3:0x87
	v_ashrrev_i32_e32 v131, 31, v71
	v_and_b32_e32 v132, 0xffffff00, v71
	v_bitop3_b32 v132, v132, v131, s41 bitop3:0x87
	v_sub_f32_e32 v132, v132, v134
	v_mul_f32_e32 v132, 0x3fb8aa3b, v132
	v_exp_f32_e32 v132, v132
	v_ashrrev_i32_e32 v130, 31, v82
	v_and_b32_e32 v131, 0xffffff00, v82
	v_bitop3_b32 v131, v131, v130, s41 bitop3:0x87
	v_sub_f32_e32 v131, v131, v134
	v_mul_f32_e32 v131, 0x3fb8aa3b, v131
	v_exp_f32_e32 v131, v131
	v_ashrrev_i32_e32 v129, 31, v114
	v_and_b32_e32 v130, 0xffffff00, v114
	v_bitop3_b32 v130, v130, v129, s41 bitop3:0x87
	v_sub_f32_e32 v130, v130, v134
	v_mul_f32_e32 v130, 0x3fb8aa3b, v130
	v_exp_f32_e32 v130, v130
	v_ashrrev_i32_e32 v128, 31, v89
	v_and_b32_e32 v129, 0xffffff00, v89
	v_bitop3_b32 v129, v129, v128, s41 bitop3:0x87
	v_sub_f32_e32 v129, v129, v134
	v_mul_f32_e32 v129, 0x3fb8aa3b, v129
	v_exp_f32_e32 v129, v129
	v_ashrrev_i32_e32 v127, 31, v116
	v_and_b32_e32 v128, 0xffffff00, v116
	v_bitop3_b32 v128, v128, v127, s41 bitop3:0x87
	v_sub_f32_e32 v128, v128, v134
	v_mul_f32_e32 v128, 0x3fb8aa3b, v128
	v_exp_f32_e32 v128, v128
	v_ashrrev_i32_e32 v126, 31, v103
	v_and_b32_e32 v127, 0xffffff00, v103
	v_bitop3_b32 v127, v127, v126, s41 bitop3:0x87
	v_sub_f32_e32 v127, v127, v134
	v_mul_f32_e32 v127, 0x3fb8aa3b, v127
	v_exp_f32_e32 v127, v127
	v_ashrrev_i32_e32 v125, 31, v80
	v_and_b32_e32 v126, 0xffffff00, v80
	v_bitop3_b32 v126, v126, v125, s41 bitop3:0x87
	v_sub_f32_e32 v126, v126, v134
	v_mul_f32_e32 v126, 0x3fb8aa3b, v126
	v_exp_f32_e32 v126, v126
	v_ashrrev_i32_e32 v124, 31, v119
	v_and_b32_e32 v125, 0xffffff00, v119
	v_bitop3_b32 v125, v125, v124, s41 bitop3:0x87
	v_sub_f32_e32 v125, v125, v134
	v_mul_f32_e32 v125, 0x3fb8aa3b, v125
	v_exp_f32_e32 v125, v125
	v_ashrrev_i32_e32 v123, 31, v88
	v_and_b32_e32 v124, 0xffffff00, v88
	v_bitop3_b32 v124, v124, v123, s41 bitop3:0x87
	v_sub_f32_e32 v124, v124, v134
	v_mul_f32_e32 v124, 0x3fb8aa3b, v124
	v_exp_f32_e32 v124, v124
	v_ashrrev_i32_e32 v122, 31, v72
	v_and_b32_e32 v123, 0xffffff00, v72
	v_bitop3_b32 v123, v123, v122, s41 bitop3:0x87
	v_sub_f32_e32 v123, v123, v134
	v_mul_f32_e32 v123, 0x3fb8aa3b, v123
	v_exp_f32_e32 v123, v123
	v_ashrrev_i32_e32 v121, 31, v83
	v_and_b32_e32 v122, 0xffffff00, v83
	v_bitop3_b32 v122, v122, v121, s41 bitop3:0x87
	v_sub_f32_e32 v122, v122, v134
	v_mul_f32_e32 v122, 0x3fb8aa3b, v122
	v_exp_f32_e32 v122, v122
	v_ashrrev_i32_e32 v120, 31, v73
	v_and_b32_e32 v121, 0xffffff00, v73
	v_bitop3_b32 v121, v121, v120, s41 bitop3:0x87
	v_sub_f32_e32 v121, v121, v134
	v_mul_f32_e32 v121, 0x3fb8aa3b, v121
	v_exp_f32_e32 v121, v121
	v_ashrrev_i32_e32 v106, 31, v90
	v_and_b32_e32 v120, 0xffffff00, v90
	v_bitop3_b32 v120, v120, v106, s41 bitop3:0x87
	v_sub_f32_e32 v120, v120, v134
	v_mul_f32_e32 v120, 0x3fb8aa3b, v120
	v_exp_f32_e32 v120, v120
	v_ashrrev_i32_e32 v118, 31, v91
	v_and_b32_e32 v106, 0xffffff00, v91
	v_bitop3_b32 v106, v106, v118, s41 bitop3:0x87
	v_sub_f32_e32 v106, v106, v134
	v_mul_f32_e32 v106, 0x3fb8aa3b, v106
	v_exp_f32_e32 v106, v106
	v_ashrrev_i32_e32 v109, 31, v101
	v_and_b32_e32 v118, 0xffffff00, v101
	v_bitop3_b32 v118, v118, v109, s41 bitop3:0x87
	v_sub_f32_e32 v118, v118, v134
	v_mul_f32_e32 v118, 0x3fb8aa3b, v118
	v_exp_f32_e32 v118, v118
	v_ashrrev_i32_e32 v108, 31, v112
	v_and_b32_e32 v109, 0xffffff00, v112
	v_bitop3_b32 v109, v109, v108, s41 bitop3:0x87
	v_sub_f32_e32 v109, v109, v134
	v_mul_f32_e32 v109, 0x3fb8aa3b, v109
	v_exp_f32_e32 v109, v109
	v_add_f32_e32 v133, 0, v132
	v_add_f32_e32 v133, v133, v131
	v_add_f32_e32 v133, v133, v130
	v_add_f32_e32 v133, v133, v129
	v_add_f32_e32 v133, v133, v128
	v_add_f32_e32 v133, v133, v127
	v_add_f32_e32 v133, v133, v126
	v_add_f32_e32 v133, v133, v125
	v_add_f32_e32 v133, v133, v124
	v_add_f32_e32 v133, v133, v123
	v_add_f32_e32 v133, v133, v122
	v_add_f32_e32 v133, v133, v121
	v_add_f32_e32 v133, v133, v120
	v_add_f32_e32 v133, v133, v106
	v_add_f32_e32 v133, v133, v118
	v_add_f32_e32 v133, v133, v109
	v_div_scale_f32 v108, s[0:1], v133, v133, 1.0
	v_rcp_f32_e32 v79, v108
	s_nop 0
	v_fma_f32 v107, -v108, v79, 1.0
	v_fmac_f32_e32 v79, v107, v79
	v_div_scale_f32 v107, vcc, 1.0, v133, 1.0
	v_mul_f32_e32 v93, v107, v79
	v_fma_f32 v117, -v108, v93, v107
	v_fmac_f32_e32 v93, v117, v79
	v_fma_f32 v108, -v108, v93, v107
	s_nop 1
	v_div_fmas_f32 v108, v108, v79, v93
	v_div_fixup_f32 v108, v108, v133, 1.0
	s_waitcnt lgkmcnt(0)
; #define LDS_WAIT() asm volatile("s_waitcnt lgkmcnt(0)" ::: "memory")
; __device__ __forceinline__ void peer_tile(const Args& A, LAS unsigned char* lds, int tile) {
;     ...
;             LDS_WAIT();
; #pragma unroll
;             for (int k = 0; k < 16; ++k) { const unsigned code = 255u - (Lf[k] & 255u); const unsigned e = idx[code >> 4] * 128u + idx[16 + (code & 15u)];
;                 u32x2 sv; sv.x = e; sv.y = __float_as_uint(fv[k] * rden); SEL[(tl * 8 + h) * 16 + k] = sv; }
	v_xor_b32_e32 v117, 0xff, v71
	v_bfe_u32 v93, v117, 4, 4
	v_and_b32_e32 v117, 15, v117
	v_lshl_add_u32 v93, v93, 2, v67
	v_lshl_add_u32 v117, v117, 2, v67
	ds_read_b32 v93, v93
	ds_read_b32 v117, v117 offset:64
	v_xor_b32_e32 v107, 0xff, v82
	v_bfe_u32 v79, v107, 4, 4
	v_and_b32_e32 v107, 15, v107
	v_lshl_add_u32 v79, v79, 2, v67
	v_lshl_add_u32 v107, v107, 2, v67
	ds_read_b32 v79, v79
	ds_read_b32 v107, v107 offset:64
	v_xor_b32_e32 v92, 0xff, v114
	v_bfe_u32 v105, v92, 4, 4
	v_and_b32_e32 v92, 15, v92
	v_lshl_add_u32 v105, v105, 2, v67
	v_lshl_add_u32 v92, v92, 2, v67
	ds_read_b32 v105, v105
	ds_read_b32 v92, v92 offset:64
	v_xor_b32_e32 v100, 0xff, v89
	v_bfe_u32 v84, v100, 4, 4
	v_and_b32_e32 v100, 15, v100
	v_lshl_add_u32 v84, v84, 2, v67
	v_lshl_add_u32 v100, v100, 2, v67
	ds_read_b32 v84, v84
	ds_read_b32 v100, v100 offset:64
	v_xor_b32_e32 v74, 0xff, v116
	v_bfe_u32 v111, v74, 4, 4
	v_and_b32_e32 v74, 15, v74
	v_lshl_add_u32 v111, v111, 2, v67
	v_lshl_add_u32 v74, v74, 2, v67
	ds_read_b32 v111, v111
	ds_read_b32 v74, v74 offset:64
	v_xor_b32_e32 v98, 0xff, v103
	v_bfe_u32 v115, v98, 4, 4
	v_and_b32_e32 v98, 15, v98
	v_lshl_add_u32 v115, v115, 2, v67
	v_lshl_add_u32 v98, v98, 2, v67
	ds_read_b32 v115, v115
	ds_read_b32 v98, v98 offset:64
	v_xor_b32_e32 v95, 0xff, v80
	v_bfe_u32 v110, v95, 4, 4
	v_and_b32_e32 v95, 15, v95
	v_lshl_add_u32 v110, v110, 2, v67
	v_lshl_add_u32 v95, v95, 2, v67
	ds_read_b32 v110, v110
	ds_read_b32 v95, v95 offset:64
	v_xor_b32_e32 v76, 0xff, v119
	v_bfe_u32 v75, v76, 4, 4
	v_and_b32_e32 v76, 15, v76
	v_lshl_add_u32 v75, v75, 2, v67
	v_lshl_add_u32 v76, v76, 2, v67
	ds_read_b32 v75, v75
	ds_read_b32 v76, v76 offset:64
	v_xor_b32_e32 v81, 0xff, v88
	v_bfe_u32 v102, v81, 4, 4
	v_and_b32_e32 v81, 15, v81
	v_lshl_add_u32 v102, v102, 2, v67
	v_lshl_add_u32 v81, v81, 2, v67
	ds_read_b32 v102, v102
	ds_read_b32 v81, v81 offset:64
	v_xor_b32_e32 v86, 0xff, v72
	v_bfe_u32 v70, v86, 4, 4
	v_and_b32_e32 v86, 15, v86
	v_lshl_add_u32 v70, v70, 2, v67
	v_lshl_add_u32 v86, v86, 2, v67
	ds_read_b32 v70, v70
	ds_read_b32 v86, v86 offset:64
	v_xor_b32_e32 v99, 0xff, v83
	v_bfe_u32 v85, v99, 4, 4
	v_and_b32_e32 v99, 15, v99
	v_lshl_add_u32 v85, v85, 2, v67
	v_lshl_add_u32 v99, v99, 2, v67
	ds_read_b32 v85, v85
	ds_read_b32 v99, v99 offset:64
	v_xor_b32_e32 v87, 0xff, v73
	v_bfe_u32 v77, v87, 4, 4
	v_and_b32_e32 v87, 15, v87
	v_lshl_add_u32 v77, v77, 2, v67
	v_lshl_add_u32 v87, v87, 2, v67
	ds_read_b32 v77, v77
	ds_read_b32 v87, v87 offset:64
	v_xor_b32_e32 v97, 0xff, v90
	v_bfe_u32 v135, v97, 4, 4
	v_and_b32_e32 v97, 15, v97
	v_lshl_add_u32 v135, v135, 2, v67
	v_lshl_add_u32 v97, v97, 2, v67
	ds_read_b32 v135, v135
	ds_read_b32 v97, v97 offset:64
	v_xor_b32_e32 v78, 0xff, v91
	v_bfe_u32 v96, v78, 4, 4
	v_and_b32_e32 v78, 15, v78
	v_lshl_add_u32 v96, v96, 2, v67
	v_lshl_add_u32 v78, v78, 2, v67
	ds_read_b32 v96, v96
	ds_read_b32 v78, v78 offset:64
	v_xor_b32_e32 v94, 0xff, v101
	v_bfe_u32 v104, v94, 4, 4
	v_and_b32_e32 v94, 15, v94
	v_lshl_add_u32 v104, v104, 2, v67
	v_lshl_add_u32 v94, v94, 2, v67
	ds_read_b32 v104, v104
	ds_read_b32 v94, v94 offset:64
	v_xor_b32_e32 v136, 0xff, v112
	v_bfe_u32 v137, v136, 4, 4
	v_and_b32_e32 v136, 15, v136
	v_lshl_add_u32 v137, v137, 2, v67
	v_lshl_add_u32 v136, v136, 2, v67
	ds_read_b32 v137, v137
	ds_read_b32 v136, v136 offset:64
	s_waitcnt lgkmcnt(0)
	v_lshl_add_u32 v138, v93, 7, v117
	v_mul_f32_e32 v139, v132, v108
	v_lshl_add_u32 v140, v79, 7, v107
	v_mul_f32_e32 v141, v131, v108
	ds_write_b128 v68, v[138:141] offset:0
	v_lshl_add_u32 v138, v105, 7, v92
	v_mul_f32_e32 v139, v130, v108
	v_lshl_add_u32 v140, v84, 7, v100
	v_mul_f32_e32 v141, v129, v108
	ds_write_b128 v68, v[138:141] offset:16
	v_lshl_add_u32 v138, v111, 7, v74
	v_mul_f32_e32 v139, v128, v108
	v_lshl_add_u32 v140, v115, 7, v98
	v_mul_f32_e32 v141, v127, v108
	ds_write_b128 v68, v[138:141] offset:32
	v_lshl_add_u32 v138, v110, 7, v95
	v_mul_f32_e32 v139, v126, v108
	v_lshl_add_u32 v140, v75, 7, v76
	v_mul_f32_e32 v141, v125, v108
	ds_write_b128 v68, v[138:141] offset:48
	v_lshl_add_u32 v138, v102, 7, v81
	v_mul_f32_e32 v139, v124, v108
	v_lshl_add_u32 v140, v70, 7, v86
	v_mul_f32_e32 v141, v123, v108
	ds_write_b128 v68, v[138:141] offset:64
	v_lshl_add_u32 v138, v85, 7, v99
	v_mul_f32_e32 v139, v122, v108
	v_lshl_add_u32 v140, v77, 7, v87
	v_mul_f32_e32 v141, v121, v108
	ds_write_b128 v68, v[138:141] offset:80
	v_lshl_add_u32 v138, v135, 7, v97
	v_mul_f32_e32 v139, v120, v108
	v_lshl_add_u32 v140, v96, 7, v78
	v_mul_f32_e32 v141, v106, v108
	ds_write_b128 v68, v[138:141] offset:96
	v_lshl_add_u32 v138, v104, 7, v94
	v_mul_f32_e32 v139, v118, v108
	v_lshl_add_u32 v140, v137, 7, v136
	v_mul_f32_e32 v141, v109, v108
	ds_write_b128 v68, v[138:141] offset:112

; __device__ __forceinline__ unsigned pk2(float lo, float hi) { const f32x2 v = {lo, hi}; const bf16x2_t b = __builtin_convertvector(v, bf16x2_t); return __builtin_bit_cast(unsigned, b); }
; __device__ __forceinline__ float bflo(unsigned u) { return __uint_as_float(u << 16); }
; __device__ __forceinline__ float bfhi(unsigned u) { return __uint_as_float(u & 0xffff0000u); }
; __device__ __forceinline__ void peer_tile(const Args& A, LAS unsigned char* lds, int tile) {
;     ...
;     const unsigned char* T8v = T8 + (size_t)16384 * 1024;
;     const bf16_t* A3 = (const bf16_t*)(A.ws + WS_A3); const float* RSq = (const float*)(A.ws + WS_RS);
;     for (int pass = 0; pass < 2; ++pass) {
;         const int tb = 8 * w + 4 * pass;
;         u32x4 xpa[4], xpb[4]; f32x2 oacc[4][8];
; #pragma unroll
;         for (int tk = 0; tk < 4; ++tk) { const size_t m = (size_t)tile * 64 + tb + tk;
;             { const u32x4 ra = *(const u32x4*)(A3 + m * 1024 + 16 * lane), rb = *(const u32x4*)(A3 + m * 1024 + 16 * lane + 8);
;               float xr_; { const f32x4 p0 = *(const f32x4*)(RSq + m * 16), p1 = *(const f32x4*)(RSq + m * 16 + 4), p2 = *(const f32x4*)(RSq + m * 16 + 8), p3 = *(const f32x4*)(RSq + m * 16 + 12);
;                 const f32x4 ps = (p0 + p1) + (p2 + p3); xr_ = rsqrtf(((ps[0] + ps[1]) + (ps[2] + ps[3])) * (1.f / 1024.f) + 1e-6f); }
;               const unsigned rr[8] = {ra.x, ra.y, ra.z, ra.w, rb.x, rb.y, rb.z, rb.w}; unsigned hh[8];
;               const float* sp = MOD + (int)(m >> 11) * 6144 + 3072 + 16 * lane;
; #pragma unroll
;               for (int q = 0; q < 8; ++q) { const f32x2 sh = *(const f32x2*)(sp + 2 * q); hh[q] = pk2(bflo(rr[q]) * xr_ + sh[0], bfhi(rr[q]) * xr_ + sh[1]); }
;               xpa[tk] = (u32x4){hh[0], hh[1], hh[2], hh[3]}; xpb[tk] = (u32x4){hh[4], hh[5], hh[6], hh[7]}; }
; #pragma unroll
;             for (int q = 0; q < 8; ++q) oacc[tk][q] = (f32x2){0.f, 0.f}; }
;     ...
;                 { const unsigned xx[8] = {xpa[tk].x, xpa[tk].y, xpa[tk].z, xpa[tk].w, xpb[tk].x, xpb[tk].y, xpb[tk].z, xpb[tk].w};
; #pragma unroll
;                   for (int q = 0; q < 8; ++q) xf[q] = (f32x2){bflo(xx[q]), bfhi(xx[q])}; }
	s_mov_b64 exec, -1
	v_and_b32_e32 v240, 63, v214
	v_lshrrev_b32_e32 v242, 6, v214
	v_lshlrev_b32_e32 v240, 4, v240
	v_readfirstlane_b32 s16, v242
	v_lshlrev_b32_e32 v245, 1, v240
	v_lshlrev_b32_e32 v246, 2, v240
	v_lshrrev_b32_e32 v247, 4, v240
	v_and_b32_e32 v247, 48, v247
	v_mov_b32_e32 v244, 0
	v_mov_b32_e32 v243, 0x358637bd
	v_mov_b32_e32 v242, 0xbf3a00e3
	s_add_u32 s4, s50, 0x1000000
	s_addc_u32 s5, s51, 0
	s_add_u32 s6, s50, 0x2000000
	s_addc_u32 s7, s51, 0
	s_add_u32 s8, s50, 0x3000000
	s_addc_u32 s9, s51, 0
	s_add_u32 s52, s50, 0x3010000
	s_addc_u32 s53, s51, 0
	s_add_u32 s12, s50, 0xb000000
	s_addc_u32 s13, s51, 0
	s_add_u32 s14, s50, 0xd000000
	s_addc_u32 s15, s51, 0
	s_lshr_b32 s0, s2, 5
	s_mul_i32 s0, s0, 0x6000
	s_add_u32 s10, s50, s0
	s_addc_u32 s11, s51, 0
	s_add_u32 s80, s10, 0x4000
	s_addc_u32 s81, s11, 0
	s_add_u32 s82, s10, 0x6000
	s_addc_u32 s83, s11, 0
	s_mul_i32 s22, s16, 9920
	s_cmp_eq_u32 s16, 7
	s_cselect_b32 s22, 0x21000, s22
	s_mov_b32 s85, 0xffffffff
	s_mov_b32 s72, 0x3e6d3388
	s_mov_b32 s56, s4
	s_and_b32 s57, s5, 0xffff
	s_or_b32 s57, s57, 0x04000000
	s_mov_b32 s58, 16384
	s_mov_b32 s59, 0x00027000
	s_mov_b32 s60, s6
	s_and_b32 s61, s7, 0xffff
	s_or_b32 s61, s61, 0x04000000
	s_mov_b32 s62, 16384
	s_mov_b32 s63, 0x00027000
	s_lshl_b32 s76, s16, 3
	s_lshl_b32 s0, s2, 6
	s_add_i32 s77, s0, s76
	global_load_dwordx4 v[192:195], v246, s[80:81] offset:0
	global_load_dwordx4 v[196:199], v246, s[80:81] offset:16
	global_load_dwordx4 v[200:203], v246, s[80:81] offset:32
	global_load_dwordx4 v[204:207], v246, s[80:81] offset:48
	s_add_i32 s0, s77, 0
	s_lshl_b32 s1, s0, 11
	s_add_u32 s78, s12, s1
	s_addc_u32 s79, s13, 0
	global_load_dwordx4 v[128:131], v245, s[78:79]
	global_load_dwordx4 v[132:135], v245, s[78:79] offset:16
	global_load_dwordx4 v[136:139], v245, s[78:79] offset:2048
	global_load_dwordx4 v[140:143], v245, s[78:79] offset:2064
	s_lshl_b32 s1, s0, 6
	s_add_u32 s78, s14, s1
	s_addc_u32 s79, s15, 0
	global_load_dwordx4 v[144:147], v244, s[78:79] offset:0
	global_load_dwordx4 v[148:151], v244, s[78:79] offset:16
	global_load_dwordx4 v[152:155], v244, s[78:79] offset:32
	global_load_dwordx4 v[156:159], v244, s[78:79] offset:48
	global_load_dwordx4 v[160:163], v244, s[78:79] offset:64
	global_load_dwordx4 v[164:167], v244, s[78:79] offset:80
	global_load_dwordx4 v[168:171], v244, s[78:79] offset:96
	global_load_dwordx4 v[172:175], v244, s[78:79] offset:112
	s_waitcnt lgkmcnt(0)
	s_barrier
	s_add_i32 s0, s77, 2
	s_lshl_b32 s1, s0, 11
	s_add_u32 s78, s12, s1
	s_addc_u32 s79, s13, 0
	global_load_dwordx4 v[176:179], v245, s[78:79]
	global_load_dwordx4 v[180:183], v245, s[78:79] offset:16
	global_load_dwordx4 v[184:187], v245, s[78:79] offset:2048
	global_load_dwordx4 v[188:191], v245, s[78:79] offset:2064
	s_lshl_b32 s1, s0, 6
	s_add_u32 s78, s14, s1
	s_addc_u32 s79, s15, 0
	global_load_dwordx4 v[216:219], v244, s[78:79] offset:0
	global_load_dwordx4 v[220:223], v244, s[78:79] offset:16
	global_load_dwordx4 v[224:227], v244, s[78:79] offset:32
	global_load_dwordx4 v[228:231], v244, s[78:79] offset:48
	global_load_dwordx4 v[232:235], v244, s[78:79] offset:64
	global_load_dwordx4 v[236:239], v244, s[78:79] offset:80
	global_load_dwordx4 v[248:251], v244, s[78:79] offset:96
	global_load_dwordx4 v[252:255], v244, s[78:79] offset:112
	s_waitcnt vmcnt(12)
	v_pk_add_f32 v[144:145], v[144:145], v[148:149]
	v_pk_add_f32 v[146:147], v[146:147], v[150:151]
	v_pk_add_f32 v[152:153], v[152:153], v[156:157]
	v_pk_add_f32 v[154:155], v[154:155], v[158:159]
	v_pk_add_f32 v[144:145], v[144:145], v[152:153]
	v_pk_add_f32 v[146:147], v[146:147], v[154:155]
	v_add_f32_e32 v144, v144, v145
	v_add_f32_e32 v146, v146, v147
	v_add_f32_e32 v144, v144, v146
	v_fmamk_f32 v144, v144, 0x3a800000, v243
	v_rsq_f32_e32 v144, v144
	v_pk_add_f32 v[160:161], v[160:161], v[164:165]
	v_pk_add_f32 v[162:163], v[162:163], v[166:167]
	v_pk_add_f32 v[168:169], v[168:169], v[172:173]
	v_pk_add_f32 v[170:171], v[170:171], v[174:175]
	v_pk_add_f32 v[160:161], v[160:161], v[168:169]
	v_pk_add_f32 v[162:163], v[162:163], v[170:171]
	v_add_f32_e32 v160, v160, v161
	v_add_f32_e32 v162, v162, v163
	v_add_f32_e32 v160, v160, v162
	v_fmamk_f32 v160, v160, 0x3a800000, v243
	v_rsq_f32_e32 v160, v160
	v_lshlrev_b32_e32 v208, 16, v128
	v_and_b32_e32 v209, 0xffff0000, v128
	v_fma_f32 v208, v208, v144, v192
	v_fma_f32 v209, v209, v144, v193
	v_cvt_pk_bf16_f32 v210, v208, v209
	v_lshlrev_b32_e32 v0, 16, v210
	v_and_b32_e32 v1, 0xffff0000, v210
	v_lshlrev_b32_e32 v208, 16, v129
	v_and_b32_e32 v209, 0xffff0000, v129
	v_fma_f32 v208, v208, v144, v194
	v_fma_f32 v209, v209, v144, v195
	v_cvt_pk_bf16_f32 v210, v208, v209
	v_lshlrev_b32_e32 v2, 16, v210
	v_and_b32_e32 v3, 0xffff0000, v210
	v_lshlrev_b32_e32 v208, 16, v130
	v_and_b32_e32 v209, 0xffff0000, v130
	v_fma_f32 v208, v208, v144, v196
	v_fma_f32 v209, v209, v144, v197
	v_cvt_pk_bf16_f32 v210, v208, v209
	v_lshlrev_b32_e32 v4, 16, v210
	v_and_b32_e32 v5, 0xffff0000, v210
	v_lshlrev_b32_e32 v208, 16, v131
	v_and_b32_e32 v209, 0xffff0000, v131
	v_fma_f32 v208, v208, v144, v198
	v_fma_f32 v209, v209, v144, v199
	v_cvt_pk_bf16_f32 v210, v208, v209
	v_lshlrev_b32_e32 v6, 16, v210
	v_and_b32_e32 v7, 0xffff0000, v210
	v_lshlrev_b32_e32 v208, 16, v132
	v_and_b32_e32 v209, 0xffff0000, v132
	v_fma_f32 v208, v208, v144, v200
	v_fma_f32 v209, v209, v144, v201
	v_cvt_pk_bf16_f32 v210, v208, v209
	v_lshlrev_b32_e32 v8, 16, v210
	v_and_b32_e32 v9, 0xffff0000, v210
	v_lshlrev_b32_e32 v208, 16, v133
	v_and_b32_e32 v209, 0xffff0000, v133
	v_fma_f32 v208, v208, v144, v202
	v_fma_f32 v209, v209, v144, v203
	v_cvt_pk_bf16_f32 v210, v208, v209
; __device__ __forceinline__ unsigned pk2(float lo, float hi) { const f32x2 v = {lo, hi}; const bf16x2_t b = __builtin_convertvector(v, bf16x2_t); return __builtin_bit_cast(unsigned, b); }
; __device__ __forceinline__ float bflo(unsigned u) { return __uint_as_float(u << 16); }
; __device__ __forceinline__ float bfhi(unsigned u) { return __uint_as_float(u & 0xffff0000u); }
; __device__ __forceinline__ void peer_tile(const Args& A, LAS unsigned char* lds, int tile) {
;     ...
;         for (int tk = 0; tk < 4; ++tk) { const size_t m = (size_t)tile * 64 + tb + tk;
;             { const u32x4 ra = *(const u32x4*)(A3 + m * 1024 + 16 * lane), rb = *(const u32x4*)(A3 + m * 1024 + 16 * lane + 8);
;               float xr_; { const f32x4 p0 = *(const f32x4*)(RSq + m * 16), p1 = *(const f32x4*)(RSq + m * 16 + 4), p2 = *(const f32x4*)(RSq + m * 16 + 8), p3 = *(const f32x4*)(RSq + m * 16 + 12);
;                 const f32x4 ps = (p0 + p1) + (p2 + p3); xr_ = rsqrtf(((ps[0] + ps[1]) + (ps[2] + ps[3])) * (1.f / 1024.f) + 1e-6f); }
;               const unsigned rr[8] = {ra.x, ra.y, ra.z, ra.w, rb.x, rb.y, rb.z, rb.w}; unsigned hh[8];
;               const float* sp = MOD + (int)(m >> 11) * 6144 + 3072 + 16 * lane;
; #pragma unroll
;               for (int q = 0; q < 8; ++q) { const f32x2 sh = *(const f32x2*)(sp + 2 * q); hh[q] = pk2(bflo(rr[q]) * xr_ + sh[0], bfhi(rr[q]) * xr_ + sh[1]); }
;               xpa[tk] = (u32x4){hh[0], hh[1], hh[2], hh[3]}; xpb[tk] = (u32x4){hh[4], hh[5], hh[6], hh[7]}; }
;     ...
;                 { const unsigned xx[8] = {xpa[tk].x, xpa[tk].y, xpa[tk].z, xpa[tk].w, xpb[tk].x, xpb[tk].y, xpb[tk].z, xpb[tk].w};
; #pragma unroll
;                   for (int q = 0; q < 8; ++q) xf[q] = (f32x2){bflo(xx[q]), bfhi(xx[q])}; }
	v_lshlrev_b32_e32 v10, 16, v210
	v_and_b32_e32 v11, 0xffff0000, v210
	v_lshlrev_b32_e32 v208, 16, v134
	v_and_b32_e32 v209, 0xffff0000, v134
	v_fma_f32 v208, v208, v144, v204
	v_fma_f32 v209, v209, v144, v205
	v_cvt_pk_bf16_f32 v210, v208, v209
	v_lshlrev_b32_e32 v12, 16, v210
	v_and_b32_e32 v13, 0xffff0000, v210
	v_lshlrev_b32_e32 v208, 16, v135
	v_and_b32_e32 v209, 0xffff0000, v135
	v_fma_f32 v208, v208, v144, v206
	v_fma_f32 v209, v209, v144, v207
	v_cvt_pk_bf16_f32 v210, v208, v209
	v_lshlrev_b32_e32 v14, 16, v210
	v_and_b32_e32 v15, 0xffff0000, v210
	v_lshlrev_b32_e32 v208, 16, v136
	v_and_b32_e32 v209, 0xffff0000, v136
	v_fma_f32 v208, v208, v160, v192
	v_fma_f32 v209, v209, v160, v193
	v_cvt_pk_bf16_f32 v210, v208, v209
	v_lshlrev_b32_e32 v16, 16, v210
	v_and_b32_e32 v17, 0xffff0000, v210
	v_lshlrev_b32_e32 v208, 16, v137
	v_and_b32_e32 v209, 0xffff0000, v137
	v_fma_f32 v208, v208, v160, v194
	v_fma_f32 v209, v209, v160, v195
	v_cvt_pk_bf16_f32 v210, v208, v209
	v_lshlrev_b32_e32 v18, 16, v210
	v_and_b32_e32 v19, 0xffff0000, v210
	v_lshlrev_b32_e32 v208, 16, v138
	v_and_b32_e32 v209, 0xffff0000, v138
	v_fma_f32 v208, v208, v160, v196
	v_fma_f32 v209, v209, v160, v197
	v_cvt_pk_bf16_f32 v210, v208, v209
	v_lshlrev_b32_e32 v20, 16, v210
	v_and_b32_e32 v21, 0xffff0000, v210
	v_lshlrev_b32_e32 v208, 16, v139
	v_and_b32_e32 v209, 0xffff0000, v139
	v_fma_f32 v208, v208, v160, v198
	v_fma_f32 v209, v209, v160, v199
	v_cvt_pk_bf16_f32 v210, v208, v209
	v_lshlrev_b32_e32 v22, 16, v210
	v_and_b32_e32 v23, 0xffff0000, v210
	v_lshlrev_b32_e32 v208, 16, v140
	v_and_b32_e32 v209, 0xffff0000, v140
	v_fma_f32 v208, v208, v160, v200
	v_fma_f32 v209, v209, v160, v201
	v_cvt_pk_bf16_f32 v210, v208, v209
	v_lshlrev_b32_e32 v24, 16, v210
	v_and_b32_e32 v25, 0xffff0000, v210
	v_lshlrev_b32_e32 v208, 16, v141
	v_and_b32_e32 v209, 0xffff0000, v141
	v_fma_f32 v208, v208, v160, v202
	v_fma_f32 v209, v209, v160, v203
	v_cvt_pk_bf16_f32 v210, v208, v209
	v_lshlrev_b32_e32 v26, 16, v210
	v_and_b32_e32 v27, 0xffff0000, v210
	v_lshlrev_b32_e32 v208, 16, v142
	v_and_b32_e32 v209, 0xffff0000, v142
	v_fma_f32 v208, v208, v160, v204
	v_fma_f32 v209, v209, v160, v205
	v_cvt_pk_bf16_f32 v210, v208, v209
	v_lshlrev_b32_e32 v28, 16, v210
	v_and_b32_e32 v29, 0xffff0000, v210
	v_lshlrev_b32_e32 v208, 16, v143
	v_and_b32_e32 v209, 0xffff0000, v143
	v_fma_f32 v208, v208, v160, v206
	v_fma_f32 v209, v209, v160, v207
	v_cvt_pk_bf16_f32 v210, v208, v209
	v_lshlrev_b32_e32 v30, 16, v210
	v_and_b32_e32 v31, 0xffff0000, v210
	s_nop 0
	s_add_i32 s0, s77, 4
	s_lshl_b32 s1, s0, 11
	s_add_u32 s78, s12, s1
	s_addc_u32 s79, s13, 0
	global_load_dwordx4 v[128:131], v245, s[78:79]
	global_load_dwordx4 v[132:135], v245, s[78:79] offset:16
	global_load_dwordx4 v[136:139], v245, s[78:79] offset:2048
	global_load_dwordx4 v[140:143], v245, s[78:79] offset:2064
	s_lshl_b32 s1, s0, 6
	s_add_u32 s78, s14, s1
	s_addc_u32 s79, s15, 0
	global_load_dwordx4 v[144:147], v244, s[78:79] offset:0
	global_load_dwordx4 v[148:151], v244, s[78:79] offset:16
	global_load_dwordx4 v[152:155], v244, s[78:79] offset:32
	global_load_dwordx4 v[156:159], v244, s[78:79] offset:48
	global_load_dwordx4 v[160:163], v244, s[78:79] offset:64
	global_load_dwordx4 v[164:167], v244, s[78:79] offset:80
	global_load_dwordx4 v[168:171], v244, s[78:79] offset:96
	global_load_dwordx4 v[172:175], v244, s[78:79] offset:112
	s_waitcnt vmcnt(12)
	v_pk_add_f32 v[216:217], v[216:217], v[220:221]
	v_pk_add_f32 v[218:219], v[218:219], v[222:223]
	v_pk_add_f32 v[224:225], v[224:225], v[228:229]
	v_pk_add_f32 v[226:227], v[226:227], v[230:231]
	v_pk_add_f32 v[216:217], v[216:217], v[224:225]
	v_pk_add_f32 v[218:219], v[218:219], v[226:227]
	v_add_f32_e32 v216, v216, v217
	v_add_f32_e32 v218, v218, v219
	v_add_f32_e32 v216, v216, v218
	v_fmamk_f32 v216, v216, 0x3a800000, v243
	v_rsq_f32_e32 v216, v216
	v_pk_add_f32 v[232:233], v[232:233], v[236:237]
	v_pk_add_f32 v[234:235], v[234:235], v[238:239]
	v_pk_add_f32 v[248:249], v[248:249], v[252:253]
	v_pk_add_f32 v[250:251], v[250:251], v[254:255]
	v_pk_add_f32 v[232:233], v[232:233], v[248:249]
	v_pk_add_f32 v[234:235], v[234:235], v[250:251]
	v_add_f32_e32 v232, v232, v233
	v_add_f32_e32 v234, v234, v235
	v_add_f32_e32 v232, v232, v234
	v_fmamk_f32 v232, v232, 0x3a800000, v243
	v_rsq_f32_e32 v232, v232
	v_lshlrev_b32_e32 v208, 16, v176
	v_and_b32_e32 v209, 0xffff0000, v176
	v_fma_f32 v208, v208, v216, v192
	v_fma_f32 v209, v209, v216, v193
	v_cvt_pk_bf16_f32 v210, v208, v209
	v_lshlrev_b32_e32 v32, 16, v210
	v_and_b32_e32 v33, 0xffff0000, v210
	v_lshlrev_b32_e32 v208, 16, v177
	v_and_b32_e32 v209, 0xffff0000, v177
	v_fma_f32 v208, v208, v216, v194
	v_fma_f32 v209, v209, v216, v195
	v_cvt_pk_bf16_f32 v210, v208, v209
	v_lshlrev_b32_e32 v34, 16, v210
	v_and_b32_e32 v35, 0xffff0000, v210
	v_lshlrev_b32_e32 v208, 16, v178
	v_and_b32_e32 v209, 0xffff0000, v178
	v_fma_f32 v208, v208, v216, v196
	v_fma_f32 v209, v209, v216, v197
	v_cvt_pk_bf16_f32 v210, v208, v209
	v_lshlrev_b32_e32 v36, 16, v210
	v_and_b32_e32 v37, 0xffff0000, v210
	v_lshlrev_b32_e32 v208, 16, v179
	v_and_b32_e32 v209, 0xffff0000, v179
	v_fma_f32 v208, v208, v216, v198
	v_fma_f32 v209, v209, v216, v199
	v_cvt_pk_bf16_f32 v210, v208, v209
	v_lshlrev_b32_e32 v38, 16, v210
	v_and_b32_e32 v39, 0xffff0000, v210
	v_lshlrev_b32_e32 v208, 16, v180
	v_and_b32_e32 v209, 0xffff0000, v180
	v_fma_f32 v208, v208, v216, v200
	v_fma_f32 v209, v209, v216, v201
	v_cvt_pk_bf16_f32 v210, v208, v209
	v_lshlrev_b32_e32 v40, 16, v210
	v_and_b32_e32 v41, 0xffff0000, v210
	v_lshlrev_b32_e32 v208, 16, v181
	v_and_b32_e32 v209, 0xffff0000, v181
; __device__ __forceinline__ unsigned pk2(float lo, float hi) { const f32x2 v = {lo, hi}; const bf16x2_t b = __builtin_convertvector(v, bf16x2_t); return __builtin_bit_cast(unsigned, b); }
; __device__ __forceinline__ float bflo(unsigned u) { return __uint_as_float(u << 16); }
; __device__ __forceinline__ float bfhi(unsigned u) { return __uint_as_float(u & 0xffff0000u); }
; __device__ __forceinline__ void peer_tile(const Args& A, LAS unsigned char* lds, int tile) {
;     ...
;         for (int tk = 0; tk < 4; ++tk) { const size_t m = (size_t)tile * 64 + tb + tk;
;             { const u32x4 ra = *(const u32x4*)(A3 + m * 1024 + 16 * lane), rb = *(const u32x4*)(A3 + m * 1024 + 16 * lane + 8);
;               float xr_; { const f32x4 p0 = *(const f32x4*)(RSq + m * 16), p1 = *(const f32x4*)(RSq + m * 16 + 4), p2 = *(const f32x4*)(RSq + m * 16 + 8), p3 = *(const f32x4*)(RSq + m * 16 + 12);
;                 const f32x4 ps = (p0 + p1) + (p2 + p3); xr_ = rsqrtf(((ps[0] + ps[1]) + (ps[2] + ps[3])) * (1.f / 1024.f) + 1e-6f); }
;               const unsigned rr[8] = {ra.x, ra.y, ra.z, ra.w, rb.x, rb.y, rb.z, rb.w}; unsigned hh[8];
;               const float* sp = MOD + (int)(m >> 11) * 6144 + 3072 + 16 * lane;
; #pragma unroll
;               for (int q = 0; q < 8; ++q) { const f32x2 sh = *(const f32x2*)(sp + 2 * q); hh[q] = pk2(bflo(rr[q]) * xr_ + sh[0], bfhi(rr[q]) * xr_ + sh[1]); }
;               xpa[tk] = (u32x4){hh[0], hh[1], hh[2], hh[3]}; xpb[tk] = (u32x4){hh[4], hh[5], hh[6], hh[7]}; }
;     ...
;                 { const unsigned xx[8] = {xpa[tk].x, xpa[tk].y, xpa[tk].z, xpa[tk].w, xpb[tk].x, xpb[tk].y, xpb[tk].z, xpb[tk].w};
; #pragma unroll
;                   for (int q = 0; q < 8; ++q) xf[q] = (f32x2){bflo(xx[q]), bfhi(xx[q])}; }
	v_fma_f32 v208, v208, v216, v202
	v_fma_f32 v209, v209, v216, v203
	v_cvt_pk_bf16_f32 v210, v208, v209
	v_lshlrev_b32_e32 v42, 16, v210
	v_and_b32_e32 v43, 0xffff0000, v210
	v_lshlrev_b32_e32 v208, 16, v182
	v_and_b32_e32 v209, 0xffff0000, v182
	v_fma_f32 v208, v208, v216, v204
	v_fma_f32 v209, v209, v216, v205
	v_cvt_pk_bf16_f32 v210, v208, v209
	v_lshlrev_b32_e32 v44, 16, v210
	v_and_b32_e32 v45, 0xffff0000, v210
	v_lshlrev_b32_e32 v208, 16, v183
	v_and_b32_e32 v209, 0xffff0000, v183
	v_fma_f32 v208, v208, v216, v206
	v_fma_f32 v209, v209, v216, v207
	v_cvt_pk_bf16_f32 v210, v208, v209
	v_lshlrev_b32_e32 v46, 16, v210
	v_and_b32_e32 v47, 0xffff0000, v210
	v_lshlrev_b32_e32 v208, 16, v184
	v_and_b32_e32 v209, 0xffff0000, v184
	v_fma_f32 v208, v208, v232, v192
	v_fma_f32 v209, v209, v232, v193
	v_cvt_pk_bf16_f32 v210, v208, v209
	v_lshlrev_b32_e32 v48, 16, v210
	v_and_b32_e32 v49, 0xffff0000, v210
	v_lshlrev_b32_e32 v208, 16, v185
	v_and_b32_e32 v209, 0xffff0000, v185
	v_fma_f32 v208, v208, v232, v194
	v_fma_f32 v209, v209, v232, v195
	v_cvt_pk_bf16_f32 v210, v208, v209
	v_lshlrev_b32_e32 v50, 16, v210
	v_and_b32_e32 v51, 0xffff0000, v210
	v_lshlrev_b32_e32 v208, 16, v186
	v_and_b32_e32 v209, 0xffff0000, v186
	v_fma_f32 v208, v208, v232, v196
	v_fma_f32 v209, v209, v232, v197
	v_cvt_pk_bf16_f32 v210, v208, v209
	v_lshlrev_b32_e32 v52, 16, v210
	v_and_b32_e32 v53, 0xffff0000, v210
	v_lshlrev_b32_e32 v208, 16, v187
	v_and_b32_e32 v209, 0xffff0000, v187
	v_fma_f32 v208, v208, v232, v198
	v_fma_f32 v209, v209, v232, v199
	v_cvt_pk_bf16_f32 v210, v208, v209
	v_lshlrev_b32_e32 v54, 16, v210
	v_and_b32_e32 v55, 0xffff0000, v210
	v_lshlrev_b32_e32 v208, 16, v188
	v_and_b32_e32 v209, 0xffff0000, v188
	v_fma_f32 v208, v208, v232, v200
	v_fma_f32 v209, v209, v232, v201
	v_cvt_pk_bf16_f32 v210, v208, v209
	v_lshlrev_b32_e32 v56, 16, v210
	v_and_b32_e32 v57, 0xffff0000, v210
	v_lshlrev_b32_e32 v208, 16, v189
	v_and_b32_e32 v209, 0xffff0000, v189
	v_fma_f32 v208, v208, v232, v202
	v_fma_f32 v209, v209, v232, v203
	v_cvt_pk_bf16_f32 v210, v208, v209
	v_lshlrev_b32_e32 v58, 16, v210
	v_and_b32_e32 v59, 0xffff0000, v210
	v_lshlrev_b32_e32 v208, 16, v190
	v_and_b32_e32 v209, 0xffff0000, v190
	v_fma_f32 v208, v208, v232, v204
	v_fma_f32 v209, v209, v232, v205
	v_cvt_pk_bf16_f32 v210, v208, v209
	v_lshlrev_b32_e32 v60, 16, v210
	v_and_b32_e32 v61, 0xffff0000, v210
	v_lshlrev_b32_e32 v208, 16, v191
	v_and_b32_e32 v209, 0xffff0000, v191
	v_fma_f32 v208, v208, v232, v206
	v_fma_f32 v209, v209, v232, v207
	v_cvt_pk_bf16_f32 v210, v208, v209
	v_lshlrev_b32_e32 v62, 16, v210
	v_and_b32_e32 v63, 0xffff0000, v210
	s_nop 0
	s_add_i32 s0, s77, 6
	s_lshl_b32 s1, s0, 11
	s_add_u32 s78, s12, s1
	s_addc_u32 s79, s13, 0
	global_load_dwordx4 v[176:179], v245, s[78:79]
	global_load_dwordx4 v[180:183], v245, s[78:79] offset:16
	global_load_dwordx4 v[184:187], v245, s[78:79] offset:2048
	global_load_dwordx4 v[188:191], v245, s[78:79] offset:2064
	s_lshl_b32 s1, s0, 6
	s_add_u32 s78, s14, s1
	s_addc_u32 s79, s15, 0
	global_load_dwordx4 v[216:219], v244, s[78:79] offset:0
	global_load_dwordx4 v[220:223], v244, s[78:79] offset:16
	global_load_dwordx4 v[224:227], v244, s[78:79] offset:32
	global_load_dwordx4 v[228:231], v244, s[78:79] offset:48
	global_load_dwordx4 v[232:235], v244, s[78:79] offset:64
	global_load_dwordx4 v[236:239], v244, s[78:79] offset:80
	global_load_dwordx4 v[248:251], v244, s[78:79] offset:96
	global_load_dwordx4 v[252:255], v244, s[78:79] offset:112
	s_waitcnt vmcnt(12)
	v_pk_add_f32 v[144:145], v[144:145], v[148:149]
	v_pk_add_f32 v[146:147], v[146:147], v[150:151]
	v_pk_add_f32 v[152:153], v[152:153], v[156:157]
	v_pk_add_f32 v[154:155], v[154:155], v[158:159]
	v_pk_add_f32 v[144:145], v[144:145], v[152:153]
	v_pk_add_f32 v[146:147], v[146:147], v[154:155]
	v_add_f32_e32 v144, v144, v145
	v_add_f32_e32 v146, v146, v147
	v_add_f32_e32 v144, v144, v146
	v_fmamk_f32 v144, v144, 0x3a800000, v243
	v_rsq_f32_e32 v144, v144
	v_pk_add_f32 v[160:161], v[160:161], v[164:165]
	v_pk_add_f32 v[162:163], v[162:163], v[166:167]
	v_pk_add_f32 v[168:169], v[168:169], v[172:173]
	v_pk_add_f32 v[170:171], v[170:171], v[174:175]
	v_pk_add_f32 v[160:161], v[160:161], v[168:169]
	v_pk_add_f32 v[162:163], v[162:163], v[170:171]
	v_add_f32_e32 v160, v160, v161
	v_add_f32_e32 v162, v162, v163
	v_add_f32_e32 v160, v160, v162
	v_fmamk_f32 v160, v160, 0x3a800000, v243
	v_rsq_f32_e32 v160, v160
	v_lshlrev_b32_e32 v208, 16, v128
	v_and_b32_e32 v209, 0xffff0000, v128
	v_fma_f32 v208, v208, v144, v192
	v_fma_f32 v209, v209, v144, v193
	v_cvt_pk_bf16_f32 v210, v208, v209
	v_lshlrev_b32_e32 v64, 16, v210
	v_and_b32_e32 v65, 0xffff0000, v210
	v_lshlrev_b32_e32 v208, 16, v129
	v_and_b32_e32 v209, 0xffff0000, v129
	v_fma_f32 v208, v208, v144, v194
	v_fma_f32 v209, v209, v144, v195
	v_cvt_pk_bf16_f32 v210, v208, v209
	v_lshlrev_b32_e32 v66, 16, v210
	v_and_b32_e32 v67, 0xffff0000, v210
	v_lshlrev_b32_e32 v208, 16, v130
	v_and_b32_e32 v209, 0xffff0000, v130
	v_fma_f32 v208, v208, v144, v196
	v_fma_f32 v209, v209, v144, v197
	v_cvt_pk_bf16_f32 v210, v208, v209
	v_lshlrev_b32_e32 v68, 16, v210
	v_and_b32_e32 v69, 0xffff0000, v210
	v_lshlrev_b32_e32 v208, 16, v131
	v_and_b32_e32 v209, 0xffff0000, v131
	v_fma_f32 v208, v208, v144, v198
	v_fma_f32 v209, v209, v144, v199
	v_cvt_pk_bf16_f32 v210, v208, v209
	v_lshlrev_b32_e32 v70, 16, v210
	v_and_b32_e32 v71, 0xffff0000, v210
	v_lshlrev_b32_e32 v208, 16, v132
	v_and_b32_e32 v209, 0xffff0000, v132
	v_fma_f32 v208, v208, v144, v200
	v_fma_f32 v209, v209, v144, v201
	v_cvt_pk_bf16_f32 v210, v208, v209
	v_lshlrev_b32_e32 v72, 16, v210
; __device__ __forceinline__ unsigned pk2(float lo, float hi) { const f32x2 v = {lo, hi}; const bf16x2_t b = __builtin_convertvector(v, bf16x2_t); return __builtin_bit_cast(unsigned, b); }
; __device__ __forceinline__ float bflo(unsigned u) { return __uint_as_float(u << 16); }
; __device__ __forceinline__ float bfhi(unsigned u) { return __uint_as_float(u & 0xffff0000u); }
; __device__ __forceinline__ void peer_tile(const Args& A, LAS unsigned char* lds, int tile) {
;     ...
;         for (int tk = 0; tk < 4; ++tk) { const size_t m = (size_t)tile * 64 + tb + tk;
;             { const u32x4 ra = *(const u32x4*)(A3 + m * 1024 + 16 * lane), rb = *(const u32x4*)(A3 + m * 1024 + 16 * lane + 8);
;               float xr_; { const f32x4 p0 = *(const f32x4*)(RSq + m * 16), p1 = *(const f32x4*)(RSq + m * 16 + 4), p2 = *(const f32x4*)(RSq + m * 16 + 8), p3 = *(const f32x4*)(RSq + m * 16 + 12);
;                 const f32x4 ps = (p0 + p1) + (p2 + p3); xr_ = rsqrtf(((ps[0] + ps[1]) + (ps[2] + ps[3])) * (1.f / 1024.f) + 1e-6f); }
;               const unsigned rr[8] = {ra.x, ra.y, ra.z, ra.w, rb.x, rb.y, rb.z, rb.w}; unsigned hh[8];
;               const float* sp = MOD + (int)(m >> 11) * 6144 + 3072 + 16 * lane;
; #pragma unroll
;               for (int q = 0; q < 8; ++q) { const f32x2 sh = *(const f32x2*)(sp + 2 * q); hh[q] = pk2(bflo(rr[q]) * xr_ + sh[0], bfhi(rr[q]) * xr_ + sh[1]); }
;               xpa[tk] = (u32x4){hh[0], hh[1], hh[2], hh[3]}; xpb[tk] = (u32x4){hh[4], hh[5], hh[6], hh[7]}; }
;     ...
;                 { const unsigned xx[8] = {xpa[tk].x, xpa[tk].y, xpa[tk].z, xpa[tk].w, xpb[tk].x, xpb[tk].y, xpb[tk].z, xpb[tk].w};
; #pragma unroll
;                   for (int q = 0; q < 8; ++q) xf[q] = (f32x2){bflo(xx[q]), bfhi(xx[q])}; }
	v_and_b32_e32 v73, 0xffff0000, v210
	v_lshlrev_b32_e32 v208, 16, v133
	v_and_b32_e32 v209, 0xffff0000, v133
	v_fma_f32 v208, v208, v144, v202
	v_fma_f32 v209, v209, v144, v203
	v_cvt_pk_bf16_f32 v210, v208, v209
	v_lshlrev_b32_e32 v74, 16, v210
	v_and_b32_e32 v75, 0xffff0000, v210
	v_lshlrev_b32_e32 v208, 16, v134
	v_and_b32_e32 v209, 0xffff0000, v134
	v_fma_f32 v208, v208, v144, v204
	v_fma_f32 v209, v209, v144, v205
	v_cvt_pk_bf16_f32 v210, v208, v209
	v_lshlrev_b32_e32 v76, 16, v210
	v_and_b32_e32 v77, 0xffff0000, v210
	v_lshlrev_b32_e32 v208, 16, v135
	v_and_b32_e32 v209, 0xffff0000, v135
	v_fma_f32 v208, v208, v144, v206
	v_fma_f32 v209, v209, v144, v207
	v_cvt_pk_bf16_f32 v210, v208, v209
	v_lshlrev_b32_e32 v78, 16, v210
	v_and_b32_e32 v79, 0xffff0000, v210
	v_lshlrev_b32_e32 v208, 16, v136
	v_and_b32_e32 v209, 0xffff0000, v136
	v_fma_f32 v208, v208, v160, v192
	v_fma_f32 v209, v209, v160, v193
	v_cvt_pk_bf16_f32 v210, v208, v209
	v_lshlrev_b32_e32 v80, 16, v210
	v_and_b32_e32 v81, 0xffff0000, v210
	v_lshlrev_b32_e32 v208, 16, v137
	v_and_b32_e32 v209, 0xffff0000, v137
	v_fma_f32 v208, v208, v160, v194
	v_fma_f32 v209, v209, v160, v195
	v_cvt_pk_bf16_f32 v210, v208, v209
	v_lshlrev_b32_e32 v82, 16, v210
	v_and_b32_e32 v83, 0xffff0000, v210
	v_lshlrev_b32_e32 v208, 16, v138
	v_and_b32_e32 v209, 0xffff0000, v138
	v_fma_f32 v208, v208, v160, v196
	v_fma_f32 v209, v209, v160, v197
	v_cvt_pk_bf16_f32 v210, v208, v209
	v_lshlrev_b32_e32 v84, 16, v210
	v_and_b32_e32 v85, 0xffff0000, v210
	v_lshlrev_b32_e32 v208, 16, v139
	v_and_b32_e32 v209, 0xffff0000, v139
	v_fma_f32 v208, v208, v160, v198
	v_fma_f32 v209, v209, v160, v199
	v_cvt_pk_bf16_f32 v210, v208, v209
	v_lshlrev_b32_e32 v86, 16, v210
	v_and_b32_e32 v87, 0xffff0000, v210
	v_lshlrev_b32_e32 v208, 16, v140
	v_and_b32_e32 v209, 0xffff0000, v140
	v_fma_f32 v208, v208, v160, v200
	v_fma_f32 v209, v209, v160, v201
	v_cvt_pk_bf16_f32 v210, v208, v209
	v_lshlrev_b32_e32 v88, 16, v210
	v_and_b32_e32 v89, 0xffff0000, v210
	v_lshlrev_b32_e32 v208, 16, v141
	v_and_b32_e32 v209, 0xffff0000, v141
	v_fma_f32 v208, v208, v160, v202
	v_fma_f32 v209, v209, v160, v203
	v_cvt_pk_bf16_f32 v210, v208, v209
	v_lshlrev_b32_e32 v90, 16, v210
	v_and_b32_e32 v91, 0xffff0000, v210
	v_lshlrev_b32_e32 v208, 16, v142
	v_and_b32_e32 v209, 0xffff0000, v142
	v_fma_f32 v208, v208, v160, v204
	v_fma_f32 v209, v209, v160, v205
	v_cvt_pk_bf16_f32 v210, v208, v209
	v_lshlrev_b32_e32 v92, 16, v210
	v_and_b32_e32 v93, 0xffff0000, v210
	v_lshlrev_b32_e32 v208, 16, v143
	v_and_b32_e32 v209, 0xffff0000, v143
	v_fma_f32 v208, v208, v160, v206
	v_fma_f32 v209, v209, v160, v207
	v_cvt_pk_bf16_f32 v210, v208, v209
	v_lshlrev_b32_e32 v94, 16, v210
	v_and_b32_e32 v95, 0xffff0000, v210
	s_nop 0
	s_waitcnt vmcnt(0)
	v_pk_add_f32 v[216:217], v[216:217], v[220:221]
	v_pk_add_f32 v[218:219], v[218:219], v[222:223]
	v_pk_add_f32 v[224:225], v[224:225], v[228:229]
	v_pk_add_f32 v[226:227], v[226:227], v[230:231]
	v_pk_add_f32 v[216:217], v[216:217], v[224:225]
	v_pk_add_f32 v[218:219], v[218:219], v[226:227]
	v_add_f32_e32 v216, v216, v217
	v_add_f32_e32 v218, v218, v219
	v_add_f32_e32 v216, v216, v218
	v_fmamk_f32 v216, v216, 0x3a800000, v243
	v_rsq_f32_e32 v216, v216
	v_pk_add_f32 v[232:233], v[232:233], v[236:237]
	v_pk_add_f32 v[234:235], v[234:235], v[238:239]
	v_pk_add_f32 v[248:249], v[248:249], v[252:253]
	v_pk_add_f32 v[250:251], v[250:251], v[254:255]
	v_pk_add_f32 v[232:233], v[232:233], v[248:249]
	v_pk_add_f32 v[234:235], v[234:235], v[250:251]
	v_add_f32_e32 v232, v232, v233
	v_add_f32_e32 v234, v234, v235
	v_add_f32_e32 v232, v232, v234
	v_fmamk_f32 v232, v232, 0x3a800000, v243
	v_rsq_f32_e32 v232, v232
	v_lshlrev_b32_e32 v208, 16, v176
	v_and_b32_e32 v209, 0xffff0000, v176
	v_fma_f32 v208, v208, v216, v192
	v_fma_f32 v209, v209, v216, v193
	v_cvt_pk_bf16_f32 v210, v208, v209
	v_lshlrev_b32_e32 v96, 16, v210
	v_and_b32_e32 v97, 0xffff0000, v210
	v_lshlrev_b32_e32 v208, 16, v177
	v_and_b32_e32 v209, 0xffff0000, v177
	v_fma_f32 v208, v208, v216, v194
	v_fma_f32 v209, v209, v216, v195
	v_cvt_pk_bf16_f32 v210, v208, v209
	v_lshlrev_b32_e32 v98, 16, v210
	v_and_b32_e32 v99, 0xffff0000, v210
	v_lshlrev_b32_e32 v208, 16, v178
	v_and_b32_e32 v209, 0xffff0000, v178
	v_fma_f32 v208, v208, v216, v196
	v_fma_f32 v209, v209, v216, v197
	v_cvt_pk_bf16_f32 v210, v208, v209
	v_lshlrev_b32_e32 v100, 16, v210
	v_and_b32_e32 v101, 0xffff0000, v210
	v_lshlrev_b32_e32 v208, 16, v179
	v_and_b32_e32 v209, 0xffff0000, v179
	v_fma_f32 v208, v208, v216, v198
	v_fma_f32 v209, v209, v216, v199
	v_cvt_pk_bf16_f32 v210, v208, v209
	v_lshlrev_b32_e32 v102, 16, v210
	v_and_b32_e32 v103, 0xffff0000, v210
	v_lshlrev_b32_e32 v208, 16, v180
	v_and_b32_e32 v209, 0xffff0000, v180
	v_fma_f32 v208, v208, v216, v200
	v_fma_f32 v209, v209, v216, v201
	v_cvt_pk_bf16_f32 v210, v208, v209
	v_lshlrev_b32_e32 v104, 16, v210
	v_and_b32_e32 v105, 0xffff0000, v210
	v_lshlrev_b32_e32 v208, 16, v181
	v_and_b32_e32 v209, 0xffff0000, v181
	v_fma_f32 v208, v208, v216, v202
	v_fma_f32 v209, v209, v216, v203
	v_cvt_pk_bf16_f32 v210, v208, v209
	v_lshlrev_b32_e32 v106, 16, v210
	v_and_b32_e32 v107, 0xffff0000, v210
	v_lshlrev_b32_e32 v208, 16, v182
	v_and_b32_e32 v209, 0xffff0000, v182
	v_fma_f32 v208, v208, v216, v204
	v_fma_f32 v209, v209, v216, v205
	v_cvt_pk_bf16_f32 v210, v208, v209
	v_lshlrev_b32_e32 v108, 16, v210
	v_and_b32_e32 v109, 0xffff0000, v210
	v_lshlrev_b32_e32 v208, 16, v183
	v_and_b32_e32 v209, 0xffff0000, v183
	v_fma_f32 v208, v208, v216, v206
	v_fma_f32 v209, v209, v216, v207
	v_cvt_pk_bf16_f32 v210, v208, v209
	v_lshlrev_b32_e32 v110, 16, v210
; __device__ __forceinline__ unsigned pk2(float lo, float hi) { const f32x2 v = {lo, hi}; const bf16x2_t b = __builtin_convertvector(v, bf16x2_t); return __builtin_bit_cast(unsigned, b); }
; __device__ __forceinline__ float bflo(unsigned u) { return __uint_as_float(u << 16); }
; __device__ __forceinline__ void peer_tile(const Args& A, LAS unsigned char* lds, int tile) {
;     ...
;     for (int ti = 0; ti < 8; ++ti) {
;         const int tl = 8 * w + ti;
;         const u32x2 e0 = SEL[tl * 128 + lane], e1 = SEL[tl * 128 + 64 + lane];
;         const int p0 = (int)(e0.x >> 10), p1 = (int)(e1.x >> 10);
;         int off = 0;
;         for (int p = 0; p < 16; ++p) {
;             const unsigned long long m0 = __ballot(p0 == p), m1 = __ballot(p1 == p);
;             const int c0 = __popcll(m0), c1 = __popcll(m1);
;             const int r0 = __builtin_amdgcn_mbcnt_hi((unsigned)(m0 >> 32), __builtin_amdgcn_mbcnt_lo((unsigned)m0, 0u));
;             const int r1 = __builtin_amdgcn_mbcnt_hi((unsigned)(m1 >> 32), __builtin_amdgcn_mbcnt_lo((unsigned)m1, 0u));
;             if (p0 == p) SORT[tl * 128 + off + r0] = e0;
;             if (p1 == p) SORT[tl * 128 + off + c0 + r1] = e1;
;             if (lane == 0) OFFS[tl * 17 + p] = off;
;             off += c0 + c1;
;         }
;         if (lane == 0) OFFS[tl * 17 + 16] = off;
;     }
;     ...
;         for (int tk = 0; tk < 4; ++tk) { const size_t m = (size_t)tile * 64 + tb + tk;
;             { const u32x4 ra = *(const u32x4*)(A3 + m * 1024 + 16 * lane), rb = *(const u32x4*)(A3 + m * 1024 + 16 * lane + 8);
;               float xr_; { const f32x4 p0 = *(const f32x4*)(RSq + m * 16), p1 = *(const f32x4*)(RSq + m * 16 + 4), p2 = *(const f32x4*)(RSq + m * 16 + 8), p3 = *(const f32x4*)(RSq + m * 16 + 12);
;                 const f32x4 ps = (p0 + p1) + (p2 + p3); xr_ = rsqrtf(((ps[0] + ps[1]) + (ps[2] + ps[3])) * (1.f / 1024.f) + 1e-6f); }
;               const unsigned rr[8] = {ra.x, ra.y, ra.z, ra.w, rb.x, rb.y, rb.z, rb.w}; unsigned hh[8];
;               const float* sp = MOD + (int)(m >> 11) * 6144 + 3072 + 16 * lane;
; #pragma unroll
;               for (int q = 0; q < 8; ++q) { const f32x2 sh = *(const f32x2*)(sp + 2 * q); hh[q] = pk2(bflo(rr[q]) * xr_ + sh[0], bfhi(rr[q]) * xr_ + sh[1]); }
;               xpa[tk] = (u32x4){hh[0], hh[1], hh[2], hh[3]}; xpb[tk] = (u32x4){hh[4], hh[5], hh[6], hh[7]}; }
	v_and_b32_e32 v111, 0xffff0000, v210
	v_lshlrev_b32_e32 v208, 16, v184
	v_and_b32_e32 v209, 0xffff0000, v184
	v_fma_f32 v208, v208, v232, v192
	v_fma_f32 v209, v209, v232, v193
	v_cvt_pk_bf16_f32 v210, v208, v209
	v_lshlrev_b32_e32 v112, 16, v210
	v_and_b32_e32 v113, 0xffff0000, v210
	v_lshlrev_b32_e32 v208, 16, v185
	v_and_b32_e32 v209, 0xffff0000, v185
	v_fma_f32 v208, v208, v232, v194
	v_fma_f32 v209, v209, v232, v195
	v_cvt_pk_bf16_f32 v210, v208, v209
	v_lshlrev_b32_e32 v114, 16, v210
	v_and_b32_e32 v115, 0xffff0000, v210
	v_lshlrev_b32_e32 v208, 16, v186
	v_and_b32_e32 v209, 0xffff0000, v186
	v_fma_f32 v208, v208, v232, v196
	v_fma_f32 v209, v209, v232, v197
	v_cvt_pk_bf16_f32 v210, v208, v209
	v_lshlrev_b32_e32 v116, 16, v210
	v_and_b32_e32 v117, 0xffff0000, v210
	v_lshlrev_b32_e32 v208, 16, v187
	v_and_b32_e32 v209, 0xffff0000, v187
	v_fma_f32 v208, v208, v232, v198
	v_fma_f32 v209, v209, v232, v199
	v_cvt_pk_bf16_f32 v210, v208, v209
	v_lshlrev_b32_e32 v118, 16, v210
	v_and_b32_e32 v119, 0xffff0000, v210
	v_lshlrev_b32_e32 v208, 16, v188
	v_and_b32_e32 v209, 0xffff0000, v188
	v_fma_f32 v208, v208, v232, v200
	v_fma_f32 v209, v209, v232, v201
	v_cvt_pk_bf16_f32 v210, v208, v209
	v_lshlrev_b32_e32 v120, 16, v210
	v_and_b32_e32 v121, 0xffff0000, v210
	v_lshlrev_b32_e32 v208, 16, v189
	v_and_b32_e32 v209, 0xffff0000, v189
	v_fma_f32 v208, v208, v232, v202
	v_fma_f32 v209, v209, v232, v203
	v_cvt_pk_bf16_f32 v210, v208, v209
	v_lshlrev_b32_e32 v122, 16, v210
	v_and_b32_e32 v123, 0xffff0000, v210
	v_lshlrev_b32_e32 v208, 16, v190
	v_and_b32_e32 v209, 0xffff0000, v190
	v_fma_f32 v208, v208, v232, v204
	v_fma_f32 v209, v209, v232, v205
	v_cvt_pk_bf16_f32 v210, v208, v209
	v_lshlrev_b32_e32 v124, 16, v210
	v_and_b32_e32 v125, 0xffff0000, v210
	v_lshlrev_b32_e32 v208, 16, v191
	v_and_b32_e32 v209, 0xffff0000, v191
	v_fma_f32 v208, v208, v232, v206
	v_fma_f32 v209, v209, v232, v207
	v_cvt_pk_bf16_f32 v210, v208, v209
	v_lshlrev_b32_e32 v126, 16, v210
	v_and_b32_e32 v127, 0xffff0000, v210
	s_nop 0
	s_mov_b32 s24, s8
	s_and_b32 s25, s9, 0xffff
	s_mov_b32 s26, 0x20000
	s_mov_b32 s27, 0x00027000
	s_lshl_b32 s0, s76, 10
	s_add_i32 s0, s0, 0x11000
	s_sub_i32 s85, s0, s22
	v_mov_b32_e32 v224, 0x7fffffff
	v_mov_b32_e32 v225, 0x7fffffff
	v_mov_b32_e32 v226, 0x7fffffff
	v_mov_b32_e32 v227, 0x7fffffff
	v_mov_b32_e32 v228, 0
	v_mov_b32_e32 v229, 0
	v_mov_b32_e32 v230, 0
	v_mov_b32_e32 v231, 0
	v_add_u32_e32 v232, s22, v240
	ds_write_b128 v232, v[224:227] offset:0
	ds_write_b128 v232, v[228:231] offset:4992
	ds_write_b128 v232, v[224:227] offset:1024
	ds_write_b128 v232, v[228:231] offset:6016
	ds_write_b128 v232, v[224:227] offset:2048
	ds_write_b128 v232, v[228:231] offset:7040
	ds_write_b128 v232, v[224:227] offset:3072
	ds_write_b128 v232, v[228:231] offset:8064
	s_mov_b32 exec_hi, 0x00ffffff
	ds_write_b128 v232, v[224:227] offset:4096
	s_mov_b32 exec_hi, 0x000fffff
	ds_write_b128 v232, v[228:231] offset:9088
	s_mov_b64 exec, -1
	v_lshrrev_b32_e32 v221, 2, v240
	v_add_u32_e32 v221, s22, v221
	ds_write_b32 v221, v228 offset:4224
	v_lshrrev_b32_e32 v233, 1, v240
	s_lshl_b32 s0, s76, 10
	s_add_i32 s0, s0, 0x11000
	v_add_u32_e32 v233, s0, v233
	ds_read_b64 v[128:129], v233 offset:0
	ds_read_b64 v[130:131], v233 offset:512
	ds_read_b64 v[132:133], v233 offset:1024
	ds_read_b64 v[134:135], v233 offset:1536
	ds_read_b64 v[136:137], v233 offset:2048
	ds_read_b64 v[138:139], v233 offset:2560
	ds_read_b64 v[140:141], v233 offset:3072
	ds_read_b64 v[142:143], v233 offset:3584
	ds_read_b64 v[144:145], v233 offset:4096
	ds_read_b64 v[146:147], v233 offset:4608
	ds_read_b64 v[148:149], v233 offset:5120
	ds_read_b64 v[150:151], v233 offset:5632
	ds_read_b64 v[152:153], v233 offset:6144
	ds_read_b64 v[154:155], v233 offset:6656
	ds_read_b64 v[156:157], v233 offset:7168
	ds_read_b64 v[158:159], v233 offset:7680
	v_mov_b32_e32 v220, 1
	v_lshrrev_b32_e32 v200, 4, v240
	v_lshrrev_b32_e32 v201, 3, v200
	v_and_b32_e32 v200, 7, v200
	s_add_i32 s3, s22, 4224
	s_and_b32 s1, s32, 7
	s_waitcnt lgkmcnt(0)
	v_lshrrev_b32_e32 v160, 11, v128
	v_subrev_u32_e32 v160, s1, v160
	v_and_b32_e32 v160, 7, v160
	v_lshl_add_u32 v176, v160, 2, s3
	v_lshrrev_b32_e32 v161, 11, v130
	v_subrev_u32_e32 v161, s1, v161
	v_and_b32_e32 v161, 7, v161
	v_lshl_add_u32 v177, v161, 2, s3
	v_lshrrev_b32_e32 v162, 11, v132
	v_subrev_u32_e32 v162, s1, v162
	v_and_b32_e32 v162, 7, v162
	v_lshl_add_u32 v178, v162, 2, s3
	v_lshrrev_b32_e32 v163, 11, v134
	v_subrev_u32_e32 v163, s1, v163
	v_and_b32_e32 v163, 7, v163
	v_lshl_add_u32 v179, v163, 2, s3
	v_lshrrev_b32_e32 v164, 11, v136
	v_subrev_u32_e32 v164, s1, v164
	v_and_b32_e32 v164, 7, v164
	v_lshl_add_u32 v180, v164, 2, s3
	v_lshrrev_b32_e32 v165, 11, v138
	v_subrev_u32_e32 v165, s1, v165
	v_and_b32_e32 v165, 7, v165
	v_lshl_add_u32 v181, v165, 2, s3
	v_lshrrev_b32_e32 v166, 11, v140
	v_subrev_u32_e32 v166, s1, v166
	v_and_b32_e32 v166, 7, v166
	v_lshl_add_u32 v182, v166, 2, s3
	v_lshrrev_b32_e32 v167, 11, v142
	v_subrev_u32_e32 v167, s1, v167
	v_and_b32_e32 v167, 7, v167
	v_lshl_add_u32 v183, v167, 2, s3
	v_lshrrev_b32_e32 v168, 11, v144
	v_subrev_u32_e32 v168, s1, v168
	v_and_b32_e32 v168, 7, v168
	v_lshl_add_u32 v184, v168, 2, s3
	v_lshrrev_b32_e32 v169, 11, v146
	v_subrev_u32_e32 v169, s1, v169
	v_and_b32_e32 v169, 7, v169
	v_lshl_add_u32 v185, v169, 2, s3
	v_lshrrev_b32_e32 v170, 11, v148
	v_subrev_u32_e32 v170, s1, v170
	v_and_b32_e32 v170, 7, v170
	v_lshl_add_u32 v186, v170, 2, s3
	v_lshrrev_b32_e32 v171, 11, v150
	v_subrev_u32_e32 v171, s1, v171
	v_and_b32_e32 v171, 7, v171
	v_lshl_add_u32 v187, v171, 2, s3
	v_lshrrev_b32_e32 v172, 11, v152
; __device__ __forceinline__ void peer_tile(const Args& A, LAS unsigned char* lds, int tile) {
;     ...
;     for (int ti = 0; ti < 8; ++ti) {
;         const int tl = 8 * w + ti;
;         const u32x2 e0 = SEL[tl * 128 + lane], e1 = SEL[tl * 128 + 64 + lane];
;         const int p0 = (int)(e0.x >> 10), p1 = (int)(e1.x >> 10);
;         int off = 0;
;         for (int p = 0; p < 16; ++p) {
;             const unsigned long long m0 = __ballot(p0 == p), m1 = __ballot(p1 == p);
;             const int c0 = __popcll(m0), c1 = __popcll(m1);
;             const int r0 = __builtin_amdgcn_mbcnt_hi((unsigned)(m0 >> 32), __builtin_amdgcn_mbcnt_lo((unsigned)m0, 0u));
;             const int r1 = __builtin_amdgcn_mbcnt_hi((unsigned)(m1 >> 32), __builtin_amdgcn_mbcnt_lo((unsigned)m1, 0u));
;             if (p0 == p) SORT[tl * 128 + off + r0] = e0;
;             if (p1 == p) SORT[tl * 128 + off + c0 + r1] = e1;
;             if (lane == 0) OFFS[tl * 17 + p] = off;
;             off += c0 + c1;
;         }
;         if (lane == 0) OFFS[tl * 17 + 16] = off;
;     }
	v_subrev_u32_e32 v172, s1, v172
	v_and_b32_e32 v172, 7, v172
	v_lshl_add_u32 v188, v172, 2, s3
	v_lshrrev_b32_e32 v173, 11, v154
	v_subrev_u32_e32 v173, s1, v173
	v_and_b32_e32 v173, 7, v173
	v_lshl_add_u32 v189, v173, 2, s3
	v_lshrrev_b32_e32 v174, 11, v156
	v_subrev_u32_e32 v174, s1, v174
	v_and_b32_e32 v174, 7, v174
	v_lshl_add_u32 v190, v174, 2, s3
	v_lshrrev_b32_e32 v175, 11, v158
	v_subrev_u32_e32 v175, s1, v175
	v_and_b32_e32 v175, 7, v175
	v_lshl_add_u32 v191, v175, 2, s3
	v_lshlrev_b32_e32 v206, 3, v128
	buffer_load_dwordx2 v[224:225], v206, s[24:27], 0 offen
	v_lshlrev_b32_e32 v206, 3, v130
	buffer_load_dwordx2 v[226:227], v206, s[24:27], 0 offen
	v_lshlrev_b32_e32 v206, 3, v132
	buffer_load_dwordx2 v[228:229], v206, s[24:27], 0 offen
	v_lshlrev_b32_e32 v206, 3, v134
	buffer_load_dwordx2 v[230:231], v206, s[24:27], 0 offen
	v_lshlrev_b32_e32 v206, 3, v136
	buffer_load_dwordx2 v[232:233], v206, s[24:27], 0 offen
	v_lshlrev_b32_e32 v206, 3, v138
	buffer_load_dwordx2 v[234:235], v206, s[24:27], 0 offen
	v_lshlrev_b32_e32 v206, 3, v140
	buffer_load_dwordx2 v[236:237], v206, s[24:27], 0 offen
	v_lshlrev_b32_e32 v206, 3, v142
	buffer_load_dwordx2 v[238:239], v206, s[24:27], 0 offen
	v_lshlrev_b32_e32 v206, 3, v144
	buffer_load_dwordx2 v[248:249], v206, s[24:27], 0 offen
	v_lshlrev_b32_e32 v206, 3, v146
	buffer_load_dwordx2 v[250:251], v206, s[24:27], 0 offen
	v_lshlrev_b32_e32 v206, 3, v148
	buffer_load_dwordx2 v[252:253], v206, s[24:27], 0 offen
	v_lshlrev_b32_e32 v206, 3, v150
	buffer_load_dwordx2 v[254:255], v206, s[24:27], 0 offen
	ds_add_rtn_u32 v176, v176, v220 offset:0
	ds_add_rtn_u32 v177, v177, v220 offset:0
	ds_add_rtn_u32 v178, v178, v220 offset:32
	ds_add_rtn_u32 v179, v179, v220 offset:32
	ds_add_rtn_u32 v180, v180, v220 offset:64
	ds_add_rtn_u32 v181, v181, v220 offset:64
	ds_add_rtn_u32 v182, v182, v220 offset:96
	ds_add_rtn_u32 v183, v183, v220 offset:96
	ds_add_rtn_u32 v184, v184, v220 offset:128
	ds_add_rtn_u32 v185, v185, v220 offset:128
	ds_add_rtn_u32 v186, v186, v220 offset:160
	ds_add_rtn_u32 v187, v187, v220 offset:160
	ds_add_rtn_u32 v188, v188, v220 offset:192
	ds_add_rtn_u32 v189, v189, v220 offset:192
	ds_add_rtn_u32 v190, v190, v220 offset:224
	ds_add_rtn_u32 v191, v191, v220 offset:224
	v_lshl_add_u32 v207, v201, 5, s3
	ds_read_b32 v203, v221 offset:4224
	ds_read_b128 v[192:195], v207
	ds_read_b128 v[196:199], v207 offset:16
	v_mov_b32_e32 v202, 0
	s_waitcnt lgkmcnt(0)
	v_cmp_lt_u32_e64 s[38:39], 0, v200
	v_cmp_lt_u32_e64 s[40:41], 1, v200
	v_cmp_lt_u32_e64 s[42:43], 2, v200
	v_cmp_lt_u32_e64 s[44:45], 3, v200
	v_cmp_lt_u32_e64 s[64:65], 4, v200
	v_cmp_lt_u32_e64 s[66:67], 5, v200
	v_cmp_lt_u32_e64 s[94:95], 6, v200
	v_cndmask_b32_e64 v206, 0, v192, s[38:39]
	v_add_u32_e32 v202, v202, v206
	v_cndmask_b32_e64 v206, 0, v193, s[40:41]
	v_add_u32_e32 v202, v202, v206
	v_cndmask_b32_e64 v206, 0, v194, s[42:43]
	v_add_u32_e32 v202, v202, v206
	v_cndmask_b32_e64 v206, 0, v195, s[44:45]
	v_add_u32_e32 v202, v202, v206
	v_cndmask_b32_e64 v206, 0, v196, s[64:65]
	v_add_u32_e32 v202, v202, v206
	v_cndmask_b32_e64 v206, 0, v197, s[66:67]
	v_add_u32_e32 v202, v202, v206
	v_cndmask_b32_e64 v206, 0, v198, s[94:95]
	v_add_u32_e32 v202, v202, v206
	v_add_u32_e32 v204, 3, v202
	v_add3_u32 v212, v202, v203, 3
	v_lshrrev_b32_e32 v204, 2, v204
	v_lshrrev_b32_e32 v212, 2, v212
	v_sub_u32_e32 v212, v212, v204
	v_lshl_add_u32 v207, v200, 3, v201
	v_lshl_add_u32 v207, v207, 2, s3
	ds_write_b32 v207, v212 offset:256
	v_lshl_add_u32 v208, v200, 5, s3
	ds_read_b128 v[192:195], v208 offset:256
	ds_read_b128 v[196:199], v208 offset:272
	v_mov_b32_e32 v205, 0
	s_waitcnt lgkmcnt(0)
	v_cmp_lt_u32_e64 s[38:39], 0, v201
	v_cmp_lt_u32_e64 s[40:41], 1, v201
	v_cmp_lt_u32_e64 s[42:43], 2, v201
	v_cmp_lt_u32_e64 s[44:45], 3, v201
	v_cmp_lt_u32_e64 s[64:65], 4, v201
	v_cmp_lt_u32_e64 s[66:67], 5, v201
	v_cmp_lt_u32_e64 s[94:95], 6, v201
	v_cndmask_b32_e64 v206, 0, v192, s[38:39]
	v_add_u32_e32 v205, v205, v206
	v_cndmask_b32_e64 v206, 0, v193, s[40:41]
	v_add_u32_e32 v205, v205, v206
	v_cndmask_b32_e64 v206, 0, v194, s[42:43]
	v_add_u32_e32 v205, v205, v206
	v_cndmask_b32_e64 v206, 0, v195, s[44:45]
	v_add_u32_e32 v205, v205, v206
	v_cndmask_b32_e64 v206, 0, v196, s[64:65]
	v_add_u32_e32 v205, v205, v206
	v_cndmask_b32_e64 v206, 0, v197, s[66:67]
	v_add_u32_e32 v205, v205, v206
	v_cndmask_b32_e64 v206, 0, v198, s[94:95]
	v_add_u32_e32 v205, v205, v206
	v_add_u32_e32 v206, v192, v193
	v_add_u32_e32 v206, v206, v194
	v_add_u32_e32 v206, v206, v195
	v_add_u32_e32 v206, v206, v196
	v_add_u32_e32 v206, v206, v197
	v_add_u32_e32 v206, v206, v198
	v_add_u32_e32 v206, v206, v199
	v_lshl_add_u32 v207, v200, 2, s3
	ds_write_b32 v207, v206 offset:512
	v_mov_b32_e32 v207, s3
	ds_read_b128 v[192:195], v207 offset:512
	ds_read_b128 v[196:199], v207 offset:528
	ds_write_b32 v221, v202 offset:4224
	s_waitcnt lgkmcnt(0)
	v_cmp_lt_u32_e64 s[38:39], 0, v200
	v_cmp_lt_u32_e64 s[40:41], 1, v200
	v_cmp_lt_u32_e64 s[42:43], 2, v200
	v_cmp_lt_u32_e64 s[44:45], 3, v200
	v_cmp_lt_u32_e64 s[64:65], 4, v200
	v_cmp_lt_u32_e64 s[66:67], 5, v200
	v_cmp_lt_u32_e64 s[94:95], 6, v200
	v_cndmask_b32_e64 v206, 0, v192, s[38:39]
	v_add_u32_e32 v205, v205, v206
	v_cndmask_b32_e64 v206, 0, v193, s[40:41]
	v_add_u32_e32 v205, v205, v206
	v_cndmask_b32_e64 v206, 0, v194, s[42:43]
	v_add_u32_e32 v205, v205, v206
	v_cndmask_b32_e64 v206, 0, v195, s[44:45]
	v_add_u32_e32 v205, v205, v206
	v_cndmask_b32_e64 v206, 0, v196, s[64:65]
	v_add_u32_e32 v205, v205, v206
	v_cndmask_b32_e64 v206, 0, v197, s[66:67]
	v_add_u32_e32 v205, v205, v206
	v_cndmask_b32_e64 v206, 0, v198, s[94:95]
	v_add_u32_e32 v205, v205, v206
	v_sub_u32_e32 v205, v205, v204
	v_lshrrev_b32_e32 v208, 4, v240
	v_and_b32_e32 v222, 31, v208
	v_lshrrev_b32_e32 v208, 5, v208
	v_add_u32_e32 v207, 0, v208
	v_lshl_add_u32 v206, v207, 5, s3
	ds_read_b128 v[192:195], v206
	ds_read_b128 v[196:199], v206 offset:16
	v_lshlrev_b32_e32 v206, 2, v222
	v_lshlrev_b32_e32 v223, 3, v207
	s_waitcnt lgkmcnt(0)
; __device__ __forceinline__ void peer_tile(const Args& A, LAS unsigned char* lds, int tile) {
;     ...
;     for (int ti = 0; ti < 8; ++ti) {
;         const int tl = 8 * w + ti;
;         const u32x2 e0 = SEL[tl * 128 + lane], e1 = SEL[tl * 128 + 64 + lane];
;         const int p0 = (int)(e0.x >> 10), p1 = (int)(e1.x >> 10);
;         int off = 0;
;         for (int p = 0; p < 16; ++p) {
;             const unsigned long long m0 = __ballot(p0 == p), m1 = __ballot(p1 == p);
;             const int c0 = __popcll(m0), c1 = __popcll(m1);
;             const int r0 = __builtin_amdgcn_mbcnt_hi((unsigned)(m0 >> 32), __builtin_amdgcn_mbcnt_lo((unsigned)m0, 0u));
;             const int r1 = __builtin_amdgcn_mbcnt_hi((unsigned)(m1 >> 32), __builtin_amdgcn_mbcnt_lo((unsigned)m1, 0u));
;             if (p0 == p) SORT[tl * 128 + off + r0] = e0;
;             if (p1 == p) SORT[tl * 128 + off + c0 + r1] = e1;
;             if (lane == 0) OFFS[tl * 17 + p] = off;
;             off += c0 + c1;
;         }
;         if (lane == 0) OFFS[tl * 17 + 16] = off;
;     }
	v_cmp_le_u32_e64 s[38:39], v193, v206
	v_cmp_le_u32_e64 s[40:41], v194, v206
	v_cmp_le_u32_e64 s[42:43], v195, v206
	v_cmp_le_u32_e64 s[44:45], v196, v206
	v_cmp_le_u32_e64 s[64:65], v197, v206
	v_cmp_le_u32_e64 s[66:67], v198, v206
	v_cmp_le_u32_e64 s[94:95], v199, v206
	v_addc_co_u32_e64 v223, s[92:93], 0, v223, s[38:39]
	v_addc_co_u32_e64 v223, s[92:93], 0, v223, s[40:41]
	v_addc_co_u32_e64 v223, s[92:93], 0, v223, s[42:43]
	v_addc_co_u32_e64 v223, s[92:93], 0, v223, s[44:45]
	v_addc_co_u32_e64 v223, s[92:93], 0, v223, s[64:65]
	v_addc_co_u32_e64 v223, s[92:93], 0, v223, s[66:67]
	v_addc_co_u32_e64 v223, s[92:93], 0, v223, s[94:95]
	v_lshlrev_b32_e32 v223, 2, v223
	ds_bpermute_b32 v216, v223, v205
	v_add_u32_e32 v207, 2, v208
	v_lshl_add_u32 v206, v207, 5, s3
	ds_read_b128 v[192:195], v206
	ds_read_b128 v[196:199], v206 offset:16
	v_lshlrev_b32_e32 v206, 2, v222
	v_lshlrev_b32_e32 v223, 3, v207
	s_waitcnt lgkmcnt(0)
	v_cmp_le_u32_e64 s[38:39], v193, v206
	v_cmp_le_u32_e64 s[40:41], v194, v206
	v_cmp_le_u32_e64 s[42:43], v195, v206
	v_cmp_le_u32_e64 s[44:45], v196, v206
	v_cmp_le_u32_e64 s[64:65], v197, v206
	v_cmp_le_u32_e64 s[66:67], v198, v206
	v_cmp_le_u32_e64 s[94:95], v199, v206
	v_addc_co_u32_e64 v223, s[92:93], 0, v223, s[38:39]
	v_addc_co_u32_e64 v223, s[92:93], 0, v223, s[40:41]
	v_addc_co_u32_e64 v223, s[92:93], 0, v223, s[42:43]
	v_addc_co_u32_e64 v223, s[92:93], 0, v223, s[44:45]
	v_addc_co_u32_e64 v223, s[92:93], 0, v223, s[64:65]
	v_addc_co_u32_e64 v223, s[92:93], 0, v223, s[66:67]
	v_addc_co_u32_e64 v223, s[92:93], 0, v223, s[94:95]
	v_lshlrev_b32_e32 v223, 2, v223
	ds_bpermute_b32 v217, v223, v205
	v_add_u32_e32 v207, 4, v208
	v_lshl_add_u32 v206, v207, 5, s3
	ds_read_b128 v[192:195], v206
	ds_read_b128 v[196:199], v206 offset:16
	v_lshlrev_b32_e32 v206, 2, v222
	v_lshlrev_b32_e32 v223, 3, v207
	s_waitcnt lgkmcnt(0)
	v_cmp_le_u32_e64 s[38:39], v193, v206
	v_cmp_le_u32_e64 s[40:41], v194, v206
	v_cmp_le_u32_e64 s[42:43], v195, v206
	v_cmp_le_u32_e64 s[44:45], v196, v206
	v_cmp_le_u32_e64 s[64:65], v197, v206
	v_cmp_le_u32_e64 s[66:67], v198, v206
	v_cmp_le_u32_e64 s[94:95], v199, v206
	v_addc_co_u32_e64 v223, s[92:93], 0, v223, s[38:39]
	v_addc_co_u32_e64 v223, s[92:93], 0, v223, s[40:41]
	v_addc_co_u32_e64 v223, s[92:93], 0, v223, s[42:43]
	v_addc_co_u32_e64 v223, s[92:93], 0, v223, s[44:45]
	v_addc_co_u32_e64 v223, s[92:93], 0, v223, s[64:65]
	v_addc_co_u32_e64 v223, s[92:93], 0, v223, s[66:67]
	v_addc_co_u32_e64 v223, s[92:93], 0, v223, s[94:95]
	v_lshlrev_b32_e32 v223, 2, v223
	ds_bpermute_b32 v218, v223, v205
	v_add_u32_e32 v207, 6, v208
	v_lshl_add_u32 v206, v207, 5, s3
	ds_read_b128 v[192:195], v206
	ds_read_b128 v[196:199], v206 offset:16
	v_lshlrev_b32_e32 v206, 2, v222
	v_lshlrev_b32_e32 v223, 3, v207
	s_waitcnt lgkmcnt(0)
	v_cmp_le_u32_e64 s[38:39], v193, v206
	v_cmp_le_u32_e64 s[40:41], v194, v206
	v_cmp_le_u32_e64 s[42:43], v195, v206
	v_cmp_le_u32_e64 s[44:45], v196, v206
	v_cmp_le_u32_e64 s[64:65], v197, v206
	v_cmp_le_u32_e64 s[66:67], v198, v206
	v_cmp_le_u32_e64 s[94:95], v199, v206
	v_addc_co_u32_e64 v223, s[92:93], 0, v223, s[38:39]
	v_addc_co_u32_e64 v223, s[92:93], 0, v223, s[40:41]
	v_addc_co_u32_e64 v223, s[92:93], 0, v223, s[42:43]
	v_addc_co_u32_e64 v223, s[92:93], 0, v223, s[44:45]
	v_addc_co_u32_e64 v223, s[92:93], 0, v223, s[64:65]
	v_addc_co_u32_e64 v223, s[92:93], 0, v223, s[66:67]
	v_addc_co_u32_e64 v223, s[92:93], 0, v223, s[94:95]
	v_lshlrev_b32_e32 v223, 2, v223
	ds_bpermute_b32 v219, v223, v205
	s_waitcnt lgkmcnt(0)
	v_add_u32_e32 v216, v216, v222
	v_add_u32_e32 v217, v217, v222
	v_add_u32_e32 v218, v218, v222
	v_add_u32_e32 v219, v219, v222
	v_lshlrev_b32_e32 v206, 3, v152
	buffer_load_dwordx2 v[192:193], v206, s[24:27], 0 offen
	v_lshlrev_b32_e32 v206, 3, v154
	buffer_load_dwordx2 v[194:195], v206, s[24:27], 0 offen
	v_lshlrev_b32_e32 v206, 3, v156
	buffer_load_dwordx2 v[196:197], v206, s[24:27], 0 offen
	v_lshlrev_b32_e32 v206, 3, v158
	buffer_load_dwordx2 v[198:199], v206, s[24:27], 0 offen
	v_lshlrev_b32_e32 v160, 2, v160
	ds_bpermute_b32 v160, v160, v202
	v_lshlrev_b32_e32 v161, 2, v161
	ds_bpermute_b32 v161, v161, v202
	v_lshlrev_b32_e32 v162, 2, v162
	v_add_u32_e32 v162, 32, v162
	ds_bpermute_b32 v162, v162, v202
	v_lshlrev_b32_e32 v163, 2, v163
	v_add_u32_e32 v163, 32, v163
	ds_bpermute_b32 v163, v163, v202
	v_lshlrev_b32_e32 v164, 2, v164
	v_add_u32_e32 v164, 64, v164
	ds_bpermute_b32 v164, v164, v202
	v_lshlrev_b32_e32 v165, 2, v165
	v_add_u32_e32 v165, 64, v165
	ds_bpermute_b32 v165, v165, v202
	v_lshlrev_b32_e32 v166, 2, v166
	v_add_u32_e32 v166, 96, v166
	ds_bpermute_b32 v166, v166, v202
	v_lshlrev_b32_e32 v167, 2, v167
	v_add_u32_e32 v167, 96, v167
	ds_bpermute_b32 v167, v167, v202
	v_lshlrev_b32_e32 v168, 2, v168
	v_add_u32_e32 v168, 128, v168
	ds_bpermute_b32 v168, v168, v202
	v_lshlrev_b32_e32 v169, 2, v169
	v_add_u32_e32 v169, 128, v169
	ds_bpermute_b32 v169, v169, v202
	v_lshlrev_b32_e32 v170, 2, v170
	v_add_u32_e32 v170, 160, v170
	ds_bpermute_b32 v170, v170, v202
	v_lshlrev_b32_e32 v171, 2, v171
	v_add_u32_e32 v171, 160, v171
	ds_bpermute_b32 v171, v171, v202
	v_lshlrev_b32_e32 v172, 2, v172
	v_add_u32_e32 v172, 192, v172
	ds_bpermute_b32 v172, v172, v202
	v_lshlrev_b32_e32 v173, 2, v173
	v_add_u32_e32 v173, 192, v173
	ds_bpermute_b32 v173, v173, v202
	v_lshlrev_b32_e32 v174, 2, v174
	v_add_u32_e32 v174, 224, v174
	ds_bpermute_b32 v174, v174, v202
	v_lshlrev_b32_e32 v175, 2, v175
	v_add_u32_e32 v175, 224, v175
	ds_bpermute_b32 v175, v175, v202
	s_waitcnt lgkmcnt(0)
; __device__ __forceinline__ void peer_tile(const Args& A, LAS unsigned char* lds, int tile) {
;     ...
;     for (int ti = 0; ti < 8; ++ti) {
;         const int tl = 8 * w + ti;
;         const u32x2 e0 = SEL[tl * 128 + lane], e1 = SEL[tl * 128 + 64 + lane];
;         const int p0 = (int)(e0.x >> 10), p1 = (int)(e1.x >> 10);
;         int off = 0;
;         for (int p = 0; p < 16; ++p) {
;             const unsigned long long m0 = __ballot(p0 == p), m1 = __ballot(p1 == p);
;             const int c0 = __popcll(m0), c1 = __popcll(m1);
;             const int r0 = __builtin_amdgcn_mbcnt_hi((unsigned)(m0 >> 32), __builtin_amdgcn_mbcnt_lo((unsigned)m0, 0u));
;             const int r1 = __builtin_amdgcn_mbcnt_hi((unsigned)(m1 >> 32), __builtin_amdgcn_mbcnt_lo((unsigned)m1, 0u));
;             if (p0 == p) SORT[tl * 128 + off + r0] = e0;
;             if (p1 == p) SORT[tl * 128 + off + c0 + r1] = e1;
;             if (lane == 0) OFFS[tl * 17 + p] = off;
;             off += c0 + c1;
;         }
;         if (lane == 0) OFFS[tl * 17 + 16] = off;
;     }
	v_add_u32_e32 v176, v176, v160
	v_lshrrev_b32_e32 v160, 2, v176
	v_and_b32_e32 v176, 3, v176
	v_lshlrev_b32_e32 v160, 2, v160
	ds_bpermute_b32 v160, v160, v216
	v_add_u32_e32 v177, v177, v161
	v_lshrrev_b32_e32 v161, 2, v177
	v_and_b32_e32 v177, 3, v177
	v_lshlrev_b32_e32 v161, 2, v161
	ds_bpermute_b32 v161, v161, v216
	v_add_u32_e32 v178, v178, v162
	v_lshrrev_b32_e32 v162, 2, v178
	v_and_b32_e32 v178, 3, v178
	v_lshlrev_b32_e32 v162, 2, v162
	v_add_u32_e32 v162, 128, v162
	ds_bpermute_b32 v162, v162, v216
	v_add_u32_e32 v179, v179, v163
	v_lshrrev_b32_e32 v163, 2, v179
	v_and_b32_e32 v179, 3, v179
	v_lshlrev_b32_e32 v163, 2, v163
	v_add_u32_e32 v163, 128, v163
	ds_bpermute_b32 v163, v163, v216
	v_add_u32_e32 v180, v180, v164
	v_lshrrev_b32_e32 v164, 2, v180
	v_and_b32_e32 v180, 3, v180
	v_lshlrev_b32_e32 v164, 2, v164
	ds_bpermute_b32 v164, v164, v217
	v_add_u32_e32 v181, v181, v165
	v_lshrrev_b32_e32 v165, 2, v181
	v_and_b32_e32 v181, 3, v181
	v_lshlrev_b32_e32 v165, 2, v165
	ds_bpermute_b32 v165, v165, v217
	v_add_u32_e32 v182, v182, v166
	v_lshrrev_b32_e32 v166, 2, v182
	v_and_b32_e32 v182, 3, v182
	v_lshlrev_b32_e32 v166, 2, v166
	v_add_u32_e32 v166, 128, v166
	ds_bpermute_b32 v166, v166, v217
	v_add_u32_e32 v183, v183, v167
	v_lshrrev_b32_e32 v167, 2, v183
	v_and_b32_e32 v183, 3, v183
	v_lshlrev_b32_e32 v167, 2, v167
	v_add_u32_e32 v167, 128, v167
	ds_bpermute_b32 v167, v167, v217
	v_add_u32_e32 v184, v184, v168
	v_lshrrev_b32_e32 v168, 2, v184
	v_and_b32_e32 v184, 3, v184
	v_lshlrev_b32_e32 v168, 2, v168
	ds_bpermute_b32 v168, v168, v218
	v_add_u32_e32 v185, v185, v169
	v_lshrrev_b32_e32 v169, 2, v185
	v_and_b32_e32 v185, 3, v185
	v_lshlrev_b32_e32 v169, 2, v169
	ds_bpermute_b32 v169, v169, v218
	v_add_u32_e32 v186, v186, v170
	v_lshrrev_b32_e32 v170, 2, v186
	v_and_b32_e32 v186, 3, v186
	v_lshlrev_b32_e32 v170, 2, v170
	v_add_u32_e32 v170, 128, v170
	ds_bpermute_b32 v170, v170, v218
	v_add_u32_e32 v187, v187, v171
	v_lshrrev_b32_e32 v171, 2, v187
	v_and_b32_e32 v187, 3, v187
	v_lshlrev_b32_e32 v171, 2, v171
	v_add_u32_e32 v171, 128, v171
	ds_bpermute_b32 v171, v171, v218
	v_add_u32_e32 v188, v188, v172
	v_lshrrev_b32_e32 v172, 2, v188
	v_and_b32_e32 v188, 3, v188
	v_lshlrev_b32_e32 v172, 2, v172
	ds_bpermute_b32 v172, v172, v219
	v_add_u32_e32 v189, v189, v173
	v_lshrrev_b32_e32 v173, 2, v189
	v_and_b32_e32 v189, 3, v189
	v_lshlrev_b32_e32 v173, 2, v173
	ds_bpermute_b32 v173, v173, v219
	v_add_u32_e32 v190, v190, v174
	v_lshrrev_b32_e32 v174, 2, v190
	v_and_b32_e32 v190, 3, v190
	v_lshlrev_b32_e32 v174, 2, v174
	v_add_u32_e32 v174, 128, v174
	ds_bpermute_b32 v174, v174, v219
	v_add_u32_e32 v191, v191, v175
	v_lshrrev_b32_e32 v175, 2, v191
	v_and_b32_e32 v191, 3, v191
	v_lshlrev_b32_e32 v175, 2, v175
	v_add_u32_e32 v175, 128, v175
	ds_bpermute_b32 v175, v175, v219
	s_waitcnt lgkmcnt(0)
	v_lshl_add_u32 v160, v160, 4, s22
	v_lshl_add_u32 v160, v176, 2, v160
	ds_write_b32 v160, v128
	ds_write_b32 v160, v129 offset:4992
	v_lshl_add_u32 v161, v161, 4, s22
	v_lshl_add_u32 v161, v177, 2, v161
	ds_write_b32 v161, v130
	ds_write_b32 v161, v131 offset:4992
	v_lshl_add_u32 v162, v162, 4, s22
	v_lshl_add_u32 v162, v178, 2, v162
	ds_write_b32 v162, v132
	ds_write_b32 v162, v133 offset:4992
	v_lshl_add_u32 v163, v163, 4, s22
	v_lshl_add_u32 v163, v179, 2, v163
	ds_write_b32 v163, v134
	ds_write_b32 v163, v135 offset:4992
	v_lshl_add_u32 v164, v164, 4, s22
	v_lshl_add_u32 v164, v180, 2, v164
	ds_write_b32 v164, v136
	ds_write_b32 v164, v137 offset:4992
	v_lshl_add_u32 v165, v165, 4, s22
	v_lshl_add_u32 v165, v181, 2, v165
	ds_write_b32 v165, v138
	ds_write_b32 v165, v139 offset:4992
	v_lshl_add_u32 v166, v166, 4, s22
	v_lshl_add_u32 v166, v182, 2, v166
	ds_write_b32 v166, v140
	ds_write_b32 v166, v141 offset:4992
	v_lshl_add_u32 v167, v167, 4, s22
	v_lshl_add_u32 v167, v183, 2, v167
	ds_write_b32 v167, v142
	ds_write_b32 v167, v143 offset:4992
	v_lshl_add_u32 v168, v168, 4, s22
	v_lshl_add_u32 v168, v184, 2, v168
	ds_write_b32 v168, v144
	ds_write_b32 v168, v145 offset:4992
	v_lshl_add_u32 v169, v169, 4, s22
	v_lshl_add_u32 v169, v185, 2, v169
	ds_write_b32 v169, v146
	ds_write_b32 v169, v147 offset:4992
	v_lshl_add_u32 v170, v170, 4, s22
	v_lshl_add_u32 v170, v186, 2, v170
	ds_write_b32 v170, v148
	ds_write_b32 v170, v149 offset:4992
	v_lshl_add_u32 v171, v171, 4, s22
	v_lshl_add_u32 v171, v187, 2, v171
	ds_write_b32 v171, v150
	ds_write_b32 v171, v151 offset:4992
	v_lshl_add_u32 v172, v172, 4, s22
	v_lshl_add_u32 v172, v188, 2, v172
	ds_write_b32 v172, v152
	ds_write_b32 v172, v153 offset:4992
	v_lshl_add_u32 v173, v173, 4, s22
	v_lshl_add_u32 v173, v189, 2, v173
	ds_write_b32 v173, v154
	ds_write_b32 v173, v155 offset:4992
	v_lshl_add_u32 v174, v174, 4, s22
	v_lshl_add_u32 v174, v190, 2, v174
	ds_write_b32 v174, v156
	ds_write_b32 v174, v157 offset:4992
	v_lshl_add_u32 v175, v175, 4, s22
	v_lshl_add_u32 v175, v191, 2, v175
	ds_write_b32 v175, v158
	ds_write_b32 v175, v159 offset:4992
	s_waitcnt vmcnt(0)
; #define IT_ADVANCE() do { it_j += 4; while (it_j >= it_end) { if (it_done) break; ++it_tk; if (it_tk == 4) { it_tk = 0; ++it_p; if (it_p == 16) { it_done = true; it_p = 15; it_j = 0; it_end = 1; break; } } \
;             it_j = __builtin_amdgcn_readfirstlane(OFFS[(tb + it_tk) * 17 + it_p]); it_end = __builtin_amdgcn_readfirstlane(OFFS[(tb + it_tk) * 17 + it_p + 1]); } } while (0)
; __device__ __forceinline__ void peer_tile(const Args& A, LAS unsigned char* lds, int tile) {
;     ...
;         int it_p = 0, it_tk = -1, it_j = 0, it_end = 0; bool it_done = false;
;     ...
;         u32x4 uA[4], vA[4], uB[4], vB[4]; float cgA = 0.f, suA = 0.f, svA = 0.f, cgB = 0.f, suB = 0.f, svB = 0.f;
; #pragma unroll
;         for (int k = 0; k < 4; ++k) { uA[k] = (u32x4){0u, 0u, 0u, 0u}; vA[k] = uA[k]; uB[k] = uA[k]; vB[k] = uA[k]; }
;         IT_ADVANCE();
;         LOAD_SET(uA, vA, cgA, suA, svA);
	v_add_u32_e32 v160, s85, v160
	ds_write_b32 v160, v224
	ds_write_b32 v160, v225 offset:4096
	v_add_u32_e32 v161, s85, v161
	ds_write_b32 v161, v226
	ds_write_b32 v161, v227 offset:4096
	v_add_u32_e32 v162, s85, v162
	ds_write_b32 v162, v228
	ds_write_b32 v162, v229 offset:4096
	v_add_u32_e32 v163, s85, v163
	ds_write_b32 v163, v230
	ds_write_b32 v163, v231 offset:4096
	v_add_u32_e32 v164, s85, v164
	ds_write_b32 v164, v232
	ds_write_b32 v164, v233 offset:4096
	v_add_u32_e32 v165, s85, v165
	ds_write_b32 v165, v234
	ds_write_b32 v165, v235 offset:4096
	v_add_u32_e32 v166, s85, v166
	ds_write_b32 v166, v236
	ds_write_b32 v166, v237 offset:4096
	v_add_u32_e32 v167, s85, v167
	ds_write_b32 v167, v238
	ds_write_b32 v167, v239 offset:4096
	v_add_u32_e32 v168, s85, v168
	ds_write_b32 v168, v248
	ds_write_b32 v168, v249 offset:4096
	v_add_u32_e32 v169, s85, v169
	ds_write_b32 v169, v250
	ds_write_b32 v169, v251 offset:4096
	v_add_u32_e32 v170, s85, v170
	ds_write_b32 v170, v252
	ds_write_b32 v170, v253 offset:4096
	v_add_u32_e32 v171, s85, v171
	ds_write_b32 v171, v254
	ds_write_b32 v171, v255 offset:4096
	v_add_u32_e32 v172, s85, v172
	ds_write_b32 v172, v192
	ds_write_b32 v172, v193 offset:4096
	v_add_u32_e32 v173, s85, v173
	ds_write_b32 v173, v194
	ds_write_b32 v173, v195 offset:4096
	v_add_u32_e32 v174, s85, v174
	ds_write_b32 v174, v196
	ds_write_b32 v174, v197 offset:4096
	v_add_u32_e32 v175, s85, v175
	ds_write_b32 v175, v198
	ds_write_b32 v175, v199 offset:4096
	v_mov_b32_e32 v206, 0x7fffffff
	ds_write_b32 v221, v206 offset:4224
	ds_write_b32 v221, v206 offset:4480
	ds_write_b32 v221, v206 offset:4736
	s_mov_b32 s91, 256
	s_add_i32 s20, s91, 3
	s_and_b32 s20, s20, -4
	s_mov_b32 s24, s8
	s_and_b32 s25, s9, 0xffff
	s_mov_b32 s26, 0x20000
	s_mov_b32 s27, 0x00027000
	s_mov_b32 s28, s52
	s_and_b32 s29, s53, 0xffff
	s_mov_b32 s30, 0x20000
	s_mov_b32 s31, 0x00027000
	s_waitcnt vmcnt(0) lgkmcnt(0)
	v_mov_b32_e32 v213, s22
	v_mov_b32_e32 v233, v240
	v_mov_b32_e32 v235, v240
	v_mov_b32_e32 v237, v240
	v_mov_b32_e32 v239, v240
	ds_read_b32 v232, v213 offset:0
	ds_read_b32 v234, v213 offset:4
	ds_read_b32 v236, v213 offset:8
	ds_read_b32 v238, v213 offset:12
	s_waitcnt lgkmcnt(0)
	buffer_load_dwordx4 v[128:131], v[232:233], s[56:59], 0 idxen offen
	buffer_load_dwordx4 v[132:135], v[234:235], s[56:59], 0 idxen offen
	buffer_load_dwordx4 v[136:139], v[236:237], s[56:59], 0 idxen offen
	buffer_load_dwordx4 v[140:143], v[238:239], s[56:59], 0 idxen offen
	ds_read_b32 v232, v213 offset:16
	ds_read_b32 v234, v213 offset:20
	ds_read_b32 v236, v213 offset:24
	ds_read_b32 v238, v213 offset:28
	s_waitcnt lgkmcnt(0)
	buffer_load_dwordx4 v[144:147], v[232:233], s[56:59], 0 idxen offen
	buffer_load_dwordx4 v[148:151], v[234:235], s[56:59], 0 idxen offen
	buffer_load_dwordx4 v[152:155], v[236:237], s[56:59], 0 idxen offen
	buffer_load_dwordx4 v[156:159], v[238:239], s[56:59], 0 idxen offen
	ds_read_b32 v232, v213 offset:32
	ds_read_b32 v234, v213 offset:36
	ds_read_b32 v236, v213 offset:40
	ds_read_b32 v238, v213 offset:44
	s_waitcnt lgkmcnt(0)
	buffer_load_dwordx4 v[160:163], v[232:233], s[56:59], 0 idxen offen
	buffer_load_dwordx4 v[164:167], v[234:235], s[56:59], 0 idxen offen
	buffer_load_dwordx4 v[168:171], v[236:237], s[56:59], 0 idxen offen
	buffer_load_dwordx4 v[172:175], v[238:239], s[56:59], 0 idxen offen
	ds_read_b32 v232, v213 offset:48
	ds_read_b32 v234, v213 offset:52
	ds_read_b32 v236, v213 offset:56
	ds_read_b32 v238, v213 offset:60
	s_mov_b32 s21, 0
	s_mov_b32 s89, -1
	s_mov_b32 s86, 0
	v_lshrrev_b32_e32 v208, 6, v240
	v_and_b32_e32 v208, 3, v208
	v_lshrrev_b32_e32 v209, 1, v208
	v_lshlrev_b32_e32 v208, 1, v208
	v_and_b32_e32 v208, 2, v208
	v_or_b32_e32 v208, v208, v209
	v_lshlrev_b32_e32 v208, 2, v208
	v_add3_u32 v211, v208, v247, s22
	v_add_u32_e32 v250, s85, v211
	ds_read_b32 v252, v250
	ds_read_b32 v253, v250 offset:4096
	ds_read_b32 v249, v211 offset:4992
	s_branch .LU_sw0
